# IEEE f32 division expansions in epilogues (silu/sigmoid/tanh) replaced by v_rcp_f32+v_mul_f32 (f32, result rounded to bf16 afterwards); scan consumer prefetch distance 2
# speedup vs baseline: 1.0579x; 1.0255x over previous
; #define EPI_ROWS(...) _Pragma("unroll") for (int ai = 0; ai < 2; ++ai) _Pragma("unroll") for (int m = 0; m < 4; ++m) { const int row = u.pm * 256 + ai * 128 + wr * 64 + m * 16 + fr; __VA_ARGS__ }
; DI void st16_wt(void* p, u32x4 v) { asm volatile("global_store_dwordx4 %0, %1, off sc0 sc1\n\ts_nop 1" :: "v"(p), "v"(v) : "memory"); }
; DI u32x4 pack8(f32x4 a, f32x4 b) { u32x4 w; w.x = pk2(a[0], a[1]); w.y = pk2(a[2], a[3]); w.z = pk2(b[0], b[1]); w.w = pk2(b[2], b[3]); return w; }
; DI float siluf_(float x) { return x / (1.f + __expf(-x)); }
;     DI void operator()(const Acc& acc, const Unit& u, int wr, int wc, int fr, int fq) const {
;         const int c0 = u.pn * 128 + wc * 32 + 8 * fq;
;         EPI_ROWS( f32x4 a, b;
;             _Pragma("unroll") for (int e = 0; e < 4; ++e) { a[e] = siluf_(acc[ai][0][m][0][e]) * acc[ai][1][m][0][e]; b[e] = siluf_(acc[ai][0][m][1][e]) * acc[ai][1][m][1][e]; }
;             st16_wt(H + (size_t)row * DFF + c0, pack8(a, b)); )
;     }
.LBB0_380:
	v_mov_b32_e32 v150, v144
	v_mov_b32_e32 v151, v145
	s_lshl_b32 s15, s51, 7
	s_or_b32 s15, s15, s41
	v_lshl_add_u32 v152, v151, 3, s15
	v_mul_f32_e32 v151, 0xbfb8aa3b, v124
	v_exp_f32_e32 v154, v151
	v_mul_f32_e32 v151, 0xbfb8aa3b, v125
	v_exp_f32_e32 v155, v151
	v_mul_f32_e32 v156, 0xbfb8aa3b, v116
	v_exp_f32_e32 v156, v156
	s_lshl_b32 s15, s22, 8
	v_pk_add_f32 v[154:155], v[154:155], 1.0 op_sel_hi:[1,0]
	s_add_i32 s15, s15, s40
	v_add_u32_e32 v150, s15, v150
	v_ashrrev_i32_e32 v153, 31, v152
	v_mul_f32_e32 v157, 0xbfb8aa3b, v117
	v_rcp_f32_e32 v151, v155
	s_nop 0
	v_mul_f32_e32 v125, v125, v151
	v_exp_f32_e32 v157, v157
	s_nop 0
	v_pk_add_f32 v[156:157], v[156:157], 1.0 op_sel_hi:[1,0]
	v_rcp_f32_e32 v151, v154
	s_nop 0
	v_mul_f32_e32 v124, v124, v151
	v_pk_mul_f32 v[120:121], v[124:125], v[120:121]
	v_rcp_f32_e32 v124, v157
	s_nop 0
	v_mul_f32_e32 v117, v117, v124
	v_mul_f32_e32 v124, 0xbfb8aa3b, v126
	v_mul_f32_e32 v125, 0xbfb8aa3b, v127
	v_exp_f32_e32 v124, v124
	v_exp_f32_e32 v125, v125
	v_rcp_f32_e32 v151, v156
	s_nop 0
	v_mul_f32_e32 v116, v116, v151
	v_pk_mul_f32 v[154:155], v[116:117], v[112:113]
	v_pk_add_f32 v[124:125], v[124:125], 1.0 op_sel_hi:[1,0]
	v_mul_f32_e32 v112, 0xbfb8aa3b, v118
	v_exp_f32_e32 v112, v112
	v_rcp_f32_e32 v113, v125
	s_nop 0
	v_mul_f32_e32 v117, v127, v113
	v_mul_f32_e32 v113, 0xbfb8aa3b, v119
	v_exp_f32_e32 v113, v113
	s_nop 0
	v_pk_add_f32 v[112:113], v[112:113], 1.0 op_sel_hi:[1,0]
	v_rcp_f32_e32 v116, v124
	s_nop 0
	v_mul_f32_e32 v116, v126, v116
	v_pk_mul_f32 v[122:123], v[116:117], v[122:123]
	v_rcp_f32_e32 v116, v113
	s_nop 0
	v_mul_f32_e32 v113, v119, v116
	v_rcp_f32_e32 v116, v112
	s_nop 0
	v_mul_f32_e32 v112, v118, v116
	v_pk_mul_f32 v[124:125], v[112:113], v[114:115]
	v_mov_b64_e32 v[112:113], s[8:9]
	v_mad_i64_i32 v[116:117], s[24:25], v150, s50, v[112:113]
	v_lshlrev_b64 v[114:115], 1, v[152:153]
	v_lshl_add_u64 v[126:127], v[116:117], 0, v[114:115]
	v_mul_f32_e32 v117, 0xbfb8aa3b, v108
	v_cvt_pk_bf16_f32 v116, v120, v121
	v_exp_f32_e32 v120, v117
	v_mul_f32_e32 v117, 0xbfb8aa3b, v109
	v_exp_f32_e32 v121, v117
	v_cvt_pk_bf16_f32 v117, v122, v123
	v_cvt_pk_bf16_f32 v118, v154, v155
	v_cvt_pk_bf16_f32 v119, v124, v125
	v_pk_add_f32 v[120:121], v[120:121], 1.0 op_sel_hi:[1,0]
	global_store_dwordx4 v[126:127], v[116:119], off sc0 sc1
	s_nop 1
	v_mul_f32_e32 v116, 0xbfb8aa3b, v100
	v_exp_f32_e32 v116, v116
	v_rcp_f32_e32 v117, v121
	s_nop 0
	v_mul_f32_e32 v109, v109, v117
	v_mul_f32_e32 v117, 0xbfb8aa3b, v101
	v_exp_f32_e32 v117, v117
	s_nop 0
	v_pk_add_f32 v[116:117], v[116:117], 1.0 op_sel_hi:[1,0]
	v_rcp_f32_e32 v118, v120
	s_nop 0
	v_mul_f32_e32 v108, v108, v118
	v_pk_mul_f32 v[104:105], v[108:109], v[104:105]
	v_rcp_f32_e32 v108, v117
	s_nop 0
	v_mul_f32_e32 v101, v101, v108
	v_mul_f32_e32 v108, 0xbfb8aa3b, v110
	v_mul_f32_e32 v109, 0xbfb8aa3b, v111
	v_exp_f32_e32 v108, v108
	v_exp_f32_e32 v109, v109
	v_rcp_f32_e32 v117, v116
	s_nop 0
	v_mul_f32_e32 v100, v100, v117
	v_pk_mul_f32 v[100:101], v[100:101], v[96:97]
	v_pk_add_f32 v[108:109], v[108:109], 1.0 op_sel_hi:[1,0]
	v_mul_f32_e32 v96, 0xbfb8aa3b, v102
	v_exp_f32_e32 v96, v96
	v_rcp_f32_e32 v97, v109
	s_nop 0
	v_mul_f32_e32 v109, v111, v97
	v_mul_f32_e32 v97, 0xbfb8aa3b, v103
	v_exp_f32_e32 v97, v97
	s_nop 0
	v_pk_add_f32 v[96:97], v[96:97], 1.0 op_sel_hi:[1,0]
	v_rcp_f32_e32 v111, v108
	s_nop 0
	v_mul_f32_e32 v108, v110, v111
	v_pk_mul_f32 v[106:107], v[108:109], v[106:107]
	v_rcp_f32_e32 v108, v97
	s_nop 0
	v_mul_f32_e32 v97, v103, v108
	v_rcp_f32_e32 v103, v96
	s_nop 0
	v_mul_f32_e32 v96, v102, v103
	v_pk_mul_f32 v[102:103], v[96:97], v[98:99]
	v_add_u32_e32 v96, 16, v150
	v_mad_i64_i32 v[96:97], s[24:25], v96, s50, v[112:113]
	v_lshl_add_u64 v[108:109], v[96:97], 0, v[114:115]
	v_mul_f32_e32 v97, 0xbfb8aa3b, v92
	v_cvt_pk_bf16_f32 v96, v104, v105
	v_exp_f32_e32 v104, v97
	v_mul_f32_e32 v97, 0xbfb8aa3b, v93
	v_exp_f32_e32 v105, v97
	v_cvt_pk_bf16_f32 v98, v100, v101
	v_cvt_pk_bf16_f32 v99, v102, v103
	v_cvt_pk_bf16_f32 v97, v106, v107
	v_pk_add_f32 v[100:101], v[104:105], 1.0 op_sel_hi:[1,0]
	global_store_dwordx4 v[108:109], v[96:99], off sc0 sc1
	s_nop 1
	v_mul_f32_e32 v96, 0xbfb8aa3b, v84
	v_exp_f32_e32 v96, v96
	v_rcp_f32_e32 v97, v101
	s_nop 0
	v_mul_f32_e32 v93, v93, v97
	v_mul_f32_e32 v97, 0xbfb8aa3b, v85
	v_exp_f32_e32 v97, v97
	s_nop 0
	v_pk_add_f32 v[96:97], v[96:97], 1.0 op_sel_hi:[1,0]
	v_rcp_f32_e32 v98, v100
	s_nop 0
	v_mul_f32_e32 v92, v92, v98
	v_pk_mul_f32 v[88:89], v[92:93], v[88:89]
	v_rcp_f32_e32 v92, v97
	s_nop 0
	v_mul_f32_e32 v85, v85, v92
	v_mul_f32_e32 v92, 0xbfb8aa3b, v94
	v_mul_f32_e32 v93, 0xbfb8aa3b, v95
	v_exp_f32_e32 v92, v92
	v_exp_f32_e32 v93, v93
	v_rcp_f32_e32 v97, v96
	s_nop 0
	v_mul_f32_e32 v84, v84, v97
	v_pk_mul_f32 v[84:85], v[84:85], v[80:81]
	v_pk_add_f32 v[92:93], v[92:93], 1.0 op_sel_hi:[1,0]
	v_mul_f32_e32 v80, 0xbfb8aa3b, v86
	v_exp_f32_e32 v80, v80
	v_rcp_f32_e32 v81, v93
	s_nop 0
	v_mul_f32_e32 v93, v95, v81
	v_mul_f32_e32 v81, 0xbfb8aa3b, v87
	v_exp_f32_e32 v81, v81
	s_nop 0
	v_pk_add_f32 v[80:81], v[80:81], 1.0 op_sel_hi:[1,0]
	v_rcp_f32_e32 v95, v92
	s_nop 0
	v_mul_f32_e32 v92, v94, v95
	v_pk_mul_f32 v[90:91], v[92:93], v[90:91]
	v_rcp_f32_e32 v92, v81
	s_nop 0
	v_mul_f32_e32 v81, v87, v92
	v_rcp_f32_e32 v87, v80
	s_nop 0
	v_mul_f32_e32 v80, v86, v87
	v_pk_mul_f32 v[86:87], v[80:81], v[82:83]
	v_add_u32_e32 v80, 32, v150
	v_mad_i64_i32 v[80:81], s[24:25], v80, s50, v[112:113]
	v_lshl_add_u64 v[92:93], v[80:81], 0, v[114:115]
	v_mul_f32_e32 v81, 0xbfb8aa3b, v76
	v_cvt_pk_bf16_f32 v80, v88, v89
	v_exp_f32_e32 v88, v81
	v_mul_f32_e32 v81, 0xbfb8aa3b, v77
	v_exp_f32_e32 v89, v81
; #define EPI_ROWS(...) _Pragma("unroll") for (int ai = 0; ai < 2; ++ai) _Pragma("unroll") for (int m = 0; m < 4; ++m) { const int row = u.pm * 256 + ai * 128 + wr * 64 + m * 16 + fr; __VA_ARGS__ }
; DI void st16_wt(void* p, u32x4 v) { asm volatile("global_store_dwordx4 %0, %1, off sc0 sc1\n\ts_nop 1" :: "v"(p), "v"(v) : "memory"); }
; DI u32x4 pack8(f32x4 a, f32x4 b) { u32x4 w; w.x = pk2(a[0], a[1]); w.y = pk2(a[2], a[3]); w.z = pk2(b[0], b[1]); w.w = pk2(b[2], b[3]); return w; }
; DI float siluf_(float x) { return x / (1.f + __expf(-x)); }
;     DI void operator()(const Acc& acc, const Unit& u, int wr, int wc, int fr, int fq) const {
;     ...
;         EPI_ROWS( f32x4 a, b;
;             _Pragma("unroll") for (int e = 0; e < 4; ++e) { a[e] = siluf_(acc[ai][0][m][0][e]) * acc[ai][1][m][0][e]; b[e] = siluf_(acc[ai][0][m][1][e]) * acc[ai][1][m][1][e]; }
;             st16_wt(H + (size_t)row * DFF + c0, pack8(a, b)); )
	v_cvt_pk_bf16_f32 v82, v84, v85
	v_cvt_pk_bf16_f32 v83, v86, v87
	v_cvt_pk_bf16_f32 v81, v90, v91
	v_pk_add_f32 v[84:85], v[88:89], 1.0 op_sel_hi:[1,0]
	global_store_dwordx4 v[92:93], v[80:83], off sc0 sc1
	s_nop 1
	v_mul_f32_e32 v80, 0xbfb8aa3b, v68
	v_exp_f32_e32 v80, v80
	v_rcp_f32_e32 v81, v85
	s_nop 0
	v_mul_f32_e32 v77, v77, v81
	v_mul_f32_e32 v81, 0xbfb8aa3b, v69
	v_exp_f32_e32 v81, v81
	s_nop 0
	v_pk_add_f32 v[80:81], v[80:81], 1.0 op_sel_hi:[1,0]
	v_rcp_f32_e32 v82, v84
	s_nop 0
	v_mul_f32_e32 v76, v76, v82
	v_pk_mul_f32 v[72:73], v[76:77], v[72:73]
	v_rcp_f32_e32 v76, v81
	s_nop 0
	v_mul_f32_e32 v69, v69, v76
	v_mul_f32_e32 v76, 0xbfb8aa3b, v78
	v_mul_f32_e32 v77, 0xbfb8aa3b, v79
	v_exp_f32_e32 v76, v76
	v_exp_f32_e32 v77, v77
	v_rcp_f32_e32 v81, v80
	s_nop 0
	v_mul_f32_e32 v68, v68, v81
	v_pk_mul_f32 v[68:69], v[68:69], v[64:65]
	v_pk_add_f32 v[76:77], v[76:77], 1.0 op_sel_hi:[1,0]
	v_mul_f32_e32 v64, 0xbfb8aa3b, v70
	v_exp_f32_e32 v64, v64
	v_rcp_f32_e32 v65, v77
	s_nop 0
	v_mul_f32_e32 v77, v79, v65
	v_mul_f32_e32 v65, 0xbfb8aa3b, v71
	v_exp_f32_e32 v65, v65
	s_nop 0
	v_pk_add_f32 v[64:65], v[64:65], 1.0 op_sel_hi:[1,0]
	v_rcp_f32_e32 v79, v76
	s_nop 0
	v_mul_f32_e32 v76, v78, v79
	v_pk_mul_f32 v[74:75], v[76:77], v[74:75]
	v_rcp_f32_e32 v76, v65
	s_nop 0
	v_mul_f32_e32 v65, v71, v76
	v_rcp_f32_e32 v71, v64
	s_nop 0
	v_mul_f32_e32 v64, v70, v71
	v_pk_mul_f32 v[70:71], v[64:65], v[66:67]
	v_add_u32_e32 v64, 48, v150
	v_mad_i64_i32 v[64:65], s[24:25], v64, s50, v[112:113]
	v_mul_f32_e32 v66, 0xbfb8aa3b, v60
	v_lshl_add_u64 v[76:77], v[64:65], 0, v[114:115]
	v_cvt_pk_bf16_f32 v64, v72, v73
	v_exp_f32_e32 v72, v66
	v_mul_f32_e32 v66, 0xbfb8aa3b, v61
	v_exp_f32_e32 v73, v66
	v_cvt_pk_bf16_f32 v65, v74, v75
	v_cvt_pk_bf16_f32 v66, v68, v69
	v_cvt_pk_bf16_f32 v67, v70, v71
	global_store_dwordx4 v[76:77], v[64:67], off sc0 sc1
	s_nop 1
	v_pk_add_f32 v[64:65], v[72:73], 1.0 op_sel_hi:[1,0]
	v_mul_f32_e32 v66, 0xbfb8aa3b, v52
	v_exp_f32_e32 v66, v66
	v_add_u32_e32 v69, 0x80, v150
	v_rcp_f32_e32 v67, v65
	s_nop 0
	v_mul_f32_e32 v61, v61, v67
	v_mul_f32_e32 v67, 0xbfb8aa3b, v53
	v_exp_f32_e32 v67, v67
	s_nop 0
	v_pk_add_f32 v[66:67], v[66:67], 1.0 op_sel_hi:[1,0]
	v_rcp_f32_e32 v65, v64
	s_nop 0
	v_mul_f32_e32 v60, v60, v65
	v_pk_mul_f32 v[56:57], v[60:61], v[56:57]
	v_rcp_f32_e32 v60, v67
	s_nop 0
	v_mul_f32_e32 v53, v53, v60
	v_mul_f32_e32 v60, 0xbfb8aa3b, v62
	v_mul_f32_e32 v61, 0xbfb8aa3b, v63
	v_exp_f32_e32 v60, v60
	v_exp_f32_e32 v61, v61
	v_rcp_f32_e32 v64, v66
	s_nop 0
	v_mul_f32_e32 v52, v52, v64
	v_pk_mul_f32 v[52:53], v[52:53], v[48:49]
	v_pk_add_f32 v[60:61], v[60:61], 1.0 op_sel_hi:[1,0]
	v_mul_f32_e32 v48, 0xbfb8aa3b, v54
	v_exp_f32_e32 v48, v48
	v_rcp_f32_e32 v49, v61
	s_nop 0
	v_mul_f32_e32 v61, v63, v49
	v_mul_f32_e32 v49, 0xbfb8aa3b, v55
	v_exp_f32_e32 v49, v49
	s_nop 0
	v_pk_add_f32 v[48:49], v[48:49], 1.0 op_sel_hi:[1,0]
	v_rcp_f32_e32 v63, v60
	s_nop 0
	v_mul_f32_e32 v60, v62, v63
	v_pk_mul_f32 v[58:59], v[60:61], v[58:59]
	v_rcp_f32_e32 v60, v49
	s_nop 0
	v_mul_f32_e32 v49, v55, v60
	v_rcp_f32_e32 v55, v48
	s_nop 0
	v_mul_f32_e32 v48, v54, v55
	v_pk_mul_f32 v[54:55], v[48:49], v[50:51]
	v_mad_i64_i32 v[48:49], s[24:25], v69, s50, v[112:113]
	v_lshl_add_u64 v[60:61], v[48:49], 0, v[114:115]
	v_mul_f32_e32 v49, 0xbfb8aa3b, v44
	v_cvt_pk_bf16_f32 v48, v56, v57
	v_exp_f32_e32 v56, v49
	v_mul_f32_e32 v49, 0xbfb8aa3b, v45
	v_exp_f32_e32 v57, v49
	v_cvt_pk_bf16_f32 v50, v52, v53
	v_cvt_pk_bf16_f32 v51, v54, v55
	v_cvt_pk_bf16_f32 v49, v58, v59
	v_pk_add_f32 v[52:53], v[56:57], 1.0 op_sel_hi:[1,0]
	global_store_dwordx4 v[60:61], v[48:51], off sc0 sc1
	s_nop 1
	v_mul_f32_e32 v48, 0xbfb8aa3b, v36
	v_exp_f32_e32 v48, v48
	v_rcp_f32_e32 v49, v53
	s_nop 0
	v_mul_f32_e32 v45, v45, v49
	v_mul_f32_e32 v49, 0xbfb8aa3b, v37
	v_exp_f32_e32 v49, v49
	s_nop 0
	v_pk_add_f32 v[48:49], v[48:49], 1.0 op_sel_hi:[1,0]
	v_rcp_f32_e32 v50, v52
	s_nop 0
	v_mul_f32_e32 v44, v44, v50
	v_pk_mul_f32 v[40:41], v[44:45], v[40:41]
	v_rcp_f32_e32 v44, v49
	s_nop 0
	v_mul_f32_e32 v37, v37, v44
	v_mul_f32_e32 v44, 0xbfb8aa3b, v46
	v_mul_f32_e32 v45, 0xbfb8aa3b, v47
	v_exp_f32_e32 v44, v44
	v_exp_f32_e32 v45, v45
	v_rcp_f32_e32 v49, v48
	s_nop 0
	v_mul_f32_e32 v36, v36, v49
	v_pk_mul_f32 v[36:37], v[36:37], v[32:33]
	v_pk_add_f32 v[44:45], v[44:45], 1.0 op_sel_hi:[1,0]
	v_mul_f32_e32 v32, 0xbfb8aa3b, v38
; DI float siluf_(float x) { return x / (1.f + __expf(-x)); }
; #define PG8_BAR __builtin_amdgcn_s_barrier()
; #define EPI_ROWS(...) _Pragma("unroll") for (int ai = 0; ai < 2; ++ai) _Pragma("unroll") for (int m = 0; m < 4; ++m) { const int row = u.pm * 256 + ai * 128 + wr * 64 + m * 16 + fr; __VA_ARGS__ }
; DI void st16_wt(void* p, u32x4 v) { asm volatile("global_store_dwordx4 %0, %1, off sc0 sc1\n\ts_nop 1" :: "v"(p), "v"(v) : "memory"); }
; DI u32x4 pack8(f32x4 a, f32x4 b) { u32x4 w; w.x = pk2(a[0], a[1]); w.y = pk2(a[2], a[3]); w.z = pk2(b[0], b[1]); w.w = pk2(b[2], b[3]); return w; }
; template <class Epi>
; DI void gemm_phase(int wv, LAS unsigned char* lds, const Gemm g, const StaticOrder& S, const Epi& E) {
;     ...
;         if (!has_next) break;
; #pragma unroll
;         for (int a = 0; a < 2; ++a)
; #pragma unroll
;             for (int b = 0; b < 2; ++b)
; #pragma unroll
;                 for (int m = 0; m < 4; ++m)
; #pragma unroll
;                     for (int n = 0; n < 2; ++n) acc[a][b][m][n] = (f32x4){0.f, 0.f, 0.f, 0.f};
;         cur = nxt; cA = nA; cB = nB; ++ui;
;         if (wr == 1) PG8_BAR;
;     DI void operator()(const Acc& acc, const Unit& u, int wr, int wc, int fr, int fq) const {
;     ...
;         EPI_ROWS( f32x4 a, b;
;             _Pragma("unroll") for (int e = 0; e < 4; ++e) { a[e] = siluf_(acc[ai][0][m][0][e]) * acc[ai][1][m][0][e]; b[e] = siluf_(acc[ai][0][m][1][e]) * acc[ai][1][m][1][e]; }
;             st16_wt(H + (size_t)row * DFF + c0, pack8(a, b)); )
	v_exp_f32_e32 v32, v32
	v_rcp_f32_e32 v33, v45
	s_nop 0
	v_mul_f32_e32 v45, v47, v33
	v_mul_f32_e32 v33, 0xbfb8aa3b, v39
	v_exp_f32_e32 v33, v33
	s_nop 0
	v_pk_add_f32 v[32:33], v[32:33], 1.0 op_sel_hi:[1,0]
	v_rcp_f32_e32 v47, v44
	s_nop 0
	v_mul_f32_e32 v44, v46, v47
	v_pk_mul_f32 v[42:43], v[44:45], v[42:43]
	v_rcp_f32_e32 v44, v33
	s_nop 0
	v_mul_f32_e32 v33, v39, v44
	v_rcp_f32_e32 v39, v32
	s_nop 0
	v_mul_f32_e32 v32, v38, v39
	v_pk_mul_f32 v[38:39], v[32:33], v[34:35]
	v_add_u32_e32 v32, 0x90, v150
	v_mad_i64_i32 v[32:33], s[24:25], v32, s50, v[112:113]
	v_lshl_add_u64 v[44:45], v[32:33], 0, v[114:115]
	v_mul_f32_e32 v33, 0xbfb8aa3b, v28
	v_cvt_pk_bf16_f32 v32, v40, v41
	v_exp_f32_e32 v40, v33
	v_mul_f32_e32 v33, 0xbfb8aa3b, v29
	v_exp_f32_e32 v41, v33
	v_cvt_pk_bf16_f32 v34, v36, v37
	v_cvt_pk_bf16_f32 v35, v38, v39
	v_cvt_pk_bf16_f32 v33, v42, v43
	v_pk_add_f32 v[36:37], v[40:41], 1.0 op_sel_hi:[1,0]
	global_store_dwordx4 v[44:45], v[32:35], off sc0 sc1
	s_nop 1
	v_mul_f32_e32 v32, 0xbfb8aa3b, v20
	v_exp_f32_e32 v32, v32
	v_rcp_f32_e32 v33, v37
	s_nop 0
	v_mul_f32_e32 v29, v29, v33
	v_mul_f32_e32 v33, 0xbfb8aa3b, v21
	v_exp_f32_e32 v33, v33
	s_nop 0
	v_pk_add_f32 v[32:33], v[32:33], 1.0 op_sel_hi:[1,0]
	v_rcp_f32_e32 v34, v36
	s_nop 0
	v_mul_f32_e32 v28, v28, v34
	v_pk_mul_f32 v[24:25], v[28:29], v[24:25]
	v_rcp_f32_e32 v28, v33
	s_nop 0
	v_mul_f32_e32 v21, v21, v28
	v_mul_f32_e32 v28, 0xbfb8aa3b, v30
	v_mul_f32_e32 v29, 0xbfb8aa3b, v31
	v_exp_f32_e32 v28, v28
	v_exp_f32_e32 v29, v29
	v_rcp_f32_e32 v33, v32
	s_nop 0
	v_mul_f32_e32 v20, v20, v33
	v_pk_mul_f32 v[20:21], v[20:21], v[16:17]
	v_pk_add_f32 v[28:29], v[28:29], 1.0 op_sel_hi:[1,0]
	v_mul_f32_e32 v16, 0xbfb8aa3b, v22
	v_exp_f32_e32 v16, v16
	v_rcp_f32_e32 v17, v29
	s_nop 0
	v_mul_f32_e32 v29, v31, v17
	v_mul_f32_e32 v17, 0xbfb8aa3b, v23
	v_exp_f32_e32 v17, v17
	s_nop 0
	v_pk_add_f32 v[16:17], v[16:17], 1.0 op_sel_hi:[1,0]
	v_rcp_f32_e32 v31, v28
	s_nop 0
	v_mul_f32_e32 v28, v30, v31
	v_pk_mul_f32 v[26:27], v[28:29], v[26:27]
	v_rcp_f32_e32 v28, v17
	s_nop 0
	v_mul_f32_e32 v17, v23, v28
	v_rcp_f32_e32 v23, v16
	s_nop 0
	v_mul_f32_e32 v16, v22, v23
	v_pk_mul_f32 v[22:23], v[16:17], v[18:19]
	v_add_u32_e32 v16, 0xa0, v150
	v_mad_i64_i32 v[16:17], s[24:25], v16, s50, v[112:113]
	v_lshl_add_u64 v[28:29], v[16:17], 0, v[114:115]
	v_mul_f32_e32 v17, 0xbfb8aa3b, v12
	v_cvt_pk_bf16_f32 v16, v24, v25
	v_exp_f32_e32 v24, v17
	v_mul_f32_e32 v17, 0xbfb8aa3b, v13
	v_exp_f32_e32 v25, v17
	v_cvt_pk_bf16_f32 v18, v20, v21
	v_cvt_pk_bf16_f32 v19, v22, v23
	v_cvt_pk_bf16_f32 v17, v26, v27
	v_pk_add_f32 v[20:21], v[24:25], 1.0 op_sel_hi:[1,0]
	global_store_dwordx4 v[28:29], v[16:19], off sc0 sc1
	s_nop 1
	v_mul_f32_e32 v16, 0xbfb8aa3b, v4
	v_exp_f32_e32 v16, v16
	v_rcp_f32_e32 v17, v21
	s_nop 0
	v_mul_f32_e32 v13, v13, v17
	v_mul_f32_e32 v17, 0xbfb8aa3b, v5
	v_exp_f32_e32 v17, v17
	s_nop 0
	v_pk_add_f32 v[16:17], v[16:17], 1.0 op_sel_hi:[1,0]
	v_rcp_f32_e32 v18, v20
	s_nop 0
	v_mul_f32_e32 v12, v12, v18
	v_pk_mul_f32 v[8:9], v[12:13], v[8:9]
	v_rcp_f32_e32 v12, v17
	s_nop 0
	v_mul_f32_e32 v5, v5, v12
	v_mul_f32_e32 v12, 0xbfb8aa3b, v14
	v_mul_f32_e32 v13, 0xbfb8aa3b, v15
	v_exp_f32_e32 v12, v12
	v_exp_f32_e32 v13, v13
	v_rcp_f32_e32 v17, v16
	s_nop 0
	v_mul_f32_e32 v4, v4, v17
	v_pk_mul_f32 v[4:5], v[4:5], v[0:1]
	v_pk_add_f32 v[12:13], v[12:13], 1.0 op_sel_hi:[1,0]
	v_mul_f32_e32 v0, 0xbfb8aa3b, v6
	v_exp_f32_e32 v0, v0
	v_rcp_f32_e32 v1, v13
	s_nop 0
	v_mul_f32_e32 v13, v15, v1
	v_mul_f32_e32 v1, 0xbfb8aa3b, v7
	v_exp_f32_e32 v1, v1
	s_nop 0
	v_pk_add_f32 v[0:1], v[0:1], 1.0 op_sel_hi:[1,0]
	v_rcp_f32_e32 v15, v12
	s_nop 0
	v_mul_f32_e32 v12, v14, v15
	v_pk_mul_f32 v[10:11], v[12:13], v[10:11]
	v_rcp_f32_e32 v12, v1
	s_nop 0
	v_mul_f32_e32 v1, v7, v12
	v_rcp_f32_e32 v7, v0
	s_nop 0
	v_mul_f32_e32 v0, v6, v7
	v_pk_mul_f32 v[6:7], v[0:1], v[2:3]
	v_add_u32_e32 v0, 0xb0, v150
	v_mad_i64_i32 v[0:1], s[24:25], v0, s50, v[112:113]
	v_lshl_add_u64 v[12:13], v[0:1], 0, v[114:115]
	v_cvt_pk_bf16_f32 v0, v8, v9
	v_cvt_pk_bf16_f32 v1, v10, v11
	v_cvt_pk_bf16_f32 v2, v4, v5
	v_cvt_pk_bf16_f32 v3, v6, v7
	global_store_dwordx4 v[12:13], v[0:3], off sc0 sc1
	s_nop 1
	s_andn2_b64 vcc, exec, s[2:3]
	s_mov_b64 s[2:3], -1
	s_cbranch_vccnz .LBB0_373
	s_andn2_b64 vcc, exec, s[6:7]
	s_cbranch_vccnz .LBB0_372
	s_barrier
	s_branch .LBB0_372

; DI float sigmoidf_(float x) { return 1.f / (1.f + __expf(-x)); }
.LBB0_899:
	v_mul_f32_e32 v197, 0xbfb8aa3b, v116
	v_exp_f32_e32 v197, v197
	s_nop 0
	v_add_f32_e32 v197, 1.0, v197
	v_rcp_f32_e32 v197, v197
	v_mad_i64_i32 v[198:199], s[92:93], v182, s95, v[178:179]
	flat_store_dword v[198:199], v197
	s_or_b64 exec, exec, s[22:23]
	s_and_saveexec_b64 s[22:23], s[16:17]
	s_xor_b64 s[92:93], exec, s[22:23]
	s_cbranch_execnz .LBB0_885

; DI float sigmoidf_(float x) { return 1.f / (1.f + __expf(-x)); }
.LBB0_901:
	v_mul_f32_e32 v197, 0xbfb8aa3b, v117
	v_exp_f32_e32 v197, v197
	s_nop 0
	v_add_f32_e32 v197, 1.0, v197
	s_nop 0
	v_rcp_f32_e32 v197, v197
	v_mov_b64_e32 v[198:199], s[40:41]
	v_mad_i64_i32 v[198:199], s[92:93], v182, s95, v[198:199]
	v_lshl_add_u64 v[198:199], v[172:173], 2, v[198:199]
	flat_store_dword v[198:199], v197
	s_or_b64 exec, exec, s[22:23]
	s_and_saveexec_b64 s[22:23], s[14:15]
	s_xor_b64 s[92:93], exec, s[22:23]
	s_cbranch_execnz .LBB0_887

; DI float sigmoidf_(float x) { return 1.f / (1.f + __expf(-x)); }
.LBB0_903:
	v_mul_f32_e32 v197, 0xbfb8aa3b, v118
	v_exp_f32_e32 v197, v197
	s_nop 0
	v_add_f32_e32 v197, 1.0, v197
	s_nop 0
	v_rcp_f32_e32 v197, v197
	v_mov_b64_e32 v[198:199], s[40:41]
	v_mad_i64_i32 v[198:199], s[92:93], v182, s95, v[198:199]
	v_lshl_add_u64 v[198:199], v[168:169], 2, v[198:199]
	flat_store_dword v[198:199], v197
	s_or_b64 exec, exec, s[22:23]
	s_and_saveexec_b64 s[22:23], s[12:13]
	s_xor_b64 s[92:93], exec, s[22:23]
	s_cbranch_execnz .LBB0_889

; DI float sigmoidf_(float x) { return 1.f / (1.f + __expf(-x)); }
.LBB0_905:
	v_mul_f32_e32 v197, 0xbfb8aa3b, v119
	v_exp_f32_e32 v197, v197
	s_nop 0
	v_add_f32_e32 v197, 1.0, v197
	s_nop 0
	v_rcp_f32_e32 v197, v197
	v_mov_b64_e32 v[198:199], s[40:41]
	v_mad_i64_i32 v[198:199], s[92:93], v182, s95, v[198:199]
	v_lshl_add_u64 v[198:199], v[164:165], 2, v[198:199]
	flat_store_dword v[198:199], v197
	s_or_b64 exec, exec, s[22:23]
	s_and_saveexec_b64 s[22:23], s[10:11]
	s_xor_b64 s[92:93], exec, s[22:23]
	s_cbranch_execnz .LBB0_891

; DI float sigmoidf_(float x) { return 1.f / (1.f + __expf(-x)); }
.LBB0_907:
	v_mul_f32_e32 v197, 0xbfb8aa3b, v112
	v_exp_f32_e32 v197, v197
	s_nop 0
	v_add_f32_e32 v197, 1.0, v197
	s_nop 0
	v_rcp_f32_e32 v197, v197
	v_mov_b64_e32 v[198:199], s[40:41]
	v_mad_i64_i32 v[198:199], s[92:93], v182, s95, v[198:199]
	v_lshl_add_u64 v[198:199], v[142:143], 2, v[198:199]
	flat_store_dword v[198:199], v197
	s_or_b64 exec, exec, s[22:23]
	s_and_saveexec_b64 s[22:23], s[8:9]
	s_xor_b64 s[92:93], exec, s[22:23]
	s_cbranch_execnz .LBB0_893

; DI float sigmoidf_(float x) { return 1.f / (1.f + __expf(-x)); }
.LBB0_909:
	v_mul_f32_e32 v197, 0xbfb8aa3b, v113
	v_exp_f32_e32 v197, v197
	s_nop 0
	v_add_f32_e32 v197, 1.0, v197
	s_nop 0
	v_rcp_f32_e32 v197, v197
	v_mov_b64_e32 v[198:199], s[40:41]
	v_mad_i64_i32 v[198:199], s[92:93], v182, s95, v[198:199]
	v_lshl_add_u64 v[198:199], v[138:139], 2, v[198:199]
	flat_store_dword v[198:199], v197
	s_or_b64 exec, exec, s[22:23]
	s_and_saveexec_b64 s[22:23], s[6:7]
	s_xor_b64 s[92:93], exec, s[22:23]
	s_cbranch_execnz .LBB0_895

; DI float sigmoidf_(float x) { return 1.f / (1.f + __expf(-x)); }
.LBB0_911:
	v_mul_f32_e32 v197, 0xbfb8aa3b, v114
	v_exp_f32_e32 v197, v197
	s_nop 0
	v_add_f32_e32 v197, 1.0, v197
	s_nop 0
	v_rcp_f32_e32 v197, v197
	v_mov_b64_e32 v[198:199], s[40:41]
	v_mad_i64_i32 v[198:199], s[92:93], v182, s95, v[198:199]
	v_lshl_add_u64 v[198:199], v[134:135], 2, v[198:199]
	flat_store_dword v[198:199], v197
	s_or_b64 exec, exec, s[22:23]
	s_and_saveexec_b64 s[22:23], s[4:5]
	s_xor_b64 s[92:93], exec, s[22:23]
	s_cbranch_execnz .LBB0_897

; DI float sigmoidf_(float x) { return 1.f / (1.f + __expf(-x)); }
.LBB0_913:
	v_mul_f32_e32 v183, 0xbfb8aa3b, v115
	v_exp_f32_e32 v183, v183
	s_nop 0
	v_add_f32_e32 v183, 1.0, v183
	s_nop 0
	v_mov_b64_e32 v[198:199], s[40:41]
	v_mad_i64_i32 v[198:199], s[22:23], v182, s95, v[198:199]
	v_rcp_f32_e32 v183, v183
	v_lshl_add_u64 v[198:199], v[130:131], 2, v[198:199]
	flat_store_dword v[198:199], v183

; DI float sigmoidf_(float x) { return 1.f / (1.f + __expf(-x)); }
.LBB0_936:
	v_mul_f32_e32 v198, 0xbfb8aa3b, v100
	v_exp_f32_e32 v198, v198
	s_nop 0
	v_add_f32_e32 v198, 1.0, v198
	v_rcp_f32_e32 v200, v198
	v_mad_i64_i32 v[198:199], s[92:93], v186, s95, v[178:179]
	flat_store_dword v[198:199], v200
	s_or_b64 exec, exec, s[24:25]
	s_and_saveexec_b64 s[24:25], s[16:17]
	s_xor_b64 s[92:93], exec, s[24:25]
	s_cbranch_execnz .LBB0_922

; DI float sigmoidf_(float x) { return 1.f / (1.f + __expf(-x)); }
.LBB0_938:
	v_mul_f32_e32 v198, 0xbfb8aa3b, v101
	v_exp_f32_e32 v198, v198
	s_nop 0
	v_add_f32_e32 v198, 1.0, v198
	s_nop 0
	v_rcp_f32_e32 v200, v198
	v_mov_b64_e32 v[198:199], s[40:41]
	v_mad_i64_i32 v[198:199], s[92:93], v186, s95, v[198:199]
	v_lshl_add_u64 v[198:199], v[172:173], 2, v[198:199]
	flat_store_dword v[198:199], v200
	s_or_b64 exec, exec, s[24:25]
	s_and_saveexec_b64 s[24:25], s[14:15]
	s_xor_b64 s[92:93], exec, s[24:25]
	s_cbranch_execnz .LBB0_924

; DI float sigmoidf_(float x) { return 1.f / (1.f + __expf(-x)); }
.LBB0_940:
	v_mul_f32_e32 v198, 0xbfb8aa3b, v102
	v_exp_f32_e32 v198, v198
	s_nop 0
	v_add_f32_e32 v198, 1.0, v198
	s_nop 0
	v_rcp_f32_e32 v200, v198
	v_mov_b64_e32 v[198:199], s[40:41]
	v_mad_i64_i32 v[198:199], s[92:93], v186, s95, v[198:199]
	v_lshl_add_u64 v[198:199], v[168:169], 2, v[198:199]
	flat_store_dword v[198:199], v200
	s_or_b64 exec, exec, s[24:25]
	s_and_saveexec_b64 s[24:25], s[12:13]
	s_xor_b64 s[92:93], exec, s[24:25]
	s_cbranch_execnz .LBB0_926

; DI float sigmoidf_(float x) { return 1.f / (1.f + __expf(-x)); }
.LBB0_942:
	v_mul_f32_e32 v198, 0xbfb8aa3b, v103
	v_exp_f32_e32 v198, v198
	s_nop 0
	v_add_f32_e32 v198, 1.0, v198
	s_nop 0
	v_rcp_f32_e32 v200, v198
	v_mov_b64_e32 v[198:199], s[40:41]
	v_mad_i64_i32 v[198:199], s[92:93], v186, s95, v[198:199]
	v_lshl_add_u64 v[198:199], v[164:165], 2, v[198:199]
	flat_store_dword v[198:199], v200
	s_or_b64 exec, exec, s[24:25]
	s_and_saveexec_b64 s[24:25], s[10:11]
	s_xor_b64 s[92:93], exec, s[24:25]
	s_cbranch_execnz .LBB0_928

; DI float sigmoidf_(float x) { return 1.f / (1.f + __expf(-x)); }
.LBB0_944:
	v_mul_f32_e32 v198, 0xbfb8aa3b, v96
	v_exp_f32_e32 v198, v198
	s_nop 0
	v_add_f32_e32 v198, 1.0, v198
	s_nop 0
	v_rcp_f32_e32 v200, v198
	v_mov_b64_e32 v[198:199], s[40:41]
	v_mad_i64_i32 v[198:199], s[92:93], v186, s95, v[198:199]
	v_lshl_add_u64 v[198:199], v[142:143], 2, v[198:199]
	flat_store_dword v[198:199], v200
	s_or_b64 exec, exec, s[24:25]
	s_and_saveexec_b64 s[24:25], s[8:9]
	s_xor_b64 s[92:93], exec, s[24:25]
	s_cbranch_execnz .LBB0_930

; DI float sigmoidf_(float x) { return 1.f / (1.f + __expf(-x)); }
.LBB0_946:
	v_mul_f32_e32 v198, 0xbfb8aa3b, v97
	v_exp_f32_e32 v198, v198
	s_nop 0
	v_add_f32_e32 v198, 1.0, v198
	s_nop 0
	v_rcp_f32_e32 v200, v198
	v_mov_b64_e32 v[198:199], s[40:41]
	v_mad_i64_i32 v[198:199], s[92:93], v186, s95, v[198:199]
	v_lshl_add_u64 v[198:199], v[138:139], 2, v[198:199]
	flat_store_dword v[198:199], v200
	s_or_b64 exec, exec, s[24:25]
	s_and_saveexec_b64 s[24:25], s[6:7]
	s_xor_b64 s[92:93], exec, s[24:25]
	s_cbranch_execnz .LBB0_932

; DI float sigmoidf_(float x) { return 1.f / (1.f + __expf(-x)); }
.LBB0_948:
	v_mul_f32_e32 v198, 0xbfb8aa3b, v98
	v_exp_f32_e32 v198, v198
	s_nop 0
	v_add_f32_e32 v198, 1.0, v198
	s_nop 0
	v_rcp_f32_e32 v200, v198
	v_mov_b64_e32 v[198:199], s[40:41]
	v_mad_i64_i32 v[198:199], s[92:93], v186, s95, v[198:199]
	v_lshl_add_u64 v[198:199], v[134:135], 2, v[198:199]
	flat_store_dword v[198:199], v200
	s_or_b64 exec, exec, s[24:25]
	s_and_saveexec_b64 s[24:25], s[4:5]
	s_xor_b64 s[92:93], exec, s[24:25]
	s_cbranch_execnz .LBB0_934

; DI float sigmoidf_(float x) { return 1.f / (1.f + __expf(-x)); }
.LBB0_950:
	v_mul_f32_e32 v187, 0xbfb8aa3b, v99
	v_exp_f32_e32 v187, v187
	s_nop 0
	v_add_f32_e32 v187, 1.0, v187
	s_nop 0
	v_rcp_f32_e32 v200, v187
	v_mov_b64_e32 v[198:199], s[40:41]
	v_mad_i64_i32 v[186:187], s[24:25], v186, s95, v[198:199]
	v_lshl_add_u64 v[186:187], v[130:131], 2, v[186:187]
	flat_store_dword v[186:187], v200

; DI float sigmoidf_(float x) { return 1.f / (1.f + __expf(-x)); }
.LBB0_973:
	v_mul_f32_e32 v198, 0xbfb8aa3b, v84
	v_exp_f32_e32 v198, v198
	s_nop 0
	v_add_f32_e32 v198, 1.0, v198
	v_rcp_f32_e32 v200, v198
	v_mad_i64_i32 v[198:199], s[92:93], v186, s95, v[178:179]
	flat_store_dword v[198:199], v200
	s_or_b64 exec, exec, s[24:25]
	s_and_saveexec_b64 s[24:25], s[16:17]
	s_xor_b64 s[92:93], exec, s[24:25]
	s_cbranch_execnz .LBB0_959

; DI float sigmoidf_(float x) { return 1.f / (1.f + __expf(-x)); }
.LBB0_975:
	v_mul_f32_e32 v198, 0xbfb8aa3b, v85
	v_exp_f32_e32 v198, v198
	s_nop 0
	v_add_f32_e32 v198, 1.0, v198
	s_nop 0
	v_rcp_f32_e32 v200, v198
	v_mov_b64_e32 v[198:199], s[40:41]
	v_mad_i64_i32 v[198:199], s[92:93], v186, s95, v[198:199]
	v_lshl_add_u64 v[198:199], v[172:173], 2, v[198:199]
	flat_store_dword v[198:199], v200
	s_or_b64 exec, exec, s[24:25]
	s_and_saveexec_b64 s[24:25], s[14:15]
	s_xor_b64 s[92:93], exec, s[24:25]
	s_cbranch_execnz .LBB0_961

; DI float sigmoidf_(float x) { return 1.f / (1.f + __expf(-x)); }
.LBB0_977:
	v_mul_f32_e32 v198, 0xbfb8aa3b, v86
	v_exp_f32_e32 v198, v198
	s_nop 0
	v_add_f32_e32 v198, 1.0, v198
	s_nop 0
	v_rcp_f32_e32 v200, v198
	v_mov_b64_e32 v[198:199], s[40:41]
	v_mad_i64_i32 v[198:199], s[92:93], v186, s95, v[198:199]
	v_lshl_add_u64 v[198:199], v[168:169], 2, v[198:199]
	flat_store_dword v[198:199], v200
	s_or_b64 exec, exec, s[24:25]
	s_and_saveexec_b64 s[24:25], s[12:13]
	s_xor_b64 s[92:93], exec, s[24:25]
	s_cbranch_execnz .LBB0_963

; DI float sigmoidf_(float x) { return 1.f / (1.f + __expf(-x)); }
.LBB0_979:
	v_mul_f32_e32 v198, 0xbfb8aa3b, v87
	v_exp_f32_e32 v198, v198
	s_nop 0
	v_add_f32_e32 v198, 1.0, v198
	s_nop 0
	v_rcp_f32_e32 v200, v198
	v_mov_b64_e32 v[198:199], s[40:41]
	v_mad_i64_i32 v[198:199], s[92:93], v186, s95, v[198:199]
	v_lshl_add_u64 v[198:199], v[164:165], 2, v[198:199]
	flat_store_dword v[198:199], v200
	s_or_b64 exec, exec, s[24:25]
	s_and_saveexec_b64 s[24:25], s[10:11]
	s_xor_b64 s[92:93], exec, s[24:25]
	s_cbranch_execnz .LBB0_965

; DI float sigmoidf_(float x) { return 1.f / (1.f + __expf(-x)); }
.LBB0_981:
	v_mul_f32_e32 v198, 0xbfb8aa3b, v80
	v_exp_f32_e32 v198, v198
	s_nop 0
	v_add_f32_e32 v198, 1.0, v198
	s_nop 0
	v_rcp_f32_e32 v200, v198
	v_mov_b64_e32 v[198:199], s[40:41]
	v_mad_i64_i32 v[198:199], s[92:93], v186, s95, v[198:199]
	v_lshl_add_u64 v[198:199], v[142:143], 2, v[198:199]
	flat_store_dword v[198:199], v200
	s_or_b64 exec, exec, s[24:25]
	s_and_saveexec_b64 s[24:25], s[8:9]
	s_xor_b64 s[92:93], exec, s[24:25]
	s_cbranch_execnz .LBB0_967

; DI float sigmoidf_(float x) { return 1.f / (1.f + __expf(-x)); }
.LBB0_983:
	v_mul_f32_e32 v198, 0xbfb8aa3b, v81
	v_exp_f32_e32 v198, v198
	s_nop 0
	v_add_f32_e32 v198, 1.0, v198
	s_nop 0
	v_rcp_f32_e32 v200, v198
	v_mov_b64_e32 v[198:199], s[40:41]
	v_mad_i64_i32 v[198:199], s[92:93], v186, s95, v[198:199]
	v_lshl_add_u64 v[198:199], v[138:139], 2, v[198:199]
	flat_store_dword v[198:199], v200
	s_or_b64 exec, exec, s[24:25]
	s_and_saveexec_b64 s[24:25], s[6:7]
	s_xor_b64 s[92:93], exec, s[24:25]
	s_cbranch_execnz .LBB0_969

; DI float sigmoidf_(float x) { return 1.f / (1.f + __expf(-x)); }
.LBB0_985:
	v_mul_f32_e32 v198, 0xbfb8aa3b, v82
	v_exp_f32_e32 v198, v198
	s_nop 0
	v_add_f32_e32 v198, 1.0, v198
	s_nop 0
	v_rcp_f32_e32 v200, v198
	v_mov_b64_e32 v[198:199], s[40:41]
	v_mad_i64_i32 v[198:199], s[92:93], v186, s95, v[198:199]
	v_lshl_add_u64 v[198:199], v[134:135], 2, v[198:199]
	flat_store_dword v[198:199], v200
	s_or_b64 exec, exec, s[24:25]
	s_and_saveexec_b64 s[24:25], s[4:5]
	s_xor_b64 s[92:93], exec, s[24:25]
	s_cbranch_execnz .LBB0_971

; DI float sigmoidf_(float x) { return 1.f / (1.f + __expf(-x)); }
.LBB0_987:
	v_mul_f32_e32 v187, 0xbfb8aa3b, v83
	v_exp_f32_e32 v187, v187
	s_nop 0
	v_add_f32_e32 v187, 1.0, v187
	s_nop 0
	v_rcp_f32_e32 v200, v187
	v_mov_b64_e32 v[198:199], s[40:41]
	v_mad_i64_i32 v[186:187], s[24:25], v186, s95, v[198:199]
	v_lshl_add_u64 v[186:187], v[130:131], 2, v[186:187]
	flat_store_dword v[186:187], v200

; DI float sigmoidf_(float x) { return 1.f / (1.f + __expf(-x)); }
.LBB0_1010:
	v_mul_f32_e32 v198, 0xbfb8aa3b, v68
	v_exp_f32_e32 v198, v198
	s_nop 0
	v_add_f32_e32 v198, 1.0, v198
	v_rcp_f32_e32 v200, v198
	v_mad_i64_i32 v[198:199], s[92:93], v186, s95, v[178:179]
	flat_store_dword v[198:199], v200
	s_or_b64 exec, exec, s[24:25]
	s_and_saveexec_b64 s[24:25], s[16:17]
	s_xor_b64 s[92:93], exec, s[24:25]
	s_cbranch_execnz .LBB0_996

.LBB0_1012:
	v_mul_f32_e32 v198, 0xbfb8aa3b, v69
	v_exp_f32_e32 v198, v198
	s_nop 0
	v_add_f32_e32 v198, 1.0, v198
	s_nop 0
	v_rcp_f32_e32 v200, v198
	v_mov_b64_e32 v[198:199], s[40:41]
	v_mad_i64_i32 v[198:199], s[92:93], v186, s95, v[198:199]
	v_lshl_add_u64 v[198:199], v[172:173], 2, v[198:199]
	flat_store_dword v[198:199], v200
	s_or_b64 exec, exec, s[24:25]
	s_and_saveexec_b64 s[24:25], s[14:15]
	s_xor_b64 s[92:93], exec, s[24:25]
	s_cbranch_execnz .LBB0_998

.LBB0_1014:
	v_mul_f32_e32 v198, 0xbfb8aa3b, v70
	v_exp_f32_e32 v198, v198
	s_nop 0
	v_add_f32_e32 v198, 1.0, v198
	s_nop 0
	v_rcp_f32_e32 v200, v198
	v_mov_b64_e32 v[198:199], s[40:41]
	v_mad_i64_i32 v[198:199], s[92:93], v186, s95, v[198:199]
	v_lshl_add_u64 v[198:199], v[168:169], 2, v[198:199]
	flat_store_dword v[198:199], v200
	s_or_b64 exec, exec, s[24:25]
	s_and_saveexec_b64 s[24:25], s[12:13]
	s_xor_b64 s[92:93], exec, s[24:25]
	s_cbranch_execnz .LBB0_1000

.LBB0_1016:
	v_mul_f32_e32 v198, 0xbfb8aa3b, v71
	v_exp_f32_e32 v198, v198
	s_nop 0
	v_add_f32_e32 v198, 1.0, v198
	s_nop 0
	v_rcp_f32_e32 v200, v198
	v_mov_b64_e32 v[198:199], s[40:41]
	v_mad_i64_i32 v[198:199], s[92:93], v186, s95, v[198:199]
	v_lshl_add_u64 v[198:199], v[164:165], 2, v[198:199]
	flat_store_dword v[198:199], v200
	s_or_b64 exec, exec, s[24:25]
	s_and_saveexec_b64 s[24:25], s[10:11]
	s_xor_b64 s[92:93], exec, s[24:25]
	s_cbranch_execnz .LBB0_1002

.LBB0_1018:
	v_mul_f32_e32 v198, 0xbfb8aa3b, v64
	v_exp_f32_e32 v198, v198
	s_nop 0
	v_add_f32_e32 v198, 1.0, v198
	s_nop 0
	v_rcp_f32_e32 v200, v198
	v_mov_b64_e32 v[198:199], s[40:41]
	v_mad_i64_i32 v[198:199], s[92:93], v186, s95, v[198:199]
	v_lshl_add_u64 v[198:199], v[142:143], 2, v[198:199]
	flat_store_dword v[198:199], v200
	s_or_b64 exec, exec, s[24:25]
	s_and_saveexec_b64 s[24:25], s[8:9]
	s_xor_b64 s[92:93], exec, s[24:25]
	s_cbranch_execnz .LBB0_1004

.LBB0_1020:
	v_mul_f32_e32 v198, 0xbfb8aa3b, v65
	v_exp_f32_e32 v198, v198
	s_nop 0
	v_add_f32_e32 v198, 1.0, v198
	s_nop 0
	v_rcp_f32_e32 v200, v198
	v_mov_b64_e32 v[198:199], s[40:41]
	v_mad_i64_i32 v[198:199], s[92:93], v186, s95, v[198:199]
	v_lshl_add_u64 v[198:199], v[138:139], 2, v[198:199]
	flat_store_dword v[198:199], v200
	s_or_b64 exec, exec, s[24:25]
	s_and_saveexec_b64 s[24:25], s[6:7]
	s_xor_b64 s[92:93], exec, s[24:25]
	s_cbranch_execnz .LBB0_1006

.LBB0_1022:
	v_mul_f32_e32 v198, 0xbfb8aa3b, v66
	v_exp_f32_e32 v198, v198
	s_nop 0
	v_add_f32_e32 v198, 1.0, v198
	s_nop 0
	v_rcp_f32_e32 v200, v198
	v_mov_b64_e32 v[198:199], s[40:41]
	v_mad_i64_i32 v[198:199], s[92:93], v186, s95, v[198:199]
	v_lshl_add_u64 v[198:199], v[134:135], 2, v[198:199]
	flat_store_dword v[198:199], v200
	s_or_b64 exec, exec, s[24:25]
	s_and_saveexec_b64 s[24:25], s[4:5]
	s_xor_b64 s[92:93], exec, s[24:25]
	s_cbranch_execnz .LBB0_1008

.LBB0_1024:
	v_mul_f32_e32 v187, 0xbfb8aa3b, v67
	v_exp_f32_e32 v187, v187
	s_nop 0
	v_add_f32_e32 v187, 1.0, v187
	s_nop 0
	v_rcp_f32_e32 v200, v187
	v_mov_b64_e32 v[198:199], s[40:41]
	v_mad_i64_i32 v[186:187], s[24:25], v186, s95, v[198:199]
	v_lshl_add_u64 v[186:187], v[130:131], 2, v[186:187]
	flat_store_dword v[186:187], v200

.LBB0_1047:
	v_mul_f32_e32 v198, 0xbfb8aa3b, v52
	v_exp_f32_e32 v198, v198
	s_nop 0
	v_add_f32_e32 v198, 1.0, v198
	v_rcp_f32_e32 v200, v198
	v_mad_i64_i32 v[198:199], s[92:93], v186, s95, v[178:179]
	flat_store_dword v[198:199], v200
	s_or_b64 exec, exec, s[24:25]
	s_and_saveexec_b64 s[24:25], s[16:17]
	s_xor_b64 s[92:93], exec, s[24:25]
	s_cbranch_execnz .LBB0_1033

.LBB0_1049:
	v_mul_f32_e32 v198, 0xbfb8aa3b, v53
	v_exp_f32_e32 v198, v198
	s_nop 0
	v_add_f32_e32 v198, 1.0, v198
	s_nop 0
	v_rcp_f32_e32 v200, v198
	v_mov_b64_e32 v[198:199], s[40:41]
	v_mad_i64_i32 v[198:199], s[92:93], v186, s95, v[198:199]
	v_lshl_add_u64 v[198:199], v[172:173], 2, v[198:199]
	flat_store_dword v[198:199], v200
	s_or_b64 exec, exec, s[24:25]
	s_and_saveexec_b64 s[24:25], s[14:15]
	s_xor_b64 s[92:93], exec, s[24:25]
	s_cbranch_execnz .LBB0_1035

.LBB0_1051:
	v_mul_f32_e32 v198, 0xbfb8aa3b, v54
	v_exp_f32_e32 v198, v198
	s_nop 0
	v_add_f32_e32 v198, 1.0, v198
	s_nop 0
	v_rcp_f32_e32 v200, v198
	v_mov_b64_e32 v[198:199], s[40:41]
	v_mad_i64_i32 v[198:199], s[92:93], v186, s95, v[198:199]
	v_lshl_add_u64 v[198:199], v[168:169], 2, v[198:199]
	flat_store_dword v[198:199], v200
	s_or_b64 exec, exec, s[24:25]
	s_and_saveexec_b64 s[24:25], s[12:13]
	s_xor_b64 s[92:93], exec, s[24:25]
	s_cbranch_execnz .LBB0_1037

.LBB0_1053:
	v_mul_f32_e32 v198, 0xbfb8aa3b, v55
	v_exp_f32_e32 v198, v198
	s_nop 0
	v_add_f32_e32 v198, 1.0, v198
	s_nop 0
	v_rcp_f32_e32 v200, v198
	v_mov_b64_e32 v[198:199], s[40:41]
	v_mad_i64_i32 v[198:199], s[92:93], v186, s95, v[198:199]
	v_lshl_add_u64 v[198:199], v[164:165], 2, v[198:199]
	flat_store_dword v[198:199], v200
	s_or_b64 exec, exec, s[24:25]
	s_and_saveexec_b64 s[24:25], s[10:11]
	s_xor_b64 s[92:93], exec, s[24:25]
	s_cbranch_execnz .LBB0_1039

.LBB0_1055:
	v_mul_f32_e32 v198, 0xbfb8aa3b, v48
	v_exp_f32_e32 v198, v198
	s_nop 0
	v_add_f32_e32 v198, 1.0, v198
	s_nop 0
	v_rcp_f32_e32 v200, v198
	v_mov_b64_e32 v[198:199], s[40:41]
	v_mad_i64_i32 v[198:199], s[92:93], v186, s95, v[198:199]
	v_lshl_add_u64 v[198:199], v[142:143], 2, v[198:199]
	flat_store_dword v[198:199], v200
	s_or_b64 exec, exec, s[24:25]
	s_and_saveexec_b64 s[24:25], s[8:9]
	s_xor_b64 s[92:93], exec, s[24:25]
	s_cbranch_execnz .LBB0_1041

.LBB0_1057:
	v_mul_f32_e32 v198, 0xbfb8aa3b, v49
	v_exp_f32_e32 v198, v198
	s_nop 0
	v_add_f32_e32 v198, 1.0, v198
	s_nop 0
	v_rcp_f32_e32 v200, v198
	v_mov_b64_e32 v[198:199], s[40:41]
	v_mad_i64_i32 v[198:199], s[92:93], v186, s95, v[198:199]
	v_lshl_add_u64 v[198:199], v[138:139], 2, v[198:199]
	flat_store_dword v[198:199], v200
	s_or_b64 exec, exec, s[24:25]
	s_and_saveexec_b64 s[24:25], s[6:7]
	s_xor_b64 s[92:93], exec, s[24:25]
	s_cbranch_execnz .LBB0_1043

.LBB0_1059:
	v_mul_f32_e32 v198, 0xbfb8aa3b, v50
	v_exp_f32_e32 v198, v198
	s_nop 0
	v_add_f32_e32 v198, 1.0, v198
	s_nop 0
	v_rcp_f32_e32 v200, v198
	v_mov_b64_e32 v[198:199], s[40:41]
	v_mad_i64_i32 v[198:199], s[92:93], v186, s95, v[198:199]
	v_lshl_add_u64 v[198:199], v[134:135], 2, v[198:199]
	flat_store_dword v[198:199], v200
	s_or_b64 exec, exec, s[24:25]
	s_and_saveexec_b64 s[24:25], s[4:5]
	s_xor_b64 s[92:93], exec, s[24:25]
	s_cbranch_execnz .LBB0_1045

.LBB0_1061:
	v_mul_f32_e32 v187, 0xbfb8aa3b, v51
	v_exp_f32_e32 v187, v187
	s_nop 0
	v_add_f32_e32 v187, 1.0, v187
	s_nop 0
	v_rcp_f32_e32 v200, v187
	v_mov_b64_e32 v[198:199], s[40:41]
	v_mad_i64_i32 v[186:187], s[24:25], v186, s95, v[198:199]
	v_lshl_add_u64 v[186:187], v[130:131], 2, v[186:187]
	flat_store_dword v[186:187], v200

.LBB0_1084:
	v_mul_f32_e32 v198, 0xbfb8aa3b, v36
	v_exp_f32_e32 v198, v198
	s_nop 0
	v_add_f32_e32 v198, 1.0, v198
	v_rcp_f32_e32 v200, v198
	v_mad_i64_i32 v[198:199], s[92:93], v186, s95, v[178:179]
	flat_store_dword v[198:199], v200
	s_or_b64 exec, exec, s[24:25]
	s_and_saveexec_b64 s[24:25], s[16:17]
	s_xor_b64 s[92:93], exec, s[24:25]
	s_cbranch_execnz .LBB0_1070

.LBB0_1086:
	v_mul_f32_e32 v198, 0xbfb8aa3b, v37
	v_exp_f32_e32 v198, v198
	s_nop 0
	v_add_f32_e32 v198, 1.0, v198
	s_nop 0
	v_rcp_f32_e32 v200, v198
	v_mov_b64_e32 v[198:199], s[40:41]
	v_mad_i64_i32 v[198:199], s[92:93], v186, s95, v[198:199]
	v_lshl_add_u64 v[198:199], v[172:173], 2, v[198:199]
	flat_store_dword v[198:199], v200
	s_or_b64 exec, exec, s[24:25]
	s_and_saveexec_b64 s[24:25], s[14:15]
	s_xor_b64 s[92:93], exec, s[24:25]
	s_cbranch_execnz .LBB0_1072

.LBB0_1088:
	v_mul_f32_e32 v198, 0xbfb8aa3b, v38
	v_exp_f32_e32 v198, v198
	s_nop 0
	v_add_f32_e32 v198, 1.0, v198
	s_nop 0
	v_rcp_f32_e32 v200, v198
	v_mov_b64_e32 v[198:199], s[40:41]
	v_mad_i64_i32 v[198:199], s[92:93], v186, s95, v[198:199]
	v_lshl_add_u64 v[198:199], v[168:169], 2, v[198:199]
	flat_store_dword v[198:199], v200
	s_or_b64 exec, exec, s[24:25]
	s_and_saveexec_b64 s[24:25], s[12:13]
	s_xor_b64 s[92:93], exec, s[24:25]
	s_cbranch_execnz .LBB0_1074

.LBB0_1090:
	v_mul_f32_e32 v198, 0xbfb8aa3b, v39
	v_exp_f32_e32 v198, v198
	s_nop 0
	v_add_f32_e32 v198, 1.0, v198
	s_nop 0
	v_rcp_f32_e32 v200, v198
	v_mov_b64_e32 v[198:199], s[40:41]
	v_mad_i64_i32 v[198:199], s[92:93], v186, s95, v[198:199]
	v_lshl_add_u64 v[198:199], v[164:165], 2, v[198:199]
	flat_store_dword v[198:199], v200
	s_or_b64 exec, exec, s[24:25]
	s_and_saveexec_b64 s[24:25], s[10:11]
	s_xor_b64 s[92:93], exec, s[24:25]
	s_cbranch_execnz .LBB0_1076

.LBB0_1092:
	v_mul_f32_e32 v198, 0xbfb8aa3b, v32
	v_exp_f32_e32 v198, v198
	s_nop 0
	v_add_f32_e32 v198, 1.0, v198
	s_nop 0
	v_rcp_f32_e32 v200, v198
	v_mov_b64_e32 v[198:199], s[40:41]
	v_mad_i64_i32 v[198:199], s[92:93], v186, s95, v[198:199]
	v_lshl_add_u64 v[198:199], v[142:143], 2, v[198:199]
	flat_store_dword v[198:199], v200
	s_or_b64 exec, exec, s[24:25]
	s_and_saveexec_b64 s[24:25], s[8:9]
	s_xor_b64 s[92:93], exec, s[24:25]
	s_cbranch_execnz .LBB0_1078

.LBB0_1094:
	v_mul_f32_e32 v198, 0xbfb8aa3b, v33
	v_exp_f32_e32 v198, v198
	s_nop 0
	v_add_f32_e32 v198, 1.0, v198
	s_nop 0
	v_rcp_f32_e32 v200, v198
	v_mov_b64_e32 v[198:199], s[40:41]
	v_mad_i64_i32 v[198:199], s[92:93], v186, s95, v[198:199]
	v_lshl_add_u64 v[198:199], v[138:139], 2, v[198:199]
	flat_store_dword v[198:199], v200
	s_or_b64 exec, exec, s[24:25]
	s_and_saveexec_b64 s[24:25], s[6:7]
	s_xor_b64 s[92:93], exec, s[24:25]
	s_cbranch_execnz .LBB0_1080

.LBB0_1096:
	v_mul_f32_e32 v198, 0xbfb8aa3b, v34
	v_exp_f32_e32 v198, v198
	s_nop 0
	v_add_f32_e32 v198, 1.0, v198
	s_nop 0
	v_rcp_f32_e32 v200, v198
	v_mov_b64_e32 v[198:199], s[40:41]
	v_mad_i64_i32 v[198:199], s[92:93], v186, s95, v[198:199]
	v_lshl_add_u64 v[198:199], v[134:135], 2, v[198:199]
	flat_store_dword v[198:199], v200
	s_or_b64 exec, exec, s[24:25]
	s_and_saveexec_b64 s[24:25], s[4:5]
	s_xor_b64 s[92:93], exec, s[24:25]
	s_cbranch_execnz .LBB0_1082

.LBB0_1098:
	v_mul_f32_e32 v187, 0xbfb8aa3b, v35
	v_exp_f32_e32 v187, v187
	s_nop 0
	v_add_f32_e32 v187, 1.0, v187
	s_nop 0
	v_rcp_f32_e32 v200, v187
	v_mov_b64_e32 v[198:199], s[40:41]
	v_mad_i64_i32 v[186:187], s[24:25], v186, s95, v[198:199]
	v_lshl_add_u64 v[186:187], v[130:131], 2, v[186:187]
	flat_store_dword v[186:187], v200

.LBB0_1121:
	v_mul_f32_e32 v198, 0xbfb8aa3b, v20
	v_exp_f32_e32 v198, v198
	s_nop 0
	v_add_f32_e32 v198, 1.0, v198
	v_rcp_f32_e32 v200, v198
	v_mad_i64_i32 v[198:199], s[92:93], v186, s95, v[178:179]
	flat_store_dword v[198:199], v200
	s_or_b64 exec, exec, s[24:25]
	s_and_saveexec_b64 s[24:25], s[16:17]
	s_xor_b64 s[92:93], exec, s[24:25]
	s_cbranch_execnz .LBB0_1107

.LBB0_1123:
	v_mul_f32_e32 v198, 0xbfb8aa3b, v21
	v_exp_f32_e32 v198, v198
	s_nop 0
	v_add_f32_e32 v198, 1.0, v198
	s_nop 0
	v_rcp_f32_e32 v200, v198
	v_mov_b64_e32 v[198:199], s[40:41]
	v_mad_i64_i32 v[198:199], s[92:93], v186, s95, v[198:199]
	v_lshl_add_u64 v[198:199], v[172:173], 2, v[198:199]
	flat_store_dword v[198:199], v200
	s_or_b64 exec, exec, s[24:25]
	s_and_saveexec_b64 s[24:25], s[14:15]
	s_xor_b64 s[92:93], exec, s[24:25]
	s_cbranch_execnz .LBB0_1109

.LBB0_1125:
	v_mul_f32_e32 v198, 0xbfb8aa3b, v22
	v_exp_f32_e32 v198, v198
	s_nop 0
	v_add_f32_e32 v198, 1.0, v198
	s_nop 0
	v_rcp_f32_e32 v200, v198
	v_mov_b64_e32 v[198:199], s[40:41]
	v_mad_i64_i32 v[198:199], s[92:93], v186, s95, v[198:199]
	v_lshl_add_u64 v[198:199], v[168:169], 2, v[198:199]
	flat_store_dword v[198:199], v200
	s_or_b64 exec, exec, s[24:25]
	s_and_saveexec_b64 s[24:25], s[12:13]
	s_xor_b64 s[92:93], exec, s[24:25]
	s_cbranch_execnz .LBB0_1111

.LBB0_1127:
	v_mul_f32_e32 v198, 0xbfb8aa3b, v23
	v_exp_f32_e32 v198, v198
	s_nop 0
	v_add_f32_e32 v198, 1.0, v198
	s_nop 0
	v_rcp_f32_e32 v200, v198
	v_mov_b64_e32 v[198:199], s[40:41]
	v_mad_i64_i32 v[198:199], s[92:93], v186, s95, v[198:199]
	v_lshl_add_u64 v[198:199], v[164:165], 2, v[198:199]
	flat_store_dword v[198:199], v200
	s_or_b64 exec, exec, s[24:25]
	s_and_saveexec_b64 s[24:25], s[10:11]
	s_xor_b64 s[92:93], exec, s[24:25]
	s_cbranch_execnz .LBB0_1113

.LBB0_1129:
	v_mul_f32_e32 v198, 0xbfb8aa3b, v16
	v_exp_f32_e32 v198, v198
	s_nop 0
	v_add_f32_e32 v198, 1.0, v198
	s_nop 0
	v_rcp_f32_e32 v200, v198
	v_mov_b64_e32 v[198:199], s[40:41]
	v_mad_i64_i32 v[198:199], s[92:93], v186, s95, v[198:199]
	v_lshl_add_u64 v[198:199], v[142:143], 2, v[198:199]
	flat_store_dword v[198:199], v200
	s_or_b64 exec, exec, s[24:25]
	s_and_saveexec_b64 s[24:25], s[8:9]
	s_xor_b64 s[92:93], exec, s[24:25]
	s_cbranch_execnz .LBB0_1115

.LBB0_1131:
	v_mul_f32_e32 v198, 0xbfb8aa3b, v17
	v_exp_f32_e32 v198, v198
	s_nop 0
	v_add_f32_e32 v198, 1.0, v198
	s_nop 0
	v_rcp_f32_e32 v200, v198
	v_mov_b64_e32 v[198:199], s[40:41]
	v_mad_i64_i32 v[198:199], s[92:93], v186, s95, v[198:199]
	v_lshl_add_u64 v[198:199], v[138:139], 2, v[198:199]
	flat_store_dword v[198:199], v200
	s_or_b64 exec, exec, s[24:25]
	s_and_saveexec_b64 s[24:25], s[6:7]
	s_xor_b64 s[92:93], exec, s[24:25]
	s_cbranch_execnz .LBB0_1117

.LBB0_1133:
	v_mul_f32_e32 v198, 0xbfb8aa3b, v18
	v_exp_f32_e32 v198, v198
	s_nop 0
	v_add_f32_e32 v198, 1.0, v198
	s_nop 0
	v_rcp_f32_e32 v200, v198
	v_mov_b64_e32 v[198:199], s[40:41]
	v_mad_i64_i32 v[198:199], s[92:93], v186, s95, v[198:199]
	v_lshl_add_u64 v[198:199], v[134:135], 2, v[198:199]
	flat_store_dword v[198:199], v200
	s_or_b64 exec, exec, s[24:25]
	s_and_saveexec_b64 s[24:25], s[4:5]
	s_xor_b64 s[92:93], exec, s[24:25]
	s_cbranch_execnz .LBB0_1119

.LBB0_1135:
	v_mul_f32_e32 v187, 0xbfb8aa3b, v19
	v_exp_f32_e32 v187, v187
	s_nop 0
	v_add_f32_e32 v187, 1.0, v187
	s_nop 0
	v_rcp_f32_e32 v200, v187
	v_mov_b64_e32 v[198:199], s[40:41]
	v_mad_i64_i32 v[186:187], s[24:25], v186, s95, v[198:199]
	v_lshl_add_u64 v[186:187], v[130:131], 2, v[186:187]
	flat_store_dword v[186:187], v200

.LBB0_1158:
	v_mul_f32_e32 v152, 0xbfb8aa3b, v4
	v_exp_f32_e32 v152, v152
	s_nop 0
	v_add_f32_e32 v152, 1.0, v152
	v_rcp_f32_e32 v152, v152
	v_mad_i64_i32 v[176:177], s[20:21], v182, s95, v[178:179]
	flat_store_dword v[176:177], v152
	s_or_b64 exec, exec, s[18:19]
	s_and_saveexec_b64 s[18:19], s[16:17]
	s_xor_b64 s[18:19], exec, s[18:19]
	s_cbranch_execnz .LBB0_1144

.LBB0_1160:
	v_mul_f32_e32 v152, 0xbfb8aa3b, v5
	v_exp_f32_e32 v152, v152
	s_nop 0
	v_add_f32_e32 v152, 1.0, v152
	s_nop 0
	v_rcp_f32_e32 v152, v152
	v_mov_b64_e32 v[174:175], s[40:41]
	v_mad_i64_i32 v[174:175], s[18:19], v182, s95, v[174:175]
	v_lshl_add_u64 v[172:173], v[172:173], 2, v[174:175]
	flat_store_dword v[172:173], v152
	s_or_b64 exec, exec, s[16:17]
	s_and_saveexec_b64 s[16:17], s[14:15]
	s_xor_b64 s[16:17], exec, s[16:17]
	s_cbranch_execnz .LBB0_1146

.LBB0_1162:
	v_mul_f32_e32 v152, 0xbfb8aa3b, v6
	v_exp_f32_e32 v152, v152
	s_nop 0
	v_add_f32_e32 v152, 1.0, v152
	s_nop 0
	v_rcp_f32_e32 v152, v152
	v_mov_b64_e32 v[170:171], s[40:41]
	v_mad_i64_i32 v[170:171], s[16:17], v182, s95, v[170:171]
	v_lshl_add_u64 v[168:169], v[168:169], 2, v[170:171]
	flat_store_dword v[168:169], v152
	s_or_b64 exec, exec, s[14:15]
	s_and_saveexec_b64 s[14:15], s[12:13]
	s_xor_b64 s[14:15], exec, s[14:15]
	s_cbranch_execnz .LBB0_1148

.LBB0_1164:
	v_mul_f32_e32 v152, 0xbfb8aa3b, v7
	v_exp_f32_e32 v152, v152
	s_nop 0
	v_add_f32_e32 v152, 1.0, v152
	s_nop 0
	v_rcp_f32_e32 v152, v152
	v_mov_b64_e32 v[166:167], s[40:41]
	v_mad_i64_i32 v[166:167], s[14:15], v182, s95, v[166:167]
	v_lshl_add_u64 v[164:165], v[164:165], 2, v[166:167]
	flat_store_dword v[164:165], v152
	s_or_b64 exec, exec, s[12:13]
	s_and_saveexec_b64 s[12:13], s[10:11]
	s_xor_b64 s[12:13], exec, s[12:13]
	s_cbranch_execnz .LBB0_1150

.LBB0_1166:
	v_mul_f32_e32 v152, 0xbfb8aa3b, v0
	v_exp_f32_e32 v152, v152
	s_nop 0
	v_add_f32_e32 v152, 1.0, v152
	s_nop 0
	v_rcp_f32_e32 v152, v152
	v_mov_b64_e32 v[162:163], s[40:41]
	v_mad_i64_i32 v[162:163], s[12:13], v182, s95, v[162:163]
	v_lshl_add_u64 v[142:143], v[142:143], 2, v[162:163]
	flat_store_dword v[142:143], v152
	s_or_b64 exec, exec, s[10:11]
	s_and_saveexec_b64 s[10:11], s[8:9]
	s_xor_b64 s[10:11], exec, s[10:11]
	s_cbranch_execnz .LBB0_1152

.LBB0_1168:
	v_mul_f32_e32 v140, 0xbfb8aa3b, v1
	v_exp_f32_e32 v140, v140
	s_nop 0
	v_add_f32_e32 v140, 1.0, v140
	s_nop 0
	v_rcp_f32_e32 v142, v140
	v_mov_b64_e32 v[140:141], s[40:41]
	v_mad_i64_i32 v[140:141], s[10:11], v182, s95, v[140:141]
	v_lshl_add_u64 v[138:139], v[138:139], 2, v[140:141]
	flat_store_dword v[138:139], v142
	s_or_b64 exec, exec, s[8:9]
	s_and_saveexec_b64 s[8:9], s[6:7]
	s_xor_b64 s[8:9], exec, s[8:9]
	s_cbranch_execnz .LBB0_1154

.LBB0_1170:
	v_mul_f32_e32 v136, 0xbfb8aa3b, v2
	v_exp_f32_e32 v136, v136
	s_nop 0
	v_add_f32_e32 v136, 1.0, v136
	s_nop 0
	v_rcp_f32_e32 v138, v136
	v_mov_b64_e32 v[136:137], s[40:41]
	v_mad_i64_i32 v[136:137], s[8:9], v182, s95, v[136:137]
	v_lshl_add_u64 v[134:135], v[134:135], 2, v[136:137]
	flat_store_dword v[134:135], v138
	s_or_b64 exec, exec, s[6:7]
	s_and_saveexec_b64 s[6:7], s[4:5]
	s_xor_b64 s[6:7], exec, s[6:7]
	s_cbranch_execnz .LBB0_1156

.LBB0_1172:
	v_mul_f32_e32 v132, 0xbfb8aa3b, v3
	v_exp_f32_e32 v132, v132
	s_nop 0
	v_add_f32_e32 v132, 1.0, v132
	s_nop 0
	v_rcp_f32_e32 v134, v132
	v_mov_b64_e32 v[132:133], s[40:41]
	v_mad_i64_i32 v[132:133], s[4:5], v182, s95, v[132:133]
	v_lshl_add_u64 v[130:131], v[130:131], 2, v[132:133]
	flat_store_dword v[130:131], v134

; DI unsigned pk2(float lo, float hi) { f32x2 v = {lo, hi}; bf16x2_t b = __builtin_convertvector(v, bf16x2_t); return __builtin_bit_cast(unsigned, b); }
; DI float bflo(unsigned u) { return __uint_as_float(u << 16); }
; DI float bfhi(unsigned u) { return __uint_as_float(u & 0xffff0000u); }
; DI float siluf_(float x) { return x / (1.f + __expf(-x)); }
; DI void conv_phase(int wv, const Params& P) {
;     ...
;     for (int it = gt; it < (MTOK / 8) * 192; it += NGT) {
;         const int tt = it / 192, cg8 = it % 192, c0 = cg8 * 8, r0 = tt * 8, t0 = r0 & (SEQ - 1), b = r0 >> 13;
;         float w[4][8], bias[8];
; #pragma unroll
;         for (int k = 0; k < 4; ++k) { const f32x4 a = *(const f32x4*)(cw + k * 1536 + c0), bq = *(const f32x4*)(cw + k * 1536 + c0 + 4);
; #pragma unroll
;             for (int e = 0; e < 4; ++e) { w[k][e] = a[e]; w[k][4 + e] = bq[e]; } }
;         { const f32x4 a = *(const f32x4*)(cb + c0), bq = *(const f32x4*)(cb + c0 + 4);
; #pragma unroll
;           for (int e = 0; e < 4; ++e) { bias[e] = a[e]; bias[4 + e] = bq[e]; } }
;         float x[11][8];
; #pragma unroll
;         for (int i = 0; i < 11; ++i) { u32x4 q = (u32x4){0u, 0u, 0u, 0u}; if (i >= 3 || t0 != 0) q = *(const u32x4*)(XBC + (size_t)(r0 + i - 3) * 1536 + c0);
; #pragma unroll
;             for (int e = 0; e < 4; ++e) { x[i][2 * e] = bflo(q[e]); x[i][2 * e + 1] = bfhi(q[e]); } }
;         unsigned o[8][4];
; #pragma unroll
;         for (int i = 0; i < 8; ++i) { float y[8];
; #pragma unroll
;             for (int e = 0; e < 8; ++e) { float s = bias[e];
; #pragma unroll
;                 for (int k = 0; k < 4; ++k) s += w[k][e] * x[i + k][e];
;                 y[e] = siluf_(s); }
; #pragma unroll
;             for (int e = 0; e < 4; ++e) o[i][e] = pk2(y[2 * e], y[2 * e + 1]); }
.LBB0_1310:
	s_or_b64 exec, exec, s[26:27]
	v_mad_i64_i32 v[4:5], s[26:27], v94, s40, v[8:9]
	flat_load_dwordx4 v[4:7], v[4:5]
	v_or_b32_e32 v102, 4, v94
	v_mad_i64_i32 v[12:13], s[26:27], v102, s40, v[8:9]
	v_or_b32_e32 v98, 5, v94
	v_or_b32_e32 v100, 6, v94
	v_or_b32_e32 v106, 2, v94
	v_or_b32_e32 v104, 3, v94
	v_mad_i64_i32 v[14:15], s[26:27], v98, s40, v[8:9]
	flat_load_dwordx4 v[50:53], v[12:13]
	flat_load_dwordx4 v[16:19], v[14:15]
	v_mad_i64_i32 v[12:13], s[26:27], v100, s40, v[8:9]
	v_or_b32_e32 v96, 7, v94
	v_or_b32_e32 v108, 1, v94
	v_mad_i64_i32 v[10:11], s[26:27], v106, s40, v[8:9]
	v_mad_i64_i32 v[20:21], s[26:27], v104, s40, v[8:9]
	flat_load_dwordx4 v[46:49], v[12:13]
	v_mad_i64_i32 v[12:13], s[26:27], v96, s40, v[8:9]
	v_mad_i64_i32 v[8:9], s[26:27], v108, s40, v[8:9]
	flat_load_dwordx4 v[54:57], v[12:13]
	s_nop 0
	flat_load_dwordx4 v[12:15], v[10:11]
	s_nop 0
	flat_load_dwordx4 v[20:23], v[20:21]
	s_waitcnt vmcnt(0) lgkmcnt(0)
	v_lshlrev_b32_e32 v36, 16, v78
	flat_load_dwordx4 v[8:11], v[8:9]
	v_and_b32_e32 v37, 0xffff0000, v78
	v_lshlrev_b32_e32 v126, 16, v82
	v_and_b32_e32 v127, 0xffff0000, v82
	v_pk_fma_f32 v[36:37], v[58:59], v[36:37], v[74:75]
	v_lshlrev_b32_e32 v128, 16, v0
	v_and_b32_e32 v129, 0xffff0000, v0
	v_pk_fma_f32 v[36:37], v[62:63], v[126:127], v[36:37]
	v_pk_fma_f32 v[126:127], v[58:59], v[126:127], v[74:75]
	v_pk_fma_f32 v[122:123], v[66:67], v[128:129], v[36:37]
	v_pk_fma_f32 v[126:127], v[62:63], v[128:129], v[126:127]
	v_pk_fma_f32 v[148:149], v[58:59], v[128:129], v[74:75]
	v_lshlrev_b32_e32 v114, 16, v79
	v_and_b32_e32 v115, 0xffff0000, v79
	v_mad_u64_u32 v[78:79], s[26:27], v89, s42, v[86:87]
	v_lshlrev_b32_e32 v112, 16, v83
	v_and_b32_e32 v113, 0xffff0000, v83
	v_pk_fma_f32 v[114:115], v[60:61], v[114:115], v[76:77]
	v_lshlrev_b32_e32 v110, 16, v84
	v_pk_fma_f32 v[114:115], v[64:65], v[112:113], v[114:115]
	v_pk_fma_f32 v[112:113], v[60:61], v[112:113], v[76:77]
	v_and_b32_e32 v111, 0xffff0000, v84
	v_lshlrev_b32_e32 v82, 16, v85
	v_and_b32_e32 v83, 0xffff0000, v85
	v_lshlrev_b32_e32 v84, 16, v80
	v_and_b32_e32 v85, 0xffff0000, v80
	v_pk_fma_f32 v[84:85], v[24:25], v[84:85], v[42:43]
	v_lshlrev_b32_e32 v80, 16, v81
	v_pk_fma_f32 v[84:85], v[28:29], v[110:111], v[84:85]
	v_pk_fma_f32 v[110:111], v[24:25], v[110:111], v[42:43]
	v_and_b32_e32 v81, 0xffff0000, v81
	v_ashrrev_i32_e32 v95, 31, v94
	v_ashrrev_i32_e32 v109, 31, v108
	v_ashrrev_i32_e32 v107, 31, v106
	v_ashrrev_i32_e32 v105, 31, v104
	v_ashrrev_i32_e32 v103, 31, v102
	v_ashrrev_i32_e32 v99, 31, v98
	v_ashrrev_i32_e32 v101, 31, v100
	v_ashrrev_i32_e32 v97, 31, v96
	v_lshlrev_b32_e32 v130, 16, v4
	v_and_b32_e32 v131, 0xffff0000, v4
	v_pk_fma_f32 v[138:139], v[70:71], v[130:131], v[122:123]
	v_pk_fma_f32 v[126:127], v[66:67], v[130:131], v[126:127]
	v_mul_f32_e32 v0, 0xbfb8aa3b, v138
	v_mul_f32_e32 v4, 0xbfb8aa3b, v139
	v_exp_f32_e32 v142, v0
	v_exp_f32_e32 v143, v4
	v_pk_fma_f32 v[146:147], v[58:59], v[130:131], v[74:75]
	v_pk_fma_f32 v[130:131], v[62:63], v[130:131], v[148:149]
	v_lshlrev_b32_e32 v116, 16, v16
	v_pk_add_f32 v[142:143], v[142:143], 1.0 op_sel_hi:[1,0]
	v_and_b32_e32 v117, 0xffff0000, v16
	v_lshlrev_b32_e32 v36, 16, v50
	v_and_b32_e32 v37, 0xffff0000, v50
	v_lshlrev_b32_e32 v118, 16, v46
	v_and_b32_e32 v119, 0xffff0000, v46
	v_lshlrev_b32_e32 v120, 16, v54
	v_lshlrev_b32_e32 v134, 16, v12
	v_and_b32_e32 v135, 0xffff0000, v12
	v_lshlrev_b32_e32 v132, 16, v20
	s_waitcnt vmcnt(0) lgkmcnt(0)
	v_lshlrev_b32_e32 v136, 16, v8
	v_and_b32_e32 v137, 0xffff0000, v8
	v_and_b32_e32 v133, 0xffff0000, v20
	v_pk_fma_f32 v[126:127], v[70:71], v[136:137], v[126:127]
	s_nop 0
	v_mul_f32_e32 v20, 0xbfb8aa3b, v126
	v_exp_f32_e32 v128, v20
	v_mul_f32_e32 v20, 0xbfb8aa3b, v127
	v_exp_f32_e32 v129, v20
	v_rcp_f32_e32 v0, v143
	s_nop 0
	v_mul_f32_e32 v0, v139, v0
	v_pk_add_f32 v[128:129], v[128:129], 1.0 op_sel_hi:[1,0]
	v_rcp_f32_e32 v4, v142
	s_nop 0
	v_mul_f32_e32 v4, v138, v4
	v_cvt_pk_bf16_f32 v0, v4, v0
	v_pk_fma_f32 v[130:131], v[66:67], v[136:137], v[130:131]
	v_pk_fma_f32 v[144:145], v[58:59], v[136:137], v[74:75]
	v_pk_fma_f32 v[130:131], v[70:71], v[134:135], v[130:131]
	v_pk_fma_f32 v[146:147], v[62:63], v[136:137], v[146:147]
	v_mul_f32_e32 v46, 0xbfb8aa3b, v130
	v_exp_f32_e32 v136, v46
	v_mul_f32_e32 v46, 0xbfb8aa3b, v131
	v_exp_f32_e32 v137, v46
	s_nop 0
	v_pk_add_f32 v[136:137], v[136:137], 1.0 op_sel_hi:[1,0]
	v_rcp_f32_e32 v4, v129
	s_nop 0
	v_mul_f32_e32 v4, v127, v4
	v_rcp_f32_e32 v8, v128
	s_nop 0
	v_mul_f32_e32 v8, v126, v8
	v_cvt_pk_bf16_f32 v4, v8, v4
	v_pk_fma_f32 v[126:127], v[66:67], v[134:135], v[146:147]
	s_nop 0
	v_pk_fma_f32 v[126:127], v[70:71], v[132:133], v[126:127]
	s_nop 0
	v_mul_f32_e32 v50, 0xbfb8aa3b, v126
	v_exp_f32_e32 v128, v50
	v_mul_f32_e32 v50, 0xbfb8aa3b, v127
	v_exp_f32_e32 v129, v50
	s_nop 0
	v_pk_add_f32 v[128:129], v[128:129], 1.0 op_sel_hi:[1,0]
	v_rcp_f32_e32 v8, v137
	s_nop 0
	v_mul_f32_e32 v8, v131, v8
	v_rcp_f32_e32 v12, v136
	s_nop 0
	v_mul_f32_e32 v12, v130, v12
	v_cvt_pk_bf16_f32 v8, v12, v8
	v_pk_fma_f32 v[144:145], v[62:63], v[134:135], v[144:145]
	s_nop 0
	v_pk_fma_f32 v[130:131], v[66:67], v[132:133], v[144:145]
	v_and_b32_e32 v121, 0xffff0000, v54
	v_pk_fma_f32 v[130:131], v[70:71], v[36:37], v[130:131]
	v_pk_fma_f32 v[140:141], v[58:59], v[134:135], v[74:75]
	v_mul_f32_e32 v54, 0xbfb8aa3b, v130
	v_pk_fma_f32 v[122:123], v[58:59], v[132:133], v[74:75]
	v_pk_fma_f32 v[140:141], v[62:63], v[132:133], v[140:141]
	v_exp_f32_e32 v132, v54
	v_mul_f32_e32 v54, 0xbfb8aa3b, v131
	v_exp_f32_e32 v133, v54
	s_nop 0
	v_pk_add_f32 v[132:133], v[132:133], 1.0 op_sel_hi:[1,0]
	v_rcp_f32_e32 v12, v129
; DI unsigned pk2(float lo, float hi) { f32x2 v = {lo, hi}; bf16x2_t b = __builtin_convertvector(v, bf16x2_t); return __builtin_bit_cast(unsigned, b); }
; DI float bflo(unsigned u) { return __uint_as_float(u << 16); }
; DI float bfhi(unsigned u) { return __uint_as_float(u & 0xffff0000u); }
; DI float siluf_(float x) { return x / (1.f + __expf(-x)); }
; DI void conv_phase(int wv, const Params& P) {
;     ...
;         for (int i = 0; i < 11; ++i) { u32x4 q = (u32x4){0u, 0u, 0u, 0u}; if (i >= 3 || t0 != 0) q = *(const u32x4*)(XBC + (size_t)(r0 + i - 3) * 1536 + c0);
; #pragma unroll
;             for (int e = 0; e < 4; ++e) { x[i][2 * e] = bflo(q[e]); x[i][2 * e + 1] = bfhi(q[e]); } }
;         unsigned o[8][4];
; #pragma unroll
;         for (int i = 0; i < 8; ++i) { float y[8];
; #pragma unroll
;             for (int e = 0; e < 8; ++e) { float s = bias[e];
; #pragma unroll
;                 for (int k = 0; k < 4; ++k) s += w[k][e] * x[i + k][e];
;                 y[e] = siluf_(s); }
; #pragma unroll
;             for (int e = 0; e < 4; ++e) o[i][e] = pk2(y[2 * e], y[2 * e + 1]); }
	s_nop 0
	v_mul_f32_e32 v12, v127, v12
	v_rcp_f32_e32 v16, v128
	s_nop 0
	v_mul_f32_e32 v16, v126, v16
	v_cvt_pk_bf16_f32 v12, v16, v12
	v_pk_fma_f32 v[126:127], v[66:67], v[36:37], v[140:141]
	s_nop 0
	v_pk_fma_f32 v[126:127], v[70:71], v[116:117], v[126:127]
	s_nop 0
	v_mul_f32_e32 v79, 0xbfb8aa3b, v126
	v_exp_f32_e32 v128, v79
	v_mul_f32_e32 v79, 0xbfb8aa3b, v127
	v_exp_f32_e32 v129, v79
	s_nop 0
	v_pk_add_f32 v[128:129], v[128:129], 1.0 op_sel_hi:[1,0]
	v_rcp_f32_e32 v16, v133
	s_nop 0
	v_mul_f32_e32 v16, v131, v16
	v_rcp_f32_e32 v20, v132
	s_nop 0
	v_mul_f32_e32 v20, v130, v20
	v_cvt_pk_bf16_f32 v16, v20, v16
	v_pk_fma_f32 v[122:123], v[62:63], v[36:37], v[122:123]
	s_nop 0
	v_pk_fma_f32 v[122:123], v[66:67], v[116:117], v[122:123]
	s_nop 0
	v_pk_fma_f32 v[122:123], v[70:71], v[118:119], v[122:123]
	s_nop 0
	v_mul_f32_e32 v90, 0xbfb8aa3b, v122
	v_exp_f32_e32 v130, v90
	v_mul_f32_e32 v90, 0xbfb8aa3b, v123
	v_exp_f32_e32 v131, v90
	s_nop 0
	v_pk_add_f32 v[130:131], v[130:131], 1.0 op_sel_hi:[1,0]
	v_rcp_f32_e32 v20, v129
	s_nop 0
	v_mul_f32_e32 v20, v127, v20
	v_rcp_f32_e32 v46, v128
	s_nop 0
	v_mul_f32_e32 v46, v126, v46
	v_cvt_pk_bf16_f32 v20, v46, v20
	v_pk_fma_f32 v[36:37], v[58:59], v[36:37], v[74:75]
	s_nop 0
	v_pk_fma_f32 v[36:37], v[62:63], v[116:117], v[36:37]
	s_nop 0
	v_pk_fma_f32 v[36:37], v[66:67], v[118:119], v[36:37]
	s_nop 0
	v_pk_fma_f32 v[58:59], v[70:71], v[120:121], v[36:37]
	s_nop 0
	v_mul_f32_e32 v36, 0xbfb8aa3b, v58
	v_mul_f32_e32 v37, 0xbfb8aa3b, v59
	v_exp_f32_e32 v36, v36
	v_exp_f32_e32 v37, v37
	s_nop 0
	v_pk_add_f32 v[62:63], v[36:37], 1.0 op_sel_hi:[1,0]
	v_rcp_f32_e32 v46, v131
	s_nop 0
	v_mul_f32_e32 v46, v123, v46
	v_rcp_f32_e32 v36, v130
	s_nop 0
	v_mul_f32_e32 v36, v122, v36
	v_cvt_pk_bf16_f32 v36, v36, v46
	v_lshlrev_b32_e32 v122, 16, v1
	v_and_b32_e32 v123, 0xffff0000, v1
	v_lshlrev_b32_e32 v120, 16, v5
	v_and_b32_e32 v121, 0xffff0000, v5
	v_pk_fma_f32 v[114:115], v[68:69], v[122:123], v[114:115]
	s_nop 0
	v_pk_fma_f32 v[114:115], v[72:73], v[120:121], v[114:115]
	s_nop 0
	v_mul_f32_e32 v1, 0xbfb8aa3b, v114
	v_exp_f32_e32 v126, v1
	v_mul_f32_e32 v1, 0xbfb8aa3b, v115
	v_exp_f32_e32 v127, v1
	v_rcp_f32_e32 v37, v63
	s_nop 0
	v_mul_f32_e32 v70, v59, v37
	v_pk_add_f32 v[126:127], v[126:127], 1.0 op_sel_hi:[1,0]
	v_lshlrev_b32_e32 v118, 16, v9
	v_and_b32_e32 v119, 0xffff0000, v9
	v_lshlrev_b32_e32 v116, 16, v13
	v_and_b32_e32 v117, 0xffff0000, v13
	v_rcp_f32_e32 v37, v62
	s_nop 0
	v_mul_f32_e32 v71, v58, v37
	v_lshlrev_b32_e32 v58, 16, v17
	v_and_b32_e32 v59, 0xffff0000, v17
	v_pk_fma_f32 v[112:113], v[64:65], v[122:123], v[112:113]
	v_lshlrev_b32_e32 v74, 16, v21
	v_pk_fma_f32 v[112:113], v[68:69], v[120:121], v[112:113]
	v_and_b32_e32 v75, 0xffff0000, v21
	v_pk_fma_f32 v[112:113], v[72:73], v[118:119], v[112:113]
	s_nop 0
	v_mul_f32_e32 v21, 0xbfb8aa3b, v112
	v_pk_fma_f32 v[132:133], v[60:61], v[122:123], v[76:77]
	v_exp_f32_e32 v122, v21
	v_mul_f32_e32 v21, 0xbfb8aa3b, v113
	v_exp_f32_e32 v123, v21
	v_rcp_f32_e32 v1, v127
	s_nop 0
	v_mul_f32_e32 v1, v115, v1
	v_pk_add_f32 v[122:123], v[122:123], 1.0 op_sel_hi:[1,0]
	v_rcp_f32_e32 v5, v126
	s_nop 0
	v_mul_f32_e32 v5, v114, v5
	v_cvt_pk_bf16_f32 v1, v5, v1
	v_pk_fma_f32 v[114:115], v[64:65], v[120:121], v[132:133]
	v_pk_fma_f32 v[130:131], v[60:61], v[120:121], v[76:77]
	v_pk_fma_f32 v[114:115], v[68:69], v[118:119], v[114:115]
	v_pk_fma_f32 v[128:129], v[60:61], v[118:119], v[76:77]
	v_pk_fma_f32 v[114:115], v[72:73], v[116:117], v[114:115]
	v_pk_fma_f32 v[130:131], v[64:65], v[118:119], v[130:131]
	v_mul_f32_e32 v37, 0xbfb8aa3b, v114
	v_exp_f32_e32 v118, v37
	v_mul_f32_e32 v37, 0xbfb8aa3b, v115
	v_exp_f32_e32 v119, v37
	s_nop 0
	v_pk_add_f32 v[118:119], v[118:119], 1.0 op_sel_hi:[1,0]
	v_rcp_f32_e32 v5, v123
	s_nop 0
	v_mul_f32_e32 v5, v113, v5
	v_rcp_f32_e32 v9, v122
	s_nop 0
	v_mul_f32_e32 v9, v112, v9
	v_cvt_pk_bf16_f32 v5, v9, v5
	v_pk_fma_f32 v[112:113], v[68:69], v[116:117], v[130:131]
	v_pk_fma_f32 v[66:67], v[60:61], v[116:117], v[76:77]
	v_pk_fma_f32 v[112:113], v[72:73], v[74:75], v[112:113]
	v_pk_fma_f32 v[128:129], v[64:65], v[116:117], v[128:129]
	v_mul_f32_e32 v79, 0xbfb8aa3b, v112
	v_exp_f32_e32 v116, v79
	v_mul_f32_e32 v79, 0xbfb8aa3b, v113
	v_exp_f32_e32 v117, v79
	s_nop 0
	v_pk_add_f32 v[116:117], v[116:117], 1.0 op_sel_hi:[1,0]
	v_rcp_f32_e32 v9, v119
	s_nop 0
	v_mul_f32_e32 v9, v115, v9
	v_rcp_f32_e32 v13, v118
	s_nop 0
	v_mul_f32_e32 v13, v114, v13
	v_cvt_pk_bf16_f32 v9, v13, v9
	v_lshlrev_b32_e32 v50, 16, v51
	v_and_b32_e32 v51, 0xffff0000, v51
	v_pk_fma_f32 v[62:63], v[60:61], v[74:75], v[76:77]
	v_pk_fma_f32 v[66:67], v[64:65], v[74:75], v[66:67]
	v_pk_fma_f32 v[74:75], v[68:69], v[74:75], v[128:129]
	s_nop 0
	v_pk_fma_f32 v[74:75], v[72:73], v[50:51], v[74:75]
	s_nop 0
	v_mul_f32_e32 v90, 0xbfb8aa3b, v74
	v_exp_f32_e32 v114, v90
	v_mul_f32_e32 v90, 0xbfb8aa3b, v75
	v_exp_f32_e32 v115, v90
	s_nop 0
	v_pk_add_f32 v[114:115], v[114:115], 1.0 op_sel_hi:[1,0]
	v_rcp_f32_e32 v13, v117
	s_nop 0
	v_mul_f32_e32 v13, v113, v13
	v_rcp_f32_e32 v17, v116
	s_nop 0
	v_mul_f32_e32 v17, v112, v17
	v_cvt_pk_bf16_f32 v13, v17, v13
	v_pk_fma_f32 v[66:67], v[68:69], v[50:51], v[66:67]
	s_nop 0
	v_pk_fma_f32 v[66:67], v[72:73], v[58:59], v[66:67]
	s_nop 0
	v_mul_f32_e32 v90, 0xbfb8aa3b, v66
	v_exp_f32_e32 v112, v90
	v_mul_f32_e32 v90, 0xbfb8aa3b, v67
	v_exp_f32_e32 v113, v90
	v_rcp_f32_e32 v17, v115
	s_nop 0
	v_mul_f32_e32 v17, v75, v17
	v_pk_add_f32 v[112:113], v[112:113], 1.0 op_sel_hi:[1,0]
	v_rcp_f32_e32 v21, v114
	s_nop 0
	v_mul_f32_e32 v21, v74, v21
	v_cvt_pk_bf16_f32 v17, v21, v17
	v_pk_fma_f32 v[62:63], v[64:65], v[50:51], v[62:63]
; DI unsigned pk2(float lo, float hi) { f32x2 v = {lo, hi}; bf16x2_t b = __builtin_convertvector(v, bf16x2_t); return __builtin_bit_cast(unsigned, b); }
; DI float bflo(unsigned u) { return __uint_as_float(u << 16); }
; DI float bfhi(unsigned u) { return __uint_as_float(u & 0xffff0000u); }
; DI float siluf_(float x) { return x / (1.f + __expf(-x)); }
; DI void conv_phase(int wv, const Params& P) {
;     ...
;         for (int i = 0; i < 11; ++i) { u32x4 q = (u32x4){0u, 0u, 0u, 0u}; if (i >= 3 || t0 != 0) q = *(const u32x4*)(XBC + (size_t)(r0 + i - 3) * 1536 + c0);
; #pragma unroll
;             for (int e = 0; e < 4; ++e) { x[i][2 * e] = bflo(q[e]); x[i][2 * e + 1] = bfhi(q[e]); } }
;         unsigned o[8][4];
; #pragma unroll
;         for (int i = 0; i < 8; ++i) { float y[8];
; #pragma unroll
;             for (int e = 0; e < 8; ++e) { float s = bias[e];
; #pragma unroll
;                 for (int k = 0; k < 4; ++k) s += w[k][e] * x[i + k][e];
;                 y[e] = siluf_(s); }
; #pragma unroll
;             for (int e = 0; e < 4; ++e) o[i][e] = pk2(y[2 * e], y[2 * e + 1]); }
	v_lshlrev_b32_e32 v46, 16, v47
	v_and_b32_e32 v47, 0xffff0000, v47
	v_pk_fma_f32 v[62:63], v[68:69], v[58:59], v[62:63]
	s_nop 0
	v_pk_fma_f32 v[62:63], v[72:73], v[46:47], v[62:63]
	v_rcp_f32_e32 v21, v113
	s_nop 0
	v_mul_f32_e32 v21, v67, v21
	v_mul_f32_e32 v74, 0xbfb8aa3b, v62
	v_mul_f32_e32 v75, 0xbfb8aa3b, v63
	v_exp_f32_e32 v74, v74
	v_exp_f32_e32 v75, v75
	s_nop 0
	v_pk_add_f32 v[74:75], v[74:75], 1.0 op_sel_hi:[1,0]
	v_rcp_f32_e32 v37, v112
	s_nop 0
	v_mul_f32_e32 v37, v66, v37
	v_cvt_pk_bf16_f32 v21, v37, v21
	v_pk_fma_f32 v[50:51], v[60:61], v[50:51], v[76:77]
	s_nop 0
	v_pk_fma_f32 v[50:51], v[64:65], v[58:59], v[50:51]
	v_lshlrev_b32_e32 v54, 16, v55
	v_and_b32_e32 v55, 0xffff0000, v55
	v_pk_fma_f32 v[46:47], v[68:69], v[46:47], v[50:51]
	s_nop 0
	v_pk_fma_f32 v[46:47], v[72:73], v[54:55], v[46:47]
	s_nop 0
	v_mul_f32_e32 v50, 0xbfb8aa3b, v46
	v_mul_f32_e32 v51, 0xbfb8aa3b, v47
	v_exp_f32_e32 v50, v50
	v_exp_f32_e32 v51, v51
	v_rcp_f32_e32 v37, v75
	s_nop 0
	v_mul_f32_e32 v37, v63, v37
	v_pk_add_f32 v[50:51], v[50:51], 1.0 op_sel_hi:[1,0]
	v_rcp_f32_e32 v54, v74
	s_nop 0
	v_mul_f32_e32 v54, v62, v54
	v_cvt_pk_bf16_f32 v37, v54, v37
	v_lshlrev_b32_e32 v76, 16, v2
	v_and_b32_e32 v77, 0xffff0000, v2
	v_lshlrev_b32_e32 v74, 16, v6
	v_and_b32_e32 v75, 0xffff0000, v6
	v_pk_fma_f32 v[84:85], v[32:33], v[76:77], v[84:85]
	s_nop 0
	v_pk_fma_f32 v[84:85], v[38:39], v[74:75], v[84:85]
	s_nop 0
	v_mul_f32_e32 v2, 0xbfb8aa3b, v84
	v_exp_f32_e32 v112, v2
	v_mul_f32_e32 v2, 0xbfb8aa3b, v85
	v_exp_f32_e32 v113, v2
	v_rcp_f32_e32 v54, v51
	s_nop 0
	v_mul_f32_e32 v64, v47, v54
	v_pk_add_f32 v[112:113], v[112:113], 1.0 op_sel_hi:[1,0]
	v_lshlrev_b32_e32 v72, 16, v10
	v_and_b32_e32 v73, 0xffff0000, v10
	v_lshlrev_b32_e32 v68, 16, v14
	v_and_b32_e32 v69, 0xffff0000, v14
	v_rcp_f32_e32 v47, v50
	s_nop 0
	v_mul_f32_e32 v65, v46, v47
	v_lshlrev_b32_e32 v50, 16, v18
	v_and_b32_e32 v51, 0xffff0000, v18
	v_pk_fma_f32 v[118:119], v[24:25], v[76:77], v[42:43]
	v_pk_fma_f32 v[76:77], v[28:29], v[76:77], v[110:111]
	s_nop 0
	v_pk_fma_f32 v[76:77], v[32:33], v[74:75], v[76:77]
	v_lshlrev_b32_e32 v66, 16, v22
	v_and_b32_e32 v67, 0xffff0000, v22
	v_pk_fma_f32 v[76:77], v[38:39], v[72:73], v[76:77]
	s_nop 0
	v_mul_f32_e32 v22, 0xbfb8aa3b, v76
	v_exp_f32_e32 v110, v22
	v_mul_f32_e32 v22, 0xbfb8aa3b, v77
	v_exp_f32_e32 v111, v22
	v_rcp_f32_e32 v2, v113
	s_nop 0
	v_mul_f32_e32 v2, v85, v2
	v_pk_add_f32 v[110:111], v[110:111], 1.0 op_sel_hi:[1,0]
	v_rcp_f32_e32 v6, v112
	s_nop 0
	v_mul_f32_e32 v6, v84, v6
	v_cvt_pk_bf16_f32 v2, v6, v2
	v_pk_fma_f32 v[116:117], v[24:25], v[74:75], v[42:43]
	v_pk_fma_f32 v[74:75], v[28:29], v[74:75], v[118:119]
	v_pk_fma_f32 v[114:115], v[24:25], v[72:73], v[42:43]
	v_pk_fma_f32 v[116:117], v[28:29], v[72:73], v[116:117]
	v_pk_fma_f32 v[72:73], v[32:33], v[72:73], v[74:75]
	v_lshlrev_b32_e32 v54, 16, v48
	v_pk_fma_f32 v[72:73], v[38:39], v[68:69], v[72:73]
	v_and_b32_e32 v55, 0xffff0000, v48
	v_mul_f32_e32 v48, 0xbfb8aa3b, v72
	v_exp_f32_e32 v74, v48
	v_mul_f32_e32 v48, 0xbfb8aa3b, v73
	v_exp_f32_e32 v75, v48
	s_nop 0
	v_pk_add_f32 v[74:75], v[74:75], 1.0 op_sel_hi:[1,0]
	v_rcp_f32_e32 v6, v111
	s_nop 0
	v_mul_f32_e32 v6, v77, v6
	v_rcp_f32_e32 v10, v110
	s_nop 0
	v_mul_f32_e32 v10, v76, v10
	v_cvt_pk_bf16_f32 v6, v10, v6
	v_pk_fma_f32 v[62:63], v[24:25], v[68:69], v[42:43]
	v_pk_fma_f32 v[114:115], v[28:29], v[68:69], v[114:115]
	v_pk_fma_f32 v[68:69], v[32:33], v[68:69], v[116:117]
	v_lshlrev_b32_e32 v46, 16, v52
	v_pk_fma_f32 v[68:69], v[38:39], v[66:67], v[68:69]
	v_and_b32_e32 v47, 0xffff0000, v52
	v_mul_f32_e32 v52, 0xbfb8aa3b, v68
	v_exp_f32_e32 v76, v52
	v_mul_f32_e32 v52, 0xbfb8aa3b, v69
	v_exp_f32_e32 v77, v52
	s_nop 0
	v_pk_add_f32 v[76:77], v[76:77], 1.0 op_sel_hi:[1,0]
	v_rcp_f32_e32 v10, v75
	s_nop 0
	v_mul_f32_e32 v10, v73, v10
	v_rcp_f32_e32 v14, v74
	s_nop 0
	v_mul_f32_e32 v14, v72, v14
	v_cvt_pk_bf16_f32 v10, v14, v10
	v_pk_fma_f32 v[60:61], v[24:25], v[66:67], v[42:43]
	v_pk_fma_f32 v[62:63], v[28:29], v[66:67], v[62:63]
	v_pk_fma_f32 v[66:67], v[32:33], v[66:67], v[114:115]
	v_lshlrev_b32_e32 v58, 16, v56
	v_pk_fma_f32 v[66:67], v[38:39], v[46:47], v[66:67]
	v_and_b32_e32 v59, 0xffff0000, v56
	v_mul_f32_e32 v56, 0xbfb8aa3b, v66
	v_exp_f32_e32 v72, v56
	v_mul_f32_e32 v56, 0xbfb8aa3b, v67
	v_exp_f32_e32 v73, v56
	s_nop 0
	v_pk_add_f32 v[72:73], v[72:73], 1.0 op_sel_hi:[1,0]
	v_rcp_f32_e32 v14, v77
	s_nop 0
	v_mul_f32_e32 v14, v69, v14
	v_rcp_f32_e32 v18, v76
	s_nop 0
	v_mul_f32_e32 v18, v68, v18
	v_cvt_pk_bf16_f32 v14, v18, v14
	v_pk_fma_f32 v[62:63], v[32:33], v[46:47], v[62:63]
	s_nop 0
	v_pk_fma_f32 v[62:63], v[38:39], v[50:51], v[62:63]
	v_rcp_f32_e32 v18, v73
	s_nop 0
	v_mul_f32_e32 v18, v67, v18
	v_mul_f32_e32 v67, 0xbfb8aa3b, v62
	v_exp_f32_e32 v68, v67
	v_mul_f32_e32 v67, 0xbfb8aa3b, v63
	v_exp_f32_e32 v69, v67
	s_nop 0
	v_pk_add_f32 v[68:69], v[68:69], 1.0 op_sel_hi:[1,0]
	v_rcp_f32_e32 v22, v72
	s_nop 0
	v_mul_f32_e32 v22, v66, v22
	v_cvt_pk_bf16_f32 v18, v22, v18
	v_pk_fma_f32 v[60:61], v[28:29], v[46:47], v[60:61]
	s_nop 0
	v_pk_fma_f32 v[60:61], v[32:33], v[50:51], v[60:61]
	s_nop 0
	v_pk_fma_f32 v[60:61], v[38:39], v[54:55], v[60:61]
	s_nop 0
	v_mul_f32_e32 v66, 0xbfb8aa3b, v60
	v_mul_f32_e32 v67, 0xbfb8aa3b, v61
	v_exp_f32_e32 v66, v66
	v_exp_f32_e32 v67, v67
	v_rcp_f32_e32 v22, v69
	s_nop 0
	v_mul_f32_e32 v22, v63, v22
	v_pk_add_f32 v[66:67], v[66:67], 1.0 op_sel_hi:[1,0]
	v_rcp_f32_e32 v48, v68
	s_nop 0
	v_mul_f32_e32 v48, v62, v48
	v_cvt_pk_bf16_f32 v22, v48, v22
	v_pk_fma_f32 v[24:25], v[24:25], v[46:47], v[42:43]
	s_nop 0
	v_pk_fma_f32 v[24:25], v[28:29], v[50:51], v[24:25]
	s_nop 0
; DI unsigned pk2(float lo, float hi) { f32x2 v = {lo, hi}; bf16x2_t b = __builtin_convertvector(v, bf16x2_t); return __builtin_bit_cast(unsigned, b); }
; DI float bflo(unsigned u) { return __uint_as_float(u << 16); }
; DI float bfhi(unsigned u) { return __uint_as_float(u & 0xffff0000u); }
; DI float siluf_(float x) { return x / (1.f + __expf(-x)); }
; DI void conv_phase(int wv, const Params& P) {
;     ...
;         for (int i = 0; i < 11; ++i) { u32x4 q = (u32x4){0u, 0u, 0u, 0u}; if (i >= 3 || t0 != 0) q = *(const u32x4*)(XBC + (size_t)(r0 + i - 3) * 1536 + c0);
; #pragma unroll
;             for (int e = 0; e < 4; ++e) { x[i][2 * e] = bflo(q[e]); x[i][2 * e + 1] = bfhi(q[e]); } }
;         unsigned o[8][4];
; #pragma unroll
;         for (int i = 0; i < 8; ++i) { float y[8];
; #pragma unroll
;             for (int e = 0; e < 8; ++e) { float s = bias[e];
; #pragma unroll
;                 for (int k = 0; k < 4; ++k) s += w[k][e] * x[i + k][e];
;                 y[e] = siluf_(s); }
; #pragma unroll
;             for (int e = 0; e < 4; ++e) o[i][e] = pk2(y[2 * e], y[2 * e + 1]); }
;         if (c0 < 1024) {
	v_pk_fma_f32 v[24:25], v[32:33], v[54:55], v[24:25]
	s_nop 0
	v_pk_fma_f32 v[24:25], v[38:39], v[58:59], v[24:25]
	s_nop 0
	v_mul_f32_e32 v28, 0xbfb8aa3b, v24
	v_mul_f32_e32 v29, 0xbfb8aa3b, v25
	v_exp_f32_e32 v28, v28
	v_exp_f32_e32 v29, v29
	v_rcp_f32_e32 v48, v67
	s_nop 0
	v_mul_f32_e32 v48, v61, v48
	v_pk_add_f32 v[28:29], v[28:29], 1.0 op_sel_hi:[1,0]
	v_rcp_f32_e32 v32, v66
	s_nop 0
	v_mul_f32_e32 v32, v60, v32
	v_cvt_pk_bf16_f32 v38, v32, v48
	v_rcp_f32_e32 v32, v29
	s_nop 0
	v_mul_f32_e32 v76, v25, v32
	v_pk_fma_f32 v[60:61], v[26:27], v[80:81], v[44:45]
	v_lshlrev_b32_e32 v58, 16, v3
	v_and_b32_e32 v59, 0xffff0000, v3
	v_pk_fma_f32 v[60:61], v[30:31], v[82:83], v[60:61]
	v_lshlrev_b32_e32 v42, 16, v57
	v_and_b32_e32 v43, 0xffff0000, v57
	v_lshlrev_b32_e32 v56, 16, v7
	v_and_b32_e32 v57, 0xffff0000, v7
	v_pk_fma_f32 v[60:61], v[34:35], v[58:59], v[60:61]
	v_lshlrev_b32_e32 v54, 16, v11
	v_pk_fma_f32 v[60:61], v[40:41], v[56:57], v[60:61]
	v_and_b32_e32 v55, 0xffff0000, v11
	v_mul_f32_e32 v3, 0xbfb8aa3b, v60
	v_exp_f32_e32 v62, v3
	v_mul_f32_e32 v3, 0xbfb8aa3b, v61
	v_exp_f32_e32 v63, v3
	v_rcp_f32_e32 v25, v28
	s_nop 0
	v_mul_f32_e32 v77, v24, v25
	v_lshlrev_b32_e32 v24, 16, v53
	v_and_b32_e32 v25, 0xffff0000, v53
	v_pk_add_f32 v[62:63], v[62:63], 1.0 op_sel_hi:[1,0]
	v_lshlrev_b32_e32 v52, 16, v15
	v_and_b32_e32 v53, 0xffff0000, v15
	v_lshlrev_b32_e32 v28, 16, v19
	v_and_b32_e32 v29, 0xffff0000, v19
	v_pk_fma_f32 v[74:75], v[26:27], v[82:83], v[44:45]
	v_pk_fma_f32 v[72:73], v[26:27], v[58:59], v[44:45]
	v_pk_fma_f32 v[58:59], v[30:31], v[58:59], v[74:75]
	s_nop 0
	v_pk_fma_f32 v[58:59], v[34:35], v[56:57], v[58:59]
	v_lshlrev_b32_e32 v50, 16, v23
	v_and_b32_e32 v51, 0xffff0000, v23
	v_pk_fma_f32 v[58:59], v[40:41], v[54:55], v[58:59]
	s_nop 0
	v_mul_f32_e32 v23, 0xbfb8aa3b, v58
	v_exp_f32_e32 v74, v23
	v_mul_f32_e32 v23, 0xbfb8aa3b, v59
	v_exp_f32_e32 v75, v23
	v_rcp_f32_e32 v3, v63
	s_nop 0
	v_mul_f32_e32 v3, v61, v3
	v_pk_add_f32 v[74:75], v[74:75], 1.0 op_sel_hi:[1,0]
	v_rcp_f32_e32 v7, v62
	s_nop 0
	v_mul_f32_e32 v7, v60, v7
	v_cvt_pk_bf16_f32 v3, v7, v3
	v_pk_fma_f32 v[68:69], v[26:27], v[56:57], v[44:45]
	v_pk_fma_f32 v[56:57], v[30:31], v[56:57], v[72:73]
	v_pk_fma_f32 v[66:67], v[26:27], v[54:55], v[44:45]
	v_pk_fma_f32 v[68:69], v[30:31], v[54:55], v[68:69]
	v_pk_fma_f32 v[54:55], v[34:35], v[54:55], v[56:57]
	s_nop 0
	v_pk_fma_f32 v[54:55], v[40:41], v[52:53], v[54:55]
	s_nop 0
	v_mul_f32_e32 v39, 0xbfb8aa3b, v54
	v_exp_f32_e32 v56, v39
	v_mul_f32_e32 v39, 0xbfb8aa3b, v55
	v_exp_f32_e32 v57, v39
	s_nop 0
	v_pk_add_f32 v[56:57], v[56:57], 1.0 op_sel_hi:[1,0]
	v_rcp_f32_e32 v7, v75
	s_nop 0
	v_mul_f32_e32 v7, v59, v7
	v_rcp_f32_e32 v11, v74
	s_nop 0
	v_mul_f32_e32 v11, v58, v11
	v_cvt_pk_bf16_f32 v7, v11, v7
	v_lshlrev_b32_e32 v32, 16, v49
	v_and_b32_e32 v33, 0xffff0000, v49
	v_pk_fma_f32 v[48:49], v[26:27], v[52:53], v[44:45]
	v_pk_fma_f32 v[66:67], v[30:31], v[52:53], v[66:67]
	v_pk_fma_f32 v[52:53], v[34:35], v[52:53], v[68:69]
	s_nop 0
	v_pk_fma_f32 v[52:53], v[40:41], v[50:51], v[52:53]
	v_rcp_f32_e32 v11, v57
	s_nop 0
	v_mul_f32_e32 v11, v55, v11
	v_mul_f32_e32 v55, 0xbfb8aa3b, v52
	v_exp_f32_e32 v58, v55
	v_mul_f32_e32 v55, 0xbfb8aa3b, v53
	v_exp_f32_e32 v59, v55
	s_nop 0
	v_pk_add_f32 v[58:59], v[58:59], 1.0 op_sel_hi:[1,0]
	v_rcp_f32_e32 v15, v56
	s_nop 0
	v_mul_f32_e32 v15, v54, v15
	v_cvt_pk_bf16_f32 v11, v15, v11
	v_pk_fma_f32 v[46:47], v[26:27], v[50:51], v[44:45]
	v_pk_fma_f32 v[48:49], v[30:31], v[50:51], v[48:49]
	v_pk_fma_f32 v[50:51], v[34:35], v[50:51], v[66:67]
	s_nop 0
	v_pk_fma_f32 v[50:51], v[40:41], v[24:25], v[50:51]
	s_nop 0
	v_mul_f32_e32 v54, 0xbfb8aa3b, v50
	v_mul_f32_e32 v55, 0xbfb8aa3b, v51
	v_exp_f32_e32 v54, v54
	v_exp_f32_e32 v55, v55
	v_rcp_f32_e32 v15, v59
	s_nop 0
	v_mul_f32_e32 v15, v53, v15
	v_pk_add_f32 v[54:55], v[54:55], 1.0 op_sel_hi:[1,0]
	v_rcp_f32_e32 v19, v58
	s_nop 0
	v_mul_f32_e32 v19, v52, v19
	v_cvt_pk_bf16_f32 v15, v19, v15
	v_pk_fma_f32 v[48:49], v[34:35], v[24:25], v[48:49]
	s_nop 0
	v_pk_fma_f32 v[48:49], v[40:41], v[28:29], v[48:49]
	s_nop 0
	v_mul_f32_e32 v52, 0xbfb8aa3b, v48
	v_mul_f32_e32 v53, 0xbfb8aa3b, v49
	v_exp_f32_e32 v52, v52
	v_exp_f32_e32 v53, v53
	v_rcp_f32_e32 v19, v55
	s_nop 0
	v_mul_f32_e32 v19, v51, v19
	v_pk_add_f32 v[52:53], v[52:53], 1.0 op_sel_hi:[1,0]
	v_rcp_f32_e32 v23, v54
	s_nop 0
	v_mul_f32_e32 v23, v50, v23
	v_cvt_pk_bf16_f32 v19, v23, v19
	v_pk_fma_f32 v[46:47], v[30:31], v[24:25], v[46:47]
	s_nop 0
	v_pk_fma_f32 v[46:47], v[34:35], v[28:29], v[46:47]
	v_rcp_f32_e32 v23, v53
	s_nop 0
	v_mul_f32_e32 v23, v49, v23
	v_pk_fma_f32 v[46:47], v[40:41], v[32:33], v[46:47]
	s_nop 0
	v_mul_f32_e32 v50, 0xbfb8aa3b, v46
	v_mul_f32_e32 v51, 0xbfb8aa3b, v47
	v_exp_f32_e32 v50, v50
	v_exp_f32_e32 v51, v51
	s_nop 0
	v_pk_add_f32 v[50:51], v[50:51], 1.0 op_sel_hi:[1,0]
	v_rcp_f32_e32 v39, v52
	s_nop 0
	v_mul_f32_e32 v39, v48, v39
	v_cvt_pk_bf16_f32 v23, v39, v23
	v_pk_fma_f32 v[24:25], v[26:27], v[24:25], v[44:45]
	s_nop 0
	v_pk_fma_f32 v[24:25], v[30:31], v[28:29], v[24:25]
	s_nop 0
	v_pk_fma_f32 v[24:25], v[34:35], v[32:33], v[24:25]
	s_nop 0
	v_pk_fma_f32 v[24:25], v[40:41], v[42:43], v[24:25]
	s_nop 0
	v_mul_f32_e32 v26, 0xbfb8aa3b, v24
	v_mul_f32_e32 v27, 0xbfb8aa3b, v25
	v_exp_f32_e32 v26, v26
	v_exp_f32_e32 v27, v27
	v_rcp_f32_e32 v39, v51
	s_nop 0
	v_mul_f32_e32 v39, v47, v39
	v_pk_add_f32 v[26:27], v[26:27], 1.0 op_sel_hi:[1,0]
	v_rcp_f32_e32 v28, v50
	s_nop 0
	v_mul_f32_e32 v28, v46, v28
	v_cvt_pk_bf16_f32 v39, v28, v39
	v_rcp_f32_e32 v28, v27
	s_nop 0
	v_mul_f32_e32 v27, v25, v28
	v_rcp_f32_e32 v25, v26
	s_nop 0
	v_mul_f32_e32 v28, v24, v25
	v_cvt_pk_bf16_f32 v24, v71, v70
	v_cvt_pk_bf16_f32 v25, v65, v64
	v_cvt_pk_bf16_f32 v26, v77, v76
	v_cvt_pk_bf16_f32 v27, v28, v27
	v_cmp_lt_i32_e32 vcc, s43, v78
	s_and_saveexec_b64 s[26:27], vcc
	s_xor_b64 s[26:27], exec, s[26:27]
	s_cbranch_execz .LBB0_1316
; DI void conv_phase(int wv, const Params& P) {
;     ...
;         } else { const int cc = c0 - 1280;
; #pragma unroll
;             for (int i = 0; i < 8; ++i) *(u32x4*)(CM + (size_t)(r0 + i) * 256 + cc) = (u32x4){o[i][0], o[i][1], o[i][2], o[i][3]};
	v_cmp_lt_u32_e32 vcc, s44, v78
	v_lshlrev_b64 v[42:43], 9, v[106:107]
	v_lshlrev_b64 v[46:47], 9, v[94:95]
	v_lshlrev_b64 v[44:45], 9, v[108:109]
	v_lshlrev_b64 v[40:41], 9, v[104:105]
	v_lshlrev_b64 v[34:35], 9, v[102:103]
	v_lshlrev_b64 v[32:33], 9, v[98:99]
	v_lshlrev_b64 v[30:31], 9, v[100:101]
	v_lshlrev_b64 v[28:29], 9, v[96:97]
	s_and_saveexec_b64 s[28:29], vcc
	s_xor_b64 s[28:29], exec, s[28:29]
	s_cbranch_execz .LBB0_1313
	v_lshl_add_u64 v[48:49], v[92:93], 1, s[2:3]
	v_lshl_add_u64 v[46:47], v[48:49], 0, v[46:47]
	v_add_co_u32_e32 v46, vcc, 0xd7ff000, v46
	s_nop 1
	v_addc_co_u32_e32 v47, vcc, 0, v47, vcc
	flat_store_dwordx4 v[46:47], v[0:3] offset:1536
	s_nop 1
	v_lshl_add_u64 v[0:1], v[48:49], 0, v[44:45]
	v_add_co_u32_e32 v0, vcc, 0xd7ff000, v0
	s_nop 1
	v_addc_co_u32_e32 v1, vcc, 0, v1, vcc
	flat_store_dwordx4 v[0:1], v[4:7] offset:1536
	v_lshl_add_u64 v[0:1], v[48:49], 0, v[42:43]
	v_add_co_u32_e32 v0, vcc, 0xd7ff000, v0
	s_nop 1
	v_addc_co_u32_e32 v1, vcc, 0, v1, vcc
	flat_store_dwordx4 v[0:1], v[8:11] offset:1536
	v_lshl_add_u64 v[0:1], v[48:49], 0, v[40:41]
	v_add_co_u32_e32 v0, vcc, 0xd7ff000, v0
	s_nop 1
	v_addc_co_u32_e32 v1, vcc, 0, v1, vcc
	flat_store_dwordx4 v[0:1], v[12:15] offset:1536
	v_lshl_add_u64 v[0:1], v[48:49], 0, v[34:35]
	v_add_co_u32_e32 v0, vcc, 0xd7ff000, v0
	s_nop 1
	v_addc_co_u32_e32 v1, vcc, 0, v1, vcc
	flat_store_dwordx4 v[0:1], v[16:19] offset:1536
	v_lshl_add_u64 v[0:1], v[48:49], 0, v[32:33]
	v_add_co_u32_e32 v0, vcc, 0xd7ff000, v0
	s_nop 1
	v_addc_co_u32_e32 v1, vcc, 0, v1, vcc
	flat_store_dwordx4 v[0:1], v[20:23] offset:1536
	v_lshl_add_u64 v[0:1], v[48:49], 0, v[30:31]
	v_add_co_u32_e32 v0, vcc, 0xd7ff000, v0
	s_nop 1
	v_addc_co_u32_e32 v1, vcc, 0, v1, vcc
	flat_store_dwordx4 v[0:1], v[36:39] offset:1536
	v_lshl_add_u64 v[0:1], v[48:49], 0, v[28:29]
	v_add_co_u32_e32 v0, vcc, 0xd7ff000, v0
	s_nop 1
	v_addc_co_u32_e32 v1, vcc, 0, v1, vcc
	flat_store_dwordx4 v[0:1], v[24:27] offset:1536

; DI float siluf_(float x) { return x / (1.f + __expf(-x)); }
; DI void cmp_finish_phase(int wv, const Params& P) {
;     ...
;     for (int r = gw; r < 4096; r += NGW) {
;         const int kv = r >> 11, bh = (r >> 9) & 3, n = r & 511;
;         const float* PP = (const float*)(ws_ + (kv ? WS_PV : WS_PK)); const float* w2 = P.in[kv ? 14 : 11];
;         float out = 0.f;
;         if (n < 511) {
;             const float pre = PP[(size_t)(bh * 512 + n) * 256 + lane] + PP[(size_t)(bh * 512 + n + 1) * 256 + 64 + lane] + peb[kv * 64 + lane];
;             const float hid = siluf_(pre);
; #pragma unroll 8
;             for (int i = 0; i < 64; ++i) out += __shfl(hid, i) * w2[i * 64 + lane];
.LBB0_1367:
	v_and_b32_e32 v16, 0x1ff, v6
	v_cmp_gt_u32_e64 s[2:3], s17, v6
	v_cmp_ne_u32_e32 vcc, s16, v16
	v_mov_b32_e32 v4, 0
	s_and_saveexec_b64 s[14:15], vcc
	s_cbranch_execz .LBB0_1366
	v_cndmask_b32_e64 v2, v11, v12, s[2:3]
	v_lshl_add_u64 v[4:5], s[0:1], 0, v[2:3]
	v_cndmask_b32_e64 v2, v13, v14, s[2:3]
	v_lshl_add_u64 v[18:19], s[4:5], 0, v[2:3]
	v_lshlrev_b32_e32 v2, 8, v6
	v_and_or_b32 v2, v2, s18, v7
	v_lshlrev_b32_e32 v2, 2, v2
	v_lshl_add_u64 v[18:19], v[18:19], 0, v[2:3]
	v_ashrrev_i32_e32 v2, 5, v6
	v_and_or_b32 v20, v2, s19, v7
	v_ashrrev_i32_e32 v21, 31, v20
	v_lshl_add_u64 v[20:21], v[20:21], 2, s[8:9]
	flat_load_dword v2, v[18:19]
	flat_load_dword v17, v[18:19] offset:1280
	s_nop 0
	flat_load_dword v18, v[20:21]
	s_nop 0
	global_load_dwordx2 v[4:5], v[4:5], off
	s_mov_b32 s21, 0
	s_waitcnt vmcnt(0) lgkmcnt(0)
	v_add_f32_e32 v2, v2, v17
	v_add_f32_e32 v2, v2, v18
	v_mul_f32_e32 v17, 0xbfb8aa3b, v2
	v_exp_f32_e32 v17, v17
	v_lshl_add_u64 v[4:5], v[4:5], 0, v[0:1]
	v_add_f32_e32 v17, 1.0, v17
	v_rcp_f32_e32 v18, v17
	s_nop 0
	v_mul_f32_e32 v17, v2, v18
	v_mov_b32_e32 v2, 0

; DI float xsum32(float v) { auto r = __builtin_amdgcn_permlane32_swap(__float_as_uint(v), __float_as_uint(v), false, false); return __uint_as_float(r[0]) + __uint_as_float(r[1]); }
; #define CMP_KLOAD(dst_, kt_) _Pragma("unroll") for (int ks = 0; ks < 4; ++ks) dst_[ks] = *(const bf16x8*)(Kc + (size_t)((kt_) * 32 + q) * 64 + 8 * hh + 16 * ks)
; DI void nsa_phase(int wv, const Params& P, LAS unsigned char* lds) {
;     ...
;         l = xsum32(l);
;         const float invl = l > 0.f ? 1.f / l : 0.f;
;         { f32x16 o[2]; o[0] = f32x16{}; o[1] = f32x16{}; float carry = 0.f;
;           if (ntile > 0) { CMP_KLOAD(kf, 0); }
.LBB0_1453:
	s_or_b64 exec, exec, s[10:11]
	v_mov_b32_e32 v17, 0
	v_mov_b32_e32 v16, v17
	v_mov_b32_e32 v15, v17
	v_mov_b32_e32 v14, v17
	v_mov_b32_e32 v13, v17
	v_mov_b32_e32 v12, v17
	v_mov_b32_e32 v11, v17
	v_mov_b32_e32 v10, v17
	v_mov_b32_e32 v9, v17
	v_mov_b32_e32 v8, v17
	v_mov_b32_e32 v7, v17
	v_mov_b32_e32 v6, v17
	v_mov_b32_e32 v5, v17
	v_mov_b32_e32 v4, v17
	v_mov_b32_e32 v3, v17
	v_mov_b32_e32 v2, v17
	v_mov_b32_e32 v33, v17
	v_mov_b32_e32 v32, v17
	v_mov_b32_e32 v31, v17
	v_mov_b32_e32 v30, v17
	v_mov_b32_e32 v29, v17
	v_mov_b32_e32 v28, v17
	v_mov_b32_e32 v27, v17
	v_mov_b32_e32 v26, v17
	v_mov_b32_e32 v25, v17
	v_mov_b32_e32 v24, v17
	v_mov_b32_e32 v23, v17
	v_mov_b32_e32 v22, v17
	v_mov_b32_e32 v21, v17
	v_mov_b32_e32 v20, v17
	v_mov_b32_e32 v19, v17
	v_mov_b32_e32 v18, v17
	s_and_saveexec_b64 s[10:11], vcc
	s_cbranch_execz .LBB0_1467
	v_add_f32_e32 v0, v34, v35
	v_mov_b32_e32 v109, 0
	v_mov_b32_e32 v99, v98
	s_mov_b32 s16, 0
	v_rcp_f32_e32 v2, v0
	v_cmp_lt_f32_e32 vcc, 0, v0
	s_mov_b64 s[12:13], 0
	v_mov_b64_e32 v[102:103], v[138:139]
	v_cndmask_b32_e32 v100, 0, v2, vcc
	v_mov_b32_e32 v101, v100
	v_mov_b64_e32 v[104:105], v[134:135]
	v_mov_b32_e32 v108, v126
	v_mov_b32_e32 v2, 0
	v_mov_b32_e32 v3, v109
	v_mov_b32_e32 v4, v109
	v_mov_b32_e32 v5, v109
	v_mov_b32_e32 v6, v109
	v_mov_b32_e32 v7, v109
	v_mov_b32_e32 v8, v109
	v_mov_b32_e32 v9, v109
	v_mov_b32_e32 v10, v109
	v_mov_b32_e32 v11, v109
	v_mov_b32_e32 v12, v109
	v_mov_b32_e32 v13, v109
	v_mov_b32_e32 v14, v109
	v_mov_b32_e32 v15, v109
	v_mov_b32_e32 v16, v109
	v_mov_b32_e32 v17, v109
	v_mov_b32_e32 v18, 0
	v_mov_b32_e32 v19, v109
	v_mov_b32_e32 v20, v109
	v_mov_b32_e32 v21, v109
	v_mov_b32_e32 v22, v109
	v_mov_b32_e32 v23, v109
	v_mov_b32_e32 v24, v109
	v_mov_b32_e32 v25, v109
	v_mov_b32_e32 v26, v109
	v_mov_b32_e32 v27, v109
	v_mov_b32_e32 v28, v109
	v_mov_b32_e32 v29, v109
	v_mov_b32_e32 v30, v109
	v_mov_b32_e32 v31, v109
	v_mov_b32_e32 v32, v109
	v_mov_b32_e32 v33, v109
	s_branch .LBB0_1456

; DI float xsum32(float v) { auto r = __builtin_amdgcn_permlane32_swap(__float_as_uint(v), __float_as_uint(v), false, false); return __uint_as_float(r[0]) + __uint_as_float(r[1]); }
; DI void nsa_phase(int wv, const Params& P, LAS unsigned char* lds) {
;     ...
;             const float lt = xsum32(st.l), gg = br ? g2 : g1, sc = lt > 0.f ? gg / lt : 0.f;
.LBB0_1610:
	v_mov_b32_e32 v0, v219
	s_nop 1
	v_permlane32_swap_b32_e32 v219, v0
	v_add_f32_e32 v34, v219, v0
	v_mov_b32_e32 v0, 0
	v_cmp_lt_f32_e32 vcc, 0, v34
	s_and_saveexec_b64 s[10:11], vcc
	s_cbranch_execz .LBB0_1564
	v_cndmask_b32_e64 v0, v120, v119, s[16:17]
	v_rcp_f32_e32 v35, v34
	s_nop 0
	v_mul_f32_e32 v0, v0, v35
	s_branch .LBB0_1564

; DI float bflo(unsigned u) { return __uint_as_float(u << 16); }
; DI float bfhi(unsigned u) { return __uint_as_float(u & 0xffff0000u); }
; DI float siluf_(float x) { return x / (1.f + __expf(-x)); }
; DI float xhalf(float v) { return __shfl_xor(v, 32); }
; DI void ssd_out_phase(int wv, const Params& P, LAS unsigned char* lds) {
;     ...
;         for (int lt = 0; lt < 4; ++lt) { const size_t rr = (size_t)(row0 + lt * 32 + q); float ss = 0.f;
; #pragma unroll
;             for (int pt = 0; pt < 2; ++pt)
; #pragma unroll
;                 for (int i4 = 0; i4 < 4; ++i4) { const int p0 = h * 64 + pt * 32 + 8 * i4 + 4 * hh; const u32x2 xv = *(const u32x2*)(XS + rr * 1024 + p0), zv = *(const u32x2*)(Z + rr * 1024 + p0);
;                     const float xs4[4] = {bflo(xv.x), bfhi(xv.x), bflo(xv.y), bfhi(xv.y)}, zs4[4] = {bflo(zv.x), bfhi(zv.x), bflo(zv.y), bfhi(zv.y)};
; #pragma unroll
;                     for (int e = 0; e < 4; ++e) { const float y = (acc[pt][lt][4 * i4 + e] + xs4[e] * dsk) * siluf_(zs4[e]); acc[pt][lt][4 * i4 + e] = y; ss += y * y; } }
;             ss += xhalf(ss); if (hh == 0) ssq[wave * 128 + lt * 32 + q] = ss; }
.LBB0_1687:
	v_ashrrev_i32_e32 v197, 31, v196
	v_or_b32_e32 v130, v204, v228
	v_lshlrev_b64 v[128:129], 11, v[196:197]
	v_ashrrev_i32_e32 v131, 31, v130
	v_lshl_add_u64 v[132:133], s[28:29], 0, v[128:129]
	v_lshl_add_u64 v[136:137], s[34:35], 0, v[128:129]
	v_lshlrev_b64 v[128:129], 1, v[130:131]
	v_lshl_add_u64 v[134:135], v[132:133], 0, v[128:129]
	v_lshl_add_u64 v[136:137], v[136:137], 0, v[128:129]
	flat_load_dwordx2 v[138:139], v[134:135]
	flat_load_dwordx2 v[140:141], v[136:137]
	flat_load_dwordx2 v[142:143], v[136:137] offset:16
	v_lshl_add_u64 v[132:133], v[198:199], 2, s[22:23]
	global_load_dword v132, v[132:133], off
	s_nop 0
	flat_load_dwordx2 v[144:145], v[134:135] offset:16
	flat_load_dwordx2 v[148:149], v[134:135] offset:32
	flat_load_dwordx2 v[156:157], v[134:135] offset:48
	flat_load_dwordx2 v[146:147], v[136:137] offset:32
	flat_load_dwordx2 v[150:151], v[136:137] offset:48
	s_waitcnt vmcnt(0) lgkmcnt(0)
	v_lshlrev_b32_e32 v133, 16, v140
	v_and_b32_e32 v158, 0xffff0000, v140
	v_lshlrev_b32_e32 v152, 16, v138
	v_and_b32_e32 v153, 0xffff0000, v138
	v_lshlrev_b32_e32 v159, 16, v141
	v_and_b32_e32 v160, 0xffff0000, v141
	v_lshlrev_b32_e32 v161, 16, v142
	v_and_b32_e32 v142, 0xffff0000, v142
	v_mul_f32_e32 v140, 0xbfb8aa3b, v133
	v_mul_f32_e32 v141, 0xbfb8aa3b, v158
	v_pk_fma_f32 v[112:113], v[132:133], v[152:153], v[112:113] op_sel_hi:[0,1,1]
	v_mul_f32_e32 v152, 0xbfb8aa3b, v159
	v_mul_f32_e32 v153, 0xbfb8aa3b, v160
	v_mul_f32_e32 v154, 0xbfb8aa3b, v161
	v_mul_f32_e32 v155, 0xbfb8aa3b, v142
	v_exp_f32_e32 v140, v140
	v_exp_f32_e32 v141, v141
	v_exp_f32_e32 v152, v152
	v_exp_f32_e32 v153, v153
	v_exp_f32_e32 v154, v154
	v_exp_f32_e32 v155, v155
	v_lshlrev_b32_e32 v138, 16, v139
	v_and_b32_e32 v139, 0xffff0000, v139
	v_pk_fma_f32 v[114:115], v[132:133], v[138:139], v[114:115] op_sel_hi:[0,1,1]
	v_pk_add_f32 v[138:139], v[140:141], 1.0 op_sel_hi:[1,0]
	v_pk_add_f32 v[140:141], v[152:153], 1.0 op_sel_hi:[1,0]
	v_pk_add_f32 v[152:153], v[154:155], 1.0 op_sel_hi:[1,0]
	s_mov_b64 vcc, s[14:15]
	v_rcp_f32_e32 v154, v139
	s_nop 0
	v_mul_f32_e32 v139, v158, v154
	s_mov_b64 vcc, s[16:17]
	v_rcp_f32_e32 v154, v138
	s_nop 0
	v_mul_f32_e32 v138, v133, v154
	s_mov_b64 vcc, s[18:19]
	v_rcp_f32_e32 v133, v141
	s_nop 0
	v_mul_f32_e32 v141, v160, v133
	v_lshlrev_b32_e32 v154, 16, v144
	v_and_b32_e32 v155, 0xffff0000, v144
	v_rcp_f32_e32 v133, v140
	s_nop 0
	v_mul_f32_e32 v140, v159, v133
	v_pk_fma_f32 v[116:117], v[132:133], v[154:155], v[116:117] op_sel_hi:[0,1,1]
	v_rcp_f32_e32 v133, v153
	s_nop 0
	v_mul_f32_e32 v153, v142, v133
	v_lshlrev_b32_e32 v158, 16, v143
	v_and_b32_e32 v159, 0xffff0000, v143
	v_mul_f32_e32 v142, 0xbfb8aa3b, v158
	v_exp_f32_e32 v154, v142
	v_mul_f32_e32 v142, 0xbfb8aa3b, v159
	v_exp_f32_e32 v155, v142
	v_rcp_f32_e32 v133, v152
	s_nop 0
	v_mul_f32_e32 v152, v161, v133
	v_pk_mul_f32 v[116:117], v[116:117], v[152:153]
	v_lshlrev_b32_e32 v144, 16, v145
	v_pk_add_f32 v[152:153], v[154:155], 1.0 op_sel_hi:[1,0]
	v_and_b32_e32 v145, 0xffff0000, v145
	v_div_scale_f32 v133, s[14:15], v153, v153, v159
	v_rcp_f32_e32 v154, v133
	v_pk_fma_f32 v[118:119], v[132:133], v[144:145], v[118:119] op_sel_hi:[0,1,1]
	v_lshlrev_b32_e32 v160, 16, v147
	v_lshlrev_b32_e32 v162, 16, v150
	v_fma_f32 v144, -v133, v154, 1.0
	v_fmac_f32_e32 v154, v144, v154
	v_div_scale_f32 v144, vcc, v159, v153, v159
	v_mul_f32_e32 v145, v144, v154
	v_fma_f32 v155, -v133, v145, v144
	v_fmac_f32_e32 v145, v155, v154
	v_fma_f32 v133, -v133, v145, v144
	v_div_fmas_f32 v133, v133, v154, v145
	v_div_fixup_f32 v145, v133, v153, v159
	v_lshlrev_b32_e32 v159, 16, v146
	v_and_b32_e32 v146, 0xffff0000, v146
	v_mul_f32_e32 v144, 0xbfb8aa3b, v159
	v_exp_f32_e32 v154, v144
	v_mul_f32_e32 v144, 0xbfb8aa3b, v146
	v_exp_f32_e32 v155, v144
	v_rcp_f32_e32 v133, v152
	s_nop 0
	v_mul_f32_e32 v144, v158, v133
	v_and_b32_e32 v150, 0xffff0000, v150
	v_lshlrev_b32_e32 v166, 16, v151
	v_pk_add_f32 v[152:153], v[154:155], 1.0 op_sel_hi:[1,0]
	v_lshlrev_b32_e32 v154, 16, v148
	v_div_scale_f32 v133, s[14:15], v153, v153, v146
	v_rcp_f32_e32 v158, v133
	v_and_b32_e32 v155, 0xffff0000, v148
	v_pk_fma_f32 v[120:121], v[132:133], v[154:155], v[120:121] op_sel_hi:[0,1,1]
	v_pk_mul_f32 v[112:113], v[112:113], v[138:139]
	v_fma_f32 v148, -v133, v158, 1.0
	v_fmac_f32_e32 v158, v148, v158
	v_div_scale_f32 v148, vcc, v146, v153, v146
	v_mul_f32_e32 v154, v148, v158
	v_fma_f32 v155, -v133, v154, v148
	v_fmac_f32_e32 v154, v155, v158
	v_fma_f32 v133, -v133, v154, v148
	v_div_fmas_f32 v133, v133, v158, v154
	v_div_fixup_f32 v153, v133, v153, v146
	v_and_b32_e32 v158, 0xffff0000, v147
	v_mul_f32_e32 v146, 0xbfb8aa3b, v160
	v_exp_f32_e32 v154, v146
	v_mul_f32_e32 v146, 0xbfb8aa3b, v158
	v_exp_f32_e32 v155, v146
	v_rcp_f32_e32 v133, v152
	s_nop 0
	v_mul_f32_e32 v152, v159, v133
	v_pk_mul_f32 v[120:121], v[120:121], v[152:153]
	v_lshlrev_b32_e32 v148, 16, v149
	v_pk_add_f32 v[154:155], v[154:155], 1.0 op_sel_hi:[1,0]
	v_and_b32_e32 v149, 0xffff0000, v149
	v_div_scale_f32 v133, s[14:15], v155, v155, v158
	v_rcp_f32_e32 v152, v133
	v_pk_fma_f32 v[122:123], v[132:133], v[148:149], v[122:123] op_sel_hi:[0,1,1]
	v_pk_mul_f32 v[138:139], v[112:113], v[112:113]
	v_pk_mul_f32 v[114:115], v[114:115], v[140:141]
	v_fma_f32 v148, -v133, v152, 1.0
	v_fmac_f32_e32 v152, v148, v152
	v_div_scale_f32 v148, vcc, v158, v155, v158
	v_mul_f32_e32 v149, v148, v152
	v_fma_f32 v153, -v133, v149, v148
	v_fmac_f32_e32 v149, v153, v152
	v_fma_f32 v133, -v133, v149, v148
	v_div_fmas_f32 v133, v133, v152, v149
	v_div_fixup_f32 v149, v133, v155, v158
	v_pk_mul_f32 v[140:141], v[114:115], v[114:115]
	flat_load_dwordx2 v[152:153], v[136:137] offset:64
; DI float bflo(unsigned u) { return __uint_as_float(u << 16); }
; DI float bfhi(unsigned u) { return __uint_as_float(u & 0xffff0000u); }
; DI float siluf_(float x) { return x / (1.f + __expf(-x)); }
; DI void ssd_out_phase(int wv, const Params& P, LAS unsigned char* lds) {
;     ...
;                 for (int i4 = 0; i4 < 4; ++i4) { const int p0 = h * 64 + pt * 32 + 8 * i4 + 4 * hh; const u32x2 xv = *(const u32x2*)(XS + rr * 1024 + p0), zv = *(const u32x2*)(Z + rr * 1024 + p0);
;                     const float xs4[4] = {bflo(xv.x), bfhi(xv.x), bflo(xv.y), bfhi(xv.y)}, zs4[4] = {bflo(zv.x), bfhi(zv.x), bflo(zv.y), bfhi(zv.y)};
; #pragma unroll
;                     for (int e = 0; e < 4; ++e) { const float y = (acc[pt][lt][4 * i4 + e] + xs4[e] * dsk) * siluf_(zs4[e]); acc[pt][lt][4 * i4 + e] = y; ss += y * y; } }
	v_mul_f32_e32 v148, 0xbfb8aa3b, v162
	v_exp_f32_e32 v158, v148
	v_mul_f32_e32 v148, 0xbfb8aa3b, v150
	v_exp_f32_e32 v159, v148
	v_rcp_f32_e32 v133, v154
	s_nop 0
	v_mul_f32_e32 v148, v160, v133
	v_lshlrev_b32_e32 v154, 16, v156
	v_and_b32_e32 v155, 0xffff0000, v156
	v_pk_add_f32 v[158:159], v[158:159], 1.0 op_sel_hi:[1,0]
	v_pk_mul_f32 v[142:143], v[116:117], v[116:117]
	v_div_scale_f32 v133, s[14:15], v159, v159, v150
	v_rcp_f32_e32 v160, v133
	v_pk_fma_f32 v[124:125], v[132:133], v[154:155], v[124:125] op_sel_hi:[0,1,1]
	v_div_scale_f32 v156, vcc, v150, v159, v150
	v_fma_f32 v154, -v133, v160, 1.0
	v_fmac_f32_e32 v160, v154, v160
	flat_load_dwordx2 v[154:155], v[134:135] offset:64
	v_mul_f32_e32 v161, v156, v160
	v_fma_f32 v163, -v133, v161, v156
	v_fmac_f32_e32 v161, v163, v160
	v_fma_f32 v133, -v133, v161, v156
	v_div_fmas_f32 v133, v133, v160, v161
	v_div_fixup_f32 v159, v133, v159, v150
	v_pk_mul_f32 v[118:119], v[118:119], v[144:145]
	v_and_b32_e32 v163, 0xffff0000, v151
	v_mul_f32_e32 v150, 0xbfb8aa3b, v166
	v_exp_f32_e32 v160, v150
	v_mul_f32_e32 v150, 0xbfb8aa3b, v163
	v_exp_f32_e32 v161, v150
	v_rcp_f32_e32 v133, v158
	s_nop 0
	v_mul_f32_e32 v158, v162, v133
	v_pk_mul_f32 v[124:125], v[124:125], v[158:159]
	v_lshlrev_b32_e32 v156, 16, v157
	v_pk_add_f32 v[158:159], v[160:161], 1.0 op_sel_hi:[1,0]
	v_and_b32_e32 v157, 0xffff0000, v157
	v_div_scale_f32 v133, s[14:15], v159, v159, v163
	v_rcp_f32_e32 v160, v133
	v_pk_fma_f32 v[126:127], v[132:133], v[156:157], v[126:127] op_sel_hi:[0,1,1]
	v_pk_mul_f32 v[144:145], v[118:119], v[118:119]
	v_pk_mul_f32 v[146:147], v[120:121], v[120:121]
	v_fma_f32 v156, -v133, v160, 1.0
	v_fmac_f32_e32 v160, v156, v160
	v_div_scale_f32 v156, vcc, v163, v159, v163
	v_mul_f32_e32 v157, v156, v160
	v_fma_f32 v161, -v133, v157, v156
	v_fmac_f32_e32 v157, v161, v160
	v_fma_f32 v133, -v133, v157, v156
	v_div_fmas_f32 v133, v133, v160, v157
	v_div_fixup_f32 v159, v133, v159, v163
	v_pk_mul_f32 v[122:123], v[122:123], v[148:149]
	flat_load_dwordx2 v[156:157], v[136:137] offset:80
	flat_load_dwordx2 v[160:161], v[136:137] offset:96
	flat_load_dwordx2 v[162:163], v[136:137] offset:112
	v_rcp_f32_e32 v133, v158
	s_nop 0
	v_mul_f32_e32 v158, v166, v133
	v_pk_mul_f32 v[126:127], v[126:127], v[158:159]
	s_waitcnt vmcnt(0) lgkmcnt(0)
	v_lshlrev_b32_e32 v170, 16, v152
	v_and_b32_e32 v152, 0xffff0000, v152
	v_mul_f32_e32 v136, 0xbfb8aa3b, v170
	v_exp_f32_e32 v164, v136
	v_mul_f32_e32 v136, 0xbfb8aa3b, v152
	v_exp_f32_e32 v165, v136
	v_and_b32_e32 v172, 0xffff0000, v153
	v_pk_mul_f32 v[148:149], v[122:123], v[122:123]
	v_pk_mul_f32 v[150:151], v[124:125], v[124:125]
	v_pk_add_f32 v[158:159], v[164:165], 1.0 op_sel_hi:[1,0]
	flat_load_dwordx2 v[164:165], v[134:135] offset:80
	flat_load_dwordx2 v[166:167], v[134:135] offset:96
	s_nop 0
	flat_load_dwordx2 v[134:135], v[134:135] offset:112
	v_div_scale_f32 v133, s[14:15], v159, v159, v152
	v_rcp_f32_e32 v171, v133
	v_pk_mul_f32 v[136:137], v[126:127], v[126:127]
	v_lshlrev_b32_e32 v168, 16, v154
	v_and_b32_e32 v169, 0xffff0000, v154
	v_fma_f32 v154, -v133, v171, 1.0
	v_fmac_f32_e32 v171, v154, v171
	v_div_scale_f32 v154, vcc, v152, v159, v152
	v_pk_fma_f32 v[96:97], v[132:133], v[168:169], v[96:97] op_sel_hi:[0,1,1]
	v_mul_f32_e32 v168, v154, v171
	v_fma_f32 v169, -v133, v168, v154
	v_fmac_f32_e32 v168, v169, v171
	v_fma_f32 v133, -v133, v168, v154
	v_div_fmas_f32 v133, v133, v171, v168
	v_div_fixup_f32 v159, v133, v159, v152
	v_lshlrev_b32_e32 v171, 16, v153
	v_mul_f32_e32 v152, 0xbfb8aa3b, v171
	v_exp_f32_e32 v168, v152
	v_mul_f32_e32 v152, 0xbfb8aa3b, v172
	v_exp_f32_e32 v169, v152
	v_rcp_f32_e32 v133, v158
	s_nop 0
	v_mul_f32_e32 v158, v170, v133
	v_pk_mul_f32 v[96:97], v[96:97], v[158:159]
	v_lshlrev_b32_e32 v154, 16, v155
	v_pk_add_f32 v[158:159], v[168:169], 1.0 op_sel_hi:[1,0]
	v_and_b32_e32 v155, 0xffff0000, v155
	v_div_scale_f32 v133, s[14:15], v159, v159, v172
	v_rcp_f32_e32 v168, v133
	v_pk_fma_f32 v[98:99], v[132:133], v[154:155], v[98:99] op_sel_hi:[0,1,1]
	v_pk_mul_f32 v[152:153], v[96:97], v[96:97]
	v_fma_f32 v154, -v133, v168, 1.0
	v_fmac_f32_e32 v168, v154, v168
	v_div_scale_f32 v154, vcc, v172, v159, v172
	v_mul_f32_e32 v155, v154, v168
	v_fma_f32 v169, -v133, v155, v154
	v_fmac_f32_e32 v155, v169, v168
	v_fma_f32 v133, -v133, v155, v154
	v_div_fmas_f32 v133, v133, v168, v155
	v_div_fixup_f32 v155, v133, v159, v172
	v_lshlrev_b32_e32 v170, 16, v156
	v_and_b32_e32 v156, 0xffff0000, v156
	v_mul_f32_e32 v154, 0xbfb8aa3b, v170
	v_exp_f32_e32 v168, v154
	v_mul_f32_e32 v154, 0xbfb8aa3b, v156
	v_exp_f32_e32 v169, v154
	v_rcp_f32_e32 v133, v158
	s_nop 0
	v_mul_f32_e32 v154, v171, v133
	v_pk_mul_f32 v[98:99], v[98:99], v[154:155]
	v_pk_add_f32 v[158:159], v[168:169], 1.0 op_sel_hi:[1,0]
	s_nop 0
	v_div_scale_f32 v133, s[14:15], v159, v159, v156
	v_rcp_f32_e32 v171, v133
	s_waitcnt vmcnt(0) lgkmcnt(0)
; DI float bflo(unsigned u) { return __uint_as_float(u << 16); }
; DI float bfhi(unsigned u) { return __uint_as_float(u & 0xffff0000u); }
; DI float siluf_(float x) { return x / (1.f + __expf(-x)); }
; DI float xhalf(float v) { return __shfl_xor(v, 32); }
; DI void ssd_out_phase(int wv, const Params& P, LAS unsigned char* lds) {
;     ...
;                 for (int i4 = 0; i4 < 4; ++i4) { const int p0 = h * 64 + pt * 32 + 8 * i4 + 4 * hh; const u32x2 xv = *(const u32x2*)(XS + rr * 1024 + p0), zv = *(const u32x2*)(Z + rr * 1024 + p0);
;                     const float xs4[4] = {bflo(xv.x), bfhi(xv.x), bflo(xv.y), bfhi(xv.y)}, zs4[4] = {bflo(zv.x), bfhi(zv.x), bflo(zv.y), bfhi(zv.y)};
; #pragma unroll
;                     for (int e = 0; e < 4; ++e) { const float y = (acc[pt][lt][4 * i4 + e] + xs4[e] * dsk) * siluf_(zs4[e]); acc[pt][lt][4 * i4 + e] = y; ss += y * y; } }
;             ss += xhalf(ss); if (hh == 0) ssq[wave * 128 + lt * 32 + q] = ss; }
	v_lshlrev_b32_e32 v168, 16, v164
	v_and_b32_e32 v169, 0xffff0000, v164
	v_pk_fma_f32 v[100:101], v[132:133], v[168:169], v[100:101] op_sel_hi:[0,1,1]
	v_fma_f32 v164, -v133, v171, 1.0
	v_fmac_f32_e32 v171, v164, v171
	v_div_scale_f32 v164, vcc, v156, v159, v156
	v_mul_f32_e32 v168, v164, v171
	v_fma_f32 v169, -v133, v168, v164
	v_fmac_f32_e32 v168, v169, v171
	v_fma_f32 v133, -v133, v168, v164
	v_div_fmas_f32 v133, v133, v171, v168
	v_div_fixup_f32 v159, v133, v159, v156
	v_pk_mul_f32 v[154:155], v[98:99], v[98:99]
	v_lshlrev_b32_e32 v168, 16, v157
	v_and_b32_e32 v169, 0xffff0000, v157
	v_mul_f32_e32 v156, 0xbfb8aa3b, v168
	v_mul_f32_e32 v157, 0xbfb8aa3b, v169
	v_exp_f32_e32 v156, v156
	v_exp_f32_e32 v157, v157
	v_rcp_f32_e32 v133, v158
	s_nop 0
	v_mul_f32_e32 v158, v170, v133
	v_lshlrev_b32_e32 v164, 16, v165
	v_and_b32_e32 v165, 0xffff0000, v165
	v_pk_add_f32 v[156:157], v[156:157], 1.0 op_sel_hi:[1,0]
	v_pk_mul_f32 v[100:101], v[100:101], v[158:159]
	v_div_scale_f32 v133, s[14:15], v157, v157, v169
	v_rcp_f32_e32 v170, v133
	v_pk_fma_f32 v[102:103], v[132:133], v[164:165], v[102:103] op_sel_hi:[0,1,1]
	v_pk_mul_f32 v[158:159], v[100:101], v[100:101]
	v_fma_f32 v164, -v133, v170, 1.0
	v_fmac_f32_e32 v170, v164, v170
	v_div_scale_f32 v164, vcc, v169, v157, v169
	v_mul_f32_e32 v165, v164, v170
	v_fma_f32 v171, -v133, v165, v164
	v_fmac_f32_e32 v165, v171, v170
	v_fma_f32 v133, -v133, v165, v164
	v_div_fmas_f32 v133, v133, v170, v165
	v_div_fixup_f32 v157, v133, v157, v169
	v_lshlrev_b32_e32 v170, 16, v160
	v_and_b32_e32 v160, 0xffff0000, v160
	v_mul_f32_e32 v164, 0xbfb8aa3b, v170
	v_mul_f32_e32 v165, 0xbfb8aa3b, v160
	v_exp_f32_e32 v164, v164
	v_exp_f32_e32 v165, v165
	v_rcp_f32_e32 v133, v156
	s_nop 0
	v_mul_f32_e32 v156, v168, v133
	v_lshlrev_b32_e32 v168, 16, v166
	v_and_b32_e32 v169, 0xffff0000, v166
	v_pk_add_f32 v[164:165], v[164:165], 1.0 op_sel_hi:[1,0]
	v_pk_mul_f32 v[102:103], v[102:103], v[156:157]
	v_div_scale_f32 v133, s[14:15], v165, v165, v160
	v_rcp_f32_e32 v171, v133
	v_pk_fma_f32 v[104:105], v[132:133], v[168:169], v[104:105] op_sel_hi:[0,1,1]
	v_pk_mul_f32 v[156:157], v[102:103], v[102:103]
	v_fma_f32 v166, -v133, v171, 1.0
	v_fmac_f32_e32 v171, v166, v171
	v_div_scale_f32 v166, vcc, v160, v165, v160
	v_mul_f32_e32 v168, v166, v171
	v_fma_f32 v169, -v133, v168, v166
	v_fmac_f32_e32 v168, v169, v171
	v_fma_f32 v133, -v133, v168, v166
	v_div_fmas_f32 v133, v133, v171, v168
	v_div_fixup_f32 v165, v133, v165, v160
	v_lshlrev_b32_e32 v168, 16, v161
	v_and_b32_e32 v169, 0xffff0000, v161
	v_mul_f32_e32 v160, 0xbfb8aa3b, v168
	v_mul_f32_e32 v161, 0xbfb8aa3b, v169
	v_exp_f32_e32 v160, v160
	v_exp_f32_e32 v161, v161
	v_rcp_f32_e32 v133, v164
	s_nop 0
	v_mul_f32_e32 v164, v170, v133
	v_lshlrev_b32_e32 v166, 16, v167
	v_and_b32_e32 v167, 0xffff0000, v167
	v_pk_add_f32 v[160:161], v[160:161], 1.0 op_sel_hi:[1,0]
	v_pk_mul_f32 v[104:105], v[104:105], v[164:165]
	v_div_scale_f32 v133, s[14:15], v161, v161, v169
	v_rcp_f32_e32 v170, v133
	v_pk_fma_f32 v[106:107], v[132:133], v[166:167], v[106:107] op_sel_hi:[0,1,1]
	v_pk_mul_f32 v[164:165], v[104:105], v[104:105]
	v_fma_f32 v166, -v133, v170, 1.0
	v_fmac_f32_e32 v170, v166, v170
	v_div_scale_f32 v166, vcc, v169, v161, v169
	v_mul_f32_e32 v167, v166, v170
	v_fma_f32 v171, -v133, v167, v166
	v_fmac_f32_e32 v167, v171, v170
	v_fma_f32 v133, -v133, v167, v166
	v_div_fmas_f32 v133, v133, v170, v167
	v_div_fixup_f32 v161, v133, v161, v169
	v_lshlrev_b32_e32 v170, 16, v162
	v_and_b32_e32 v162, 0xffff0000, v162
	v_mul_f32_e32 v166, 0xbfb8aa3b, v170
	v_mul_f32_e32 v167, 0xbfb8aa3b, v162
	v_exp_f32_e32 v166, v166
	v_exp_f32_e32 v167, v167
	v_rcp_f32_e32 v133, v160
	s_nop 0
	v_mul_f32_e32 v160, v168, v133
	v_lshlrev_b32_e32 v168, 16, v134
	v_and_b32_e32 v169, 0xffff0000, v134
	v_pk_add_f32 v[166:167], v[166:167], 1.0 op_sel_hi:[1,0]
	v_pk_mul_f32 v[106:107], v[106:107], v[160:161]
	v_div_scale_f32 v133, s[14:15], v167, v167, v162
	v_rcp_f32_e32 v171, v133
	v_pk_fma_f32 v[108:109], v[132:133], v[168:169], v[108:109] op_sel_hi:[0,1,1]
	v_pk_mul_f32 v[160:161], v[106:107], v[106:107]
	v_fma_f32 v134, -v133, v171, 1.0
	v_fmac_f32_e32 v171, v134, v171
	v_div_scale_f32 v134, vcc, v162, v167, v162
	v_mul_f32_e32 v168, v134, v171
	v_fma_f32 v169, -v133, v168, v134
	v_fmac_f32_e32 v168, v169, v171
	v_fma_f32 v133, -v133, v168, v134
	v_div_fmas_f32 v133, v133, v171, v168
	v_div_fixup_f32 v167, v133, v167, v162
	v_lshlrev_b32_e32 v168, 16, v163
	v_and_b32_e32 v169, 0xffff0000, v163
	v_mul_f32_e32 v134, 0xbfb8aa3b, v168
	v_exp_f32_e32 v162, v134
	v_mul_f32_e32 v134, 0xbfb8aa3b, v169
	v_exp_f32_e32 v163, v134
	v_rcp_f32_e32 v133, v166
	s_nop 0
	v_mul_f32_e32 v166, v170, v133
	v_lshlrev_b32_e32 v134, 16, v135
	v_and_b32_e32 v135, 0xffff0000, v135
	v_pk_add_f32 v[162:163], v[162:163], 1.0 op_sel_hi:[1,0]
	v_pk_mul_f32 v[108:109], v[108:109], v[166:167]
	v_div_scale_f32 v133, s[14:15], v163, v163, v169
	v_rcp_f32_e32 v170, v133
	v_pk_fma_f32 v[110:111], v[132:133], v[134:135], v[110:111] op_sel_hi:[0,1,1]
	v_pk_mul_f32 v[166:167], v[108:109], v[108:109]
	v_fma_f32 v134, -v133, v170, 1.0
	v_fmac_f32_e32 v170, v134, v170
	v_div_scale_f32 v134, vcc, v169, v163, v169
	v_mul_f32_e32 v135, v134, v170
	v_fma_f32 v171, -v133, v135, v134
	v_fmac_f32_e32 v135, v171, v170
	v_fma_f32 v133, -v133, v135, v134
	v_div_fmas_f32 v133, v133, v170, v135
	v_div_fixup_f32 v135, v133, v163, v169
	v_rcp_f32_e32 v133, v162
	s_nop 0
	v_mul_f32_e32 v134, v168, v133
	v_add_f32_e32 v133, v138, v139
	v_add_f32_e32 v133, v140, v133
	v_add_f32_e32 v133, v141, v133
	v_add_f32_e32 v133, v142, v133
	v_add_f32_e32 v133, v143, v133
	v_add_f32_e32 v133, v144, v133
	v_add_f32_e32 v133, v145, v133
	v_add_f32_e32 v133, v146, v133
	v_add_f32_e32 v133, v147, v133
	v_add_f32_e32 v133, v148, v133
	v_add_f32_e32 v133, v149, v133
	v_add_f32_e32 v133, v150, v133
	v_add_f32_e32 v133, v151, v133
	v_add_f32_e32 v133, v136, v133
	v_add_f32_e32 v133, v137, v133
	v_add_f32_e32 v133, v152, v133
	v_add_f32_e32 v133, v153, v133
	v_add_f32_e32 v133, v154, v133
	v_add_f32_e32 v133, v155, v133
	v_add_f32_e32 v133, v158, v133
	v_add_f32_e32 v133, v159, v133
	v_add_f32_e32 v133, v156, v133
	v_add_f32_e32 v133, v157, v133
	v_add_f32_e32 v133, v164, v133
	v_add_f32_e32 v133, v165, v133
	v_add_f32_e32 v133, v160, v133
	v_add_f32_e32 v133, v161, v133
	v_pk_mul_f32 v[134:135], v[110:111], v[134:135]
	v_add_f32_e32 v133, v166, v133
	v_pk_mul_f32 v[110:111], v[134:135], v[134:135]
	v_add_f32_e32 v133, v167, v133
	v_add_f32_e32 v110, v110, v133
	v_add_f32_e32 v110, v111, v110
	ds_bpermute_b32 v111, v229, v110
	s_and_saveexec_b64 s[14:15], s[12:13]
	s_cbranch_execz .LBB0_1689
	s_waitcnt lgkmcnt(0)
	v_add_f32_e32 v110, v110, v111
	ds_write_b32 v231, v110
; DI float bflo(unsigned u) { return __uint_as_float(u << 16); }
; DI float bfhi(unsigned u) { return __uint_as_float(u & 0xffff0000u); }
; DI float siluf_(float x) { return x / (1.f + __expf(-x)); }
; DI void ssd_out_phase(int wv, const Params& P, LAS unsigned char* lds) {
;     ...
;         for (int lt = 0; lt < 4; ++lt) { const size_t rr = (size_t)(row0 + lt * 32 + q); float ss = 0.f;
; #pragma unroll
;             for (int pt = 0; pt < 2; ++pt)
; #pragma unroll
;                 for (int i4 = 0; i4 < 4; ++i4) { const int p0 = h * 64 + pt * 32 + 8 * i4 + 4 * hh; const u32x2 xv = *(const u32x2*)(XS + rr * 1024 + p0), zv = *(const u32x2*)(Z + rr * 1024 + p0);
;                     const float xs4[4] = {bflo(xv.x), bfhi(xv.x), bflo(xv.y), bfhi(xv.y)}, zs4[4] = {bflo(zv.x), bfhi(zv.x), bflo(zv.y), bfhi(zv.y)};
; #pragma unroll
;                     for (int e = 0; e < 4; ++e) { const float y = (acc[pt][lt][4 * i4 + e] + xs4[e] * dsk) * siluf_(zs4[e]); acc[pt][lt][4 * i4 + e] = y; ss += y * y; } }
.LBB0_1689:
	s_or_b64 exec, exec, s[14:15]
	v_or_b32_e32 v110, 32, v196
	s_waitcnt lgkmcnt(0)
	v_ashrrev_i32_e32 v111, 31, v110
	v_lshlrev_b64 v[136:137], 11, v[110:111]
	v_lshl_add_u64 v[138:139], s[28:29], 0, v[136:137]
	v_lshl_add_u64 v[142:143], s[34:35], 0, v[136:137]
	v_lshl_add_u64 v[136:137], v[138:139], 0, v[128:129]
	flat_load_dwordx2 v[140:141], v[136:137]
	v_lshl_add_u64 v[138:139], v[142:143], 0, v[128:129]
	flat_load_dwordx2 v[142:143], v[138:139]
	flat_load_dwordx2 v[146:147], v[136:137] offset:16
	flat_load_dwordx2 v[144:145], v[138:139] offset:16
	flat_load_dwordx2 v[150:151], v[136:137] offset:32
	flat_load_dwordx2 v[158:159], v[136:137] offset:48
	flat_load_dwordx2 v[148:149], v[138:139] offset:32
	flat_load_dwordx2 v[152:153], v[138:139] offset:48
	v_mov_b32_e32 v133, v132
	s_waitcnt vmcnt(0) lgkmcnt(0)
	v_lshlrev_b32_e32 v111, 16, v142
	v_lshlrev_b32_e32 v154, 16, v140
	v_and_b32_e32 v155, 0xffff0000, v140
	v_and_b32_e32 v160, 0xffff0000, v142
	v_lshlrev_b32_e32 v140, 16, v141
	v_and_b32_e32 v141, 0xffff0000, v141
	v_lshlrev_b32_e32 v161, 16, v143
	v_and_b32_e32 v162, 0xffff0000, v143
	v_lshlrev_b32_e32 v142, 16, v146
	v_and_b32_e32 v143, 0xffff0000, v146
	v_lshlrev_b32_e32 v146, 16, v144
	v_and_b32_e32 v144, 0xffff0000, v144
	v_mul_f32_e32 v156, 0xbfb8aa3b, v111
	v_pk_fma_f32 v[80:81], v[132:133], v[154:155], v[80:81]
	v_mul_f32_e32 v154, 0xbfb8aa3b, v160
	v_mul_f32_e32 v155, 0xbfb8aa3b, v161
	v_pk_fma_f32 v[82:83], v[132:133], v[140:141], v[82:83]
	v_mul_f32_e32 v157, 0xbfb8aa3b, v162
	v_mul_f32_e32 v163, 0xbfb8aa3b, v146
	v_mul_f32_e32 v164, 0xbfb8aa3b, v144
	v_exp_f32_e32 v140, v156
	v_exp_f32_e32 v141, v154
	v_exp_f32_e32 v154, v155
	v_exp_f32_e32 v155, v157
	v_exp_f32_e32 v156, v163
	v_exp_f32_e32 v157, v164
	v_pk_add_f32 v[140:141], v[140:141], 1.0 op_sel_hi:[1,0]
	v_pk_fma_f32 v[84:85], v[132:133], v[142:143], v[84:85]
	v_pk_add_f32 v[142:143], v[154:155], 1.0 op_sel_hi:[1,0]
	v_pk_add_f32 v[154:155], v[156:157], 1.0 op_sel_hi:[1,0]
	s_mov_b64 vcc, s[14:15]
	v_rcp_f32_e32 v156, v141
	s_nop 0
	v_mul_f32_e32 v141, v160, v156
	s_mov_b64 vcc, s[16:17]
	v_rcp_f32_e32 v156, v140
	s_nop 0
	v_mul_f32_e32 v140, v111, v156
	s_mov_b64 vcc, s[18:19]
	v_rcp_f32_e32 v111, v143
	s_nop 0
	v_mul_f32_e32 v143, v162, v111
	v_rcp_f32_e32 v111, v142
	s_nop 0
	v_mul_f32_e32 v142, v161, v111
	v_rcp_f32_e32 v111, v155
	s_nop 0
	v_mul_f32_e32 v155, v144, v111
	v_lshlrev_b32_e32 v160, 16, v145
	v_and_b32_e32 v161, 0xffff0000, v145
	v_mul_f32_e32 v144, 0xbfb8aa3b, v160
	v_exp_f32_e32 v156, v144
	v_mul_f32_e32 v144, 0xbfb8aa3b, v161
	v_exp_f32_e32 v157, v144
	v_rcp_f32_e32 v111, v154
	s_nop 0
	v_mul_f32_e32 v154, v146, v111
	v_pk_mul_f32 v[84:85], v[84:85], v[154:155]
	v_lshlrev_b32_e32 v146, 16, v147
	v_pk_add_f32 v[154:155], v[156:157], 1.0 op_sel_hi:[1,0]
	v_and_b32_e32 v147, 0xffff0000, v147
	v_pk_fma_f32 v[86:87], v[132:133], v[146:147], v[86:87]
	v_lshlrev_b32_e32 v162, 16, v149
	v_lshlrev_b32_e32 v164, 16, v152
	v_rcp_f32_e32 v111, v155
	s_nop 0
	v_mul_f32_e32 v147, v161, v111
	v_lshlrev_b32_e32 v161, 16, v148
	v_and_b32_e32 v148, 0xffff0000, v148
	v_mul_f32_e32 v146, 0xbfb8aa3b, v161
	v_exp_f32_e32 v156, v146
	v_mul_f32_e32 v146, 0xbfb8aa3b, v148
	v_exp_f32_e32 v157, v146
	v_rcp_f32_e32 v111, v154
	s_nop 0
	v_mul_f32_e32 v146, v160, v111
	v_and_b32_e32 v152, 0xffff0000, v152
	v_lshlrev_b32_e32 v168, 16, v153
	v_pk_add_f32 v[154:155], v[156:157], 1.0 op_sel_hi:[1,0]
	v_lshlrev_b32_e32 v156, 16, v150
	v_and_b32_e32 v157, 0xffff0000, v150
	v_pk_fma_f32 v[88:89], v[132:133], v[156:157], v[88:89]
	v_pk_mul_f32 v[80:81], v[80:81], v[140:141]
	v_rcp_f32_e32 v111, v155
	s_nop 0
	v_mul_f32_e32 v155, v148, v111
	v_and_b32_e32 v160, 0xffff0000, v149
	v_mul_f32_e32 v148, 0xbfb8aa3b, v162
	v_exp_f32_e32 v156, v148
	v_mul_f32_e32 v148, 0xbfb8aa3b, v160
	v_exp_f32_e32 v157, v148
	v_rcp_f32_e32 v111, v154
	s_nop 0
	v_mul_f32_e32 v154, v161, v111
	v_pk_mul_f32 v[88:89], v[88:89], v[154:155]
	v_lshlrev_b32_e32 v150, 16, v151
	v_pk_add_f32 v[156:157], v[156:157], 1.0 op_sel_hi:[1,0]
	v_and_b32_e32 v151, 0xffff0000, v151
	v_pk_fma_f32 v[90:91], v[132:133], v[150:151], v[90:91]
	v_pk_mul_f32 v[140:141], v[80:81], v[80:81]
	v_pk_mul_f32 v[82:83], v[82:83], v[142:143]
	v_rcp_f32_e32 v111, v157
	s_nop 0
	v_mul_f32_e32 v151, v160, v111
	v_pk_mul_f32 v[142:143], v[82:83], v[82:83]
	flat_load_dwordx2 v[154:155], v[138:139] offset:64
	v_mul_f32_e32 v150, 0xbfb8aa3b, v164
	v_exp_f32_e32 v160, v150
	v_mul_f32_e32 v150, 0xbfb8aa3b, v152
	v_exp_f32_e32 v161, v150
	v_rcp_f32_e32 v111, v156
	s_nop 0
	v_mul_f32_e32 v150, v162, v111
	v_lshlrev_b32_e32 v156, 16, v158
	v_and_b32_e32 v157, 0xffff0000, v158
	v_pk_add_f32 v[160:161], v[160:161], 1.0 op_sel_hi:[1,0]
	v_pk_fma_f32 v[92:93], v[132:133], v[156:157], v[92:93]
	v_pk_mul_f32 v[144:145], v[84:85], v[84:85]
	flat_load_dwordx2 v[156:157], v[136:137] offset:64
	v_rcp_f32_e32 v111, v161
	s_nop 0
	v_mul_f32_e32 v161, v152, v111
	v_pk_mul_f32 v[86:87], v[86:87], v[146:147]
	v_and_b32_e32 v165, 0xffff0000, v153
	v_mul_f32_e32 v152, 0xbfb8aa3b, v168
	v_exp_f32_e32 v162, v152
	v_mul_f32_e32 v152, 0xbfb8aa3b, v165
	v_exp_f32_e32 v163, v152
	v_rcp_f32_e32 v111, v160
	s_nop 0
	v_mul_f32_e32 v160, v164, v111
	v_pk_mul_f32 v[92:93], v[92:93], v[160:161]
	v_lshlrev_b32_e32 v158, 16, v159
	v_pk_add_f32 v[160:161], v[162:163], 1.0 op_sel_hi:[1,0]
	v_and_b32_e32 v159, 0xffff0000, v159
	v_pk_fma_f32 v[94:95], v[132:133], v[158:159], v[94:95]
	v_pk_mul_f32 v[146:147], v[86:87], v[86:87]
	v_pk_mul_f32 v[148:149], v[88:89], v[88:89]
	v_rcp_f32_e32 v111, v161
	s_nop 0
	v_mul_f32_e32 v161, v165, v111
	v_pk_mul_f32 v[90:91], v[90:91], v[150:151]
	flat_load_dwordx2 v[158:159], v[138:139] offset:80
	flat_load_dwordx2 v[162:163], v[138:139] offset:96
	flat_load_dwordx2 v[164:165], v[138:139] offset:112
	v_rcp_f32_e32 v111, v160
	s_nop 0
	v_mul_f32_e32 v160, v168, v111
	v_pk_mul_f32 v[94:95], v[94:95], v[160:161]
	s_waitcnt vmcnt(0) lgkmcnt(0)
; DI float bflo(unsigned u) { return __uint_as_float(u << 16); }
; DI float bfhi(unsigned u) { return __uint_as_float(u & 0xffff0000u); }
; DI float xhalf(float v) { return __shfl_xor(v, 32); }
; DI float siluf_(float x) { return x / (1.f + __expf(-x)); }
; DI void ssd_out_phase(int wv, const Params& P, LAS unsigned char* lds) {
;     ...
;         for (int lt = 0; lt < 4; ++lt) { const size_t rr = (size_t)(row0 + lt * 32 + q); float ss = 0.f;
; #pragma unroll
;             for (int pt = 0; pt < 2; ++pt)
; #pragma unroll
;                 for (int i4 = 0; i4 < 4; ++i4) { const int p0 = h * 64 + pt * 32 + 8 * i4 + 4 * hh; const u32x2 xv = *(const u32x2*)(XS + rr * 1024 + p0), zv = *(const u32x2*)(Z + rr * 1024 + p0);
;                     const float xs4[4] = {bflo(xv.x), bfhi(xv.x), bflo(xv.y), bfhi(xv.y)}, zs4[4] = {bflo(zv.x), bfhi(zv.x), bflo(zv.y), bfhi(zv.y)};
; #pragma unroll
;                     for (int e = 0; e < 4; ++e) { const float y = (acc[pt][lt][4 * i4 + e] + xs4[e] * dsk) * siluf_(zs4[e]); acc[pt][lt][4 * i4 + e] = y; ss += y * y; } }
;             ss += xhalf(ss); if (hh == 0) ssq[wave * 128 + lt * 32 + q] = ss; }
	v_lshlrev_b32_e32 v172, 16, v154
	v_and_b32_e32 v154, 0xffff0000, v154
	v_mul_f32_e32 v138, 0xbfb8aa3b, v172
	v_exp_f32_e32 v166, v138
	v_mul_f32_e32 v138, 0xbfb8aa3b, v154
	v_exp_f32_e32 v167, v138
	v_and_b32_e32 v174, 0xffff0000, v155
	v_pk_mul_f32 v[150:151], v[90:91], v[90:91]
	v_pk_mul_f32 v[152:153], v[92:93], v[92:93]
	v_pk_add_f32 v[160:161], v[166:167], 1.0 op_sel_hi:[1,0]
	flat_load_dwordx2 v[166:167], v[136:137] offset:80
	flat_load_dwordx2 v[168:169], v[136:137] offset:96
	s_nop 0
	flat_load_dwordx2 v[136:137], v[136:137] offset:112
	v_pk_mul_f32 v[138:139], v[94:95], v[94:95]
	v_lshlrev_b32_e32 v170, 16, v156
	v_and_b32_e32 v171, 0xffff0000, v156
	v_pk_fma_f32 v[48:49], v[132:133], v[170:171], v[48:49]
	v_rcp_f32_e32 v111, v161
	s_nop 0
	v_mul_f32_e32 v161, v154, v111
	v_lshlrev_b32_e32 v173, 16, v155
	v_mul_f32_e32 v154, 0xbfb8aa3b, v173
	v_exp_f32_e32 v170, v154
	v_mul_f32_e32 v154, 0xbfb8aa3b, v174
	v_exp_f32_e32 v171, v154
	v_rcp_f32_e32 v111, v160
	s_nop 0
	v_mul_f32_e32 v160, v172, v111
	v_pk_mul_f32 v[48:49], v[48:49], v[160:161]
	v_lshlrev_b32_e32 v156, 16, v157
	v_pk_add_f32 v[160:161], v[170:171], 1.0 op_sel_hi:[1,0]
	v_and_b32_e32 v157, 0xffff0000, v157
	v_pk_fma_f32 v[50:51], v[132:133], v[156:157], v[50:51]
	v_pk_mul_f32 v[154:155], v[48:49], v[48:49]
	v_rcp_f32_e32 v111, v161
	s_nop 0
	v_mul_f32_e32 v157, v174, v111
	v_lshlrev_b32_e32 v172, 16, v158
	v_and_b32_e32 v158, 0xffff0000, v158
	v_mul_f32_e32 v156, 0xbfb8aa3b, v172
	v_exp_f32_e32 v170, v156
	v_mul_f32_e32 v156, 0xbfb8aa3b, v158
	v_exp_f32_e32 v171, v156
	v_rcp_f32_e32 v111, v160
	s_nop 0
	v_mul_f32_e32 v156, v173, v111
	v_pk_mul_f32 v[50:51], v[50:51], v[156:157]
	v_pk_add_f32 v[160:161], v[170:171], 1.0 op_sel_hi:[1,0]
	s_nop 0
	s_waitcnt vmcnt(0) lgkmcnt(0)
	v_lshlrev_b32_e32 v170, 16, v166
	v_and_b32_e32 v171, 0xffff0000, v166
	v_pk_fma_f32 v[52:53], v[132:133], v[170:171], v[52:53]
	v_rcp_f32_e32 v111, v161
	s_nop 0
	v_mul_f32_e32 v161, v158, v111
	v_pk_mul_f32 v[156:157], v[50:51], v[50:51]
	v_lshlrev_b32_e32 v170, 16, v159
	v_and_b32_e32 v171, 0xffff0000, v159
	v_mul_f32_e32 v158, 0xbfb8aa3b, v170
	v_mul_f32_e32 v159, 0xbfb8aa3b, v171
	v_exp_f32_e32 v158, v158
	v_exp_f32_e32 v159, v159
	v_rcp_f32_e32 v111, v160
	s_nop 0
	v_mul_f32_e32 v160, v172, v111
	v_lshlrev_b32_e32 v166, 16, v167
	v_and_b32_e32 v167, 0xffff0000, v167
	v_pk_add_f32 v[158:159], v[158:159], 1.0 op_sel_hi:[1,0]
	v_pk_fma_f32 v[54:55], v[132:133], v[166:167], v[54:55]
	v_pk_mul_f32 v[52:53], v[52:53], v[160:161]
	v_rcp_f32_e32 v111, v159
	s_nop 0
	v_mul_f32_e32 v159, v171, v111
	v_lshlrev_b32_e32 v172, 16, v162
	v_and_b32_e32 v162, 0xffff0000, v162
	v_mul_f32_e32 v166, 0xbfb8aa3b, v172
	v_mul_f32_e32 v167, 0xbfb8aa3b, v162
	v_exp_f32_e32 v166, v166
	v_exp_f32_e32 v167, v167
	v_rcp_f32_e32 v111, v158
	s_nop 0
	v_mul_f32_e32 v158, v170, v111
	v_lshlrev_b32_e32 v170, 16, v168
	v_and_b32_e32 v171, 0xffff0000, v168
	v_pk_add_f32 v[166:167], v[166:167], 1.0 op_sel_hi:[1,0]
	v_pk_fma_f32 v[56:57], v[132:133], v[170:171], v[56:57]
	v_pk_mul_f32 v[160:161], v[52:53], v[52:53]
	v_pk_mul_f32 v[54:55], v[54:55], v[158:159]
	v_rcp_f32_e32 v111, v167
	s_nop 0
	v_mul_f32_e32 v167, v162, v111
	v_pk_mul_f32 v[158:159], v[54:55], v[54:55]
	v_lshlrev_b32_e32 v170, 16, v163
	v_and_b32_e32 v171, 0xffff0000, v163
	v_mul_f32_e32 v162, 0xbfb8aa3b, v170
	v_mul_f32_e32 v163, 0xbfb8aa3b, v171
	v_exp_f32_e32 v162, v162
	v_exp_f32_e32 v163, v163
	v_rcp_f32_e32 v111, v166
	s_nop 0
	v_mul_f32_e32 v166, v172, v111
	v_lshlrev_b32_e32 v168, 16, v169
	v_and_b32_e32 v169, 0xffff0000, v169
	v_pk_add_f32 v[162:163], v[162:163], 1.0 op_sel_hi:[1,0]
	v_pk_fma_f32 v[58:59], v[132:133], v[168:169], v[58:59]
	v_pk_mul_f32 v[56:57], v[56:57], v[166:167]
	v_rcp_f32_e32 v111, v163
	s_nop 0
	v_mul_f32_e32 v163, v171, v111
	v_lshlrev_b32_e32 v172, 16, v164
	v_and_b32_e32 v164, 0xffff0000, v164
	v_mul_f32_e32 v168, 0xbfb8aa3b, v172
	v_mul_f32_e32 v169, 0xbfb8aa3b, v164
	v_exp_f32_e32 v168, v168
	v_exp_f32_e32 v169, v169
	v_rcp_f32_e32 v111, v162
	s_nop 0
	v_mul_f32_e32 v162, v170, v111
	v_lshlrev_b32_e32 v170, 16, v136
	v_and_b32_e32 v171, 0xffff0000, v136
	v_pk_add_f32 v[168:169], v[168:169], 1.0 op_sel_hi:[1,0]
	v_pk_fma_f32 v[60:61], v[132:133], v[170:171], v[60:61]
	v_pk_mul_f32 v[166:167], v[56:57], v[56:57]
	v_pk_mul_f32 v[58:59], v[58:59], v[162:163]
	v_rcp_f32_e32 v111, v169
	s_nop 0
	v_mul_f32_e32 v169, v164, v111
	v_pk_mul_f32 v[162:163], v[58:59], v[58:59]
	v_lshlrev_b32_e32 v170, 16, v165
	v_and_b32_e32 v171, 0xffff0000, v165
	v_mul_f32_e32 v136, 0xbfb8aa3b, v170
	v_exp_f32_e32 v164, v136
	v_mul_f32_e32 v136, 0xbfb8aa3b, v171
	v_exp_f32_e32 v165, v136
	v_rcp_f32_e32 v111, v168
	s_nop 0
	v_mul_f32_e32 v168, v172, v111
	v_lshlrev_b32_e32 v136, 16, v137
	v_and_b32_e32 v137, 0xffff0000, v137
	v_pk_add_f32 v[164:165], v[164:165], 1.0 op_sel_hi:[1,0]
	v_pk_fma_f32 v[62:63], v[132:133], v[136:137], v[62:63]
	v_pk_mul_f32 v[60:61], v[60:61], v[168:169]
	v_rcp_f32_e32 v111, v165
	s_nop 0
	v_mul_f32_e32 v137, v171, v111
	v_pk_mul_f32 v[168:169], v[60:61], v[60:61]
	v_rcp_f32_e32 v111, v164
	s_nop 0
	v_mul_f32_e32 v136, v170, v111
	v_add_f32_e32 v111, v140, v141
	v_add_f32_e32 v111, v142, v111
	v_add_f32_e32 v111, v143, v111
	v_add_f32_e32 v111, v144, v111
	v_add_f32_e32 v111, v145, v111
	v_add_f32_e32 v111, v146, v111
	v_add_f32_e32 v111, v147, v111
	v_add_f32_e32 v111, v148, v111
	v_add_f32_e32 v111, v149, v111
	v_add_f32_e32 v111, v150, v111
	v_add_f32_e32 v111, v151, v111
	v_add_f32_e32 v111, v152, v111
	v_add_f32_e32 v111, v153, v111
	v_add_f32_e32 v111, v138, v111
	v_add_f32_e32 v111, v139, v111
	v_add_f32_e32 v111, v154, v111
	v_add_f32_e32 v111, v155, v111
	v_add_f32_e32 v111, v156, v111
	v_add_f32_e32 v111, v157, v111
	v_add_f32_e32 v111, v160, v111
	v_add_f32_e32 v111, v161, v111
	v_add_f32_e32 v111, v158, v111
	v_add_f32_e32 v111, v159, v111
	v_add_f32_e32 v111, v166, v111
	v_add_f32_e32 v111, v167, v111
	v_add_f32_e32 v111, v162, v111
	v_add_f32_e32 v111, v163, v111
	v_pk_mul_f32 v[136:137], v[62:63], v[136:137]
	v_add_f32_e32 v111, v168, v111
	v_pk_mul_f32 v[62:63], v[136:137], v[136:137]
	v_add_f32_e32 v111, v169, v111
	v_add_f32_e32 v62, v62, v111
	v_add_f32_e32 v62, v63, v62
	ds_bpermute_b32 v63, v229, v62
	s_and_saveexec_b64 s[14:15], s[12:13]
	s_cbranch_execz .LBB0_1691
	s_waitcnt lgkmcnt(0)
	v_add_f32_e32 v62, v62, v63
	ds_write_b32 v231, v62 offset:128
; DI float bflo(unsigned u) { return __uint_as_float(u << 16); }
; DI float bfhi(unsigned u) { return __uint_as_float(u & 0xffff0000u); }
; DI float xhalf(float v) { return __shfl_xor(v, 32); }
; DI float siluf_(float x) { return x / (1.f + __expf(-x)); }
; DI void ssd_out_phase(int wv, const Params& P, LAS unsigned char* lds) {
;     ...
;         for (int lt = 0; lt < 4; ++lt) { const size_t rr = (size_t)(row0 + lt * 32 + q); float ss = 0.f;
; #pragma unroll
;             for (int pt = 0; pt < 2; ++pt)
; #pragma unroll
;                 for (int i4 = 0; i4 < 4; ++i4) { const int p0 = h * 64 + pt * 32 + 8 * i4 + 4 * hh; const u32x2 xv = *(const u32x2*)(XS + rr * 1024 + p0), zv = *(const u32x2*)(Z + rr * 1024 + p0);
;                     const float xs4[4] = {bflo(xv.x), bfhi(xv.x), bflo(xv.y), bfhi(xv.y)}, zs4[4] = {bflo(zv.x), bfhi(zv.x), bflo(zv.y), bfhi(zv.y)};
; #pragma unroll
;                     for (int e = 0; e < 4; ++e) { const float y = (acc[pt][lt][4 * i4 + e] + xs4[e] * dsk) * siluf_(zs4[e]); acc[pt][lt][4 * i4 + e] = y; ss += y * y; } }
;             ss += xhalf(ss); if (hh == 0) ssq[wave * 128 + lt * 32 + q] = ss; }
.LBB0_1691:
	s_or_b64 exec, exec, s[14:15]
	v_or_b32_e32 v62, 64, v196
	s_waitcnt lgkmcnt(0)
	v_ashrrev_i32_e32 v63, 31, v62
	v_lshlrev_b64 v[138:139], 11, v[62:63]
	v_lshl_add_u64 v[140:141], s[28:29], 0, v[138:139]
	v_lshl_add_u64 v[144:145], s[34:35], 0, v[138:139]
	v_lshl_add_u64 v[138:139], v[140:141], 0, v[128:129]
	flat_load_dwordx2 v[142:143], v[138:139]
	v_lshl_add_u64 v[140:141], v[144:145], 0, v[128:129]
	flat_load_dwordx2 v[144:145], v[140:141]
	flat_load_dwordx2 v[148:149], v[138:139] offset:16
	flat_load_dwordx2 v[146:147], v[140:141] offset:16
	flat_load_dwordx2 v[152:153], v[138:139] offset:32
	flat_load_dwordx2 v[160:161], v[138:139] offset:48
	flat_load_dwordx2 v[150:151], v[140:141] offset:32
	flat_load_dwordx2 v[154:155], v[140:141] offset:48
	s_waitcnt vmcnt(0) lgkmcnt(0)
	v_lshlrev_b32_e32 v63, 16, v144
	v_and_b32_e32 v111, 0xffff0000, v144
	v_lshlrev_b32_e32 v162, 16, v145
	v_and_b32_e32 v163, 0xffff0000, v145
	v_lshlrev_b32_e32 v156, 16, v142
	v_and_b32_e32 v157, 0xffff0000, v142
	v_lshlrev_b32_e32 v142, 16, v143
	v_and_b32_e32 v143, 0xffff0000, v143
	v_lshlrev_b32_e32 v144, 16, v148
	v_and_b32_e32 v145, 0xffff0000, v148
	v_lshlrev_b32_e32 v148, 16, v146
	v_and_b32_e32 v146, 0xffff0000, v146
	v_mul_f32_e32 v158, 0xbfb8aa3b, v63
	v_pk_fma_f32 v[64:65], v[132:133], v[156:157], v[64:65]
	v_mul_f32_e32 v156, 0xbfb8aa3b, v111
	v_mul_f32_e32 v157, 0xbfb8aa3b, v162
	v_pk_fma_f32 v[66:67], v[132:133], v[142:143], v[66:67]
	v_mul_f32_e32 v159, 0xbfb8aa3b, v163
	v_mul_f32_e32 v164, 0xbfb8aa3b, v148
	v_mul_f32_e32 v165, 0xbfb8aa3b, v146
	v_exp_f32_e32 v142, v158
	v_exp_f32_e32 v143, v156
	v_exp_f32_e32 v156, v157
	v_exp_f32_e32 v157, v159
	v_exp_f32_e32 v158, v164
	v_exp_f32_e32 v159, v165
	v_pk_add_f32 v[142:143], v[142:143], 1.0 op_sel_hi:[1,0]
	v_pk_fma_f32 v[68:69], v[132:133], v[144:145], v[68:69]
	v_pk_add_f32 v[144:145], v[156:157], 1.0 op_sel_hi:[1,0]
	v_pk_add_f32 v[156:157], v[158:159], 1.0 op_sel_hi:[1,0]
	s_mov_b64 vcc, s[14:15]
	v_rcp_f32_e32 v158, v143
	s_nop 0
	v_mul_f32_e32 v143, v111, v158
	s_mov_b64 vcc, s[16:17]
	v_rcp_f32_e32 v111, v142
	s_nop 0
	v_mul_f32_e32 v142, v63, v111
	s_mov_b64 vcc, s[18:19]
	v_rcp_f32_e32 v63, v145
	s_nop 0
	v_mul_f32_e32 v145, v163, v63
	v_rcp_f32_e32 v63, v144
	s_nop 0
	v_mul_f32_e32 v144, v162, v63
	v_rcp_f32_e32 v63, v157
	s_nop 0
	v_mul_f32_e32 v157, v146, v63
	v_lshlrev_b32_e32 v111, 16, v147
	v_and_b32_e32 v162, 0xffff0000, v147
	v_mul_f32_e32 v146, 0xbfb8aa3b, v111
	v_exp_f32_e32 v158, v146
	v_mul_f32_e32 v146, 0xbfb8aa3b, v162
	v_exp_f32_e32 v159, v146
	v_rcp_f32_e32 v63, v156
	s_nop 0
	v_mul_f32_e32 v156, v148, v63
	v_pk_mul_f32 v[68:69], v[68:69], v[156:157]
	v_lshlrev_b32_e32 v148, 16, v149
	v_pk_add_f32 v[156:157], v[158:159], 1.0 op_sel_hi:[1,0]
	v_and_b32_e32 v149, 0xffff0000, v149
	v_pk_fma_f32 v[70:71], v[132:133], v[148:149], v[70:71]
	v_and_b32_e32 v163, 0xffff0000, v151
	v_lshlrev_b32_e32 v166, 16, v154
	v_rcp_f32_e32 v63, v157
	s_nop 0
	v_mul_f32_e32 v149, v162, v63
	v_lshlrev_b32_e32 v162, 16, v150
	v_and_b32_e32 v150, 0xffff0000, v150
	v_mul_f32_e32 v148, 0xbfb8aa3b, v162
	v_exp_f32_e32 v158, v148
	v_mul_f32_e32 v148, 0xbfb8aa3b, v150
	v_exp_f32_e32 v159, v148
	v_rcp_f32_e32 v63, v156
	s_nop 0
	v_mul_f32_e32 v148, v111, v63
	v_and_b32_e32 v154, 0xffff0000, v154
	v_and_b32_e32 v167, 0xffff0000, v155
	v_pk_add_f32 v[156:157], v[158:159], 1.0 op_sel_hi:[1,0]
	v_lshlrev_b32_e32 v158, 16, v152
	v_and_b32_e32 v159, 0xffff0000, v152
	v_pk_fma_f32 v[72:73], v[132:133], v[158:159], v[72:73]
	v_pk_mul_f32 v[64:65], v[64:65], v[142:143]
	v_rcp_f32_e32 v63, v157
	s_nop 0
	v_mul_f32_e32 v157, v150, v63
	v_pk_mul_f32 v[142:143], v[64:65], v[64:65]
	v_lshlrev_b32_e32 v111, 16, v151
	v_mul_f32_e32 v150, 0xbfb8aa3b, v111
	v_exp_f32_e32 v158, v150
	v_mul_f32_e32 v150, 0xbfb8aa3b, v163
	v_exp_f32_e32 v159, v150
	v_rcp_f32_e32 v63, v156
	s_nop 0
	v_mul_f32_e32 v156, v162, v63
	v_pk_mul_f32 v[72:73], v[72:73], v[156:157]
	v_lshlrev_b32_e32 v152, 16, v153
	v_pk_add_f32 v[158:159], v[158:159], 1.0 op_sel_hi:[1,0]
	v_and_b32_e32 v153, 0xffff0000, v153
	v_pk_fma_f32 v[74:75], v[132:133], v[152:153], v[74:75]
	v_pk_mul_f32 v[66:67], v[66:67], v[144:145]
	v_pk_mul_f32 v[146:147], v[68:69], v[68:69]
	v_rcp_f32_e32 v63, v159
	s_nop 0
	v_mul_f32_e32 v153, v163, v63
	v_pk_mul_f32 v[144:145], v[66:67], v[66:67]
	flat_load_dwordx2 v[156:157], v[140:141] offset:64
	v_mul_f32_e32 v152, 0xbfb8aa3b, v166
	v_exp_f32_e32 v162, v152
	v_mul_f32_e32 v152, 0xbfb8aa3b, v154
	v_exp_f32_e32 v163, v152
	v_rcp_f32_e32 v63, v158
	s_nop 0
	v_mul_f32_e32 v152, v111, v63
	v_lshlrev_b32_e32 v158, 16, v160
	v_and_b32_e32 v159, 0xffff0000, v160
	v_pk_add_f32 v[162:163], v[162:163], 1.0 op_sel_hi:[1,0]
	v_pk_fma_f32 v[76:77], v[132:133], v[158:159], v[76:77]
	v_pk_mul_f32 v[70:71], v[70:71], v[148:149]
	flat_load_dwordx2 v[158:159], v[138:139] offset:64
	v_rcp_f32_e32 v63, v163
	s_nop 0
	v_mul_f32_e32 v163, v154, v63
	v_pk_mul_f32 v[148:149], v[70:71], v[70:71]
	v_lshlrev_b32_e32 v111, 16, v155
	v_mul_f32_e32 v154, 0xbfb8aa3b, v111
	v_exp_f32_e32 v164, v154
	v_mul_f32_e32 v154, 0xbfb8aa3b, v167
	v_exp_f32_e32 v165, v154
	v_rcp_f32_e32 v63, v162
	s_nop 0
	v_mul_f32_e32 v162, v166, v63
	v_pk_mul_f32 v[76:77], v[76:77], v[162:163]
	v_lshlrev_b32_e32 v160, 16, v161
	v_pk_add_f32 v[162:163], v[164:165], 1.0 op_sel_hi:[1,0]
	v_and_b32_e32 v161, 0xffff0000, v161
	v_pk_fma_f32 v[78:79], v[132:133], v[160:161], v[78:79]
	v_pk_mul_f32 v[150:151], v[72:73], v[72:73]
	v_pk_mul_f32 v[74:75], v[74:75], v[152:153]
	v_rcp_f32_e32 v63, v163
	s_nop 0
	v_mul_f32_e32 v163, v167, v63
	v_pk_mul_f32 v[152:153], v[74:75], v[74:75]
	flat_load_dwordx2 v[160:161], v[140:141] offset:80
	flat_load_dwordx2 v[164:165], v[140:141] offset:96
	flat_load_dwordx2 v[166:167], v[140:141] offset:112
	v_rcp_f32_e32 v63, v162
	s_nop 0
	v_mul_f32_e32 v162, v111, v63
	v_pk_mul_f32 v[78:79], v[78:79], v[162:163]
	s_waitcnt vmcnt(0) lgkmcnt(0)
; DI float bflo(unsigned u) { return __uint_as_float(u << 16); }
; DI float bfhi(unsigned u) { return __uint_as_float(u & 0xffff0000u); }
; DI float xhalf(float v) { return __shfl_xor(v, 32); }
; DI float siluf_(float x) { return x / (1.f + __expf(-x)); }
; DI void ssd_out_phase(int wv, const Params& P, LAS unsigned char* lds) {
;     ...
;         for (int lt = 0; lt < 4; ++lt) { const size_t rr = (size_t)(row0 + lt * 32 + q); float ss = 0.f;
; #pragma unroll
;             for (int pt = 0; pt < 2; ++pt)
; #pragma unroll
;                 for (int i4 = 0; i4 < 4; ++i4) { const int p0 = h * 64 + pt * 32 + 8 * i4 + 4 * hh; const u32x2 xv = *(const u32x2*)(XS + rr * 1024 + p0), zv = *(const u32x2*)(Z + rr * 1024 + p0);
;                     const float xs4[4] = {bflo(xv.x), bfhi(xv.x), bflo(xv.y), bfhi(xv.y)}, zs4[4] = {bflo(zv.x), bfhi(zv.x), bflo(zv.y), bfhi(zv.y)};
; #pragma unroll
;                     for (int e = 0; e < 4; ++e) { const float y = (acc[pt][lt][4 * i4 + e] + xs4[e] * dsk) * siluf_(zs4[e]); acc[pt][lt][4 * i4 + e] = y; ss += y * y; } }
;             ss += xhalf(ss); if (hh == 0) ssq[wave * 128 + lt * 32 + q] = ss; }
	v_lshlrev_b32_e32 v174, 16, v156
	v_and_b32_e32 v156, 0xffff0000, v156
	v_mul_f32_e32 v140, 0xbfb8aa3b, v174
	v_exp_f32_e32 v168, v140
	v_mul_f32_e32 v140, 0xbfb8aa3b, v156
	v_exp_f32_e32 v169, v140
	v_and_b32_e32 v175, 0xffff0000, v157
	v_pk_mul_f32 v[154:155], v[76:77], v[76:77]
	v_pk_mul_f32 v[140:141], v[78:79], v[78:79]
	v_pk_add_f32 v[162:163], v[168:169], 1.0 op_sel_hi:[1,0]
	flat_load_dwordx2 v[168:169], v[138:139] offset:80
	flat_load_dwordx2 v[170:171], v[138:139] offset:96
	s_nop 0
	flat_load_dwordx2 v[138:139], v[138:139] offset:112
	v_lshlrev_b32_e32 v172, 16, v158
	v_and_b32_e32 v173, 0xffff0000, v158
	v_pk_fma_f32 v[32:33], v[132:133], v[172:173], v[32:33]
	v_rcp_f32_e32 v63, v163
	s_nop 0
	v_mul_f32_e32 v163, v156, v63
	v_lshlrev_b32_e32 v111, 16, v157
	v_mul_f32_e32 v156, 0xbfb8aa3b, v111
	v_exp_f32_e32 v172, v156
	v_mul_f32_e32 v156, 0xbfb8aa3b, v175
	v_exp_f32_e32 v173, v156
	v_rcp_f32_e32 v63, v162
	s_nop 0
	v_mul_f32_e32 v162, v174, v63
	v_pk_mul_f32 v[32:33], v[32:33], v[162:163]
	v_lshlrev_b32_e32 v158, 16, v159
	v_pk_add_f32 v[162:163], v[172:173], 1.0 op_sel_hi:[1,0]
	v_and_b32_e32 v159, 0xffff0000, v159
	v_pk_fma_f32 v[34:35], v[132:133], v[158:159], v[34:35]
	v_pk_mul_f32 v[156:157], v[32:33], v[32:33]
	v_rcp_f32_e32 v63, v163
	s_nop 0
	v_mul_f32_e32 v159, v175, v63
	v_lshlrev_b32_e32 v174, 16, v160
	v_and_b32_e32 v160, 0xffff0000, v160
	v_mul_f32_e32 v158, 0xbfb8aa3b, v174
	v_exp_f32_e32 v172, v158
	v_mul_f32_e32 v158, 0xbfb8aa3b, v160
	v_exp_f32_e32 v173, v158
	v_rcp_f32_e32 v63, v162
	s_nop 0
	v_mul_f32_e32 v158, v111, v63
	v_pk_mul_f32 v[34:35], v[34:35], v[158:159]
	v_pk_add_f32 v[162:163], v[172:173], 1.0 op_sel_hi:[1,0]
	s_nop 0
	s_waitcnt vmcnt(0) lgkmcnt(0)
	v_lshlrev_b32_e32 v172, 16, v168
	v_and_b32_e32 v173, 0xffff0000, v168
	v_pk_fma_f32 v[36:37], v[132:133], v[172:173], v[36:37]
	v_rcp_f32_e32 v63, v163
	s_nop 0
	v_mul_f32_e32 v163, v160, v63
	v_and_b32_e32 v172, 0xffff0000, v161
	v_lshlrev_b32_e32 v111, 16, v161
	v_mul_f32_e32 v160, 0xbfb8aa3b, v111
	v_mul_f32_e32 v161, 0xbfb8aa3b, v172
	v_exp_f32_e32 v160, v160
	v_exp_f32_e32 v161, v161
	v_rcp_f32_e32 v63, v162
	s_nop 0
	v_mul_f32_e32 v162, v174, v63
	v_lshlrev_b32_e32 v168, 16, v169
	v_and_b32_e32 v169, 0xffff0000, v169
	v_pk_add_f32 v[160:161], v[160:161], 1.0 op_sel_hi:[1,0]
	v_pk_fma_f32 v[38:39], v[132:133], v[168:169], v[38:39]
	v_pk_mul_f32 v[158:159], v[34:35], v[34:35]
	v_pk_mul_f32 v[36:37], v[36:37], v[162:163]
	v_rcp_f32_e32 v63, v161
	s_nop 0
	v_mul_f32_e32 v161, v172, v63
	v_and_b32_e32 v173, 0xffff0000, v170
	v_lshlrev_b32_e32 v174, 16, v164
	v_and_b32_e32 v164, 0xffff0000, v164
	v_mul_f32_e32 v168, 0xbfb8aa3b, v174
	v_mul_f32_e32 v169, 0xbfb8aa3b, v164
	v_exp_f32_e32 v168, v168
	v_exp_f32_e32 v169, v169
	v_rcp_f32_e32 v63, v160
	s_nop 0
	v_mul_f32_e32 v160, v111, v63
	v_lshlrev_b32_e32 v172, 16, v170
	v_pk_fma_f32 v[40:41], v[132:133], v[172:173], v[40:41]
	v_pk_add_f32 v[168:169], v[168:169], 1.0 op_sel_hi:[1,0]
	v_pk_mul_f32 v[162:163], v[36:37], v[36:37]
	v_pk_mul_f32 v[38:39], v[38:39], v[160:161]
	v_rcp_f32_e32 v63, v169
	s_nop 0
	v_mul_f32_e32 v169, v164, v63
	v_and_b32_e32 v172, 0xffff0000, v165
	v_lshlrev_b32_e32 v111, 16, v165
	v_mul_f32_e32 v164, 0xbfb8aa3b, v111
	v_mul_f32_e32 v165, 0xbfb8aa3b, v172
	v_exp_f32_e32 v164, v164
	v_exp_f32_e32 v165, v165
	v_rcp_f32_e32 v63, v168
	s_nop 0
	v_mul_f32_e32 v168, v174, v63
	v_lshlrev_b32_e32 v170, 16, v171
	v_and_b32_e32 v171, 0xffff0000, v171
	v_pk_add_f32 v[164:165], v[164:165], 1.0 op_sel_hi:[1,0]
	v_pk_fma_f32 v[42:43], v[132:133], v[170:171], v[42:43]
	v_pk_mul_f32 v[160:161], v[38:39], v[38:39]
	v_pk_mul_f32 v[40:41], v[40:41], v[168:169]
	v_rcp_f32_e32 v63, v165
	s_nop 0
	v_mul_f32_e32 v165, v172, v63
	v_and_b32_e32 v173, 0xffff0000, v138
	v_lshlrev_b32_e32 v174, 16, v166
	v_and_b32_e32 v166, 0xffff0000, v166
	v_mul_f32_e32 v170, 0xbfb8aa3b, v174
	v_mul_f32_e32 v171, 0xbfb8aa3b, v166
	v_exp_f32_e32 v170, v170
	v_exp_f32_e32 v171, v171
	v_rcp_f32_e32 v63, v164
	s_nop 0
	v_mul_f32_e32 v164, v111, v63
	v_lshlrev_b32_e32 v172, 16, v138
	v_pk_fma_f32 v[44:45], v[132:133], v[172:173], v[44:45]
	v_pk_add_f32 v[170:171], v[170:171], 1.0 op_sel_hi:[1,0]
	v_pk_mul_f32 v[168:169], v[40:41], v[40:41]
	v_pk_mul_f32 v[42:43], v[42:43], v[164:165]
	v_rcp_f32_e32 v63, v171
	s_nop 0
	v_mul_f32_e32 v171, v166, v63
	v_and_b32_e32 v172, 0xffff0000, v167
	v_lshlrev_b32_e32 v111, 16, v167
	v_mul_f32_e32 v138, 0xbfb8aa3b, v111
	v_exp_f32_e32 v166, v138
	v_mul_f32_e32 v138, 0xbfb8aa3b, v172
	v_exp_f32_e32 v167, v138
	v_rcp_f32_e32 v63, v170
	s_nop 0
	v_mul_f32_e32 v170, v174, v63
	v_lshlrev_b32_e32 v138, 16, v139
	v_and_b32_e32 v139, 0xffff0000, v139
	v_pk_add_f32 v[166:167], v[166:167], 1.0 op_sel_hi:[1,0]
	v_pk_fma_f32 v[46:47], v[132:133], v[138:139], v[46:47]
	v_pk_mul_f32 v[164:165], v[42:43], v[42:43]
	v_pk_mul_f32 v[44:45], v[44:45], v[170:171]
	v_rcp_f32_e32 v63, v167
	s_nop 0
	v_mul_f32_e32 v139, v172, v63
	v_pk_mul_f32 v[170:171], v[44:45], v[44:45]
	v_rcp_f32_e32 v63, v166
	s_nop 0
	v_mul_f32_e32 v138, v111, v63
	v_add_f32_e32 v63, v142, v143
	v_add_f32_e32 v63, v144, v63
	v_add_f32_e32 v63, v145, v63
	v_add_f32_e32 v63, v146, v63
	v_add_f32_e32 v63, v147, v63
	v_add_f32_e32 v63, v148, v63
	v_add_f32_e32 v63, v149, v63
	v_add_f32_e32 v63, v150, v63
	v_add_f32_e32 v63, v151, v63
	v_add_f32_e32 v63, v152, v63
	v_add_f32_e32 v63, v153, v63
	v_add_f32_e32 v63, v154, v63
	v_add_f32_e32 v63, v155, v63
	v_add_f32_e32 v63, v140, v63
	v_add_f32_e32 v63, v141, v63
	v_add_f32_e32 v63, v156, v63
	v_add_f32_e32 v63, v157, v63
	v_add_f32_e32 v63, v158, v63
	v_add_f32_e32 v63, v159, v63
	v_add_f32_e32 v63, v162, v63
	v_add_f32_e32 v63, v163, v63
	v_add_f32_e32 v63, v160, v63
	v_add_f32_e32 v63, v161, v63
	v_add_f32_e32 v63, v168, v63
	v_add_f32_e32 v63, v169, v63
	v_add_f32_e32 v63, v164, v63
	v_add_f32_e32 v63, v165, v63
	v_pk_mul_f32 v[138:139], v[46:47], v[138:139]
	v_add_f32_e32 v63, v170, v63
	v_pk_mul_f32 v[46:47], v[138:139], v[138:139]
	v_add_f32_e32 v63, v171, v63
	v_add_f32_e32 v46, v46, v63
	v_add_f32_e32 v46, v47, v46
	ds_bpermute_b32 v47, v229, v46
	s_and_saveexec_b64 s[14:15], s[12:13]
	s_cbranch_execz .LBB0_1693
	s_waitcnt lgkmcnt(0)
	v_add_f32_e32 v46, v46, v47
	ds_write_b32 v231, v46 offset:256
; DI float bflo(unsigned u) { return __uint_as_float(u << 16); }
; DI float bfhi(unsigned u) { return __uint_as_float(u & 0xffff0000u); }
; DI float xhalf(float v) { return __shfl_xor(v, 32); }
; DI float siluf_(float x) { return x / (1.f + __expf(-x)); }
; DI void ssd_out_phase(int wv, const Params& P, LAS unsigned char* lds) {
;     ...
;         for (int lt = 0; lt < 4; ++lt) { const size_t rr = (size_t)(row0 + lt * 32 + q); float ss = 0.f;
; #pragma unroll
;             for (int pt = 0; pt < 2; ++pt)
; #pragma unroll
;                 for (int i4 = 0; i4 < 4; ++i4) { const int p0 = h * 64 + pt * 32 + 8 * i4 + 4 * hh; const u32x2 xv = *(const u32x2*)(XS + rr * 1024 + p0), zv = *(const u32x2*)(Z + rr * 1024 + p0);
;                     const float xs4[4] = {bflo(xv.x), bfhi(xv.x), bflo(xv.y), bfhi(xv.y)}, zs4[4] = {bflo(zv.x), bfhi(zv.x), bflo(zv.y), bfhi(zv.y)};
; #pragma unroll
;                     for (int e = 0; e < 4; ++e) { const float y = (acc[pt][lt][4 * i4 + e] + xs4[e] * dsk) * siluf_(zs4[e]); acc[pt][lt][4 * i4 + e] = y; ss += y * y; } }
;             ss += xhalf(ss); if (hh == 0) ssq[wave * 128 + lt * 32 + q] = ss; }
.LBB0_1693:
	s_or_b64 exec, exec, s[14:15]
	v_or_b32_e32 v46, 0x60, v196
	s_waitcnt lgkmcnt(0)
	v_ashrrev_i32_e32 v47, 31, v46
	v_lshlrev_b64 v[140:141], 11, v[46:47]
	v_lshl_add_u64 v[142:143], s[28:29], 0, v[140:141]
	v_lshl_add_u64 v[146:147], s[34:35], 0, v[140:141]
	v_lshl_add_u64 v[140:141], v[142:143], 0, v[128:129]
	flat_load_dwordx2 v[144:145], v[140:141]
	v_lshl_add_u64 v[142:143], v[146:147], 0, v[128:129]
	flat_load_dwordx2 v[146:147], v[142:143]
	flat_load_dwordx2 v[150:151], v[140:141] offset:16
	flat_load_dwordx2 v[148:149], v[142:143] offset:16
	flat_load_dwordx2 v[154:155], v[140:141] offset:32
	flat_load_dwordx2 v[162:163], v[140:141] offset:48
	flat_load_dwordx2 v[152:153], v[142:143] offset:32
	flat_load_dwordx2 v[156:157], v[142:143] offset:48
	s_waitcnt vmcnt(0) lgkmcnt(0)
	v_lshlrev_b32_e32 v47, 16, v146
	v_and_b32_e32 v63, 0xffff0000, v146
	v_lshlrev_b32_e32 v111, 16, v147
	v_and_b32_e32 v164, 0xffff0000, v147
	v_lshlrev_b32_e32 v158, 16, v144
	v_and_b32_e32 v159, 0xffff0000, v144
	v_lshlrev_b32_e32 v144, 16, v145
	v_and_b32_e32 v145, 0xffff0000, v145
	v_lshlrev_b32_e32 v146, 16, v150
	v_and_b32_e32 v147, 0xffff0000, v150
	v_lshlrev_b32_e32 v150, 16, v148
	v_and_b32_e32 v148, 0xffff0000, v148
	v_mul_f32_e32 v160, 0xbfb8aa3b, v47
	v_pk_fma_f32 v[16:17], v[132:133], v[158:159], v[16:17]
	v_mul_f32_e32 v158, 0xbfb8aa3b, v63
	v_mul_f32_e32 v159, 0xbfb8aa3b, v111
	v_pk_fma_f32 v[18:19], v[132:133], v[144:145], v[18:19]
	v_mul_f32_e32 v161, 0xbfb8aa3b, v164
	v_mul_f32_e32 v165, 0xbfb8aa3b, v150
	v_mul_f32_e32 v166, 0xbfb8aa3b, v148
	v_exp_f32_e32 v144, v160
	v_exp_f32_e32 v145, v158
	v_exp_f32_e32 v158, v159
	v_exp_f32_e32 v159, v161
	v_exp_f32_e32 v160, v165
	v_exp_f32_e32 v161, v166
	v_pk_add_f32 v[144:145], v[144:145], 1.0 op_sel_hi:[1,0]
	v_pk_fma_f32 v[20:21], v[132:133], v[146:147], v[20:21]
	v_pk_add_f32 v[146:147], v[158:159], 1.0 op_sel_hi:[1,0]
	v_pk_add_f32 v[158:159], v[160:161], 1.0 op_sel_hi:[1,0]
	s_mov_b64 vcc, s[14:15]
	v_rcp_f32_e32 v160, v145
	s_nop 0
	v_mul_f32_e32 v145, v63, v160
	s_mov_b64 vcc, s[16:17]
	v_rcp_f32_e32 v63, v144
	s_nop 0
	v_mul_f32_e32 v144, v47, v63
	s_mov_b64 vcc, s[18:19]
	v_rcp_f32_e32 v47, v147
	s_nop 0
	v_mul_f32_e32 v147, v164, v47
	v_rcp_f32_e32 v47, v146
	s_nop 0
	v_mul_f32_e32 v146, v111, v47
	v_rcp_f32_e32 v47, v159
	s_nop 0
	v_mul_f32_e32 v159, v148, v47
	v_lshlrev_b32_e32 v63, 16, v149
	v_and_b32_e32 v111, 0xffff0000, v149
	v_mul_f32_e32 v148, 0xbfb8aa3b, v63
	v_exp_f32_e32 v160, v148
	v_mul_f32_e32 v148, 0xbfb8aa3b, v111
	v_exp_f32_e32 v161, v148
	v_rcp_f32_e32 v47, v158
	s_nop 0
	v_mul_f32_e32 v158, v150, v47
	v_pk_mul_f32 v[20:21], v[20:21], v[158:159]
	v_lshlrev_b32_e32 v150, 16, v151
	v_pk_add_f32 v[158:159], v[160:161], 1.0 op_sel_hi:[1,0]
	v_and_b32_e32 v151, 0xffff0000, v151
	v_pk_fma_f32 v[22:23], v[132:133], v[150:151], v[22:23]
	v_and_b32_e32 v164, 0xffff0000, v153
	v_and_b32_e32 v168, 0xffff0000, v157
	v_rcp_f32_e32 v47, v159
	s_nop 0
	v_mul_f32_e32 v151, v111, v47
	v_pk_mul_f32 v[16:17], v[16:17], v[144:145]
	v_lshlrev_b32_e32 v111, 16, v152
	v_and_b32_e32 v152, 0xffff0000, v152
	v_mul_f32_e32 v150, 0xbfb8aa3b, v111
	v_exp_f32_e32 v160, v150
	v_mul_f32_e32 v150, 0xbfb8aa3b, v152
	v_exp_f32_e32 v161, v150
	v_rcp_f32_e32 v47, v158
	s_nop 0
	v_mul_f32_e32 v150, v63, v47
	v_pk_mul_f32 v[144:145], v[16:17], v[16:17]
	v_pk_mul_f32 v[18:19], v[18:19], v[146:147]
	v_pk_add_f32 v[158:159], v[160:161], 1.0 op_sel_hi:[1,0]
	v_lshlrev_b32_e32 v160, 16, v154
	v_and_b32_e32 v161, 0xffff0000, v154
	v_pk_fma_f32 v[24:25], v[132:133], v[160:161], v[24:25]
	v_pk_mul_f32 v[146:147], v[18:19], v[18:19]
	v_rcp_f32_e32 v47, v159
	s_nop 0
	v_mul_f32_e32 v159, v152, v47
	v_pk_mul_f32 v[148:149], v[20:21], v[20:21]
	v_lshlrev_b32_e32 v63, 16, v153
	v_mul_f32_e32 v152, 0xbfb8aa3b, v63
	v_exp_f32_e32 v160, v152
	v_mul_f32_e32 v152, 0xbfb8aa3b, v164
	v_exp_f32_e32 v161, v152
	v_rcp_f32_e32 v47, v158
	s_nop 0
	v_mul_f32_e32 v158, v111, v47
	v_lshlrev_b32_e32 v154, 16, v155
	v_and_b32_e32 v155, 0xffff0000, v155
	v_pk_add_f32 v[160:161], v[160:161], 1.0 op_sel_hi:[1,0]
	v_pk_fma_f32 v[26:27], v[132:133], v[154:155], v[26:27]
	v_pk_mul_f32 v[24:25], v[24:25], v[158:159]
	v_pk_mul_f32 v[22:23], v[22:23], v[150:151]
	v_pk_mul_f32 v[152:153], v[24:25], v[24:25]
	v_rcp_f32_e32 v47, v161
	s_nop 0
	v_mul_f32_e32 v155, v164, v47
	v_and_b32_e32 v161, 0xffff0000, v162
	v_lshlrev_b32_e32 v111, 16, v156
	v_and_b32_e32 v156, 0xffff0000, v156
	v_mul_f32_e32 v154, 0xbfb8aa3b, v111
	v_exp_f32_e32 v164, v154
	v_mul_f32_e32 v154, 0xbfb8aa3b, v156
	flat_load_dwordx2 v[158:159], v[142:143] offset:64
	v_exp_f32_e32 v165, v154
	v_rcp_f32_e32 v47, v160
	s_nop 0
	v_mul_f32_e32 v154, v63, v47
	v_lshlrev_b32_e32 v160, 16, v162
	v_pk_fma_f32 v[28:29], v[132:133], v[160:161], v[28:29]
	v_pk_add_f32 v[164:165], v[164:165], 1.0 op_sel_hi:[1,0]
	v_pk_mul_f32 v[150:151], v[22:23], v[22:23]
	v_pk_mul_f32 v[26:27], v[26:27], v[154:155]
	flat_load_dwordx2 v[160:161], v[140:141] offset:64
	v_rcp_f32_e32 v47, v165
	s_nop 0
	v_mul_f32_e32 v165, v156, v47
	v_pk_mul_f32 v[154:155], v[26:27], v[26:27]
	v_lshlrev_b32_e32 v63, 16, v157
	v_mul_f32_e32 v156, 0xbfb8aa3b, v63
	v_exp_f32_e32 v166, v156
	v_mul_f32_e32 v156, 0xbfb8aa3b, v168
	v_exp_f32_e32 v167, v156
	v_rcp_f32_e32 v47, v164
	s_nop 0
	v_mul_f32_e32 v164, v111, v47
	v_pk_mul_f32 v[28:29], v[28:29], v[164:165]
	v_lshlrev_b32_e32 v162, 16, v163
	v_pk_add_f32 v[164:165], v[166:167], 1.0 op_sel_hi:[1,0]
	v_and_b32_e32 v163, 0xffff0000, v163
	v_pk_fma_f32 v[30:31], v[132:133], v[162:163], v[30:31]
	v_pk_mul_f32 v[156:157], v[28:29], v[28:29]
	v_rcp_f32_e32 v47, v165
	s_nop 0
	v_mul_f32_e32 v165, v168, v47
	flat_load_dwordx2 v[162:163], v[142:143] offset:80
	flat_load_dwordx2 v[166:167], v[142:143] offset:96
	flat_load_dwordx2 v[168:169], v[142:143] offset:112
	v_rcp_f32_e32 v47, v164
	s_nop 0
	v_mul_f32_e32 v164, v63, v47
	v_pk_mul_f32 v[30:31], v[30:31], v[164:165]
	flat_load_dwordx2 v[172:173], v[140:141] offset:80
	flat_load_dwordx2 v[174:175], v[140:141] offset:96
	flat_load_dwordx2 v[164:165], v[140:141] offset:112
	s_waitcnt vmcnt(0) lgkmcnt(0)
; DI float bflo(unsigned u) { return __uint_as_float(u << 16); }
; DI float bfhi(unsigned u) { return __uint_as_float(u & 0xffff0000u); }
; DI float xhalf(float v) { return __shfl_xor(v, 32); }
; DI float siluf_(float x) { return x / (1.f + __expf(-x)); }
; DI void ssd_out_phase(int wv, const Params& P, LAS unsigned char* lds) {
;     ...
;         for (int lt = 0; lt < 4; ++lt) { const size_t rr = (size_t)(row0 + lt * 32 + q); float ss = 0.f;
; #pragma unroll
;             for (int pt = 0; pt < 2; ++pt)
; #pragma unroll
;                 for (int i4 = 0; i4 < 4; ++i4) { const int p0 = h * 64 + pt * 32 + 8 * i4 + 4 * hh; const u32x2 xv = *(const u32x2*)(XS + rr * 1024 + p0), zv = *(const u32x2*)(Z + rr * 1024 + p0);
;                     const float xs4[4] = {bflo(xv.x), bfhi(xv.x), bflo(xv.y), bfhi(xv.y)}, zs4[4] = {bflo(zv.x), bfhi(zv.x), bflo(zv.y), bfhi(zv.y)};
; #pragma unroll
;                     for (int e = 0; e < 4; ++e) { const float y = (acc[pt][lt][4 * i4 + e] + xs4[e] * dsk) * siluf_(zs4[e]); acc[pt][lt][4 * i4 + e] = y; ss += y * y; } }
;             ss += xhalf(ss); if (hh == 0) ssq[wave * 128 + lt * 32 + q] = ss; }
	v_lshlrev_b32_e32 v111, 16, v158
	v_and_b32_e32 v158, 0xffff0000, v158
	v_mul_f32_e32 v142, 0xbfb8aa3b, v111
	v_exp_f32_e32 v170, v142
	v_mul_f32_e32 v142, 0xbfb8aa3b, v158
	v_exp_f32_e32 v171, v142
	v_pk_mul_f32 v[142:143], v[30:31], v[30:31]
	v_pk_add_f32 v[170:171], v[170:171], 1.0 op_sel_hi:[1,0]
	s_nop 0
	v_lshlrev_b32_e32 v140, 16, v160
	v_and_b32_e32 v141, 0xffff0000, v160
	v_pk_fma_f32 v[0:1], v[132:133], v[140:141], v[0:1]
	v_rcp_f32_e32 v47, v171
	s_nop 0
	v_mul_f32_e32 v141, v158, v47
	v_and_b32_e32 v171, 0xffff0000, v159
	v_lshlrev_b32_e32 v63, 16, v159
	v_mul_f32_e32 v140, 0xbfb8aa3b, v63
	v_exp_f32_e32 v158, v140
	v_mul_f32_e32 v140, 0xbfb8aa3b, v171
	v_exp_f32_e32 v159, v140
	v_rcp_f32_e32 v47, v170
	s_nop 0
	v_mul_f32_e32 v140, v111, v47
	v_lshlrev_b32_e32 v160, 16, v161
	v_and_b32_e32 v161, 0xffff0000, v161
	v_pk_add_f32 v[158:159], v[158:159], 1.0 op_sel_hi:[1,0]
	v_pk_fma_f32 v[2:3], v[132:133], v[160:161], v[2:3]
	v_pk_mul_f32 v[0:1], v[0:1], v[140:141]
	v_rcp_f32_e32 v47, v159
	s_nop 0
	v_mul_f32_e32 v159, v171, v47
	v_pk_mul_f32 v[140:141], v[0:1], v[0:1]
	v_lshlrev_b32_e32 v111, 16, v162
	v_and_b32_e32 v162, 0xffff0000, v162
	v_mul_f32_e32 v160, 0xbfb8aa3b, v111
	v_mul_f32_e32 v161, 0xbfb8aa3b, v162
	v_exp_f32_e32 v160, v160
	v_exp_f32_e32 v161, v161
	v_rcp_f32_e32 v47, v158
	s_nop 0
	v_mul_f32_e32 v158, v63, v47
	v_lshlrev_b32_e32 v170, 16, v172
	v_and_b32_e32 v171, 0xffff0000, v172
	v_pk_add_f32 v[160:161], v[160:161], 1.0 op_sel_hi:[1,0]
	v_pk_fma_f32 v[4:5], v[132:133], v[170:171], v[4:5]
	v_pk_mul_f32 v[2:3], v[2:3], v[158:159]
	v_rcp_f32_e32 v47, v161
	s_nop 0
	v_mul_f32_e32 v161, v162, v47
	v_and_b32_e32 v171, 0xffff0000, v173
	v_lshlrev_b32_e32 v63, 16, v163
	v_and_b32_e32 v172, 0xffff0000, v163
	v_mul_f32_e32 v162, 0xbfb8aa3b, v63
	v_mul_f32_e32 v163, 0xbfb8aa3b, v172
	v_exp_f32_e32 v162, v162
	v_exp_f32_e32 v163, v163
	v_rcp_f32_e32 v47, v160
	s_nop 0
	v_mul_f32_e32 v160, v111, v47
	v_lshlrev_b32_e32 v170, 16, v173
	v_pk_fma_f32 v[6:7], v[132:133], v[170:171], v[6:7]
	v_pk_add_f32 v[162:163], v[162:163], 1.0 op_sel_hi:[1,0]
	v_pk_mul_f32 v[158:159], v[2:3], v[2:3]
	v_pk_mul_f32 v[4:5], v[4:5], v[160:161]
	v_rcp_f32_e32 v47, v163
	s_nop 0
	v_mul_f32_e32 v163, v172, v47
	v_lshlrev_b32_e32 v172, 16, v174
	v_lshlrev_b32_e32 v111, 16, v166
	v_and_b32_e32 v166, 0xffff0000, v166
	v_mul_f32_e32 v170, 0xbfb8aa3b, v111
	v_mul_f32_e32 v171, 0xbfb8aa3b, v166
	v_exp_f32_e32 v170, v170
	v_exp_f32_e32 v171, v171
	v_rcp_f32_e32 v47, v162
	s_nop 0
	v_mul_f32_e32 v162, v63, v47
	v_and_b32_e32 v173, 0xffff0000, v174
	v_pk_fma_f32 v[8:9], v[132:133], v[172:173], v[8:9]
	v_pk_add_f32 v[170:171], v[170:171], 1.0 op_sel_hi:[1,0]
	v_pk_mul_f32 v[160:161], v[4:5], v[4:5]
	v_pk_mul_f32 v[6:7], v[6:7], v[162:163]
	v_rcp_f32_e32 v47, v171
	s_nop 0
	v_mul_f32_e32 v171, v166, v47
	v_and_b32_e32 v173, 0xffff0000, v175
	v_lshlrev_b32_e32 v63, 16, v167
	v_and_b32_e32 v174, 0xffff0000, v167
	v_mul_f32_e32 v166, 0xbfb8aa3b, v63
	v_mul_f32_e32 v167, 0xbfb8aa3b, v174
	v_exp_f32_e32 v166, v166
	v_exp_f32_e32 v167, v167
	v_rcp_f32_e32 v47, v170
	s_nop 0
	v_mul_f32_e32 v170, v111, v47
	v_lshlrev_b32_e32 v172, 16, v175
	v_pk_fma_f32 v[10:11], v[132:133], v[172:173], v[10:11]
	v_pk_add_f32 v[166:167], v[166:167], 1.0 op_sel_hi:[1,0]
	v_pk_mul_f32 v[162:163], v[6:7], v[6:7]
	v_pk_mul_f32 v[8:9], v[8:9], v[170:171]
	v_rcp_f32_e32 v47, v167
	s_nop 0
	v_mul_f32_e32 v167, v174, v47
	v_lshlrev_b32_e32 v174, 16, v164
	v_lshlrev_b32_e32 v111, 16, v168
	v_and_b32_e32 v168, 0xffff0000, v168
	v_mul_f32_e32 v172, 0xbfb8aa3b, v111
	v_mul_f32_e32 v173, 0xbfb8aa3b, v168
	v_exp_f32_e32 v172, v172
	v_exp_f32_e32 v173, v173
	v_rcp_f32_e32 v47, v166
	s_nop 0
	v_mul_f32_e32 v166, v63, v47
	v_and_b32_e32 v175, 0xffff0000, v164
	v_pk_fma_f32 v[12:13], v[132:133], v[174:175], v[12:13]
	v_pk_add_f32 v[172:173], v[172:173], 1.0 op_sel_hi:[1,0]
	v_pk_mul_f32 v[170:171], v[8:9], v[8:9]
	v_pk_mul_f32 v[10:11], v[10:11], v[166:167]
	v_rcp_f32_e32 v47, v173
	s_nop 0
	v_mul_f32_e32 v173, v168, v47
	v_and_b32_e32 v174, 0xffff0000, v169
	v_lshlrev_b32_e32 v63, 16, v169
	v_mul_f32_e32 v164, 0xbfb8aa3b, v63
	v_exp_f32_e32 v168, v164
	v_mul_f32_e32 v164, 0xbfb8aa3b, v174
	v_exp_f32_e32 v169, v164
	v_rcp_f32_e32 v47, v172
	s_nop 0
	v_mul_f32_e32 v172, v111, v47
	v_lshlrev_b32_e32 v164, 16, v165
	v_and_b32_e32 v165, 0xffff0000, v165
	v_pk_add_f32 v[168:169], v[168:169], 1.0 op_sel_hi:[1,0]
	v_pk_fma_f32 v[14:15], v[132:133], v[164:165], v[14:15]
	v_pk_mul_f32 v[166:167], v[10:11], v[10:11]
	v_pk_mul_f32 v[12:13], v[12:13], v[172:173]
	v_rcp_f32_e32 v47, v169
	s_nop 0
	v_mul_f32_e32 v133, v174, v47
	v_pk_mul_f32 v[172:173], v[12:13], v[12:13]
	v_rcp_f32_e32 v47, v168
	s_nop 0
	v_mul_f32_e32 v132, v63, v47
	v_add_f32_e32 v47, v144, v145
	v_add_f32_e32 v47, v146, v47
	v_add_f32_e32 v47, v147, v47
	v_add_f32_e32 v47, v148, v47
	v_add_f32_e32 v47, v149, v47
	v_add_f32_e32 v47, v150, v47
	v_add_f32_e32 v47, v151, v47
	v_add_f32_e32 v47, v152, v47
	v_add_f32_e32 v47, v153, v47
	v_add_f32_e32 v47, v154, v47
	v_add_f32_e32 v47, v155, v47
	v_add_f32_e32 v47, v156, v47
	v_add_f32_e32 v47, v157, v47
	v_add_f32_e32 v47, v142, v47
	v_add_f32_e32 v47, v143, v47
	v_add_f32_e32 v47, v140, v47
	v_add_f32_e32 v47, v141, v47
	v_add_f32_e32 v47, v158, v47
	v_add_f32_e32 v47, v159, v47
	v_add_f32_e32 v47, v160, v47
	v_add_f32_e32 v47, v161, v47
	v_add_f32_e32 v47, v162, v47
	v_add_f32_e32 v47, v163, v47
	v_add_f32_e32 v47, v170, v47
	v_add_f32_e32 v47, v171, v47
	v_add_f32_e32 v47, v166, v47
	v_add_f32_e32 v47, v167, v47
	v_pk_mul_f32 v[14:15], v[14:15], v[132:133]
	v_add_f32_e32 v47, v172, v47
	v_pk_mul_f32 v[132:133], v[14:15], v[14:15]
	v_add_f32_e32 v47, v173, v47
	v_add_f32_e32 v47, v132, v47
	v_add_f32_e32 v47, v133, v47
	ds_bpermute_b32 v63, v229, v47
	s_and_saveexec_b64 s[14:15], s[12:13]
	s_cbranch_execz .LBB0_1668
	s_waitcnt lgkmcnt(0)
	v_add_f32_e32 v47, v47, v63
	ds_write_b32 v231, v47 offset:384
	s_branch .LBB0_1668

; #define EPI_ROWS(...) _Pragma("unroll") for (int ai = 0; ai < 2; ++ai) _Pragma("unroll") for (int m = 0; m < 4; ++m) { const int row = u.pm * 256 + ai * 128 + wr * 64 + m * 16 + fr; __VA_ARGS__ }
; DI void st16_wt(void* p, u32x4 v) { asm volatile("global_store_dwordx4 %0, %1, off sc0 sc1\n\ts_nop 1" :: "v"(p), "v"(v) : "memory"); }
; DI u32x4 pack8(f32x4 a, f32x4 b) { u32x4 w; w.x = pk2(a[0], a[1]); w.y = pk2(a[2], a[3]); w.z = pk2(b[0], b[1]); w.w = pk2(b[2], b[3]); return w; }
; DI float siluf_(float x) { return x / (1.f + __expf(-x)); }
;     DI void operator()(const Acc& acc, const Unit& u, int wr, int wc, int fr, int fq) const {
;         const int c0 = u.pn * 128 + wc * 32 + 8 * fq;
;         EPI_ROWS( f32x4 a, b;
;             _Pragma("unroll") for (int e = 0; e < 4; ++e) { a[e] = siluf_(acc[ai][0][m][0][e]) * acc[ai][1][m][0][e]; b[e] = siluf_(acc[ai][0][m][1][e]) * acc[ai][1][m][1][e]; }
;             st16_wt(H + (size_t)row * DFF + c0, pack8(a, b)); )
;     }
.LBB0_1891:
	v_mov_b32_e32 v150, v144
	v_mov_b32_e32 v151, v145
	s_lshl_b32 s15, s50, 7
	s_or_b32 s15, s15, s42
	v_lshl_add_u32 v152, v151, 3, s15
	v_mul_f32_e32 v151, 0xbfb8aa3b, v124
	v_exp_f32_e32 v154, v151
	v_mul_f32_e32 v151, 0xbfb8aa3b, v125
	v_exp_f32_e32 v155, v151
	v_mul_f32_e32 v156, 0xbfb8aa3b, v116
	v_exp_f32_e32 v156, v156
	s_lshl_b32 s15, s22, 8
	v_pk_add_f32 v[154:155], v[154:155], 1.0 op_sel_hi:[1,0]
	s_add_i32 s15, s15, s41
	v_add_u32_e32 v150, s15, v150
	v_ashrrev_i32_e32 v153, 31, v152
	v_mul_f32_e32 v157, 0xbfb8aa3b, v117
	v_rcp_f32_e32 v151, v155
	s_nop 0
	v_mul_f32_e32 v125, v125, v151
	v_exp_f32_e32 v157, v157
	s_nop 0
	v_pk_add_f32 v[156:157], v[156:157], 1.0 op_sel_hi:[1,0]
	v_rcp_f32_e32 v151, v154
	s_nop 0
	v_mul_f32_e32 v124, v124, v151
	v_pk_mul_f32 v[120:121], v[124:125], v[120:121]
	v_rcp_f32_e32 v124, v157
	s_nop 0
	v_mul_f32_e32 v117, v117, v124
	v_mul_f32_e32 v124, 0xbfb8aa3b, v126
	v_mul_f32_e32 v125, 0xbfb8aa3b, v127
	v_exp_f32_e32 v124, v124
	v_exp_f32_e32 v125, v125
	v_rcp_f32_e32 v151, v156
	s_nop 0
	v_mul_f32_e32 v116, v116, v151
	v_pk_mul_f32 v[154:155], v[116:117], v[112:113]
	v_pk_add_f32 v[124:125], v[124:125], 1.0 op_sel_hi:[1,0]
	v_mul_f32_e32 v112, 0xbfb8aa3b, v118
	v_exp_f32_e32 v112, v112
	v_rcp_f32_e32 v113, v125
	s_nop 0
	v_mul_f32_e32 v117, v127, v113
	v_mul_f32_e32 v113, 0xbfb8aa3b, v119
	v_exp_f32_e32 v113, v113
	s_nop 0
	v_pk_add_f32 v[112:113], v[112:113], 1.0 op_sel_hi:[1,0]
	v_rcp_f32_e32 v116, v124
	s_nop 0
	v_mul_f32_e32 v116, v126, v116
	v_pk_mul_f32 v[122:123], v[116:117], v[122:123]
	v_rcp_f32_e32 v116, v113
	s_nop 0
	v_mul_f32_e32 v113, v119, v116
	v_rcp_f32_e32 v116, v112
	s_nop 0
	v_mul_f32_e32 v112, v118, v116
	v_pk_mul_f32 v[124:125], v[112:113], v[114:115]
	v_mov_b64_e32 v[112:113], s[8:9]
	v_mad_i64_i32 v[116:117], s[24:25], v150, s47, v[112:113]
	v_lshlrev_b64 v[114:115], 1, v[152:153]
	v_lshl_add_u64 v[126:127], v[116:117], 0, v[114:115]
	v_mul_f32_e32 v117, 0xbfb8aa3b, v108
	v_cvt_pk_bf16_f32 v116, v120, v121
	v_exp_f32_e32 v120, v117
	v_mul_f32_e32 v117, 0xbfb8aa3b, v109
	v_exp_f32_e32 v121, v117
	v_cvt_pk_bf16_f32 v117, v122, v123
	v_cvt_pk_bf16_f32 v118, v154, v155
	v_cvt_pk_bf16_f32 v119, v124, v125
	v_pk_add_f32 v[120:121], v[120:121], 1.0 op_sel_hi:[1,0]
	global_store_dwordx4 v[126:127], v[116:119], off sc0 sc1
	s_nop 1
	v_mul_f32_e32 v116, 0xbfb8aa3b, v100
	v_exp_f32_e32 v116, v116
	v_rcp_f32_e32 v117, v121
	s_nop 0
	v_mul_f32_e32 v109, v109, v117
	v_mul_f32_e32 v117, 0xbfb8aa3b, v101
	v_exp_f32_e32 v117, v117
	s_nop 0
	v_pk_add_f32 v[116:117], v[116:117], 1.0 op_sel_hi:[1,0]
	v_rcp_f32_e32 v118, v120
	s_nop 0
	v_mul_f32_e32 v108, v108, v118
	v_pk_mul_f32 v[104:105], v[108:109], v[104:105]
	v_rcp_f32_e32 v108, v117
	s_nop 0
	v_mul_f32_e32 v101, v101, v108
	v_mul_f32_e32 v108, 0xbfb8aa3b, v110
	v_mul_f32_e32 v109, 0xbfb8aa3b, v111
	v_exp_f32_e32 v108, v108
	v_exp_f32_e32 v109, v109
	v_rcp_f32_e32 v117, v116
	s_nop 0
	v_mul_f32_e32 v100, v100, v117
	v_pk_mul_f32 v[100:101], v[100:101], v[96:97]
	v_pk_add_f32 v[108:109], v[108:109], 1.0 op_sel_hi:[1,0]
	v_mul_f32_e32 v96, 0xbfb8aa3b, v102
	v_exp_f32_e32 v96, v96
	v_rcp_f32_e32 v97, v109
	s_nop 0
	v_mul_f32_e32 v109, v111, v97
	v_mul_f32_e32 v97, 0xbfb8aa3b, v103
	v_exp_f32_e32 v97, v97
	s_nop 0
	v_pk_add_f32 v[96:97], v[96:97], 1.0 op_sel_hi:[1,0]
	v_rcp_f32_e32 v111, v108
	s_nop 0
	v_mul_f32_e32 v108, v110, v111
	v_pk_mul_f32 v[106:107], v[108:109], v[106:107]
	v_rcp_f32_e32 v108, v97
	s_nop 0
	v_mul_f32_e32 v97, v103, v108
	v_rcp_f32_e32 v103, v96
	s_nop 0
	v_mul_f32_e32 v96, v102, v103
	v_pk_mul_f32 v[102:103], v[96:97], v[98:99]
	v_add_u32_e32 v96, 16, v150
	v_mad_i64_i32 v[96:97], s[24:25], v96, s47, v[112:113]
	v_lshl_add_u64 v[108:109], v[96:97], 0, v[114:115]
	v_mul_f32_e32 v97, 0xbfb8aa3b, v92
	v_cvt_pk_bf16_f32 v96, v104, v105
	v_exp_f32_e32 v104, v97
	v_mul_f32_e32 v97, 0xbfb8aa3b, v93
	v_exp_f32_e32 v105, v97
	v_cvt_pk_bf16_f32 v98, v100, v101
	v_cvt_pk_bf16_f32 v99, v102, v103
	v_cvt_pk_bf16_f32 v97, v106, v107
	v_pk_add_f32 v[100:101], v[104:105], 1.0 op_sel_hi:[1,0]
	global_store_dwordx4 v[108:109], v[96:99], off sc0 sc1
	s_nop 1
	v_mul_f32_e32 v96, 0xbfb8aa3b, v84
	v_exp_f32_e32 v96, v96
	v_rcp_f32_e32 v97, v101
	s_nop 0
	v_mul_f32_e32 v93, v93, v97
	v_mul_f32_e32 v97, 0xbfb8aa3b, v85
	v_exp_f32_e32 v97, v97
	s_nop 0
	v_pk_add_f32 v[96:97], v[96:97], 1.0 op_sel_hi:[1,0]
	v_rcp_f32_e32 v98, v100
	s_nop 0
	v_mul_f32_e32 v92, v92, v98
	v_pk_mul_f32 v[88:89], v[92:93], v[88:89]
	v_rcp_f32_e32 v92, v97
	s_nop 0
	v_mul_f32_e32 v85, v85, v92
	v_mul_f32_e32 v92, 0xbfb8aa3b, v94
	v_mul_f32_e32 v93, 0xbfb8aa3b, v95
	v_exp_f32_e32 v92, v92
	v_exp_f32_e32 v93, v93
	v_rcp_f32_e32 v97, v96
	s_nop 0
	v_mul_f32_e32 v84, v84, v97
	v_pk_mul_f32 v[84:85], v[84:85], v[80:81]
	v_pk_add_f32 v[92:93], v[92:93], 1.0 op_sel_hi:[1,0]
	v_mul_f32_e32 v80, 0xbfb8aa3b, v86
	v_exp_f32_e32 v80, v80
	v_rcp_f32_e32 v81, v93
	s_nop 0
	v_mul_f32_e32 v93, v95, v81
	v_mul_f32_e32 v81, 0xbfb8aa3b, v87
	v_exp_f32_e32 v81, v81
	s_nop 0
	v_pk_add_f32 v[80:81], v[80:81], 1.0 op_sel_hi:[1,0]
	v_rcp_f32_e32 v95, v92
	s_nop 0
	v_mul_f32_e32 v92, v94, v95
	v_pk_mul_f32 v[90:91], v[92:93], v[90:91]
	v_rcp_f32_e32 v92, v81
	s_nop 0
	v_mul_f32_e32 v81, v87, v92
	v_rcp_f32_e32 v87, v80
	s_nop 0
	v_mul_f32_e32 v80, v86, v87
	v_pk_mul_f32 v[86:87], v[80:81], v[82:83]
	v_add_u32_e32 v80, 32, v150
	v_mad_i64_i32 v[80:81], s[24:25], v80, s47, v[112:113]
	v_lshl_add_u64 v[92:93], v[80:81], 0, v[114:115]
	v_mul_f32_e32 v81, 0xbfb8aa3b, v76
	v_cvt_pk_bf16_f32 v80, v88, v89
	v_exp_f32_e32 v88, v81
	v_mul_f32_e32 v81, 0xbfb8aa3b, v77
	v_exp_f32_e32 v89, v81
; #define EPI_ROWS(...) _Pragma("unroll") for (int ai = 0; ai < 2; ++ai) _Pragma("unroll") for (int m = 0; m < 4; ++m) { const int row = u.pm * 256 + ai * 128 + wr * 64 + m * 16 + fr; __VA_ARGS__ }
; DI void st16_wt(void* p, u32x4 v) { asm volatile("global_store_dwordx4 %0, %1, off sc0 sc1\n\ts_nop 1" :: "v"(p), "v"(v) : "memory"); }
; DI u32x4 pack8(f32x4 a, f32x4 b) { u32x4 w; w.x = pk2(a[0], a[1]); w.y = pk2(a[2], a[3]); w.z = pk2(b[0], b[1]); w.w = pk2(b[2], b[3]); return w; }
; DI float siluf_(float x) { return x / (1.f + __expf(-x)); }
;     DI void operator()(const Acc& acc, const Unit& u, int wr, int wc, int fr, int fq) const {
;         const int c0 = u.pn * 128 + wc * 32 + 8 * fq;
;         EPI_ROWS( f32x4 a, b;
;             _Pragma("unroll") for (int e = 0; e < 4; ++e) { a[e] = siluf_(acc[ai][0][m][0][e]) * acc[ai][1][m][0][e]; b[e] = siluf_(acc[ai][0][m][1][e]) * acc[ai][1][m][1][e]; }
;             st16_wt(H + (size_t)row * DFF + c0, pack8(a, b)); )
;     }
	v_cvt_pk_bf16_f32 v82, v84, v85
	v_cvt_pk_bf16_f32 v83, v86, v87
	v_cvt_pk_bf16_f32 v81, v90, v91
	v_pk_add_f32 v[84:85], v[88:89], 1.0 op_sel_hi:[1,0]
	global_store_dwordx4 v[92:93], v[80:83], off sc0 sc1
	s_nop 1
	v_mul_f32_e32 v80, 0xbfb8aa3b, v68
	v_exp_f32_e32 v80, v80
	v_rcp_f32_e32 v81, v85
	s_nop 0
	v_mul_f32_e32 v77, v77, v81
	v_mul_f32_e32 v81, 0xbfb8aa3b, v69
	v_exp_f32_e32 v81, v81
	s_nop 0
	v_pk_add_f32 v[80:81], v[80:81], 1.0 op_sel_hi:[1,0]
	v_rcp_f32_e32 v82, v84
	s_nop 0
	v_mul_f32_e32 v76, v76, v82
	v_pk_mul_f32 v[72:73], v[76:77], v[72:73]
	v_rcp_f32_e32 v76, v81
	s_nop 0
	v_mul_f32_e32 v69, v69, v76
	v_mul_f32_e32 v76, 0xbfb8aa3b, v78
	v_mul_f32_e32 v77, 0xbfb8aa3b, v79
	v_exp_f32_e32 v76, v76
	v_exp_f32_e32 v77, v77
	v_rcp_f32_e32 v81, v80
	s_nop 0
	v_mul_f32_e32 v68, v68, v81
	v_pk_mul_f32 v[68:69], v[68:69], v[64:65]
	v_pk_add_f32 v[76:77], v[76:77], 1.0 op_sel_hi:[1,0]
	v_mul_f32_e32 v64, 0xbfb8aa3b, v70
	v_exp_f32_e32 v64, v64
	v_rcp_f32_e32 v65, v77
	s_nop 0
	v_mul_f32_e32 v77, v79, v65
	v_mul_f32_e32 v65, 0xbfb8aa3b, v71
	v_exp_f32_e32 v65, v65
	s_nop 0
	v_pk_add_f32 v[64:65], v[64:65], 1.0 op_sel_hi:[1,0]
	v_rcp_f32_e32 v79, v76
	s_nop 0
	v_mul_f32_e32 v76, v78, v79
	v_pk_mul_f32 v[74:75], v[76:77], v[74:75]
	v_rcp_f32_e32 v76, v65
	s_nop 0
	v_mul_f32_e32 v65, v71, v76
	v_rcp_f32_e32 v71, v64
	s_nop 0
	v_mul_f32_e32 v64, v70, v71
	v_pk_mul_f32 v[70:71], v[64:65], v[66:67]
	v_add_u32_e32 v64, 48, v150
	v_mad_i64_i32 v[64:65], s[24:25], v64, s47, v[112:113]
	v_mul_f32_e32 v66, 0xbfb8aa3b, v60
	v_lshl_add_u64 v[76:77], v[64:65], 0, v[114:115]
	v_cvt_pk_bf16_f32 v64, v72, v73
	v_exp_f32_e32 v72, v66
	v_mul_f32_e32 v66, 0xbfb8aa3b, v61
	v_exp_f32_e32 v73, v66
	v_cvt_pk_bf16_f32 v65, v74, v75
	v_cvt_pk_bf16_f32 v66, v68, v69
	v_cvt_pk_bf16_f32 v67, v70, v71
	global_store_dwordx4 v[76:77], v[64:67], off sc0 sc1
	s_nop 1
	v_pk_add_f32 v[64:65], v[72:73], 1.0 op_sel_hi:[1,0]
	v_mul_f32_e32 v66, 0xbfb8aa3b, v52
	v_exp_f32_e32 v66, v66
	v_add_u32_e32 v69, 0x80, v150
	v_rcp_f32_e32 v67, v65
	s_nop 0
	v_mul_f32_e32 v61, v61, v67
	v_mul_f32_e32 v67, 0xbfb8aa3b, v53
	v_exp_f32_e32 v67, v67
	s_nop 0
	v_pk_add_f32 v[66:67], v[66:67], 1.0 op_sel_hi:[1,0]
	v_rcp_f32_e32 v65, v64
	s_nop 0
	v_mul_f32_e32 v60, v60, v65
	v_pk_mul_f32 v[56:57], v[60:61], v[56:57]
	v_rcp_f32_e32 v60, v67
	s_nop 0
	v_mul_f32_e32 v53, v53, v60
	v_mul_f32_e32 v60, 0xbfb8aa3b, v62
	v_mul_f32_e32 v61, 0xbfb8aa3b, v63
	v_exp_f32_e32 v60, v60
	v_exp_f32_e32 v61, v61
	v_rcp_f32_e32 v64, v66
	s_nop 0
	v_mul_f32_e32 v52, v52, v64
	v_pk_mul_f32 v[52:53], v[52:53], v[48:49]
	v_pk_add_f32 v[60:61], v[60:61], 1.0 op_sel_hi:[1,0]
	v_mul_f32_e32 v48, 0xbfb8aa3b, v54
	v_exp_f32_e32 v48, v48
	v_rcp_f32_e32 v49, v61
	s_nop 0
	v_mul_f32_e32 v61, v63, v49
	v_mul_f32_e32 v49, 0xbfb8aa3b, v55
	v_exp_f32_e32 v49, v49
	s_nop 0
	v_pk_add_f32 v[48:49], v[48:49], 1.0 op_sel_hi:[1,0]
	v_rcp_f32_e32 v63, v60
	s_nop 0
	v_mul_f32_e32 v60, v62, v63
	v_pk_mul_f32 v[58:59], v[60:61], v[58:59]
	v_rcp_f32_e32 v60, v49
	s_nop 0
	v_mul_f32_e32 v49, v55, v60
	v_rcp_f32_e32 v55, v48
	s_nop 0
	v_mul_f32_e32 v48, v54, v55
	v_pk_mul_f32 v[54:55], v[48:49], v[50:51]
	v_mad_i64_i32 v[48:49], s[24:25], v69, s47, v[112:113]
	v_lshl_add_u64 v[60:61], v[48:49], 0, v[114:115]
	v_mul_f32_e32 v49, 0xbfb8aa3b, v44
	v_cvt_pk_bf16_f32 v48, v56, v57
	v_exp_f32_e32 v56, v49
	v_mul_f32_e32 v49, 0xbfb8aa3b, v45
	v_exp_f32_e32 v57, v49
	v_cvt_pk_bf16_f32 v50, v52, v53
	v_cvt_pk_bf16_f32 v51, v54, v55
	v_cvt_pk_bf16_f32 v49, v58, v59
	v_pk_add_f32 v[52:53], v[56:57], 1.0 op_sel_hi:[1,0]
	global_store_dwordx4 v[60:61], v[48:51], off sc0 sc1
	s_nop 1
	v_mul_f32_e32 v48, 0xbfb8aa3b, v36
	v_exp_f32_e32 v48, v48
	v_rcp_f32_e32 v49, v53
	s_nop 0
	v_mul_f32_e32 v45, v45, v49
	v_mul_f32_e32 v49, 0xbfb8aa3b, v37
	v_exp_f32_e32 v49, v49
	s_nop 0
	v_pk_add_f32 v[48:49], v[48:49], 1.0 op_sel_hi:[1,0]
	v_rcp_f32_e32 v50, v52
	s_nop 0
	v_mul_f32_e32 v44, v44, v50
	v_pk_mul_f32 v[40:41], v[44:45], v[40:41]
	v_rcp_f32_e32 v44, v49
	s_nop 0
	v_mul_f32_e32 v37, v37, v44
	v_mul_f32_e32 v44, 0xbfb8aa3b, v46
	v_mul_f32_e32 v45, 0xbfb8aa3b, v47
	v_exp_f32_e32 v44, v44
	v_exp_f32_e32 v45, v45
	v_rcp_f32_e32 v49, v48
	s_nop 0
	v_mul_f32_e32 v36, v36, v49
	v_pk_mul_f32 v[36:37], v[36:37], v[32:33]
	v_pk_add_f32 v[44:45], v[44:45], 1.0 op_sel_hi:[1,0]
	v_mul_f32_e32 v32, 0xbfb8aa3b, v38
; #define PG8_BAR __builtin_amdgcn_s_barrier()
; #define EPI_ROWS(...) _Pragma("unroll") for (int ai = 0; ai < 2; ++ai) _Pragma("unroll") for (int m = 0; m < 4; ++m) { const int row = u.pm * 256 + ai * 128 + wr * 64 + m * 16 + fr; __VA_ARGS__ }
; DI void st16_wt(void* p, u32x4 v) { asm volatile("global_store_dwordx4 %0, %1, off sc0 sc1\n\ts_nop 1" :: "v"(p), "v"(v) : "memory"); }
; DI u32x4 pack8(f32x4 a, f32x4 b) { u32x4 w; w.x = pk2(a[0], a[1]); w.y = pk2(a[2], a[3]); w.z = pk2(b[0], b[1]); w.w = pk2(b[2], b[3]); return w; }
; DI float siluf_(float x) { return x / (1.f + __expf(-x)); }
; template <class Epi>
; DI void gemm_phase(int wv, LAS unsigned char* lds, const Gemm g, const StaticOrder& S, const Epi& E) {
;     ...
;         if (!has_next) break;
; #pragma unroll
;         for (int a = 0; a < 2; ++a)
; #pragma unroll
;             for (int b = 0; b < 2; ++b)
; #pragma unroll
;                 for (int m = 0; m < 4; ++m)
; #pragma unroll
;                     for (int n = 0; n < 2; ++n) acc[a][b][m][n] = (f32x4){0.f, 0.f, 0.f, 0.f};
;         cur = nxt; cA = nA; cB = nB; ++ui;
;         if (wr == 1) PG8_BAR;
;     DI void operator()(const Acc& acc, const Unit& u, int wr, int wc, int fr, int fq) const {
;         const int c0 = u.pn * 128 + wc * 32 + 8 * fq;
;         EPI_ROWS( f32x4 a, b;
;             _Pragma("unroll") for (int e = 0; e < 4; ++e) { a[e] = siluf_(acc[ai][0][m][0][e]) * acc[ai][1][m][0][e]; b[e] = siluf_(acc[ai][0][m][1][e]) * acc[ai][1][m][1][e]; }
;             st16_wt(H + (size_t)row * DFF + c0, pack8(a, b)); )
;     }
	v_exp_f32_e32 v32, v32
	v_rcp_f32_e32 v33, v45
	s_nop 0
	v_mul_f32_e32 v45, v47, v33
	v_mul_f32_e32 v33, 0xbfb8aa3b, v39
	v_exp_f32_e32 v33, v33
	s_nop 0
	v_pk_add_f32 v[32:33], v[32:33], 1.0 op_sel_hi:[1,0]
	v_rcp_f32_e32 v47, v44
	s_nop 0
	v_mul_f32_e32 v44, v46, v47
	v_pk_mul_f32 v[42:43], v[44:45], v[42:43]
	v_rcp_f32_e32 v44, v33
	s_nop 0
	v_mul_f32_e32 v33, v39, v44
	v_rcp_f32_e32 v39, v32
	s_nop 0
	v_mul_f32_e32 v32, v38, v39
	v_pk_mul_f32 v[38:39], v[32:33], v[34:35]
	v_add_u32_e32 v32, 0x90, v150
	v_mad_i64_i32 v[32:33], s[24:25], v32, s47, v[112:113]
	v_lshl_add_u64 v[44:45], v[32:33], 0, v[114:115]
	v_mul_f32_e32 v33, 0xbfb8aa3b, v28
	v_cvt_pk_bf16_f32 v32, v40, v41
	v_exp_f32_e32 v40, v33
	v_mul_f32_e32 v33, 0xbfb8aa3b, v29
	v_exp_f32_e32 v41, v33
	v_cvt_pk_bf16_f32 v34, v36, v37
	v_cvt_pk_bf16_f32 v35, v38, v39
	v_cvt_pk_bf16_f32 v33, v42, v43
	v_pk_add_f32 v[36:37], v[40:41], 1.0 op_sel_hi:[1,0]
	global_store_dwordx4 v[44:45], v[32:35], off sc0 sc1
	s_nop 1
	v_mul_f32_e32 v32, 0xbfb8aa3b, v20
	v_exp_f32_e32 v32, v32
	v_rcp_f32_e32 v33, v37
	s_nop 0
	v_mul_f32_e32 v29, v29, v33
	v_mul_f32_e32 v33, 0xbfb8aa3b, v21
	v_exp_f32_e32 v33, v33
	s_nop 0
	v_pk_add_f32 v[32:33], v[32:33], 1.0 op_sel_hi:[1,0]
	v_rcp_f32_e32 v34, v36
	s_nop 0
	v_mul_f32_e32 v28, v28, v34
	v_pk_mul_f32 v[24:25], v[28:29], v[24:25]
	v_rcp_f32_e32 v28, v33
	s_nop 0
	v_mul_f32_e32 v21, v21, v28
	v_mul_f32_e32 v28, 0xbfb8aa3b, v30
	v_mul_f32_e32 v29, 0xbfb8aa3b, v31
	v_exp_f32_e32 v28, v28
	v_exp_f32_e32 v29, v29
	v_rcp_f32_e32 v33, v32
	s_nop 0
	v_mul_f32_e32 v20, v20, v33
	v_pk_mul_f32 v[20:21], v[20:21], v[16:17]
	v_pk_add_f32 v[28:29], v[28:29], 1.0 op_sel_hi:[1,0]
	v_mul_f32_e32 v16, 0xbfb8aa3b, v22
	v_exp_f32_e32 v16, v16
	v_rcp_f32_e32 v17, v29
	s_nop 0
	v_mul_f32_e32 v29, v31, v17
	v_mul_f32_e32 v17, 0xbfb8aa3b, v23
	v_exp_f32_e32 v17, v17
	s_nop 0
	v_pk_add_f32 v[16:17], v[16:17], 1.0 op_sel_hi:[1,0]
	v_rcp_f32_e32 v31, v28
	s_nop 0
	v_mul_f32_e32 v28, v30, v31
	v_pk_mul_f32 v[26:27], v[28:29], v[26:27]
	v_rcp_f32_e32 v28, v17
	s_nop 0
	v_mul_f32_e32 v17, v23, v28
	v_rcp_f32_e32 v23, v16
	s_nop 0
	v_mul_f32_e32 v16, v22, v23
	v_pk_mul_f32 v[22:23], v[16:17], v[18:19]
	v_add_u32_e32 v16, 0xa0, v150
	v_mad_i64_i32 v[16:17], s[24:25], v16, s47, v[112:113]
	v_lshl_add_u64 v[28:29], v[16:17], 0, v[114:115]
	v_mul_f32_e32 v17, 0xbfb8aa3b, v12
	v_cvt_pk_bf16_f32 v16, v24, v25
	v_exp_f32_e32 v24, v17
	v_mul_f32_e32 v17, 0xbfb8aa3b, v13
	v_exp_f32_e32 v25, v17
	v_cvt_pk_bf16_f32 v18, v20, v21
	v_cvt_pk_bf16_f32 v19, v22, v23
	v_cvt_pk_bf16_f32 v17, v26, v27
	v_pk_add_f32 v[20:21], v[24:25], 1.0 op_sel_hi:[1,0]
	global_store_dwordx4 v[28:29], v[16:19], off sc0 sc1
	s_nop 1
	v_mul_f32_e32 v16, 0xbfb8aa3b, v4
	v_exp_f32_e32 v16, v16
	v_rcp_f32_e32 v17, v21
	s_nop 0
	v_mul_f32_e32 v13, v13, v17
	v_mul_f32_e32 v17, 0xbfb8aa3b, v5
	v_exp_f32_e32 v17, v17
	s_nop 0
	v_pk_add_f32 v[16:17], v[16:17], 1.0 op_sel_hi:[1,0]
	v_rcp_f32_e32 v18, v20
	s_nop 0
	v_mul_f32_e32 v12, v12, v18
	v_pk_mul_f32 v[8:9], v[12:13], v[8:9]
	v_rcp_f32_e32 v12, v17
	s_nop 0
	v_mul_f32_e32 v5, v5, v12
	v_mul_f32_e32 v12, 0xbfb8aa3b, v14
	v_mul_f32_e32 v13, 0xbfb8aa3b, v15
	v_exp_f32_e32 v12, v12
	v_exp_f32_e32 v13, v13
	v_rcp_f32_e32 v17, v16
	s_nop 0
	v_mul_f32_e32 v4, v4, v17
	v_pk_mul_f32 v[4:5], v[4:5], v[0:1]
	v_pk_add_f32 v[12:13], v[12:13], 1.0 op_sel_hi:[1,0]
	v_mul_f32_e32 v0, 0xbfb8aa3b, v6
	v_exp_f32_e32 v0, v0
	v_rcp_f32_e32 v1, v13
	s_nop 0
	v_mul_f32_e32 v13, v15, v1
	v_mul_f32_e32 v1, 0xbfb8aa3b, v7
	v_exp_f32_e32 v1, v1
	s_nop 0
	v_pk_add_f32 v[0:1], v[0:1], 1.0 op_sel_hi:[1,0]
	v_rcp_f32_e32 v15, v12
	s_nop 0
	v_mul_f32_e32 v12, v14, v15
	v_pk_mul_f32 v[10:11], v[12:13], v[10:11]
	v_rcp_f32_e32 v12, v1
	s_nop 0
	v_mul_f32_e32 v1, v7, v12
	v_rcp_f32_e32 v7, v0
	s_nop 0
	v_mul_f32_e32 v0, v6, v7
	v_pk_mul_f32 v[6:7], v[0:1], v[2:3]
	v_add_u32_e32 v0, 0xb0, v150
	v_mad_i64_i32 v[0:1], s[24:25], v0, s47, v[112:113]
	v_lshl_add_u64 v[12:13], v[0:1], 0, v[114:115]
	v_cvt_pk_bf16_f32 v0, v8, v9
	v_cvt_pk_bf16_f32 v1, v10, v11
	v_cvt_pk_bf16_f32 v2, v4, v5
	v_cvt_pk_bf16_f32 v3, v6, v7
	global_store_dwordx4 v[12:13], v[0:3], off sc0 sc1
	s_nop 1
	s_andn2_b64 vcc, exec, s[2:3]
	s_mov_b64 s[2:3], -1
	s_cbranch_vccnz .LBB0_1884
	s_andn2_b64 vcc, exec, s[6:7]
	s_cbranch_vccnz .LBB0_1883
	s_barrier
	s_branch .LBB0_1883

; #define EPI_ROWS(...) _Pragma("unroll") for (int ai = 0; ai < 2; ++ai) _Pragma("unroll") for (int m = 0; m < 4; ++m) { const int row = u.pm * 256 + ai * 128 + wr * 64 + m * 16 + fr; __VA_ARGS__ }
; DI void st16_wt(void* p, u32x4 v) { asm volatile("global_store_dwordx4 %0, %1, off sc0 sc1\n\ts_nop 1" :: "v"(p), "v"(v) : "memory"); }
; DI u32x4 pack8(f32x4 a, f32x4 b) { u32x4 w; w.x = pk2(a[0], a[1]); w.y = pk2(a[2], a[3]); w.z = pk2(b[0], b[1]); w.w = pk2(b[2], b[3]); return w; }
; DI float siluf_(float x) { return x / (1.f + __expf(-x)); }
;     DI void operator()(const Acc& acc, const Unit& u, int wr, int wc, int fr, int fq) const {
;         const int c0 = u.pn * 128 + wc * 32 + 8 * fq;
;         EPI_ROWS( f32x4 a, b;
;             _Pragma("unroll") for (int e = 0; e < 4; ++e) { a[e] = siluf_(acc[ai][0][m][0][e]) * acc[ai][1][m][0][e]; b[e] = siluf_(acc[ai][0][m][1][e]) * acc[ai][1][m][1][e]; }
;             st16_wt(H + (size_t)row * DFF + c0, pack8(a, b)); )
;     }
.LBB0_2384:
	v_mov_b32_e32 v150, v145
	v_mov_b32_e32 v151, v144
	s_lshl_b32 s15, s50, 7
	s_or_b32 s15, s15, s42
	v_lshl_add_u32 v152, v150, 3, s15
	v_mul_f32_e32 v150, 0xbfb8aa3b, v124
	v_exp_f32_e32 v154, v150
	v_mul_f32_e32 v150, 0xbfb8aa3b, v125
	v_exp_f32_e32 v155, v150
	s_lshl_b32 s15, s22, 8
	s_add_i32 s15, s15, s41
	v_add_u32_e32 v150, s15, v151
	v_pk_add_f32 v[154:155], v[154:155], 1.0 op_sel_hi:[1,0]
	v_mul_f32_e32 v156, 0xbfb8aa3b, v116
	v_exp_f32_e32 v156, v156
	v_ashrrev_i32_e32 v153, 31, v152
	v_mul_f32_e32 v157, 0xbfb8aa3b, v117
	v_rcp_f32_e32 v151, v155
	s_nop 0
	v_mul_f32_e32 v125, v125, v151
	v_exp_f32_e32 v157, v157
	s_nop 0
	v_pk_add_f32 v[156:157], v[156:157], 1.0 op_sel_hi:[1,0]
	v_rcp_f32_e32 v151, v154
	s_nop 0
	v_mul_f32_e32 v124, v124, v151
	v_pk_mul_f32 v[120:121], v[124:125], v[120:121]
	v_rcp_f32_e32 v124, v157
	s_nop 0
	v_mul_f32_e32 v117, v117, v124
	v_mul_f32_e32 v124, 0xbfb8aa3b, v126
	v_mul_f32_e32 v125, 0xbfb8aa3b, v127
	v_exp_f32_e32 v124, v124
	v_exp_f32_e32 v125, v125
	v_rcp_f32_e32 v151, v156
	s_nop 0
	v_mul_f32_e32 v116, v116, v151
	v_pk_mul_f32 v[154:155], v[116:117], v[112:113]
	v_pk_add_f32 v[124:125], v[124:125], 1.0 op_sel_hi:[1,0]
	v_mul_f32_e32 v112, 0xbfb8aa3b, v118
	v_exp_f32_e32 v112, v112
	v_rcp_f32_e32 v113, v125
	s_nop 0
	v_mul_f32_e32 v117, v127, v113
	v_mul_f32_e32 v113, 0xbfb8aa3b, v119
	v_exp_f32_e32 v113, v113
	s_nop 0
	v_pk_add_f32 v[112:113], v[112:113], 1.0 op_sel_hi:[1,0]
	v_rcp_f32_e32 v116, v124
	s_nop 0
	v_mul_f32_e32 v116, v126, v116
	v_pk_mul_f32 v[122:123], v[116:117], v[122:123]
	v_rcp_f32_e32 v116, v113
	s_nop 0
	v_mul_f32_e32 v113, v119, v116
	v_rcp_f32_e32 v116, v112
	s_nop 0
	v_mul_f32_e32 v112, v118, v116
	v_pk_mul_f32 v[124:125], v[112:113], v[114:115]
	v_mov_b64_e32 v[112:113], s[8:9]
	v_mad_i64_i32 v[116:117], s[24:25], v150, s47, v[112:113]
	v_lshlrev_b64 v[114:115], 1, v[152:153]
	v_lshl_add_u64 v[126:127], v[116:117], 0, v[114:115]
	v_mul_f32_e32 v117, 0xbfb8aa3b, v108
	v_cvt_pk_bf16_f32 v116, v120, v121
	v_exp_f32_e32 v120, v117
	v_mul_f32_e32 v117, 0xbfb8aa3b, v109
	v_exp_f32_e32 v121, v117
	v_cvt_pk_bf16_f32 v117, v122, v123
	v_cvt_pk_bf16_f32 v118, v154, v155
	v_cvt_pk_bf16_f32 v119, v124, v125
	v_pk_add_f32 v[120:121], v[120:121], 1.0 op_sel_hi:[1,0]
	global_store_dwordx4 v[126:127], v[116:119], off sc0 sc1
	s_nop 1
	v_mul_f32_e32 v116, 0xbfb8aa3b, v100
	v_exp_f32_e32 v116, v116
	v_rcp_f32_e32 v117, v121
	s_nop 0
	v_mul_f32_e32 v109, v109, v117
	v_mul_f32_e32 v117, 0xbfb8aa3b, v101
	v_exp_f32_e32 v117, v117
	s_nop 0
	v_pk_add_f32 v[116:117], v[116:117], 1.0 op_sel_hi:[1,0]
	v_rcp_f32_e32 v118, v120
	s_nop 0
	v_mul_f32_e32 v108, v108, v118
	v_pk_mul_f32 v[104:105], v[108:109], v[104:105]
	v_rcp_f32_e32 v108, v117
	s_nop 0
	v_mul_f32_e32 v101, v101, v108
	v_mul_f32_e32 v108, 0xbfb8aa3b, v110
	v_mul_f32_e32 v109, 0xbfb8aa3b, v111
	v_exp_f32_e32 v108, v108
	v_exp_f32_e32 v109, v109
	v_rcp_f32_e32 v117, v116
	s_nop 0
	v_mul_f32_e32 v100, v100, v117
	v_pk_mul_f32 v[100:101], v[100:101], v[96:97]
	v_pk_add_f32 v[108:109], v[108:109], 1.0 op_sel_hi:[1,0]
	v_mul_f32_e32 v96, 0xbfb8aa3b, v102
	v_exp_f32_e32 v96, v96
	v_rcp_f32_e32 v97, v109
	s_nop 0
	v_mul_f32_e32 v109, v111, v97
	v_mul_f32_e32 v97, 0xbfb8aa3b, v103
	v_exp_f32_e32 v97, v97
	s_nop 0
	v_pk_add_f32 v[96:97], v[96:97], 1.0 op_sel_hi:[1,0]
	v_rcp_f32_e32 v111, v108
	s_nop 0
	v_mul_f32_e32 v108, v110, v111
	v_pk_mul_f32 v[106:107], v[108:109], v[106:107]
	v_rcp_f32_e32 v108, v97
	s_nop 0
	v_mul_f32_e32 v97, v103, v108
	v_rcp_f32_e32 v103, v96
	s_nop 0
	v_mul_f32_e32 v96, v102, v103
	v_pk_mul_f32 v[102:103], v[96:97], v[98:99]
	v_add_u32_e32 v96, 16, v150
	v_mad_i64_i32 v[96:97], s[24:25], v96, s47, v[112:113]
	v_lshl_add_u64 v[108:109], v[96:97], 0, v[114:115]
	v_mul_f32_e32 v97, 0xbfb8aa3b, v92
	v_cvt_pk_bf16_f32 v96, v104, v105
	v_exp_f32_e32 v104, v97
	v_mul_f32_e32 v97, 0xbfb8aa3b, v93
	v_exp_f32_e32 v105, v97
	v_cvt_pk_bf16_f32 v98, v100, v101
	v_cvt_pk_bf16_f32 v99, v102, v103
	v_cvt_pk_bf16_f32 v97, v106, v107
	v_pk_add_f32 v[100:101], v[104:105], 1.0 op_sel_hi:[1,0]
	global_store_dwordx4 v[108:109], v[96:99], off sc0 sc1
	s_nop 1
	v_mul_f32_e32 v96, 0xbfb8aa3b, v84
	v_exp_f32_e32 v96, v96
	v_rcp_f32_e32 v97, v101
	s_nop 0
	v_mul_f32_e32 v93, v93, v97
	v_mul_f32_e32 v97, 0xbfb8aa3b, v85
	v_exp_f32_e32 v97, v97
	s_nop 0
	v_pk_add_f32 v[96:97], v[96:97], 1.0 op_sel_hi:[1,0]
	v_rcp_f32_e32 v98, v100
	s_nop 0
	v_mul_f32_e32 v92, v92, v98
	v_pk_mul_f32 v[88:89], v[92:93], v[88:89]
	v_rcp_f32_e32 v92, v97
	s_nop 0
	v_mul_f32_e32 v85, v85, v92
	v_mul_f32_e32 v92, 0xbfb8aa3b, v94
	v_mul_f32_e32 v93, 0xbfb8aa3b, v95
	v_exp_f32_e32 v92, v92
	v_exp_f32_e32 v93, v93
	v_rcp_f32_e32 v97, v96
	s_nop 0
	v_mul_f32_e32 v84, v84, v97
	v_pk_mul_f32 v[84:85], v[84:85], v[80:81]
	v_pk_add_f32 v[92:93], v[92:93], 1.0 op_sel_hi:[1,0]
	v_mul_f32_e32 v80, 0xbfb8aa3b, v86
	v_exp_f32_e32 v80, v80
	v_rcp_f32_e32 v81, v93
	s_nop 0
	v_mul_f32_e32 v93, v95, v81
	v_mul_f32_e32 v81, 0xbfb8aa3b, v87
	v_exp_f32_e32 v81, v81
	s_nop 0
	v_pk_add_f32 v[80:81], v[80:81], 1.0 op_sel_hi:[1,0]
	v_rcp_f32_e32 v95, v92
	s_nop 0
	v_mul_f32_e32 v92, v94, v95
	v_pk_mul_f32 v[90:91], v[92:93], v[90:91]
	v_rcp_f32_e32 v92, v81
	s_nop 0
	v_mul_f32_e32 v81, v87, v92
	v_rcp_f32_e32 v87, v80
	s_nop 0
	v_mul_f32_e32 v80, v86, v87
	v_pk_mul_f32 v[86:87], v[80:81], v[82:83]
	v_add_u32_e32 v80, 32, v150
	v_mad_i64_i32 v[80:81], s[24:25], v80, s47, v[112:113]
	v_lshl_add_u64 v[92:93], v[80:81], 0, v[114:115]
	v_mul_f32_e32 v81, 0xbfb8aa3b, v76
	v_cvt_pk_bf16_f32 v80, v88, v89
	v_exp_f32_e32 v88, v81
	v_mul_f32_e32 v81, 0xbfb8aa3b, v77
	v_exp_f32_e32 v89, v81
; #define EPI_ROWS(...) _Pragma("unroll") for (int ai = 0; ai < 2; ++ai) _Pragma("unroll") for (int m = 0; m < 4; ++m) { const int row = u.pm * 256 + ai * 128 + wr * 64 + m * 16 + fr; __VA_ARGS__ }
; DI void st16_wt(void* p, u32x4 v) { asm volatile("global_store_dwordx4 %0, %1, off sc0 sc1\n\ts_nop 1" :: "v"(p), "v"(v) : "memory"); }
; DI u32x4 pack8(f32x4 a, f32x4 b) { u32x4 w; w.x = pk2(a[0], a[1]); w.y = pk2(a[2], a[3]); w.z = pk2(b[0], b[1]); w.w = pk2(b[2], b[3]); return w; }
; DI float siluf_(float x) { return x / (1.f + __expf(-x)); }
;     DI void operator()(const Acc& acc, const Unit& u, int wr, int wc, int fr, int fq) const {
;     ...
;         EPI_ROWS( f32x4 a, b;
;             _Pragma("unroll") for (int e = 0; e < 4; ++e) { a[e] = siluf_(acc[ai][0][m][0][e]) * acc[ai][1][m][0][e]; b[e] = siluf_(acc[ai][0][m][1][e]) * acc[ai][1][m][1][e]; }
;             st16_wt(H + (size_t)row * DFF + c0, pack8(a, b)); )
	v_cvt_pk_bf16_f32 v82, v84, v85
	v_cvt_pk_bf16_f32 v83, v86, v87
	v_cvt_pk_bf16_f32 v81, v90, v91
	v_pk_add_f32 v[84:85], v[88:89], 1.0 op_sel_hi:[1,0]
	global_store_dwordx4 v[92:93], v[80:83], off sc0 sc1
	s_nop 1
	v_mul_f32_e32 v80, 0xbfb8aa3b, v68
	v_exp_f32_e32 v80, v80
	v_rcp_f32_e32 v81, v85
	s_nop 0
	v_mul_f32_e32 v77, v77, v81
	v_mul_f32_e32 v81, 0xbfb8aa3b, v69
	v_exp_f32_e32 v81, v81
	s_nop 0
	v_pk_add_f32 v[80:81], v[80:81], 1.0 op_sel_hi:[1,0]
	v_rcp_f32_e32 v82, v84
	s_nop 0
	v_mul_f32_e32 v76, v76, v82
	v_pk_mul_f32 v[72:73], v[76:77], v[72:73]
	v_rcp_f32_e32 v76, v81
	s_nop 0
	v_mul_f32_e32 v69, v69, v76
	v_mul_f32_e32 v76, 0xbfb8aa3b, v78
	v_mul_f32_e32 v77, 0xbfb8aa3b, v79
	v_exp_f32_e32 v76, v76
	v_exp_f32_e32 v77, v77
	v_rcp_f32_e32 v81, v80
	s_nop 0
	v_mul_f32_e32 v68, v68, v81
	v_pk_mul_f32 v[68:69], v[68:69], v[64:65]
	v_pk_add_f32 v[76:77], v[76:77], 1.0 op_sel_hi:[1,0]
	v_mul_f32_e32 v64, 0xbfb8aa3b, v70
	v_exp_f32_e32 v64, v64
	v_rcp_f32_e32 v65, v77
	s_nop 0
	v_mul_f32_e32 v77, v79, v65
	v_mul_f32_e32 v65, 0xbfb8aa3b, v71
	v_exp_f32_e32 v65, v65
	s_nop 0
	v_pk_add_f32 v[64:65], v[64:65], 1.0 op_sel_hi:[1,0]
	v_rcp_f32_e32 v79, v76
	s_nop 0
	v_mul_f32_e32 v76, v78, v79
	v_pk_mul_f32 v[74:75], v[76:77], v[74:75]
	v_rcp_f32_e32 v76, v65
	s_nop 0
	v_mul_f32_e32 v65, v71, v76
	v_rcp_f32_e32 v71, v64
	s_nop 0
	v_mul_f32_e32 v64, v70, v71
	v_pk_mul_f32 v[70:71], v[64:65], v[66:67]
	v_add_u32_e32 v64, 48, v150
	v_mad_i64_i32 v[64:65], s[24:25], v64, s47, v[112:113]
	v_mul_f32_e32 v66, 0xbfb8aa3b, v60
	v_lshl_add_u64 v[76:77], v[64:65], 0, v[114:115]
	v_cvt_pk_bf16_f32 v64, v72, v73
	v_exp_f32_e32 v72, v66
	v_mul_f32_e32 v66, 0xbfb8aa3b, v61
	v_exp_f32_e32 v73, v66
	v_cvt_pk_bf16_f32 v65, v74, v75
	v_cvt_pk_bf16_f32 v66, v68, v69
	v_cvt_pk_bf16_f32 v67, v70, v71
	global_store_dwordx4 v[76:77], v[64:67], off sc0 sc1
	s_nop 1
	v_pk_add_f32 v[64:65], v[72:73], 1.0 op_sel_hi:[1,0]
	v_mul_f32_e32 v66, 0xbfb8aa3b, v52
	v_exp_f32_e32 v66, v66
	v_add_u32_e32 v69, 0x80, v150
	v_rcp_f32_e32 v67, v65
	s_nop 0
	v_mul_f32_e32 v61, v61, v67
	v_mul_f32_e32 v67, 0xbfb8aa3b, v53
	v_exp_f32_e32 v67, v67
	s_nop 0
	v_pk_add_f32 v[66:67], v[66:67], 1.0 op_sel_hi:[1,0]
	v_rcp_f32_e32 v65, v64
	s_nop 0
	v_mul_f32_e32 v60, v60, v65
	v_pk_mul_f32 v[56:57], v[60:61], v[56:57]
	v_rcp_f32_e32 v60, v67
	s_nop 0
	v_mul_f32_e32 v53, v53, v60
	v_mul_f32_e32 v60, 0xbfb8aa3b, v62
	v_mul_f32_e32 v61, 0xbfb8aa3b, v63
	v_exp_f32_e32 v60, v60
	v_exp_f32_e32 v61, v61
	v_rcp_f32_e32 v64, v66
	s_nop 0
	v_mul_f32_e32 v52, v52, v64
	v_pk_mul_f32 v[52:53], v[52:53], v[48:49]
	v_pk_add_f32 v[60:61], v[60:61], 1.0 op_sel_hi:[1,0]
	v_mul_f32_e32 v48, 0xbfb8aa3b, v54
	v_exp_f32_e32 v48, v48
	v_rcp_f32_e32 v49, v61
	s_nop 0
	v_mul_f32_e32 v61, v63, v49
	v_mul_f32_e32 v49, 0xbfb8aa3b, v55
	v_exp_f32_e32 v49, v49
	s_nop 0
	v_pk_add_f32 v[48:49], v[48:49], 1.0 op_sel_hi:[1,0]
	v_rcp_f32_e32 v63, v60
	s_nop 0
	v_mul_f32_e32 v60, v62, v63
	v_pk_mul_f32 v[58:59], v[60:61], v[58:59]
	v_rcp_f32_e32 v60, v49
	s_nop 0
	v_mul_f32_e32 v49, v55, v60
	v_rcp_f32_e32 v55, v48
	s_nop 0
	v_mul_f32_e32 v48, v54, v55
	v_pk_mul_f32 v[54:55], v[48:49], v[50:51]
	v_mad_i64_i32 v[48:49], s[24:25], v69, s47, v[112:113]
	v_lshl_add_u64 v[60:61], v[48:49], 0, v[114:115]
	v_mul_f32_e32 v49, 0xbfb8aa3b, v44
	v_cvt_pk_bf16_f32 v48, v56, v57
	v_exp_f32_e32 v56, v49
	v_mul_f32_e32 v49, 0xbfb8aa3b, v45
	v_exp_f32_e32 v57, v49
	v_cvt_pk_bf16_f32 v50, v52, v53
	v_cvt_pk_bf16_f32 v51, v54, v55
	v_cvt_pk_bf16_f32 v49, v58, v59
	v_pk_add_f32 v[52:53], v[56:57], 1.0 op_sel_hi:[1,0]
	global_store_dwordx4 v[60:61], v[48:51], off sc0 sc1
	s_nop 1
	v_mul_f32_e32 v48, 0xbfb8aa3b, v36
	v_exp_f32_e32 v48, v48
	v_rcp_f32_e32 v49, v53
	s_nop 0
	v_mul_f32_e32 v45, v45, v49
	v_mul_f32_e32 v49, 0xbfb8aa3b, v37
	v_exp_f32_e32 v49, v49
	s_nop 0
	v_pk_add_f32 v[48:49], v[48:49], 1.0 op_sel_hi:[1,0]
	v_rcp_f32_e32 v50, v52
	s_nop 0
	v_mul_f32_e32 v44, v44, v50
	v_pk_mul_f32 v[40:41], v[44:45], v[40:41]
	v_rcp_f32_e32 v44, v49
	s_nop 0
	v_mul_f32_e32 v37, v37, v44
	v_mul_f32_e32 v44, 0xbfb8aa3b, v46
	v_mul_f32_e32 v45, 0xbfb8aa3b, v47
	v_exp_f32_e32 v44, v44
	v_exp_f32_e32 v45, v45
	v_rcp_f32_e32 v49, v48
	s_nop 0
	v_mul_f32_e32 v36, v36, v49
	v_pk_mul_f32 v[36:37], v[36:37], v[32:33]
	v_pk_add_f32 v[44:45], v[44:45], 1.0 op_sel_hi:[1,0]
	v_mul_f32_e32 v32, 0xbfb8aa3b, v38
; #define EPI_ROWS(...) _Pragma("unroll") for (int ai = 0; ai < 2; ++ai) _Pragma("unroll") for (int m = 0; m < 4; ++m) { const int row = u.pm * 256 + ai * 128 + wr * 64 + m * 16 + fr; __VA_ARGS__ }
; DI void st16_wt(void* p, u32x4 v) { asm volatile("global_store_dwordx4 %0, %1, off sc0 sc1\n\ts_nop 1" :: "v"(p), "v"(v) : "memory"); }
; DI u32x4 pack8(f32x4 a, f32x4 b) { u32x4 w; w.x = pk2(a[0], a[1]); w.y = pk2(a[2], a[3]); w.z = pk2(b[0], b[1]); w.w = pk2(b[2], b[3]); return w; }
; DI float siluf_(float x) { return x / (1.f + __expf(-x)); }
;     DI void operator()(const Acc& acc, const Unit& u, int wr, int wc, int fr, int fq) const {
;     ...
;         EPI_ROWS( f32x4 a, b;
;             _Pragma("unroll") for (int e = 0; e < 4; ++e) { a[e] = siluf_(acc[ai][0][m][0][e]) * acc[ai][1][m][0][e]; b[e] = siluf_(acc[ai][0][m][1][e]) * acc[ai][1][m][1][e]; }
;             st16_wt(H + (size_t)row * DFF + c0, pack8(a, b)); )
	v_exp_f32_e32 v32, v32
	v_rcp_f32_e32 v33, v45
	s_nop 0
	v_mul_f32_e32 v45, v47, v33
	v_mul_f32_e32 v33, 0xbfb8aa3b, v39
	v_exp_f32_e32 v33, v33
	s_nop 0
	v_pk_add_f32 v[32:33], v[32:33], 1.0 op_sel_hi:[1,0]
	v_rcp_f32_e32 v47, v44
	s_nop 0
	v_mul_f32_e32 v44, v46, v47
	v_pk_mul_f32 v[42:43], v[44:45], v[42:43]
	v_rcp_f32_e32 v44, v33
	s_nop 0
	v_mul_f32_e32 v33, v39, v44
	v_rcp_f32_e32 v39, v32
	s_nop 0
	v_mul_f32_e32 v32, v38, v39
	v_pk_mul_f32 v[38:39], v[32:33], v[34:35]
	v_add_u32_e32 v32, 0x90, v150
	v_mad_i64_i32 v[32:33], s[24:25], v32, s47, v[112:113]
	v_lshl_add_u64 v[44:45], v[32:33], 0, v[114:115]
	v_mul_f32_e32 v33, 0xbfb8aa3b, v28
	v_cvt_pk_bf16_f32 v32, v40, v41
	v_exp_f32_e32 v40, v33
	v_mul_f32_e32 v33, 0xbfb8aa3b, v29
	v_exp_f32_e32 v41, v33
	v_cvt_pk_bf16_f32 v34, v36, v37
	v_cvt_pk_bf16_f32 v35, v38, v39
	v_cvt_pk_bf16_f32 v33, v42, v43
	v_pk_add_f32 v[36:37], v[40:41], 1.0 op_sel_hi:[1,0]
	global_store_dwordx4 v[44:45], v[32:35], off sc0 sc1
	s_nop 1
	v_mul_f32_e32 v32, 0xbfb8aa3b, v20
	v_exp_f32_e32 v32, v32
	v_rcp_f32_e32 v33, v37
	s_nop 0
	v_mul_f32_e32 v29, v29, v33
	v_mul_f32_e32 v33, 0xbfb8aa3b, v21
	v_exp_f32_e32 v33, v33
	s_nop 0
	v_pk_add_f32 v[32:33], v[32:33], 1.0 op_sel_hi:[1,0]
	v_rcp_f32_e32 v34, v36
	s_nop 0
	v_mul_f32_e32 v28, v28, v34
	v_pk_mul_f32 v[24:25], v[28:29], v[24:25]
	v_rcp_f32_e32 v28, v33
	s_nop 0
	v_mul_f32_e32 v21, v21, v28
	v_mul_f32_e32 v28, 0xbfb8aa3b, v30
	v_mul_f32_e32 v29, 0xbfb8aa3b, v31
	v_exp_f32_e32 v28, v28
	v_exp_f32_e32 v29, v29
	v_rcp_f32_e32 v33, v32
	s_nop 0
	v_mul_f32_e32 v20, v20, v33
	v_pk_mul_f32 v[20:21], v[20:21], v[16:17]
	v_pk_add_f32 v[28:29], v[28:29], 1.0 op_sel_hi:[1,0]
	v_mul_f32_e32 v16, 0xbfb8aa3b, v22
	v_exp_f32_e32 v16, v16
	v_rcp_f32_e32 v17, v29
	s_nop 0
	v_mul_f32_e32 v29, v31, v17
	v_mul_f32_e32 v17, 0xbfb8aa3b, v23
	v_exp_f32_e32 v17, v17
	s_nop 0
	v_pk_add_f32 v[16:17], v[16:17], 1.0 op_sel_hi:[1,0]
	v_rcp_f32_e32 v31, v28
	s_nop 0
	v_mul_f32_e32 v28, v30, v31
	v_pk_mul_f32 v[26:27], v[28:29], v[26:27]
	v_rcp_f32_e32 v28, v17
	s_nop 0
	v_mul_f32_e32 v17, v23, v28
	v_rcp_f32_e32 v23, v16
	s_nop 0
	v_mul_f32_e32 v16, v22, v23
	v_pk_mul_f32 v[22:23], v[16:17], v[18:19]
	v_add_u32_e32 v16, 0xa0, v150
	v_mad_i64_i32 v[16:17], s[24:25], v16, s47, v[112:113]
	v_lshl_add_u64 v[28:29], v[16:17], 0, v[114:115]
	v_mul_f32_e32 v17, 0xbfb8aa3b, v12
	v_cvt_pk_bf16_f32 v16, v24, v25
	v_exp_f32_e32 v24, v17
	v_mul_f32_e32 v17, 0xbfb8aa3b, v13
	v_exp_f32_e32 v25, v17
	v_cvt_pk_bf16_f32 v18, v20, v21
	v_cvt_pk_bf16_f32 v19, v22, v23
	v_cvt_pk_bf16_f32 v17, v26, v27
	v_pk_add_f32 v[20:21], v[24:25], 1.0 op_sel_hi:[1,0]
	global_store_dwordx4 v[28:29], v[16:19], off sc0 sc1
	s_nop 1
	v_mul_f32_e32 v16, 0xbfb8aa3b, v4
	v_exp_f32_e32 v16, v16
	v_rcp_f32_e32 v17, v21
	s_nop 0
	v_mul_f32_e32 v13, v13, v17
	v_mul_f32_e32 v17, 0xbfb8aa3b, v5
	v_exp_f32_e32 v17, v17
	s_nop 0
	v_pk_add_f32 v[16:17], v[16:17], 1.0 op_sel_hi:[1,0]
	v_rcp_f32_e32 v18, v20
	s_nop 0
	v_mul_f32_e32 v12, v12, v18
	v_pk_mul_f32 v[8:9], v[12:13], v[8:9]
	v_rcp_f32_e32 v12, v17
	s_nop 0
	v_mul_f32_e32 v5, v5, v12
	v_mul_f32_e32 v12, 0xbfb8aa3b, v14
	v_mul_f32_e32 v13, 0xbfb8aa3b, v15
	v_exp_f32_e32 v12, v12
	v_exp_f32_e32 v13, v13
	v_rcp_f32_e32 v17, v16
	s_nop 0
	v_mul_f32_e32 v4, v4, v17
	v_pk_mul_f32 v[4:5], v[4:5], v[0:1]
	v_pk_add_f32 v[12:13], v[12:13], 1.0 op_sel_hi:[1,0]
	v_mul_f32_e32 v0, 0xbfb8aa3b, v6
	v_exp_f32_e32 v0, v0
	v_rcp_f32_e32 v1, v13
	s_nop 0
	v_mul_f32_e32 v13, v15, v1
	v_mul_f32_e32 v1, 0xbfb8aa3b, v7
	v_exp_f32_e32 v1, v1
	s_nop 0
	v_pk_add_f32 v[0:1], v[0:1], 1.0 op_sel_hi:[1,0]
	v_rcp_f32_e32 v15, v12
	s_nop 0
	v_mul_f32_e32 v12, v14, v15
	v_pk_mul_f32 v[10:11], v[12:13], v[10:11]
	v_rcp_f32_e32 v12, v1
	s_nop 0
	v_mul_f32_e32 v1, v7, v12
	v_rcp_f32_e32 v7, v0
	s_nop 0
	v_mul_f32_e32 v0, v6, v7
	v_pk_mul_f32 v[6:7], v[0:1], v[2:3]
	v_add_u32_e32 v0, 0xb0, v150
	v_mad_i64_i32 v[0:1], s[24:25], v0, s47, v[112:113]
	v_lshl_add_u64 v[12:13], v[0:1], 0, v[114:115]
	v_cvt_pk_bf16_f32 v0, v8, v9
	v_cvt_pk_bf16_f32 v1, v10, v11
	v_cvt_pk_bf16_f32 v2, v4, v5
	v_cvt_pk_bf16_f32 v3, v6, v7
	global_store_dwordx4 v[12:13], v[0:3], off sc0 sc1
	s_nop 1
	s_andn2_b64 vcc, exec, s[2:3]
	s_mov_b64 s[2:3], -1
	s_cbranch_vccnz .LBB0_2377
	s_andn2_b64 vcc, exec, s[6:7]
	s_cbranch_vccnz .LBB0_2376
	s_barrier
	s_branch .LBB0_2376

; DI float sigmoidf_(float x) { return 1.f / (1.f + __expf(-x)); }
; DI float tanh_fast(float x) { const float e = __expf(2.f * x); return 1.f - 2.f / (e + 1.f); }
; #define EPI_ROWS(...) _Pragma("unroll") for (int ai = 0; ai < 2; ++ai) _Pragma("unroll") for (int m = 0; m < 4; ++m) { const int row = u.pm * 256 + ai * 128 + wr * 64 + m * 16 + fr; __VA_ARGS__ }
; DI void st16_wt(void* p, u32x4 v) { asm volatile("global_store_dwordx4 %0, %1, off sc0 sc1\n\ts_nop 1" :: "v"(p), "v"(v) : "memory"); }
; DI u32x4 pack8(f32x4 a, f32x4 b) { u32x4 w; w.x = pk2(a[0], a[1]); w.y = pk2(a[2], a[3]); w.z = pk2(b[0], b[1]); w.w = pk2(b[2], b[3]); return w; }
; #define ws ws_fresh(P.ws)
;     DI void operator()(const Acc& acc, const Unit& u, int wr, int wc, int fr, int fq) const {
;     ...
;         if (pn < 12) { bf16_t* O = (bf16_t*)(ws + (pn < 4 ? WS_R : (pn < 8 ? WS_K : WS_V))); const int c0 = (pn & 3) * 256 + wc * 32 + 8 * fq;
;             EPI_ROWS( bf16_t* rp = O + (size_t)row * 1024 + c0;
;                 _Pragma("unroll") for (int bj = 0; bj < 2; ++bj) st16_wt(rp + bj * 128, pack8(acc[ai][bj][m][0], acc[ai][bj][m][1])); )
;         } else {
;             EPI_ROWS( _Pragma("unroll") for (int bj = 0; bj < 2; ++bj) { const int c0 = (pn - 12) * 256 + bj * 128 + wc * 32 + 8 * fq; f32x4 a = acc[ai][bj][m][0], b = acc[ai][bj][m][1];
;                     if (c0 < 64) { _Pragma("unroll") for (int e = 0; e < 4; ++e) { a[e] = tanh_fast(a[e]); b[e] = tanh_fast(b[e]); } }
;                     else if (c0 >= 128) { _Pragma("unroll") for (int e = 0; e < 4; ++e) { a[e] = sigmoidf_(a[e]); b[e] = sigmoidf_(b[e]); } }
;                     *(u32x4*)(LH + (size_t)row * 512 + c0) = pack8(a, b); } )
.LBB0_2874:
	v_mov_b32_e32 v164, v158
	v_mov_b32_e32 v165, v159
	s_cmp_lt_i32 s20, 12
	s_mov_b64 s[4:5], -1
	s_cbranch_scc1 .LBB0_2973
	s_lshl_b32 s4, s20, 8
	s_add_i32 s4, s54, s4
	v_lshl_add_u32 v152, v165, 3, s4
	v_cmp_lt_i32_e64 s[4:5], 63, v152
	s_and_saveexec_b64 s[6:7], s[4:5]
	s_xor_b64 s[6:7], exec, s[6:7]
	s_cbranch_execz .LBB0_2879
	v_mov_b64_e32 v[134:135], v[122:123]
	v_mov_b64_e32 v[130:131], v[126:127]
	v_cmp_lt_u32_e32 vcc, s61, v152
	v_mov_b64_e32 v[132:133], v[120:121]
	v_mov_b64_e32 v[128:129], v[124:125]
	s_and_saveexec_b64 s[34:35], vcc
	s_cbranch_execz .LBB0_2878
	v_mul_f32_e32 v130, 0xbfb8aa3b, v126
	v_mul_f32_e32 v131, 0xbfb8aa3b, v127
	v_exp_f32_e32 v130, v130
	v_exp_f32_e32 v131, v131
	v_mul_f32_e32 v129, 0xbfb8aa3b, v120
	v_mul_f32_e32 v128, 0xbfb8aa3b, v124
	v_exp_f32_e32 v132, v129
	v_pk_add_f32 v[130:131], v[130:131], 1.0 op_sel_hi:[1,0]
	v_mul_f32_e32 v129, 0xbfb8aa3b, v125
	v_exp_f32_e32 v128, v128
	v_exp_f32_e32 v129, v129
	v_mul_f32_e32 v134, 0xbfb8aa3b, v122
	v_rcp_f32_e32 v131, v131
	v_pk_add_f32 v[128:129], v[128:129], 1.0 op_sel_hi:[1,0]
	v_rcp_f32_e32 v130, v130
	v_exp_f32_e32 v134, v134
	v_rcp_f32_e32 v129, v129
	v_mul_f32_e32 v135, 0xbfb8aa3b, v123
	v_exp_f32_e32 v135, v135
	s_nop 0
	v_pk_add_f32 v[134:135], v[134:135], 1.0 op_sel_hi:[1,0]
	v_rcp_f32_e32 v128, v128
	v_mul_f32_e32 v133, 0xbfb8aa3b, v121
	v_exp_f32_e32 v133, v133
	v_rcp_f32_e32 v135, v135
	v_pk_add_f32 v[132:133], v[132:133], 1.0 op_sel_hi:[1,0]
	v_rcp_f32_e32 v134, v134
	v_rcp_f32_e32 v133, v133
	v_rcp_f32_e32 v132, v132

; #define EPI_ROWS(...) _Pragma("unroll") for (int ai = 0; ai < 2; ++ai) _Pragma("unroll") for (int m = 0; m < 4; ++m) { const int row = u.pm * 256 + ai * 128 + wr * 64 + m * 16 + fr; __VA_ARGS__ }
; DI u32x4 pack8(f32x4 a, f32x4 b) { u32x4 w; w.x = pk2(a[0], a[1]); w.y = pk2(a[2], a[3]); w.z = pk2(b[0], b[1]); w.w = pk2(b[2], b[3]); return w; }
; DI float sigmoidf_(float x) { return 1.f / (1.f + __expf(-x)); }
; DI float siluf_(float x) { return x / (1.f + __expf(-x)); }
; DI float softplusf_(float x) { return fmaxf(x, 0.f) + log1pf(expf(-fabsf(x))); }
; DI float softplus_fast(float x) { return fmaxf(x, 0.f) + __logf(1.f + __expf(-fabsf(x))); }
; DI float tanh_fast(float x) { const float e = __expf(2.f * x); return 1.f - 2.f / (e + 1.f); }
;     DI void operator()(const Acc& acc, const Unit& u, int wr, int wc, int fr, int fq) const {
;     ...
;             EPI_ROWS( _Pragma("unroll") for (int bj = 0; bj < 2; ++bj) { const int c0 = (pn - 12) * 256 + bj * 128 + wc * 32 + 8 * fq; f32x4 a = acc[ai][bj][m][0], b = acc[ai][bj][m][1];
;                     if (c0 < 64) { _Pragma("unroll") for (int e = 0; e < 4; ++e) { a[e] = tanh_fast(a[e]); b[e] = tanh_fast(b[e]); } }
;                     else if (c0 >= 128) { _Pragma("unroll") for (int e = 0; e < 4; ++e) { a[e] = sigmoidf_(a[e]); b[e] = sigmoidf_(b[e]); } }
;                     *(u32x4*)(LH + (size_t)row * 512 + c0) = pack8(a, b); } )
.LBB0_2879:
	s_andn2_saveexec_b64 s[6:7], s[6:7]
	s_cbranch_execz .LBB0_2881
	v_add_f32_e32 v129, v120, v120
	v_mul_f32_e32 v129, 0x3fb8aa3b, v129
	v_add_f32_e32 v128, v124, v124
	v_exp_f32_e32 v132, v129
	v_add_f32_e32 v129, v125, v125
	v_mul_f32_e32 v128, 0x3fb8aa3b, v128
	v_mul_f32_e32 v129, 0x3fb8aa3b, v129
	v_exp_f32_e32 v128, v128
	v_exp_f32_e32 v129, v129
	v_add_f32_e32 v130, v121, v121
	v_mul_f32_e32 v130, 0x3fb8aa3b, v130
	v_exp_f32_e32 v133, v130
	v_pk_add_f32 v[128:129], v[128:129], 1.0 op_sel_hi:[1,0]
	v_add_f32_e32 v130, v126, v126
	v_add_f32_e32 v131, v127, v127
	v_mul_f32_e32 v130, 0x3fb8aa3b, v130
	v_mul_f32_e32 v131, 0x3fb8aa3b, v131
	v_exp_f32_e32 v130, v130
	v_exp_f32_e32 v131, v131
	v_rcp_f32_e32 v135, v128
	s_nop 0
	v_mul_f32_e32 v128, 2.0, v135
	v_pk_add_f32 v[130:131], v[130:131], 1.0 op_sel_hi:[1,0]
	v_rcp_f32_e32 v135, v129
	s_nop 0
	v_mul_f32_e32 v129, 2.0, v135
	v_pk_add_f32 v[132:133], v[132:133], 1.0 op_sel_hi:[1,0]
	v_rcp_f32_e32 v135, v130
	s_nop 0
	v_mul_f32_e32 v130, 2.0, v135
	v_add_f32_e32 v134, v122, v122
	v_rcp_f32_e32 v135, v131
	s_nop 0
	v_mul_f32_e32 v131, 2.0, v135
	v_add_f32_e32 v135, v123, v123
	v_mul_f32_e32 v134, 0x3fb8aa3b, v134
	v_mul_f32_e32 v135, 0x3fb8aa3b, v135
	v_exp_f32_e32 v134, v134
	v_exp_f32_e32 v135, v135
	v_rcp_f32_e32 v153, v132
	s_nop 0
	v_mul_f32_e32 v132, 2.0, v153
	v_pk_add_f32 v[134:135], v[134:135], 1.0 op_sel_hi:[1,0]
	v_rcp_f32_e32 v153, v133
	s_nop 0
	v_mul_f32_e32 v133, 2.0, v153
	v_sub_f32_e32 v131, 1.0, v131
	v_rcp_f32_e32 v153, v134
	s_nop 0
	v_mul_f32_e32 v134, 2.0, v153
	v_sub_f32_e32 v130, 1.0, v130
	v_rcp_f32_e32 v153, v135
	s_nop 0
	v_mul_f32_e32 v135, 2.0, v153
	v_sub_f32_e32 v129, 1.0, v129
	v_sub_f32_e32 v128, 1.0, v128
	v_sub_f32_e32 v135, 1.0, v135
	v_sub_f32_e32 v134, 1.0, v134
	v_sub_f32_e32 v133, 1.0, v133
	v_sub_f32_e32 v132, 1.0, v132
.LBB0_2881:
	s_or_b64 exec, exec, s[6:7]
	s_lshl_b32 s6, s18, 8
	s_add_i32 s6, s6, s46
	v_add_u32_e32 v154, s6, v164
	v_ashrrev_i32_e32 v155, 31, v154
	v_lshlrev_b64 v[156:157], 10, v[154:155]
	v_lshl_add_u64 v[156:157], s[12:13], 0, v[156:157]
	v_ashrrev_i32_e32 v153, 31, v152
	v_cvt_pk_bf16_f32 v128, v128, v129
	v_cvt_pk_bf16_f32 v129, v130, v131
	v_cvt_pk_bf16_f32 v130, v132, v133
	v_cvt_pk_bf16_f32 v131, v134, v135
	v_lshl_add_u64 v[156:157], v[152:153], 1, v[156:157]
	flat_store_dwordx4 v[156:157], v[128:131]
	s_nop 1
	v_add_u32_e32 v128, 0x80, v152
	v_cmp_lt_i32_e64 s[6:7], 63, v128
	s_and_saveexec_b64 s[34:35], s[6:7]
	s_xor_b64 s[34:35], exec, s[34:35]
	s_cbranch_execz .LBB0_2885
	v_mov_b64_e32 v[134:135], v[106:107]
	v_mov_b64_e32 v[130:131], v[110:111]
	v_cmp_gt_u32_e32 vcc, s66, v152
	v_mov_b64_e32 v[132:133], v[104:105]
	v_mov_b64_e32 v[128:129], v[108:109]
	s_and_saveexec_b64 s[36:37], vcc
	s_cbranch_execz .LBB0_2884
	v_mul_f32_e32 v130, 0xbfb8aa3b, v110
	v_mul_f32_e32 v131, 0xbfb8aa3b, v111
	v_exp_f32_e32 v130, v130
	v_exp_f32_e32 v131, v131
	v_mul_f32_e32 v129, 0xbfb8aa3b, v104
	v_mul_f32_e32 v128, 0xbfb8aa3b, v108
	v_exp_f32_e32 v132, v129
	v_pk_add_f32 v[130:131], v[130:131], 1.0 op_sel_hi:[1,0]
	v_mul_f32_e32 v129, 0xbfb8aa3b, v109
	v_exp_f32_e32 v128, v128
	v_exp_f32_e32 v129, v129
	v_mul_f32_e32 v134, 0xbfb8aa3b, v106
	v_rcp_f32_e32 v131, v131
	v_pk_add_f32 v[128:129], v[128:129], 1.0 op_sel_hi:[1,0]
	v_rcp_f32_e32 v130, v130
	v_exp_f32_e32 v134, v134
	v_rcp_f32_e32 v129, v129
	v_mul_f32_e32 v135, 0xbfb8aa3b, v107
	v_exp_f32_e32 v135, v135
	s_nop 0
	v_pk_add_f32 v[134:135], v[134:135], 1.0 op_sel_hi:[1,0]
	v_rcp_f32_e32 v128, v128
	v_mul_f32_e32 v133, 0xbfb8aa3b, v105
	v_exp_f32_e32 v133, v133
	v_rcp_f32_e32 v135, v135
	v_pk_add_f32 v[132:133], v[132:133], 1.0 op_sel_hi:[1,0]
	v_rcp_f32_e32 v134, v134
	v_rcp_f32_e32 v133, v133
	v_rcp_f32_e32 v132, v132

; #define EPI_ROWS(...) _Pragma("unroll") for (int ai = 0; ai < 2; ++ai) _Pragma("unroll") for (int m = 0; m < 4; ++m) { const int row = u.pm * 256 + ai * 128 + wr * 64 + m * 16 + fr; __VA_ARGS__ }
; DI u32x4 pack8(f32x4 a, f32x4 b) { u32x4 w; w.x = pk2(a[0], a[1]); w.y = pk2(a[2], a[3]); w.z = pk2(b[0], b[1]); w.w = pk2(b[2], b[3]); return w; }
; DI float sigmoidf_(float x) { return 1.f / (1.f + __expf(-x)); }
; DI float siluf_(float x) { return x / (1.f + __expf(-x)); }
; DI float softplusf_(float x) { return fmaxf(x, 0.f) + log1pf(expf(-fabsf(x))); }
; DI float softplus_fast(float x) { return fmaxf(x, 0.f) + __logf(1.f + __expf(-fabsf(x))); }
; DI float tanh_fast(float x) { const float e = __expf(2.f * x); return 1.f - 2.f / (e + 1.f); }
;     DI void operator()(const Acc& acc, const Unit& u, int wr, int wc, int fr, int fq) const {
;     ...
;             EPI_ROWS( _Pragma("unroll") for (int bj = 0; bj < 2; ++bj) { const int c0 = (pn - 12) * 256 + bj * 128 + wc * 32 + 8 * fq; f32x4 a = acc[ai][bj][m][0], b = acc[ai][bj][m][1];
;                     if (c0 < 64) { _Pragma("unroll") for (int e = 0; e < 4; ++e) { a[e] = tanh_fast(a[e]); b[e] = tanh_fast(b[e]); } }
;                     else if (c0 >= 128) { _Pragma("unroll") for (int e = 0; e < 4; ++e) { a[e] = sigmoidf_(a[e]); b[e] = sigmoidf_(b[e]); } }
;                     *(u32x4*)(LH + (size_t)row * 512 + c0) = pack8(a, b); } )
.LBB0_2885:
	s_andn2_saveexec_b64 s[34:35], s[34:35]
	s_cbranch_execz .LBB0_2887
	v_add_f32_e32 v129, v104, v104
	v_mul_f32_e32 v129, 0x3fb8aa3b, v129
	v_add_f32_e32 v128, v108, v108
	v_exp_f32_e32 v132, v129
	v_add_f32_e32 v129, v109, v109
	v_mul_f32_e32 v128, 0x3fb8aa3b, v128
	v_mul_f32_e32 v129, 0x3fb8aa3b, v129
	v_exp_f32_e32 v128, v128
	v_exp_f32_e32 v129, v129
	v_add_f32_e32 v130, v105, v105
	v_mul_f32_e32 v130, 0x3fb8aa3b, v130
	v_exp_f32_e32 v133, v130
	v_pk_add_f32 v[128:129], v[128:129], 1.0 op_sel_hi:[1,0]
	v_add_f32_e32 v130, v110, v110
	v_add_f32_e32 v131, v111, v111
	v_mul_f32_e32 v130, 0x3fb8aa3b, v130
	v_mul_f32_e32 v131, 0x3fb8aa3b, v131
	v_exp_f32_e32 v130, v130
	v_exp_f32_e32 v131, v131
	v_rcp_f32_e32 v135, v128
	s_nop 0
	v_mul_f32_e32 v128, 2.0, v135
	v_pk_add_f32 v[130:131], v[130:131], 1.0 op_sel_hi:[1,0]
	v_rcp_f32_e32 v135, v129
	s_nop 0
	v_mul_f32_e32 v129, 2.0, v135
	v_pk_add_f32 v[132:133], v[132:133], 1.0 op_sel_hi:[1,0]
	v_rcp_f32_e32 v135, v130
	s_nop 0
	v_mul_f32_e32 v130, 2.0, v135
	v_add_f32_e32 v134, v106, v106
	v_rcp_f32_e32 v135, v131
	s_nop 0
	v_mul_f32_e32 v131, 2.0, v135
	v_add_f32_e32 v135, v107, v107
	v_mul_f32_e32 v134, 0x3fb8aa3b, v134
	v_mul_f32_e32 v135, 0x3fb8aa3b, v135
	v_exp_f32_e32 v134, v134
	v_exp_f32_e32 v135, v135
	v_rcp_f32_e32 v155, v132
	s_nop 0
	v_mul_f32_e32 v132, 2.0, v155
	v_pk_add_f32 v[134:135], v[134:135], 1.0 op_sel_hi:[1,0]
	v_rcp_f32_e32 v155, v133
	s_nop 0
	v_mul_f32_e32 v133, 2.0, v155
	v_sub_f32_e32 v131, 1.0, v131
	v_rcp_f32_e32 v155, v134
	s_nop 0
	v_mul_f32_e32 v134, 2.0, v155
	v_sub_f32_e32 v130, 1.0, v130
	v_rcp_f32_e32 v155, v135
	s_nop 0
	v_mul_f32_e32 v135, 2.0, v155
	v_sub_f32_e32 v129, 1.0, v129
	v_sub_f32_e32 v128, 1.0, v128
	v_sub_f32_e32 v135, 1.0, v135
	v_sub_f32_e32 v134, 1.0, v134
	v_sub_f32_e32 v133, 1.0, v133
	v_sub_f32_e32 v132, 1.0, v132
.LBB0_2887:
	s_or_b64 exec, exec, s[34:35]
	v_cvt_pk_bf16_f32 v128, v128, v129
	v_cvt_pk_bf16_f32 v129, v130, v131
	v_cvt_pk_bf16_f32 v130, v132, v133
	v_cvt_pk_bf16_f32 v131, v134, v135
	flat_store_dwordx4 v[156:157], v[128:131] offset:256
	s_and_saveexec_b64 s[34:35], s[4:5]
	s_xor_b64 s[34:35], exec, s[34:35]
	s_cbranch_execz .LBB0_2891
	v_mov_b64_e32 v[134:135], v[114:115]
	v_mov_b64_e32 v[130:131], v[118:119]
	v_cmp_lt_u32_e32 vcc, s61, v152
	v_mov_b64_e32 v[132:133], v[112:113]
	v_mov_b64_e32 v[128:129], v[116:117]
	s_and_saveexec_b64 s[36:37], vcc
	s_cbranch_execz .LBB0_2890
	v_mul_f32_e32 v130, 0xbfb8aa3b, v118
	v_mul_f32_e32 v131, 0xbfb8aa3b, v119
	v_exp_f32_e32 v130, v130
	v_exp_f32_e32 v131, v131
	v_mul_f32_e32 v129, 0xbfb8aa3b, v112
	v_mul_f32_e32 v128, 0xbfb8aa3b, v116
	v_exp_f32_e32 v132, v129
	v_pk_add_f32 v[130:131], v[130:131], 1.0 op_sel_hi:[1,0]
	v_mul_f32_e32 v129, 0xbfb8aa3b, v117
	v_exp_f32_e32 v128, v128
	v_exp_f32_e32 v129, v129
	v_mul_f32_e32 v134, 0xbfb8aa3b, v114
	v_rcp_f32_e32 v131, v131
	v_pk_add_f32 v[128:129], v[128:129], 1.0 op_sel_hi:[1,0]
	v_rcp_f32_e32 v130, v130
	v_exp_f32_e32 v134, v134
	v_rcp_f32_e32 v129, v129
	v_mul_f32_e32 v135, 0xbfb8aa3b, v115
	v_exp_f32_e32 v135, v135
	s_nop 0
	v_pk_add_f32 v[134:135], v[134:135], 1.0 op_sel_hi:[1,0]
	v_rcp_f32_e32 v128, v128
	v_mul_f32_e32 v133, 0xbfb8aa3b, v113
	v_exp_f32_e32 v133, v133
	v_rcp_f32_e32 v135, v135
	v_pk_add_f32 v[132:133], v[132:133], 1.0 op_sel_hi:[1,0]
	v_rcp_f32_e32 v134, v134
	v_rcp_f32_e32 v133, v133
	v_rcp_f32_e32 v132, v132

; #define EPI_ROWS(...) _Pragma("unroll") for (int ai = 0; ai < 2; ++ai) _Pragma("unroll") for (int m = 0; m < 4; ++m) { const int row = u.pm * 256 + ai * 128 + wr * 64 + m * 16 + fr; __VA_ARGS__ }
; DI u32x4 pack8(f32x4 a, f32x4 b) { u32x4 w; w.x = pk2(a[0], a[1]); w.y = pk2(a[2], a[3]); w.z = pk2(b[0], b[1]); w.w = pk2(b[2], b[3]); return w; }
; DI float sigmoidf_(float x) { return 1.f / (1.f + __expf(-x)); }
; DI float siluf_(float x) { return x / (1.f + __expf(-x)); }
; DI float softplusf_(float x) { return fmaxf(x, 0.f) + log1pf(expf(-fabsf(x))); }
; DI float softplus_fast(float x) { return fmaxf(x, 0.f) + __logf(1.f + __expf(-fabsf(x))); }
; DI float tanh_fast(float x) { const float e = __expf(2.f * x); return 1.f - 2.f / (e + 1.f); }
;     DI void operator()(const Acc& acc, const Unit& u, int wr, int wc, int fr, int fq) const {
;     ...
;             EPI_ROWS( _Pragma("unroll") for (int bj = 0; bj < 2; ++bj) { const int c0 = (pn - 12) * 256 + bj * 128 + wc * 32 + 8 * fq; f32x4 a = acc[ai][bj][m][0], b = acc[ai][bj][m][1];
;                     if (c0 < 64) { _Pragma("unroll") for (int e = 0; e < 4; ++e) { a[e] = tanh_fast(a[e]); b[e] = tanh_fast(b[e]); } }
;                     else if (c0 >= 128) { _Pragma("unroll") for (int e = 0; e < 4; ++e) { a[e] = sigmoidf_(a[e]); b[e] = sigmoidf_(b[e]); } }
;                     *(u32x4*)(LH + (size_t)row * 512 + c0) = pack8(a, b); } )
.LBB0_2891:
	s_andn2_saveexec_b64 s[34:35], s[34:35]
	s_cbranch_execz .LBB0_2893
	v_add_f32_e32 v129, v112, v112
	v_mul_f32_e32 v129, 0x3fb8aa3b, v129
	v_add_f32_e32 v128, v116, v116
	v_exp_f32_e32 v132, v129
	v_add_f32_e32 v129, v117, v117
	v_mul_f32_e32 v128, 0x3fb8aa3b, v128
	v_mul_f32_e32 v129, 0x3fb8aa3b, v129
	v_exp_f32_e32 v128, v128
	v_exp_f32_e32 v129, v129
	v_add_f32_e32 v130, v113, v113
	v_mul_f32_e32 v130, 0x3fb8aa3b, v130
	v_exp_f32_e32 v133, v130
	v_pk_add_f32 v[128:129], v[128:129], 1.0 op_sel_hi:[1,0]
	v_add_f32_e32 v130, v118, v118
	v_add_f32_e32 v131, v119, v119
	v_mul_f32_e32 v130, 0x3fb8aa3b, v130
	v_mul_f32_e32 v131, 0x3fb8aa3b, v131
	v_exp_f32_e32 v130, v130
	v_exp_f32_e32 v131, v131
	v_rcp_f32_e32 v135, v128
	s_nop 0
	v_mul_f32_e32 v128, 2.0, v135
	v_pk_add_f32 v[130:131], v[130:131], 1.0 op_sel_hi:[1,0]
	v_rcp_f32_e32 v135, v129
	s_nop 0
	v_mul_f32_e32 v129, 2.0, v135
	v_pk_add_f32 v[132:133], v[132:133], 1.0 op_sel_hi:[1,0]
	v_rcp_f32_e32 v135, v130
	s_nop 0
	v_mul_f32_e32 v130, 2.0, v135
	v_add_f32_e32 v134, v114, v114
	v_rcp_f32_e32 v135, v131
	s_nop 0
	v_mul_f32_e32 v131, 2.0, v135
	v_add_f32_e32 v135, v115, v115
	v_mul_f32_e32 v134, 0x3fb8aa3b, v134
	v_mul_f32_e32 v135, 0x3fb8aa3b, v135
	v_exp_f32_e32 v134, v134
	v_exp_f32_e32 v135, v135
	v_rcp_f32_e32 v155, v132
	s_nop 0
	v_mul_f32_e32 v132, 2.0, v155
	v_pk_add_f32 v[134:135], v[134:135], 1.0 op_sel_hi:[1,0]
	v_rcp_f32_e32 v155, v133
	s_nop 0
	v_mul_f32_e32 v133, 2.0, v155
	v_sub_f32_e32 v131, 1.0, v131
	v_rcp_f32_e32 v155, v134
	s_nop 0
	v_mul_f32_e32 v134, 2.0, v155
	v_sub_f32_e32 v130, 1.0, v130
	v_rcp_f32_e32 v155, v135
	s_nop 0
	v_mul_f32_e32 v135, 2.0, v155
	v_sub_f32_e32 v129, 1.0, v129
	v_sub_f32_e32 v128, 1.0, v128
	v_sub_f32_e32 v135, 1.0, v135
	v_sub_f32_e32 v134, 1.0, v134
	v_sub_f32_e32 v133, 1.0, v133
	v_sub_f32_e32 v132, 1.0, v132
.LBB0_2893:
	s_or_b64 exec, exec, s[34:35]
	v_add_u32_e32 v156, 16, v154
	v_ashrrev_i32_e32 v157, 31, v156
	v_lshlrev_b64 v[156:157], 10, v[156:157]
	v_lshl_add_u64 v[156:157], s[12:13], 0, v[156:157]
	v_cvt_pk_bf16_f32 v128, v128, v129
	v_cvt_pk_bf16_f32 v129, v130, v131
	v_cvt_pk_bf16_f32 v130, v132, v133
	v_cvt_pk_bf16_f32 v131, v134, v135
	v_lshl_add_u64 v[156:157], v[152:153], 1, v[156:157]
	flat_store_dwordx4 v[156:157], v[128:131]
	s_and_saveexec_b64 s[34:35], s[6:7]
	s_xor_b64 s[34:35], exec, s[34:35]
	s_cbranch_execz .LBB0_2897
	v_mov_b64_e32 v[134:135], v[90:91]
	v_mov_b64_e32 v[130:131], v[94:95]
	v_cmp_gt_u32_e32 vcc, s66, v152
	v_mov_b64_e32 v[132:133], v[88:89]
	v_mov_b64_e32 v[128:129], v[92:93]
	s_and_saveexec_b64 s[36:37], vcc
	s_cbranch_execz .LBB0_2896
	v_mul_f32_e32 v130, 0xbfb8aa3b, v94
	v_mul_f32_e32 v131, 0xbfb8aa3b, v95
	v_exp_f32_e32 v130, v130
	v_exp_f32_e32 v131, v131
	v_mul_f32_e32 v129, 0xbfb8aa3b, v88
	v_mul_f32_e32 v128, 0xbfb8aa3b, v92
	v_exp_f32_e32 v132, v129
	v_pk_add_f32 v[130:131], v[130:131], 1.0 op_sel_hi:[1,0]
	v_mul_f32_e32 v129, 0xbfb8aa3b, v93
	v_exp_f32_e32 v128, v128
	v_exp_f32_e32 v129, v129
	v_mul_f32_e32 v134, 0xbfb8aa3b, v90
	v_rcp_f32_e32 v131, v131
	v_pk_add_f32 v[128:129], v[128:129], 1.0 op_sel_hi:[1,0]
	v_rcp_f32_e32 v130, v130
	v_exp_f32_e32 v134, v134
	v_rcp_f32_e32 v129, v129
	v_mul_f32_e32 v135, 0xbfb8aa3b, v91
	v_exp_f32_e32 v135, v135
	s_nop 0
	v_pk_add_f32 v[134:135], v[134:135], 1.0 op_sel_hi:[1,0]
	v_rcp_f32_e32 v128, v128
	v_mul_f32_e32 v133, 0xbfb8aa3b, v89
	v_exp_f32_e32 v133, v133
	v_rcp_f32_e32 v135, v135
	v_pk_add_f32 v[132:133], v[132:133], 1.0 op_sel_hi:[1,0]
	v_rcp_f32_e32 v134, v134
	v_rcp_f32_e32 v133, v133
	v_rcp_f32_e32 v132, v132

; #define EPI_ROWS(...) _Pragma("unroll") for (int ai = 0; ai < 2; ++ai) _Pragma("unroll") for (int m = 0; m < 4; ++m) { const int row = u.pm * 256 + ai * 128 + wr * 64 + m * 16 + fr; __VA_ARGS__ }
; DI u32x4 pack8(f32x4 a, f32x4 b) { u32x4 w; w.x = pk2(a[0], a[1]); w.y = pk2(a[2], a[3]); w.z = pk2(b[0], b[1]); w.w = pk2(b[2], b[3]); return w; }
; DI float sigmoidf_(float x) { return 1.f / (1.f + __expf(-x)); }
; DI float siluf_(float x) { return x / (1.f + __expf(-x)); }
; DI float softplusf_(float x) { return fmaxf(x, 0.f) + log1pf(expf(-fabsf(x))); }
; DI float softplus_fast(float x) { return fmaxf(x, 0.f) + __logf(1.f + __expf(-fabsf(x))); }
; DI float tanh_fast(float x) { const float e = __expf(2.f * x); return 1.f - 2.f / (e + 1.f); }
;     DI void operator()(const Acc& acc, const Unit& u, int wr, int wc, int fr, int fq) const {
;     ...
;             EPI_ROWS( _Pragma("unroll") for (int bj = 0; bj < 2; ++bj) { const int c0 = (pn - 12) * 256 + bj * 128 + wc * 32 + 8 * fq; f32x4 a = acc[ai][bj][m][0], b = acc[ai][bj][m][1];
;                     if (c0 < 64) { _Pragma("unroll") for (int e = 0; e < 4; ++e) { a[e] = tanh_fast(a[e]); b[e] = tanh_fast(b[e]); } }
;                     else if (c0 >= 128) { _Pragma("unroll") for (int e = 0; e < 4; ++e) { a[e] = sigmoidf_(a[e]); b[e] = sigmoidf_(b[e]); } }
;                     *(u32x4*)(LH + (size_t)row * 512 + c0) = pack8(a, b); } )
.LBB0_2897:
	s_andn2_saveexec_b64 s[34:35], s[34:35]
	s_cbranch_execz .LBB0_2899
	v_add_f32_e32 v129, v88, v88
	v_mul_f32_e32 v129, 0x3fb8aa3b, v129
	v_add_f32_e32 v128, v92, v92
	v_exp_f32_e32 v132, v129
	v_add_f32_e32 v129, v93, v93
	v_mul_f32_e32 v128, 0x3fb8aa3b, v128
	v_mul_f32_e32 v129, 0x3fb8aa3b, v129
	v_exp_f32_e32 v128, v128
	v_exp_f32_e32 v129, v129
	v_add_f32_e32 v130, v89, v89
	v_mul_f32_e32 v130, 0x3fb8aa3b, v130
	v_exp_f32_e32 v133, v130
	v_pk_add_f32 v[128:129], v[128:129], 1.0 op_sel_hi:[1,0]
	v_add_f32_e32 v130, v94, v94
	v_add_f32_e32 v131, v95, v95
	v_mul_f32_e32 v130, 0x3fb8aa3b, v130
	v_mul_f32_e32 v131, 0x3fb8aa3b, v131
	v_exp_f32_e32 v130, v130
	v_exp_f32_e32 v131, v131
	v_rcp_f32_e32 v135, v128
	s_nop 0
	v_mul_f32_e32 v128, 2.0, v135
	v_pk_add_f32 v[130:131], v[130:131], 1.0 op_sel_hi:[1,0]
	v_rcp_f32_e32 v135, v129
	s_nop 0
	v_mul_f32_e32 v129, 2.0, v135
	v_pk_add_f32 v[132:133], v[132:133], 1.0 op_sel_hi:[1,0]
	v_rcp_f32_e32 v135, v130
	s_nop 0
	v_mul_f32_e32 v130, 2.0, v135
	v_add_f32_e32 v134, v90, v90
	v_rcp_f32_e32 v135, v131
	s_nop 0
	v_mul_f32_e32 v131, 2.0, v135
	v_add_f32_e32 v135, v91, v91
	v_mul_f32_e32 v134, 0x3fb8aa3b, v134
	v_mul_f32_e32 v135, 0x3fb8aa3b, v135
	v_exp_f32_e32 v134, v134
	v_exp_f32_e32 v135, v135
	v_rcp_f32_e32 v155, v132
	s_nop 0
	v_mul_f32_e32 v132, 2.0, v155
	v_pk_add_f32 v[134:135], v[134:135], 1.0 op_sel_hi:[1,0]
	v_rcp_f32_e32 v155, v133
	s_nop 0
	v_mul_f32_e32 v133, 2.0, v155
	v_sub_f32_e32 v131, 1.0, v131
	v_rcp_f32_e32 v155, v134
	s_nop 0
	v_mul_f32_e32 v134, 2.0, v155
	v_sub_f32_e32 v130, 1.0, v130
	v_rcp_f32_e32 v155, v135
	s_nop 0
	v_mul_f32_e32 v135, 2.0, v155
	v_sub_f32_e32 v129, 1.0, v129
	v_sub_f32_e32 v128, 1.0, v128
	v_sub_f32_e32 v135, 1.0, v135
	v_sub_f32_e32 v134, 1.0, v134
	v_sub_f32_e32 v133, 1.0, v133
	v_sub_f32_e32 v132, 1.0, v132
.LBB0_2899:
	s_or_b64 exec, exec, s[34:35]
	v_cvt_pk_bf16_f32 v128, v128, v129
	v_cvt_pk_bf16_f32 v129, v130, v131
	v_cvt_pk_bf16_f32 v130, v132, v133
	v_cvt_pk_bf16_f32 v131, v134, v135
	flat_store_dwordx4 v[156:157], v[128:131] offset:256
	s_and_saveexec_b64 s[34:35], s[4:5]
	s_xor_b64 s[34:35], exec, s[34:35]
	s_cbranch_execz .LBB0_2903
	v_mov_b64_e32 v[134:135], v[98:99]
	v_mov_b64_e32 v[130:131], v[102:103]
	v_cmp_lt_u32_e32 vcc, s61, v152
	v_mov_b64_e32 v[132:133], v[96:97]
	v_mov_b64_e32 v[128:129], v[100:101]
	s_and_saveexec_b64 s[36:37], vcc
	s_cbranch_execz .LBB0_2902
	v_mul_f32_e32 v130, 0xbfb8aa3b, v102
	v_mul_f32_e32 v131, 0xbfb8aa3b, v103
	v_exp_f32_e32 v130, v130
	v_exp_f32_e32 v131, v131
	v_mul_f32_e32 v129, 0xbfb8aa3b, v96
	v_mul_f32_e32 v128, 0xbfb8aa3b, v100
	v_exp_f32_e32 v132, v129
	v_pk_add_f32 v[130:131], v[130:131], 1.0 op_sel_hi:[1,0]
	v_mul_f32_e32 v129, 0xbfb8aa3b, v101
	v_exp_f32_e32 v128, v128
	v_exp_f32_e32 v129, v129
	v_mul_f32_e32 v134, 0xbfb8aa3b, v98
	v_rcp_f32_e32 v131, v131
	v_pk_add_f32 v[128:129], v[128:129], 1.0 op_sel_hi:[1,0]
	v_rcp_f32_e32 v130, v130
	v_exp_f32_e32 v134, v134
	v_rcp_f32_e32 v129, v129
	v_mul_f32_e32 v135, 0xbfb8aa3b, v99
	v_exp_f32_e32 v135, v135
	s_nop 0
	v_pk_add_f32 v[134:135], v[134:135], 1.0 op_sel_hi:[1,0]
	v_rcp_f32_e32 v128, v128
	v_mul_f32_e32 v133, 0xbfb8aa3b, v97
	v_exp_f32_e32 v133, v133
	v_rcp_f32_e32 v135, v135
	v_pk_add_f32 v[132:133], v[132:133], 1.0 op_sel_hi:[1,0]
	v_rcp_f32_e32 v134, v134
	v_rcp_f32_e32 v133, v133
	v_rcp_f32_e32 v132, v132

; #define EPI_ROWS(...) _Pragma("unroll") for (int ai = 0; ai < 2; ++ai) _Pragma("unroll") for (int m = 0; m < 4; ++m) { const int row = u.pm * 256 + ai * 128 + wr * 64 + m * 16 + fr; __VA_ARGS__ }
; DI u32x4 pack8(f32x4 a, f32x4 b) { u32x4 w; w.x = pk2(a[0], a[1]); w.y = pk2(a[2], a[3]); w.z = pk2(b[0], b[1]); w.w = pk2(b[2], b[3]); return w; }
; DI float sigmoidf_(float x) { return 1.f / (1.f + __expf(-x)); }
; DI float siluf_(float x) { return x / (1.f + __expf(-x)); }
; DI float softplusf_(float x) { return fmaxf(x, 0.f) + log1pf(expf(-fabsf(x))); }
; DI float softplus_fast(float x) { return fmaxf(x, 0.f) + __logf(1.f + __expf(-fabsf(x))); }
; DI float tanh_fast(float x) { const float e = __expf(2.f * x); return 1.f - 2.f / (e + 1.f); }
;     DI void operator()(const Acc& acc, const Unit& u, int wr, int wc, int fr, int fq) const {
;     ...
;             EPI_ROWS( _Pragma("unroll") for (int bj = 0; bj < 2; ++bj) { const int c0 = (pn - 12) * 256 + bj * 128 + wc * 32 + 8 * fq; f32x4 a = acc[ai][bj][m][0], b = acc[ai][bj][m][1];
;                     if (c0 < 64) { _Pragma("unroll") for (int e = 0; e < 4; ++e) { a[e] = tanh_fast(a[e]); b[e] = tanh_fast(b[e]); } }
;                     else if (c0 >= 128) { _Pragma("unroll") for (int e = 0; e < 4; ++e) { a[e] = sigmoidf_(a[e]); b[e] = sigmoidf_(b[e]); } }
;                     *(u32x4*)(LH + (size_t)row * 512 + c0) = pack8(a, b); } )
.LBB0_2903:
	s_andn2_saveexec_b64 s[34:35], s[34:35]
	s_cbranch_execz .LBB0_2905
	v_add_f32_e32 v129, v96, v96
	v_mul_f32_e32 v129, 0x3fb8aa3b, v129
	v_add_f32_e32 v128, v100, v100
	v_exp_f32_e32 v132, v129
	v_add_f32_e32 v129, v101, v101
	v_mul_f32_e32 v128, 0x3fb8aa3b, v128
	v_mul_f32_e32 v129, 0x3fb8aa3b, v129
	v_exp_f32_e32 v128, v128
	v_exp_f32_e32 v129, v129
	v_add_f32_e32 v130, v97, v97
	v_mul_f32_e32 v130, 0x3fb8aa3b, v130
	v_exp_f32_e32 v133, v130
	v_pk_add_f32 v[128:129], v[128:129], 1.0 op_sel_hi:[1,0]
	v_add_f32_e32 v130, v102, v102
	v_add_f32_e32 v131, v103, v103
	v_mul_f32_e32 v130, 0x3fb8aa3b, v130
	v_mul_f32_e32 v131, 0x3fb8aa3b, v131
	v_exp_f32_e32 v130, v130
	v_exp_f32_e32 v131, v131
	v_rcp_f32_e32 v135, v128
	s_nop 0
	v_mul_f32_e32 v128, 2.0, v135
	v_pk_add_f32 v[130:131], v[130:131], 1.0 op_sel_hi:[1,0]
	v_rcp_f32_e32 v135, v129
	s_nop 0
	v_mul_f32_e32 v129, 2.0, v135
	v_pk_add_f32 v[132:133], v[132:133], 1.0 op_sel_hi:[1,0]
	v_rcp_f32_e32 v135, v130
	s_nop 0
	v_mul_f32_e32 v130, 2.0, v135
	v_add_f32_e32 v134, v98, v98
	v_rcp_f32_e32 v135, v131
	s_nop 0
	v_mul_f32_e32 v131, 2.0, v135
	v_add_f32_e32 v135, v99, v99
	v_mul_f32_e32 v134, 0x3fb8aa3b, v134
	v_mul_f32_e32 v135, 0x3fb8aa3b, v135
	v_exp_f32_e32 v134, v134
	v_exp_f32_e32 v135, v135
	v_rcp_f32_e32 v155, v132
	s_nop 0
	v_mul_f32_e32 v132, 2.0, v155
	v_pk_add_f32 v[134:135], v[134:135], 1.0 op_sel_hi:[1,0]
	v_rcp_f32_e32 v155, v133
	s_nop 0
	v_mul_f32_e32 v133, 2.0, v155
	v_sub_f32_e32 v131, 1.0, v131
	v_rcp_f32_e32 v155, v134
	s_nop 0
	v_mul_f32_e32 v134, 2.0, v155
	v_sub_f32_e32 v130, 1.0, v130
	v_rcp_f32_e32 v155, v135
	s_nop 0
	v_mul_f32_e32 v135, 2.0, v155
	v_sub_f32_e32 v129, 1.0, v129
	v_sub_f32_e32 v128, 1.0, v128
	v_sub_f32_e32 v135, 1.0, v135
	v_sub_f32_e32 v134, 1.0, v134
	v_sub_f32_e32 v133, 1.0, v133
	v_sub_f32_e32 v132, 1.0, v132
.LBB0_2905:
	s_or_b64 exec, exec, s[34:35]
	v_add_u32_e32 v156, 32, v154
	v_ashrrev_i32_e32 v157, 31, v156
	v_lshlrev_b64 v[156:157], 10, v[156:157]
	v_lshl_add_u64 v[156:157], s[12:13], 0, v[156:157]
	v_cvt_pk_bf16_f32 v128, v128, v129
	v_cvt_pk_bf16_f32 v129, v130, v131
	v_cvt_pk_bf16_f32 v130, v132, v133
	v_cvt_pk_bf16_f32 v131, v134, v135
	v_lshl_add_u64 v[156:157], v[152:153], 1, v[156:157]
	flat_store_dwordx4 v[156:157], v[128:131]
	s_and_saveexec_b64 s[34:35], s[6:7]
	s_xor_b64 s[34:35], exec, s[34:35]
	s_cbranch_execz .LBB0_2909
	v_mov_b64_e32 v[134:135], v[74:75]
	v_mov_b64_e32 v[130:131], v[78:79]
	v_cmp_gt_u32_e32 vcc, s66, v152
	v_mov_b64_e32 v[132:133], v[72:73]
	v_mov_b64_e32 v[128:129], v[76:77]
	s_and_saveexec_b64 s[36:37], vcc
	s_cbranch_execz .LBB0_2908
	v_mul_f32_e32 v130, 0xbfb8aa3b, v78
	v_mul_f32_e32 v131, 0xbfb8aa3b, v79
	v_exp_f32_e32 v130, v130
	v_exp_f32_e32 v131, v131
	v_mul_f32_e32 v129, 0xbfb8aa3b, v72
	v_mul_f32_e32 v128, 0xbfb8aa3b, v76
	v_exp_f32_e32 v132, v129
	v_pk_add_f32 v[130:131], v[130:131], 1.0 op_sel_hi:[1,0]
	v_mul_f32_e32 v129, 0xbfb8aa3b, v77
	v_exp_f32_e32 v128, v128
	v_exp_f32_e32 v129, v129
	v_mul_f32_e32 v134, 0xbfb8aa3b, v74
	v_rcp_f32_e32 v131, v131
	v_pk_add_f32 v[128:129], v[128:129], 1.0 op_sel_hi:[1,0]
	v_rcp_f32_e32 v130, v130
	v_exp_f32_e32 v134, v134
	v_rcp_f32_e32 v129, v129
	v_mul_f32_e32 v135, 0xbfb8aa3b, v75
	v_exp_f32_e32 v135, v135
	s_nop 0
	v_pk_add_f32 v[134:135], v[134:135], 1.0 op_sel_hi:[1,0]
	v_rcp_f32_e32 v128, v128
	v_mul_f32_e32 v133, 0xbfb8aa3b, v73
	v_exp_f32_e32 v133, v133
	v_rcp_f32_e32 v135, v135
	v_pk_add_f32 v[132:133], v[132:133], 1.0 op_sel_hi:[1,0]
	v_rcp_f32_e32 v134, v134
	v_rcp_f32_e32 v133, v133
	v_rcp_f32_e32 v132, v132

; #define EPI_ROWS(...) _Pragma("unroll") for (int ai = 0; ai < 2; ++ai) _Pragma("unroll") for (int m = 0; m < 4; ++m) { const int row = u.pm * 256 + ai * 128 + wr * 64 + m * 16 + fr; __VA_ARGS__ }
; DI u32x4 pack8(f32x4 a, f32x4 b) { u32x4 w; w.x = pk2(a[0], a[1]); w.y = pk2(a[2], a[3]); w.z = pk2(b[0], b[1]); w.w = pk2(b[2], b[3]); return w; }
; DI float sigmoidf_(float x) { return 1.f / (1.f + __expf(-x)); }
; DI float siluf_(float x) { return x / (1.f + __expf(-x)); }
; DI float softplusf_(float x) { return fmaxf(x, 0.f) + log1pf(expf(-fabsf(x))); }
; DI float softplus_fast(float x) { return fmaxf(x, 0.f) + __logf(1.f + __expf(-fabsf(x))); }
; DI float tanh_fast(float x) { const float e = __expf(2.f * x); return 1.f - 2.f / (e + 1.f); }
;     DI void operator()(const Acc& acc, const Unit& u, int wr, int wc, int fr, int fq) const {
;     ...
;             EPI_ROWS( _Pragma("unroll") for (int bj = 0; bj < 2; ++bj) { const int c0 = (pn - 12) * 256 + bj * 128 + wc * 32 + 8 * fq; f32x4 a = acc[ai][bj][m][0], b = acc[ai][bj][m][1];
;                     if (c0 < 64) { _Pragma("unroll") for (int e = 0; e < 4; ++e) { a[e] = tanh_fast(a[e]); b[e] = tanh_fast(b[e]); } }
;                     else if (c0 >= 128) { _Pragma("unroll") for (int e = 0; e < 4; ++e) { a[e] = sigmoidf_(a[e]); b[e] = sigmoidf_(b[e]); } }
;                     *(u32x4*)(LH + (size_t)row * 512 + c0) = pack8(a, b); } )
.LBB0_2909:
	s_andn2_saveexec_b64 s[34:35], s[34:35]
	s_cbranch_execz .LBB0_2911
	v_add_f32_e32 v129, v72, v72
	v_mul_f32_e32 v129, 0x3fb8aa3b, v129
	v_add_f32_e32 v128, v76, v76
	v_exp_f32_e32 v132, v129
	v_add_f32_e32 v129, v77, v77
	v_mul_f32_e32 v128, 0x3fb8aa3b, v128
	v_mul_f32_e32 v129, 0x3fb8aa3b, v129
	v_exp_f32_e32 v128, v128
	v_exp_f32_e32 v129, v129
	v_add_f32_e32 v130, v73, v73
	v_mul_f32_e32 v130, 0x3fb8aa3b, v130
	v_exp_f32_e32 v133, v130
	v_pk_add_f32 v[128:129], v[128:129], 1.0 op_sel_hi:[1,0]
	v_add_f32_e32 v130, v78, v78
	v_add_f32_e32 v131, v79, v79
	v_mul_f32_e32 v130, 0x3fb8aa3b, v130
	v_mul_f32_e32 v131, 0x3fb8aa3b, v131
	v_exp_f32_e32 v130, v130
	v_exp_f32_e32 v131, v131
	v_rcp_f32_e32 v135, v128
	s_nop 0
	v_mul_f32_e32 v128, 2.0, v135
	v_pk_add_f32 v[130:131], v[130:131], 1.0 op_sel_hi:[1,0]
	v_rcp_f32_e32 v135, v129
	s_nop 0
	v_mul_f32_e32 v129, 2.0, v135
	v_pk_add_f32 v[132:133], v[132:133], 1.0 op_sel_hi:[1,0]
	v_rcp_f32_e32 v135, v130
	s_nop 0
	v_mul_f32_e32 v130, 2.0, v135
	v_add_f32_e32 v134, v74, v74
	v_rcp_f32_e32 v135, v131
	s_nop 0
	v_mul_f32_e32 v131, 2.0, v135
	v_add_f32_e32 v135, v75, v75
	v_mul_f32_e32 v134, 0x3fb8aa3b, v134
	v_mul_f32_e32 v135, 0x3fb8aa3b, v135
	v_exp_f32_e32 v134, v134
	v_exp_f32_e32 v135, v135
	v_rcp_f32_e32 v155, v132
	s_nop 0
	v_mul_f32_e32 v132, 2.0, v155
	v_pk_add_f32 v[134:135], v[134:135], 1.0 op_sel_hi:[1,0]
	v_rcp_f32_e32 v155, v133
	s_nop 0
	v_mul_f32_e32 v133, 2.0, v155
	v_sub_f32_e32 v131, 1.0, v131
	v_rcp_f32_e32 v155, v134
	s_nop 0
	v_mul_f32_e32 v134, 2.0, v155
	v_sub_f32_e32 v130, 1.0, v130
	v_rcp_f32_e32 v155, v135
	s_nop 0
	v_mul_f32_e32 v135, 2.0, v155
	v_sub_f32_e32 v129, 1.0, v129
	v_sub_f32_e32 v128, 1.0, v128
	v_sub_f32_e32 v135, 1.0, v135
	v_sub_f32_e32 v134, 1.0, v134
	v_sub_f32_e32 v133, 1.0, v133
	v_sub_f32_e32 v132, 1.0, v132
.LBB0_2911:
	s_or_b64 exec, exec, s[34:35]
	v_cvt_pk_bf16_f32 v128, v128, v129
	v_cvt_pk_bf16_f32 v129, v130, v131
	v_cvt_pk_bf16_f32 v130, v132, v133
	v_cvt_pk_bf16_f32 v131, v134, v135
	flat_store_dwordx4 v[156:157], v[128:131] offset:256
	s_and_saveexec_b64 s[34:35], s[4:5]
	s_xor_b64 s[34:35], exec, s[34:35]
	s_cbranch_execz .LBB0_2915
	v_mov_b64_e32 v[134:135], v[82:83]
	v_mov_b64_e32 v[130:131], v[86:87]
	v_cmp_lt_u32_e32 vcc, s61, v152
	v_mov_b64_e32 v[132:133], v[80:81]
	v_mov_b64_e32 v[128:129], v[84:85]
	s_and_saveexec_b64 s[36:37], vcc
	s_cbranch_execz .LBB0_2914
	v_mul_f32_e32 v130, 0xbfb8aa3b, v86
	v_mul_f32_e32 v131, 0xbfb8aa3b, v87
	v_exp_f32_e32 v130, v130
	v_exp_f32_e32 v131, v131
	v_mul_f32_e32 v129, 0xbfb8aa3b, v80
	v_mul_f32_e32 v128, 0xbfb8aa3b, v84
	v_exp_f32_e32 v132, v129
	v_pk_add_f32 v[130:131], v[130:131], 1.0 op_sel_hi:[1,0]
	v_mul_f32_e32 v129, 0xbfb8aa3b, v85
	v_exp_f32_e32 v128, v128
	v_exp_f32_e32 v129, v129
	v_mul_f32_e32 v134, 0xbfb8aa3b, v82
	v_rcp_f32_e32 v131, v131
	v_pk_add_f32 v[128:129], v[128:129], 1.0 op_sel_hi:[1,0]
	v_rcp_f32_e32 v130, v130
	v_exp_f32_e32 v134, v134
	v_rcp_f32_e32 v129, v129
	v_mul_f32_e32 v135, 0xbfb8aa3b, v83
	v_exp_f32_e32 v135, v135
	s_nop 0
	v_pk_add_f32 v[134:135], v[134:135], 1.0 op_sel_hi:[1,0]
	v_rcp_f32_e32 v128, v128
	v_mul_f32_e32 v133, 0xbfb8aa3b, v81
	v_exp_f32_e32 v133, v133
	v_rcp_f32_e32 v135, v135
	v_pk_add_f32 v[132:133], v[132:133], 1.0 op_sel_hi:[1,0]
	v_rcp_f32_e32 v134, v134
	v_rcp_f32_e32 v133, v133
	v_rcp_f32_e32 v132, v132

; #define EPI_ROWS(...) _Pragma("unroll") for (int ai = 0; ai < 2; ++ai) _Pragma("unroll") for (int m = 0; m < 4; ++m) { const int row = u.pm * 256 + ai * 128 + wr * 64 + m * 16 + fr; __VA_ARGS__ }
; DI u32x4 pack8(f32x4 a, f32x4 b) { u32x4 w; w.x = pk2(a[0], a[1]); w.y = pk2(a[2], a[3]); w.z = pk2(b[0], b[1]); w.w = pk2(b[2], b[3]); return w; }
; DI float sigmoidf_(float x) { return 1.f / (1.f + __expf(-x)); }
; DI float siluf_(float x) { return x / (1.f + __expf(-x)); }
; DI float softplusf_(float x) { return fmaxf(x, 0.f) + log1pf(expf(-fabsf(x))); }
; DI float softplus_fast(float x) { return fmaxf(x, 0.f) + __logf(1.f + __expf(-fabsf(x))); }
; DI float tanh_fast(float x) { const float e = __expf(2.f * x); return 1.f - 2.f / (e + 1.f); }
;     DI void operator()(const Acc& acc, const Unit& u, int wr, int wc, int fr, int fq) const {
;     ...
;             EPI_ROWS( _Pragma("unroll") for (int bj = 0; bj < 2; ++bj) { const int c0 = (pn - 12) * 256 + bj * 128 + wc * 32 + 8 * fq; f32x4 a = acc[ai][bj][m][0], b = acc[ai][bj][m][1];
;                     if (c0 < 64) { _Pragma("unroll") for (int e = 0; e < 4; ++e) { a[e] = tanh_fast(a[e]); b[e] = tanh_fast(b[e]); } }
;                     else if (c0 >= 128) { _Pragma("unroll") for (int e = 0; e < 4; ++e) { a[e] = sigmoidf_(a[e]); b[e] = sigmoidf_(b[e]); } }
;                     *(u32x4*)(LH + (size_t)row * 512 + c0) = pack8(a, b); } )
.LBB0_2915:
	s_andn2_saveexec_b64 s[34:35], s[34:35]
	s_cbranch_execz .LBB0_2917
	v_add_f32_e32 v129, v80, v80
	v_mul_f32_e32 v129, 0x3fb8aa3b, v129
	v_add_f32_e32 v128, v84, v84
	v_exp_f32_e32 v132, v129
	v_add_f32_e32 v129, v85, v85
	v_mul_f32_e32 v128, 0x3fb8aa3b, v128
	v_mul_f32_e32 v129, 0x3fb8aa3b, v129
	v_exp_f32_e32 v128, v128
	v_exp_f32_e32 v129, v129
	v_add_f32_e32 v130, v81, v81
	v_mul_f32_e32 v130, 0x3fb8aa3b, v130
	v_exp_f32_e32 v133, v130
	v_pk_add_f32 v[128:129], v[128:129], 1.0 op_sel_hi:[1,0]
	v_add_f32_e32 v130, v86, v86
	v_add_f32_e32 v131, v87, v87
	v_mul_f32_e32 v130, 0x3fb8aa3b, v130
	v_mul_f32_e32 v131, 0x3fb8aa3b, v131
	v_exp_f32_e32 v130, v130
	v_exp_f32_e32 v131, v131
	v_rcp_f32_e32 v135, v128
	s_nop 0
	v_mul_f32_e32 v128, 2.0, v135
	v_pk_add_f32 v[130:131], v[130:131], 1.0 op_sel_hi:[1,0]
	v_rcp_f32_e32 v135, v129
	s_nop 0
	v_mul_f32_e32 v129, 2.0, v135
	v_pk_add_f32 v[132:133], v[132:133], 1.0 op_sel_hi:[1,0]
	v_rcp_f32_e32 v135, v130
	s_nop 0
	v_mul_f32_e32 v130, 2.0, v135
	v_add_f32_e32 v134, v82, v82
	v_rcp_f32_e32 v135, v131
	s_nop 0
	v_mul_f32_e32 v131, 2.0, v135
	v_add_f32_e32 v135, v83, v83
	v_mul_f32_e32 v134, 0x3fb8aa3b, v134
	v_mul_f32_e32 v135, 0x3fb8aa3b, v135
	v_exp_f32_e32 v134, v134
	v_exp_f32_e32 v135, v135
	v_rcp_f32_e32 v155, v132
	s_nop 0
	v_mul_f32_e32 v132, 2.0, v155
	v_pk_add_f32 v[134:135], v[134:135], 1.0 op_sel_hi:[1,0]
	v_rcp_f32_e32 v155, v133
	s_nop 0
	v_mul_f32_e32 v133, 2.0, v155
	v_sub_f32_e32 v131, 1.0, v131
	v_rcp_f32_e32 v155, v134
	s_nop 0
	v_mul_f32_e32 v134, 2.0, v155
	v_sub_f32_e32 v130, 1.0, v130
	v_rcp_f32_e32 v155, v135
	s_nop 0
	v_mul_f32_e32 v135, 2.0, v155
	v_sub_f32_e32 v129, 1.0, v129
	v_sub_f32_e32 v128, 1.0, v128
	v_sub_f32_e32 v135, 1.0, v135
	v_sub_f32_e32 v134, 1.0, v134
	v_sub_f32_e32 v133, 1.0, v133
	v_sub_f32_e32 v132, 1.0, v132
.LBB0_2917:
	s_or_b64 exec, exec, s[34:35]
	v_add_u32_e32 v156, 48, v154
	v_ashrrev_i32_e32 v157, 31, v156
	v_lshlrev_b64 v[156:157], 10, v[156:157]
	v_lshl_add_u64 v[156:157], s[12:13], 0, v[156:157]
	v_cvt_pk_bf16_f32 v128, v128, v129
	v_cvt_pk_bf16_f32 v129, v130, v131
	v_cvt_pk_bf16_f32 v130, v132, v133
	v_cvt_pk_bf16_f32 v131, v134, v135
	v_lshl_add_u64 v[156:157], v[152:153], 1, v[156:157]
	flat_store_dwordx4 v[156:157], v[128:131]
	s_and_saveexec_b64 s[34:35], s[6:7]
	s_xor_b64 s[34:35], exec, s[34:35]
	s_cbranch_execz .LBB0_2921
	v_mov_b64_e32 v[134:135], v[66:67]
	v_mov_b64_e32 v[130:131], v[70:71]
	v_cmp_gt_u32_e32 vcc, s66, v152
	v_mov_b64_e32 v[132:133], v[64:65]
	v_mov_b64_e32 v[128:129], v[68:69]
	s_and_saveexec_b64 s[36:37], vcc
	s_cbranch_execz .LBB0_2920
	v_mul_f32_e32 v130, 0xbfb8aa3b, v70
	v_mul_f32_e32 v131, 0xbfb8aa3b, v71
	v_exp_f32_e32 v130, v130
	v_exp_f32_e32 v131, v131
	v_mul_f32_e32 v129, 0xbfb8aa3b, v64
	v_mul_f32_e32 v128, 0xbfb8aa3b, v68
	v_exp_f32_e32 v132, v129
	v_pk_add_f32 v[130:131], v[130:131], 1.0 op_sel_hi:[1,0]
	v_mul_f32_e32 v129, 0xbfb8aa3b, v69
	v_exp_f32_e32 v128, v128
	v_exp_f32_e32 v129, v129
	v_mul_f32_e32 v134, 0xbfb8aa3b, v66
	v_rcp_f32_e32 v131, v131
	v_pk_add_f32 v[128:129], v[128:129], 1.0 op_sel_hi:[1,0]
	v_rcp_f32_e32 v130, v130
	v_exp_f32_e32 v134, v134
	v_rcp_f32_e32 v129, v129
	v_mul_f32_e32 v135, 0xbfb8aa3b, v67
	v_exp_f32_e32 v135, v135
	s_nop 0
	v_pk_add_f32 v[134:135], v[134:135], 1.0 op_sel_hi:[1,0]
	v_rcp_f32_e32 v128, v128
	v_mul_f32_e32 v133, 0xbfb8aa3b, v65
	v_exp_f32_e32 v133, v133
	v_rcp_f32_e32 v135, v135
	v_pk_add_f32 v[132:133], v[132:133], 1.0 op_sel_hi:[1,0]
	v_rcp_f32_e32 v134, v134
	v_rcp_f32_e32 v133, v133
	v_rcp_f32_e32 v132, v132

; #define EPI_ROWS(...) _Pragma("unroll") for (int ai = 0; ai < 2; ++ai) _Pragma("unroll") for (int m = 0; m < 4; ++m) { const int row = u.pm * 256 + ai * 128 + wr * 64 + m * 16 + fr; __VA_ARGS__ }
; DI u32x4 pack8(f32x4 a, f32x4 b) { u32x4 w; w.x = pk2(a[0], a[1]); w.y = pk2(a[2], a[3]); w.z = pk2(b[0], b[1]); w.w = pk2(b[2], b[3]); return w; }
; DI float sigmoidf_(float x) { return 1.f / (1.f + __expf(-x)); }
; DI float siluf_(float x) { return x / (1.f + __expf(-x)); }
; DI float softplusf_(float x) { return fmaxf(x, 0.f) + log1pf(expf(-fabsf(x))); }
; DI float softplus_fast(float x) { return fmaxf(x, 0.f) + __logf(1.f + __expf(-fabsf(x))); }
; DI float tanh_fast(float x) { const float e = __expf(2.f * x); return 1.f - 2.f / (e + 1.f); }
;     DI void operator()(const Acc& acc, const Unit& u, int wr, int wc, int fr, int fq) const {
;     ...
;             EPI_ROWS( _Pragma("unroll") for (int bj = 0; bj < 2; ++bj) { const int c0 = (pn - 12) * 256 + bj * 128 + wc * 32 + 8 * fq; f32x4 a = acc[ai][bj][m][0], b = acc[ai][bj][m][1];
;                     if (c0 < 64) { _Pragma("unroll") for (int e = 0; e < 4; ++e) { a[e] = tanh_fast(a[e]); b[e] = tanh_fast(b[e]); } }
;                     else if (c0 >= 128) { _Pragma("unroll") for (int e = 0; e < 4; ++e) { a[e] = sigmoidf_(a[e]); b[e] = sigmoidf_(b[e]); } }
;                     *(u32x4*)(LH + (size_t)row * 512 + c0) = pack8(a, b); } )
.LBB0_2921:
	s_andn2_saveexec_b64 s[34:35], s[34:35]
	s_cbranch_execz .LBB0_2923
	v_add_f32_e32 v129, v64, v64
	v_mul_f32_e32 v129, 0x3fb8aa3b, v129
	v_add_f32_e32 v128, v68, v68
	v_exp_f32_e32 v132, v129
	v_add_f32_e32 v129, v69, v69
	v_mul_f32_e32 v128, 0x3fb8aa3b, v128
	v_mul_f32_e32 v129, 0x3fb8aa3b, v129
	v_exp_f32_e32 v128, v128
	v_exp_f32_e32 v129, v129
	v_add_f32_e32 v130, v65, v65
	v_mul_f32_e32 v130, 0x3fb8aa3b, v130
	v_exp_f32_e32 v133, v130
	v_pk_add_f32 v[128:129], v[128:129], 1.0 op_sel_hi:[1,0]
	v_add_f32_e32 v130, v70, v70
	v_add_f32_e32 v131, v71, v71
	v_mul_f32_e32 v130, 0x3fb8aa3b, v130
	v_mul_f32_e32 v131, 0x3fb8aa3b, v131
	v_exp_f32_e32 v130, v130
	v_exp_f32_e32 v131, v131
	v_rcp_f32_e32 v135, v128
	s_nop 0
	v_mul_f32_e32 v128, 2.0, v135
	v_pk_add_f32 v[130:131], v[130:131], 1.0 op_sel_hi:[1,0]
	v_rcp_f32_e32 v135, v129
	s_nop 0
	v_mul_f32_e32 v129, 2.0, v135
	v_pk_add_f32 v[132:133], v[132:133], 1.0 op_sel_hi:[1,0]
	v_rcp_f32_e32 v135, v130
	s_nop 0
	v_mul_f32_e32 v130, 2.0, v135
	v_add_f32_e32 v134, v66, v66
	v_rcp_f32_e32 v135, v131
	s_nop 0
	v_mul_f32_e32 v131, 2.0, v135
	v_add_f32_e32 v135, v67, v67
	v_mul_f32_e32 v134, 0x3fb8aa3b, v134
	v_mul_f32_e32 v135, 0x3fb8aa3b, v135
	v_exp_f32_e32 v134, v134
	v_exp_f32_e32 v135, v135
	v_rcp_f32_e32 v155, v132
	s_nop 0
	v_mul_f32_e32 v132, 2.0, v155
	v_pk_add_f32 v[134:135], v[134:135], 1.0 op_sel_hi:[1,0]
	v_rcp_f32_e32 v155, v133
	s_nop 0
	v_mul_f32_e32 v133, 2.0, v155
	v_sub_f32_e32 v131, 1.0, v131
	v_rcp_f32_e32 v155, v134
	s_nop 0
	v_mul_f32_e32 v134, 2.0, v155
	v_sub_f32_e32 v130, 1.0, v130
	v_rcp_f32_e32 v155, v135
	s_nop 0
	v_mul_f32_e32 v135, 2.0, v155
	v_sub_f32_e32 v129, 1.0, v129
	v_sub_f32_e32 v128, 1.0, v128
	v_sub_f32_e32 v135, 1.0, v135
	v_sub_f32_e32 v134, 1.0, v134
	v_sub_f32_e32 v133, 1.0, v133
	v_sub_f32_e32 v132, 1.0, v132
.LBB0_2923:
	s_or_b64 exec, exec, s[34:35]
	v_cvt_pk_bf16_f32 v128, v128, v129
	v_cvt_pk_bf16_f32 v129, v130, v131
	v_cvt_pk_bf16_f32 v130, v132, v133
	v_cvt_pk_bf16_f32 v131, v134, v135
	flat_store_dwordx4 v[156:157], v[128:131] offset:256
	s_and_saveexec_b64 s[34:35], s[4:5]
	s_xor_b64 s[34:35], exec, s[34:35]
	s_cbranch_execz .LBB0_2927
	v_mov_b64_e32 v[134:135], v[58:59]
	v_mov_b64_e32 v[130:131], v[62:63]
	v_cmp_lt_u32_e32 vcc, s61, v152
	v_mov_b64_e32 v[132:133], v[56:57]
	v_mov_b64_e32 v[128:129], v[60:61]
	s_and_saveexec_b64 s[36:37], vcc
	s_cbranch_execz .LBB0_2926
	v_mul_f32_e32 v130, 0xbfb8aa3b, v62
	v_mul_f32_e32 v131, 0xbfb8aa3b, v63
	v_exp_f32_e32 v130, v130
	v_exp_f32_e32 v131, v131
	v_mul_f32_e32 v129, 0xbfb8aa3b, v56
	v_mul_f32_e32 v128, 0xbfb8aa3b, v60
	v_exp_f32_e32 v132, v129
	v_pk_add_f32 v[130:131], v[130:131], 1.0 op_sel_hi:[1,0]
	v_mul_f32_e32 v129, 0xbfb8aa3b, v61
	v_exp_f32_e32 v128, v128
	v_exp_f32_e32 v129, v129
	v_mul_f32_e32 v134, 0xbfb8aa3b, v58
	v_rcp_f32_e32 v131, v131
	v_pk_add_f32 v[128:129], v[128:129], 1.0 op_sel_hi:[1,0]
	v_rcp_f32_e32 v130, v130
	v_exp_f32_e32 v134, v134
	v_rcp_f32_e32 v129, v129
	v_mul_f32_e32 v135, 0xbfb8aa3b, v59
	v_exp_f32_e32 v135, v135
	s_nop 0
	v_pk_add_f32 v[134:135], v[134:135], 1.0 op_sel_hi:[1,0]
	v_rcp_f32_e32 v128, v128
	v_mul_f32_e32 v133, 0xbfb8aa3b, v57
	v_exp_f32_e32 v133, v133
	v_rcp_f32_e32 v135, v135
	v_pk_add_f32 v[132:133], v[132:133], 1.0 op_sel_hi:[1,0]
	v_rcp_f32_e32 v134, v134
	v_rcp_f32_e32 v133, v133
	v_rcp_f32_e32 v132, v132

; #define EPI_ROWS(...) _Pragma("unroll") for (int ai = 0; ai < 2; ++ai) _Pragma("unroll") for (int m = 0; m < 4; ++m) { const int row = u.pm * 256 + ai * 128 + wr * 64 + m * 16 + fr; __VA_ARGS__ }
; DI u32x4 pack8(f32x4 a, f32x4 b) { u32x4 w; w.x = pk2(a[0], a[1]); w.y = pk2(a[2], a[3]); w.z = pk2(b[0], b[1]); w.w = pk2(b[2], b[3]); return w; }
; DI float sigmoidf_(float x) { return 1.f / (1.f + __expf(-x)); }
; DI float siluf_(float x) { return x / (1.f + __expf(-x)); }
; DI float softplusf_(float x) { return fmaxf(x, 0.f) + log1pf(expf(-fabsf(x))); }
; DI float softplus_fast(float x) { return fmaxf(x, 0.f) + __logf(1.f + __expf(-fabsf(x))); }
; DI float tanh_fast(float x) { const float e = __expf(2.f * x); return 1.f - 2.f / (e + 1.f); }
;     DI void operator()(const Acc& acc, const Unit& u, int wr, int wc, int fr, int fq) const {
;     ...
;             EPI_ROWS( _Pragma("unroll") for (int bj = 0; bj < 2; ++bj) { const int c0 = (pn - 12) * 256 + bj * 128 + wc * 32 + 8 * fq; f32x4 a = acc[ai][bj][m][0], b = acc[ai][bj][m][1];
;                     if (c0 < 64) { _Pragma("unroll") for (int e = 0; e < 4; ++e) { a[e] = tanh_fast(a[e]); b[e] = tanh_fast(b[e]); } }
;                     else if (c0 >= 128) { _Pragma("unroll") for (int e = 0; e < 4; ++e) { a[e] = sigmoidf_(a[e]); b[e] = sigmoidf_(b[e]); } }
;                     *(u32x4*)(LH + (size_t)row * 512 + c0) = pack8(a, b); } )
.LBB0_2927:
	s_andn2_saveexec_b64 s[34:35], s[34:35]
	s_cbranch_execz .LBB0_2929
	v_add_f32_e32 v129, v56, v56
	v_mul_f32_e32 v129, 0x3fb8aa3b, v129
	v_add_f32_e32 v128, v60, v60
	v_exp_f32_e32 v132, v129
	v_add_f32_e32 v129, v61, v61
	v_mul_f32_e32 v128, 0x3fb8aa3b, v128
	v_mul_f32_e32 v129, 0x3fb8aa3b, v129
	v_exp_f32_e32 v128, v128
	v_exp_f32_e32 v129, v129
	v_add_f32_e32 v130, v57, v57
	v_mul_f32_e32 v130, 0x3fb8aa3b, v130
	v_exp_f32_e32 v133, v130
	v_pk_add_f32 v[128:129], v[128:129], 1.0 op_sel_hi:[1,0]
	v_add_f32_e32 v130, v62, v62
	v_add_f32_e32 v131, v63, v63
	v_mul_f32_e32 v130, 0x3fb8aa3b, v130
	v_mul_f32_e32 v131, 0x3fb8aa3b, v131
	v_exp_f32_e32 v130, v130
	v_exp_f32_e32 v131, v131
	v_rcp_f32_e32 v135, v128
	s_nop 0
	v_mul_f32_e32 v128, 2.0, v135
	v_pk_add_f32 v[130:131], v[130:131], 1.0 op_sel_hi:[1,0]
	v_rcp_f32_e32 v135, v129
	s_nop 0
	v_mul_f32_e32 v129, 2.0, v135
	v_pk_add_f32 v[132:133], v[132:133], 1.0 op_sel_hi:[1,0]
	v_rcp_f32_e32 v135, v130
	s_nop 0
	v_mul_f32_e32 v130, 2.0, v135
	v_add_f32_e32 v134, v58, v58
	v_rcp_f32_e32 v135, v131
	s_nop 0
	v_mul_f32_e32 v131, 2.0, v135
	v_add_f32_e32 v135, v59, v59
	v_mul_f32_e32 v134, 0x3fb8aa3b, v134
	v_mul_f32_e32 v135, 0x3fb8aa3b, v135
	v_exp_f32_e32 v134, v134
	v_exp_f32_e32 v135, v135
	v_rcp_f32_e32 v155, v132
	s_nop 0
	v_mul_f32_e32 v132, 2.0, v155
	v_pk_add_f32 v[134:135], v[134:135], 1.0 op_sel_hi:[1,0]
	v_rcp_f32_e32 v155, v133
	s_nop 0
	v_mul_f32_e32 v133, 2.0, v155
	v_sub_f32_e32 v131, 1.0, v131
	v_rcp_f32_e32 v155, v134
	s_nop 0
	v_mul_f32_e32 v134, 2.0, v155
	v_sub_f32_e32 v130, 1.0, v130
	v_rcp_f32_e32 v155, v135
	s_nop 0
	v_mul_f32_e32 v135, 2.0, v155
	v_sub_f32_e32 v129, 1.0, v129
	v_sub_f32_e32 v128, 1.0, v128
	v_sub_f32_e32 v135, 1.0, v135
	v_sub_f32_e32 v134, 1.0, v134
	v_sub_f32_e32 v133, 1.0, v133
	v_sub_f32_e32 v132, 1.0, v132
.LBB0_2929:
	s_or_b64 exec, exec, s[34:35]
	v_add_u32_e32 v156, 0x80, v154
	v_ashrrev_i32_e32 v157, 31, v156
	v_lshlrev_b64 v[156:157], 10, v[156:157]
	v_lshl_add_u64 v[156:157], s[12:13], 0, v[156:157]
	v_cvt_pk_bf16_f32 v128, v128, v129
	v_cvt_pk_bf16_f32 v129, v130, v131
	v_cvt_pk_bf16_f32 v130, v132, v133
	v_cvt_pk_bf16_f32 v131, v134, v135
	v_lshl_add_u64 v[156:157], v[152:153], 1, v[156:157]
	flat_store_dwordx4 v[156:157], v[128:131]
	s_and_saveexec_b64 s[34:35], s[6:7]
	s_xor_b64 s[34:35], exec, s[34:35]
	s_cbranch_execz .LBB0_2933
	v_mov_b64_e32 v[134:135], v[42:43]
	v_mov_b64_e32 v[130:131], v[46:47]
	v_cmp_gt_u32_e32 vcc, s66, v152
	v_mov_b64_e32 v[132:133], v[40:41]
	v_mov_b64_e32 v[128:129], v[44:45]
	s_and_saveexec_b64 s[36:37], vcc
	s_cbranch_execz .LBB0_2932
	v_mul_f32_e32 v130, 0xbfb8aa3b, v46
	v_mul_f32_e32 v131, 0xbfb8aa3b, v47
	v_exp_f32_e32 v130, v130
	v_exp_f32_e32 v131, v131
	v_mul_f32_e32 v129, 0xbfb8aa3b, v40
	v_mul_f32_e32 v128, 0xbfb8aa3b, v44
	v_exp_f32_e32 v132, v129
	v_pk_add_f32 v[130:131], v[130:131], 1.0 op_sel_hi:[1,0]
	v_mul_f32_e32 v129, 0xbfb8aa3b, v45
	v_exp_f32_e32 v128, v128
	v_exp_f32_e32 v129, v129
	v_mul_f32_e32 v134, 0xbfb8aa3b, v42
	v_rcp_f32_e32 v131, v131
	v_pk_add_f32 v[128:129], v[128:129], 1.0 op_sel_hi:[1,0]
	v_rcp_f32_e32 v130, v130
	v_exp_f32_e32 v134, v134
	v_rcp_f32_e32 v129, v129
	v_mul_f32_e32 v135, 0xbfb8aa3b, v43
	v_exp_f32_e32 v135, v135
	s_nop 0
	v_pk_add_f32 v[134:135], v[134:135], 1.0 op_sel_hi:[1,0]
	v_rcp_f32_e32 v128, v128
	v_mul_f32_e32 v133, 0xbfb8aa3b, v41
	v_exp_f32_e32 v133, v133
	v_rcp_f32_e32 v135, v135
	v_pk_add_f32 v[132:133], v[132:133], 1.0 op_sel_hi:[1,0]
	v_rcp_f32_e32 v134, v134
	v_rcp_f32_e32 v133, v133
	v_rcp_f32_e32 v132, v132

; #define EPI_ROWS(...) _Pragma("unroll") for (int ai = 0; ai < 2; ++ai) _Pragma("unroll") for (int m = 0; m < 4; ++m) { const int row = u.pm * 256 + ai * 128 + wr * 64 + m * 16 + fr; __VA_ARGS__ }
; DI u32x4 pack8(f32x4 a, f32x4 b) { u32x4 w; w.x = pk2(a[0], a[1]); w.y = pk2(a[2], a[3]); w.z = pk2(b[0], b[1]); w.w = pk2(b[2], b[3]); return w; }
; DI float sigmoidf_(float x) { return 1.f / (1.f + __expf(-x)); }
; DI float siluf_(float x) { return x / (1.f + __expf(-x)); }
; DI float softplusf_(float x) { return fmaxf(x, 0.f) + log1pf(expf(-fabsf(x))); }
; DI float softplus_fast(float x) { return fmaxf(x, 0.f) + __logf(1.f + __expf(-fabsf(x))); }
; DI float tanh_fast(float x) { const float e = __expf(2.f * x); return 1.f - 2.f / (e + 1.f); }
;     DI void operator()(const Acc& acc, const Unit& u, int wr, int wc, int fr, int fq) const {
;     ...
;             EPI_ROWS( _Pragma("unroll") for (int bj = 0; bj < 2; ++bj) { const int c0 = (pn - 12) * 256 + bj * 128 + wc * 32 + 8 * fq; f32x4 a = acc[ai][bj][m][0], b = acc[ai][bj][m][1];
;                     if (c0 < 64) { _Pragma("unroll") for (int e = 0; e < 4; ++e) { a[e] = tanh_fast(a[e]); b[e] = tanh_fast(b[e]); } }
;                     else if (c0 >= 128) { _Pragma("unroll") for (int e = 0; e < 4; ++e) { a[e] = sigmoidf_(a[e]); b[e] = sigmoidf_(b[e]); } }
;                     *(u32x4*)(LH + (size_t)row * 512 + c0) = pack8(a, b); } )
.LBB0_2933:
	s_andn2_saveexec_b64 s[34:35], s[34:35]
	s_cbranch_execz .LBB0_2935
	v_add_f32_e32 v129, v40, v40
	v_mul_f32_e32 v129, 0x3fb8aa3b, v129
	v_add_f32_e32 v128, v44, v44
	v_exp_f32_e32 v132, v129
	v_add_f32_e32 v129, v45, v45
	v_mul_f32_e32 v128, 0x3fb8aa3b, v128
	v_mul_f32_e32 v129, 0x3fb8aa3b, v129
	v_exp_f32_e32 v128, v128
	v_exp_f32_e32 v129, v129
	v_add_f32_e32 v130, v41, v41
	v_mul_f32_e32 v130, 0x3fb8aa3b, v130
	v_exp_f32_e32 v133, v130
	v_pk_add_f32 v[128:129], v[128:129], 1.0 op_sel_hi:[1,0]
	v_add_f32_e32 v130, v46, v46
	v_add_f32_e32 v131, v47, v47
	v_mul_f32_e32 v130, 0x3fb8aa3b, v130
	v_mul_f32_e32 v131, 0x3fb8aa3b, v131
	v_exp_f32_e32 v130, v130
	v_exp_f32_e32 v131, v131
	v_rcp_f32_e32 v135, v128
	s_nop 0
	v_mul_f32_e32 v128, 2.0, v135
	v_pk_add_f32 v[130:131], v[130:131], 1.0 op_sel_hi:[1,0]
	v_rcp_f32_e32 v135, v129
	s_nop 0
	v_mul_f32_e32 v129, 2.0, v135
	v_pk_add_f32 v[132:133], v[132:133], 1.0 op_sel_hi:[1,0]
	v_rcp_f32_e32 v135, v130
	s_nop 0
	v_mul_f32_e32 v130, 2.0, v135
	v_add_f32_e32 v134, v42, v42
	v_rcp_f32_e32 v135, v131
	s_nop 0
	v_mul_f32_e32 v131, 2.0, v135
	v_add_f32_e32 v135, v43, v43
	v_mul_f32_e32 v134, 0x3fb8aa3b, v134
	v_mul_f32_e32 v135, 0x3fb8aa3b, v135
	v_exp_f32_e32 v134, v134
	v_exp_f32_e32 v135, v135
	v_rcp_f32_e32 v155, v132
	s_nop 0
	v_mul_f32_e32 v132, 2.0, v155
	v_pk_add_f32 v[134:135], v[134:135], 1.0 op_sel_hi:[1,0]
	v_rcp_f32_e32 v155, v133
	s_nop 0
	v_mul_f32_e32 v133, 2.0, v155
	v_sub_f32_e32 v131, 1.0, v131
	v_rcp_f32_e32 v155, v134
	s_nop 0
	v_mul_f32_e32 v134, 2.0, v155
	v_sub_f32_e32 v130, 1.0, v130
	v_rcp_f32_e32 v155, v135
	s_nop 0
	v_mul_f32_e32 v135, 2.0, v155
	v_sub_f32_e32 v129, 1.0, v129
	v_sub_f32_e32 v128, 1.0, v128
	v_sub_f32_e32 v135, 1.0, v135
	v_sub_f32_e32 v134, 1.0, v134
	v_sub_f32_e32 v133, 1.0, v133
	v_sub_f32_e32 v132, 1.0, v132
.LBB0_2935:
	s_or_b64 exec, exec, s[34:35]
	v_cvt_pk_bf16_f32 v128, v128, v129
	v_cvt_pk_bf16_f32 v129, v130, v131
	v_cvt_pk_bf16_f32 v130, v132, v133
	v_cvt_pk_bf16_f32 v131, v134, v135
	flat_store_dwordx4 v[156:157], v[128:131] offset:256
	s_and_saveexec_b64 s[34:35], s[4:5]
	s_xor_b64 s[34:35], exec, s[34:35]
	s_cbranch_execz .LBB0_2939
	v_mov_b64_e32 v[134:135], v[50:51]
	v_mov_b64_e32 v[130:131], v[54:55]
	v_cmp_lt_u32_e32 vcc, s61, v152
	v_mov_b64_e32 v[132:133], v[48:49]
	v_mov_b64_e32 v[128:129], v[52:53]
	s_and_saveexec_b64 s[36:37], vcc
	s_cbranch_execz .LBB0_2938
	v_mul_f32_e32 v130, 0xbfb8aa3b, v54
	v_mul_f32_e32 v131, 0xbfb8aa3b, v55
	v_exp_f32_e32 v130, v130
	v_exp_f32_e32 v131, v131
	v_mul_f32_e32 v129, 0xbfb8aa3b, v48
	v_mul_f32_e32 v128, 0xbfb8aa3b, v52
	v_exp_f32_e32 v132, v129
	v_pk_add_f32 v[130:131], v[130:131], 1.0 op_sel_hi:[1,0]
	v_mul_f32_e32 v129, 0xbfb8aa3b, v53
	v_exp_f32_e32 v128, v128
	v_exp_f32_e32 v129, v129
	v_mul_f32_e32 v134, 0xbfb8aa3b, v50
	v_rcp_f32_e32 v131, v131
	v_pk_add_f32 v[128:129], v[128:129], 1.0 op_sel_hi:[1,0]
	v_rcp_f32_e32 v130, v130
	v_exp_f32_e32 v134, v134
	v_rcp_f32_e32 v129, v129
	v_mul_f32_e32 v135, 0xbfb8aa3b, v51
	v_exp_f32_e32 v135, v135
	s_nop 0
	v_pk_add_f32 v[134:135], v[134:135], 1.0 op_sel_hi:[1,0]
	v_rcp_f32_e32 v128, v128
	v_mul_f32_e32 v133, 0xbfb8aa3b, v49
	v_exp_f32_e32 v133, v133
	v_rcp_f32_e32 v135, v135
	v_pk_add_f32 v[132:133], v[132:133], 1.0 op_sel_hi:[1,0]
	v_rcp_f32_e32 v134, v134
	v_rcp_f32_e32 v133, v133
	v_rcp_f32_e32 v132, v132

; #define EPI_ROWS(...) _Pragma("unroll") for (int ai = 0; ai < 2; ++ai) _Pragma("unroll") for (int m = 0; m < 4; ++m) { const int row = u.pm * 256 + ai * 128 + wr * 64 + m * 16 + fr; __VA_ARGS__ }
; DI u32x4 pack8(f32x4 a, f32x4 b) { u32x4 w; w.x = pk2(a[0], a[1]); w.y = pk2(a[2], a[3]); w.z = pk2(b[0], b[1]); w.w = pk2(b[2], b[3]); return w; }
; DI float sigmoidf_(float x) { return 1.f / (1.f + __expf(-x)); }
; DI float siluf_(float x) { return x / (1.f + __expf(-x)); }
; DI float softplusf_(float x) { return fmaxf(x, 0.f) + log1pf(expf(-fabsf(x))); }
; DI float softplus_fast(float x) { return fmaxf(x, 0.f) + __logf(1.f + __expf(-fabsf(x))); }
; DI float tanh_fast(float x) { const float e = __expf(2.f * x); return 1.f - 2.f / (e + 1.f); }
;     DI void operator()(const Acc& acc, const Unit& u, int wr, int wc, int fr, int fq) const {
;     ...
;             EPI_ROWS( _Pragma("unroll") for (int bj = 0; bj < 2; ++bj) { const int c0 = (pn - 12) * 256 + bj * 128 + wc * 32 + 8 * fq; f32x4 a = acc[ai][bj][m][0], b = acc[ai][bj][m][1];
;                     if (c0 < 64) { _Pragma("unroll") for (int e = 0; e < 4; ++e) { a[e] = tanh_fast(a[e]); b[e] = tanh_fast(b[e]); } }
;                     else if (c0 >= 128) { _Pragma("unroll") for (int e = 0; e < 4; ++e) { a[e] = sigmoidf_(a[e]); b[e] = sigmoidf_(b[e]); } }
;                     *(u32x4*)(LH + (size_t)row * 512 + c0) = pack8(a, b); } )
.LBB0_2939:
	s_andn2_saveexec_b64 s[34:35], s[34:35]
	s_cbranch_execz .LBB0_2941
	v_add_f32_e32 v129, v48, v48
	v_mul_f32_e32 v129, 0x3fb8aa3b, v129
	v_add_f32_e32 v128, v52, v52
	v_exp_f32_e32 v132, v129
	v_add_f32_e32 v129, v53, v53
	v_mul_f32_e32 v128, 0x3fb8aa3b, v128
	v_mul_f32_e32 v129, 0x3fb8aa3b, v129
	v_exp_f32_e32 v128, v128
	v_exp_f32_e32 v129, v129
	v_add_f32_e32 v130, v49, v49
	v_mul_f32_e32 v130, 0x3fb8aa3b, v130
	v_exp_f32_e32 v133, v130
	v_pk_add_f32 v[128:129], v[128:129], 1.0 op_sel_hi:[1,0]
	v_add_f32_e32 v130, v54, v54
	v_add_f32_e32 v131, v55, v55
	v_mul_f32_e32 v130, 0x3fb8aa3b, v130
	v_mul_f32_e32 v131, 0x3fb8aa3b, v131
	v_exp_f32_e32 v130, v130
	v_exp_f32_e32 v131, v131
	v_rcp_f32_e32 v135, v128
	s_nop 0
	v_mul_f32_e32 v128, 2.0, v135
	v_pk_add_f32 v[130:131], v[130:131], 1.0 op_sel_hi:[1,0]
	v_rcp_f32_e32 v135, v129
	s_nop 0
	v_mul_f32_e32 v129, 2.0, v135
	v_pk_add_f32 v[132:133], v[132:133], 1.0 op_sel_hi:[1,0]
	v_rcp_f32_e32 v135, v130
	s_nop 0
	v_mul_f32_e32 v130, 2.0, v135
	v_add_f32_e32 v134, v50, v50
	v_rcp_f32_e32 v135, v131
	s_nop 0
	v_mul_f32_e32 v131, 2.0, v135
	v_add_f32_e32 v135, v51, v51
	v_mul_f32_e32 v134, 0x3fb8aa3b, v134
	v_mul_f32_e32 v135, 0x3fb8aa3b, v135
	v_exp_f32_e32 v134, v134
	v_exp_f32_e32 v135, v135
	v_rcp_f32_e32 v155, v132
	s_nop 0
	v_mul_f32_e32 v132, 2.0, v155
	v_pk_add_f32 v[134:135], v[134:135], 1.0 op_sel_hi:[1,0]
	v_rcp_f32_e32 v155, v133
	s_nop 0
	v_mul_f32_e32 v133, 2.0, v155
	v_sub_f32_e32 v131, 1.0, v131
	v_rcp_f32_e32 v155, v134
	s_nop 0
	v_mul_f32_e32 v134, 2.0, v155
	v_sub_f32_e32 v130, 1.0, v130
	v_rcp_f32_e32 v155, v135
	s_nop 0
	v_mul_f32_e32 v135, 2.0, v155
	v_sub_f32_e32 v129, 1.0, v129
	v_sub_f32_e32 v128, 1.0, v128
	v_sub_f32_e32 v135, 1.0, v135
	v_sub_f32_e32 v134, 1.0, v134
	v_sub_f32_e32 v133, 1.0, v133
	v_sub_f32_e32 v132, 1.0, v132
.LBB0_2941:
	s_or_b64 exec, exec, s[34:35]
	v_add_u32_e32 v156, 0x90, v154
	v_ashrrev_i32_e32 v157, 31, v156
	v_lshlrev_b64 v[156:157], 10, v[156:157]
	v_lshl_add_u64 v[156:157], s[12:13], 0, v[156:157]
	v_cvt_pk_bf16_f32 v128, v128, v129
	v_cvt_pk_bf16_f32 v129, v130, v131
	v_cvt_pk_bf16_f32 v130, v132, v133
	v_cvt_pk_bf16_f32 v131, v134, v135
	v_lshl_add_u64 v[156:157], v[152:153], 1, v[156:157]
	flat_store_dwordx4 v[156:157], v[128:131]
	s_and_saveexec_b64 s[34:35], s[6:7]
	s_xor_b64 s[34:35], exec, s[34:35]
	s_cbranch_execz .LBB0_2945
	v_mov_b64_e32 v[134:135], v[26:27]
	v_mov_b64_e32 v[130:131], v[30:31]
	v_cmp_gt_u32_e32 vcc, s66, v152
	v_mov_b64_e32 v[132:133], v[24:25]
	v_mov_b64_e32 v[128:129], v[28:29]
	s_and_saveexec_b64 s[36:37], vcc
	s_cbranch_execz .LBB0_2944
	v_mul_f32_e32 v130, 0xbfb8aa3b, v30
	v_mul_f32_e32 v131, 0xbfb8aa3b, v31
	v_exp_f32_e32 v130, v130
	v_exp_f32_e32 v131, v131
	v_mul_f32_e32 v129, 0xbfb8aa3b, v24
	v_mul_f32_e32 v128, 0xbfb8aa3b, v28
	v_exp_f32_e32 v132, v129
	v_pk_add_f32 v[130:131], v[130:131], 1.0 op_sel_hi:[1,0]
	v_mul_f32_e32 v129, 0xbfb8aa3b, v29
	v_exp_f32_e32 v128, v128
	v_exp_f32_e32 v129, v129
	v_mul_f32_e32 v134, 0xbfb8aa3b, v26
	v_rcp_f32_e32 v131, v131
	v_pk_add_f32 v[128:129], v[128:129], 1.0 op_sel_hi:[1,0]
	v_rcp_f32_e32 v130, v130
	v_exp_f32_e32 v134, v134
	v_rcp_f32_e32 v129, v129
	v_mul_f32_e32 v135, 0xbfb8aa3b, v27
	v_exp_f32_e32 v135, v135
	s_nop 0
	v_pk_add_f32 v[134:135], v[134:135], 1.0 op_sel_hi:[1,0]
	v_rcp_f32_e32 v128, v128
	v_mul_f32_e32 v133, 0xbfb8aa3b, v25
	v_exp_f32_e32 v133, v133
	v_rcp_f32_e32 v135, v135
	v_pk_add_f32 v[132:133], v[132:133], 1.0 op_sel_hi:[1,0]
	v_rcp_f32_e32 v134, v134
	v_rcp_f32_e32 v133, v133
	v_rcp_f32_e32 v132, v132

; #define EPI_ROWS(...) _Pragma("unroll") for (int ai = 0; ai < 2; ++ai) _Pragma("unroll") for (int m = 0; m < 4; ++m) { const int row = u.pm * 256 + ai * 128 + wr * 64 + m * 16 + fr; __VA_ARGS__ }
; DI u32x4 pack8(f32x4 a, f32x4 b) { u32x4 w; w.x = pk2(a[0], a[1]); w.y = pk2(a[2], a[3]); w.z = pk2(b[0], b[1]); w.w = pk2(b[2], b[3]); return w; }
; DI float sigmoidf_(float x) { return 1.f / (1.f + __expf(-x)); }
; DI float siluf_(float x) { return x / (1.f + __expf(-x)); }
; DI float softplusf_(float x) { return fmaxf(x, 0.f) + log1pf(expf(-fabsf(x))); }
; DI float softplus_fast(float x) { return fmaxf(x, 0.f) + __logf(1.f + __expf(-fabsf(x))); }
; DI float tanh_fast(float x) { const float e = __expf(2.f * x); return 1.f - 2.f / (e + 1.f); }
;     DI void operator()(const Acc& acc, const Unit& u, int wr, int wc, int fr, int fq) const {
;     ...
;             EPI_ROWS( _Pragma("unroll") for (int bj = 0; bj < 2; ++bj) { const int c0 = (pn - 12) * 256 + bj * 128 + wc * 32 + 8 * fq; f32x4 a = acc[ai][bj][m][0], b = acc[ai][bj][m][1];
;                     if (c0 < 64) { _Pragma("unroll") for (int e = 0; e < 4; ++e) { a[e] = tanh_fast(a[e]); b[e] = tanh_fast(b[e]); } }
;                     else if (c0 >= 128) { _Pragma("unroll") for (int e = 0; e < 4; ++e) { a[e] = sigmoidf_(a[e]); b[e] = sigmoidf_(b[e]); } }
;                     *(u32x4*)(LH + (size_t)row * 512 + c0) = pack8(a, b); } )
.LBB0_2945:
	s_andn2_saveexec_b64 s[34:35], s[34:35]
	s_cbranch_execz .LBB0_2947
	v_add_f32_e32 v129, v24, v24
	v_mul_f32_e32 v129, 0x3fb8aa3b, v129
	v_add_f32_e32 v128, v28, v28
	v_exp_f32_e32 v132, v129
	v_add_f32_e32 v129, v29, v29
	v_mul_f32_e32 v128, 0x3fb8aa3b, v128
	v_mul_f32_e32 v129, 0x3fb8aa3b, v129
	v_exp_f32_e32 v128, v128
	v_exp_f32_e32 v129, v129
	v_add_f32_e32 v130, v25, v25
	v_mul_f32_e32 v130, 0x3fb8aa3b, v130
	v_exp_f32_e32 v133, v130
	v_pk_add_f32 v[128:129], v[128:129], 1.0 op_sel_hi:[1,0]
	v_add_f32_e32 v130, v30, v30
	v_add_f32_e32 v131, v31, v31
	v_mul_f32_e32 v130, 0x3fb8aa3b, v130
	v_mul_f32_e32 v131, 0x3fb8aa3b, v131
	v_exp_f32_e32 v130, v130
	v_exp_f32_e32 v131, v131
	v_rcp_f32_e32 v135, v128
	s_nop 0
	v_mul_f32_e32 v128, 2.0, v135
	v_pk_add_f32 v[130:131], v[130:131], 1.0 op_sel_hi:[1,0]
	v_rcp_f32_e32 v135, v129
	s_nop 0
	v_mul_f32_e32 v129, 2.0, v135
	v_pk_add_f32 v[132:133], v[132:133], 1.0 op_sel_hi:[1,0]
	v_rcp_f32_e32 v135, v130
	s_nop 0
	v_mul_f32_e32 v130, 2.0, v135
	v_add_f32_e32 v134, v26, v26
	v_rcp_f32_e32 v135, v131
	s_nop 0
	v_mul_f32_e32 v131, 2.0, v135
	v_add_f32_e32 v135, v27, v27
	v_mul_f32_e32 v134, 0x3fb8aa3b, v134
	v_mul_f32_e32 v135, 0x3fb8aa3b, v135
	v_exp_f32_e32 v134, v134
	v_exp_f32_e32 v135, v135
	v_rcp_f32_e32 v155, v132
	s_nop 0
	v_mul_f32_e32 v132, 2.0, v155
	v_pk_add_f32 v[134:135], v[134:135], 1.0 op_sel_hi:[1,0]
	v_rcp_f32_e32 v155, v133
	s_nop 0
	v_mul_f32_e32 v133, 2.0, v155
	v_sub_f32_e32 v131, 1.0, v131
	v_rcp_f32_e32 v155, v134
	s_nop 0
	v_mul_f32_e32 v134, 2.0, v155
	v_sub_f32_e32 v130, 1.0, v130
	v_rcp_f32_e32 v155, v135
	s_nop 0
	v_mul_f32_e32 v135, 2.0, v155
	v_sub_f32_e32 v129, 1.0, v129
	v_sub_f32_e32 v128, 1.0, v128
	v_sub_f32_e32 v135, 1.0, v135
	v_sub_f32_e32 v134, 1.0, v134
	v_sub_f32_e32 v133, 1.0, v133
	v_sub_f32_e32 v132, 1.0, v132
.LBB0_2947:
	s_or_b64 exec, exec, s[34:35]
	v_cvt_pk_bf16_f32 v128, v128, v129
	v_cvt_pk_bf16_f32 v129, v130, v131
	v_cvt_pk_bf16_f32 v130, v132, v133
	v_cvt_pk_bf16_f32 v131, v134, v135
	flat_store_dwordx4 v[156:157], v[128:131] offset:256
	s_and_saveexec_b64 s[34:35], s[4:5]
	s_xor_b64 s[34:35], exec, s[34:35]
	s_cbranch_execz .LBB0_2951
	v_mov_b64_e32 v[134:135], v[34:35]
	v_mov_b64_e32 v[130:131], v[38:39]
	v_cmp_lt_u32_e32 vcc, s61, v152
	v_mov_b64_e32 v[132:133], v[32:33]
	v_mov_b64_e32 v[128:129], v[36:37]
	s_and_saveexec_b64 s[36:37], vcc
	s_cbranch_execz .LBB0_2950
	v_mul_f32_e32 v130, 0xbfb8aa3b, v38
	v_mul_f32_e32 v131, 0xbfb8aa3b, v39
	v_exp_f32_e32 v130, v130
	v_exp_f32_e32 v131, v131
	v_mul_f32_e32 v129, 0xbfb8aa3b, v32
	v_mul_f32_e32 v128, 0xbfb8aa3b, v36
	v_exp_f32_e32 v132, v129
	v_pk_add_f32 v[130:131], v[130:131], 1.0 op_sel_hi:[1,0]
	v_mul_f32_e32 v129, 0xbfb8aa3b, v37
	v_exp_f32_e32 v128, v128
	v_exp_f32_e32 v129, v129
	v_mul_f32_e32 v134, 0xbfb8aa3b, v34
	v_rcp_f32_e32 v131, v131
	v_pk_add_f32 v[128:129], v[128:129], 1.0 op_sel_hi:[1,0]
	v_rcp_f32_e32 v130, v130
	v_exp_f32_e32 v134, v134
	v_rcp_f32_e32 v129, v129
	v_mul_f32_e32 v135, 0xbfb8aa3b, v35
	v_exp_f32_e32 v135, v135
	s_nop 0
	v_pk_add_f32 v[134:135], v[134:135], 1.0 op_sel_hi:[1,0]
	v_rcp_f32_e32 v128, v128
	v_mul_f32_e32 v133, 0xbfb8aa3b, v33
	v_exp_f32_e32 v133, v133
	v_rcp_f32_e32 v135, v135
	v_pk_add_f32 v[132:133], v[132:133], 1.0 op_sel_hi:[1,0]
	v_rcp_f32_e32 v134, v134
	v_rcp_f32_e32 v133, v133
	v_rcp_f32_e32 v132, v132

; #define EPI_ROWS(...) _Pragma("unroll") for (int ai = 0; ai < 2; ++ai) _Pragma("unroll") for (int m = 0; m < 4; ++m) { const int row = u.pm * 256 + ai * 128 + wr * 64 + m * 16 + fr; __VA_ARGS__ }
; DI u32x4 pack8(f32x4 a, f32x4 b) { u32x4 w; w.x = pk2(a[0], a[1]); w.y = pk2(a[2], a[3]); w.z = pk2(b[0], b[1]); w.w = pk2(b[2], b[3]); return w; }
; DI float sigmoidf_(float x) { return 1.f / (1.f + __expf(-x)); }
; DI float siluf_(float x) { return x / (1.f + __expf(-x)); }
; DI float softplusf_(float x) { return fmaxf(x, 0.f) + log1pf(expf(-fabsf(x))); }
; DI float softplus_fast(float x) { return fmaxf(x, 0.f) + __logf(1.f + __expf(-fabsf(x))); }
; DI float tanh_fast(float x) { const float e = __expf(2.f * x); return 1.f - 2.f / (e + 1.f); }
;     DI void operator()(const Acc& acc, const Unit& u, int wr, int wc, int fr, int fq) const {
;     ...
;             EPI_ROWS( _Pragma("unroll") for (int bj = 0; bj < 2; ++bj) { const int c0 = (pn - 12) * 256 + bj * 128 + wc * 32 + 8 * fq; f32x4 a = acc[ai][bj][m][0], b = acc[ai][bj][m][1];
;                     if (c0 < 64) { _Pragma("unroll") for (int e = 0; e < 4; ++e) { a[e] = tanh_fast(a[e]); b[e] = tanh_fast(b[e]); } }
;                     else if (c0 >= 128) { _Pragma("unroll") for (int e = 0; e < 4; ++e) { a[e] = sigmoidf_(a[e]); b[e] = sigmoidf_(b[e]); } }
;                     *(u32x4*)(LH + (size_t)row * 512 + c0) = pack8(a, b); } )
.LBB0_2951:
	s_andn2_saveexec_b64 s[34:35], s[34:35]
	s_cbranch_execz .LBB0_2953
	v_add_f32_e32 v129, v32, v32
	v_mul_f32_e32 v129, 0x3fb8aa3b, v129
	v_add_f32_e32 v128, v36, v36
	v_exp_f32_e32 v132, v129
	v_add_f32_e32 v129, v37, v37
	v_mul_f32_e32 v128, 0x3fb8aa3b, v128
	v_mul_f32_e32 v129, 0x3fb8aa3b, v129
	v_exp_f32_e32 v128, v128
	v_exp_f32_e32 v129, v129
	v_add_f32_e32 v130, v33, v33
	v_mul_f32_e32 v130, 0x3fb8aa3b, v130
	v_exp_f32_e32 v133, v130
	v_pk_add_f32 v[128:129], v[128:129], 1.0 op_sel_hi:[1,0]
	v_add_f32_e32 v130, v38, v38
	v_add_f32_e32 v131, v39, v39
	v_mul_f32_e32 v130, 0x3fb8aa3b, v130
	v_mul_f32_e32 v131, 0x3fb8aa3b, v131
	v_exp_f32_e32 v130, v130
	v_exp_f32_e32 v131, v131
	v_rcp_f32_e32 v135, v128
	s_nop 0
	v_mul_f32_e32 v128, 2.0, v135
	v_pk_add_f32 v[130:131], v[130:131], 1.0 op_sel_hi:[1,0]
	v_rcp_f32_e32 v135, v129
	s_nop 0
	v_mul_f32_e32 v129, 2.0, v135
	v_pk_add_f32 v[132:133], v[132:133], 1.0 op_sel_hi:[1,0]
	v_rcp_f32_e32 v135, v130
	s_nop 0
	v_mul_f32_e32 v130, 2.0, v135
	v_add_f32_e32 v134, v34, v34
	v_rcp_f32_e32 v135, v131
	s_nop 0
	v_mul_f32_e32 v131, 2.0, v135
	v_add_f32_e32 v135, v35, v35
	v_mul_f32_e32 v134, 0x3fb8aa3b, v134
	v_mul_f32_e32 v135, 0x3fb8aa3b, v135
	v_exp_f32_e32 v134, v134
	v_exp_f32_e32 v135, v135
	v_rcp_f32_e32 v155, v132
	s_nop 0
	v_mul_f32_e32 v132, 2.0, v155
	v_pk_add_f32 v[134:135], v[134:135], 1.0 op_sel_hi:[1,0]
	v_rcp_f32_e32 v155, v133
	s_nop 0
	v_mul_f32_e32 v133, 2.0, v155
	v_sub_f32_e32 v131, 1.0, v131
	v_rcp_f32_e32 v155, v134
	s_nop 0
	v_mul_f32_e32 v134, 2.0, v155
	v_sub_f32_e32 v130, 1.0, v130
	v_rcp_f32_e32 v155, v135
	s_nop 0
	v_mul_f32_e32 v135, 2.0, v155
	v_sub_f32_e32 v129, 1.0, v129
	v_sub_f32_e32 v128, 1.0, v128
	v_sub_f32_e32 v135, 1.0, v135
	v_sub_f32_e32 v134, 1.0, v134
	v_sub_f32_e32 v133, 1.0, v133
	v_sub_f32_e32 v132, 1.0, v132
.LBB0_2953:
	s_or_b64 exec, exec, s[34:35]
	v_add_u32_e32 v156, 0xa0, v154
	v_ashrrev_i32_e32 v157, 31, v156
	v_lshlrev_b64 v[156:157], 10, v[156:157]
	v_lshl_add_u64 v[156:157], s[12:13], 0, v[156:157]
	v_cvt_pk_bf16_f32 v128, v128, v129
	v_cvt_pk_bf16_f32 v129, v130, v131
	v_cvt_pk_bf16_f32 v130, v132, v133
	v_cvt_pk_bf16_f32 v131, v134, v135
	v_lshl_add_u64 v[156:157], v[152:153], 1, v[156:157]
	flat_store_dwordx4 v[156:157], v[128:131]
	s_and_saveexec_b64 s[34:35], s[6:7]
	s_xor_b64 s[34:35], exec, s[34:35]
	s_cbranch_execz .LBB0_2957
	v_mov_b64_e32 v[134:135], v[10:11]
	v_mov_b64_e32 v[130:131], v[14:15]
	v_cmp_gt_u32_e32 vcc, s66, v152
	v_mov_b64_e32 v[132:133], v[8:9]
	v_mov_b64_e32 v[128:129], v[12:13]
	s_and_saveexec_b64 s[36:37], vcc
	s_cbranch_execz .LBB0_2956
	v_mul_f32_e32 v130, 0xbfb8aa3b, v14
	v_mul_f32_e32 v131, 0xbfb8aa3b, v15
	v_exp_f32_e32 v130, v130
	v_exp_f32_e32 v131, v131
	v_mul_f32_e32 v129, 0xbfb8aa3b, v8
	v_mul_f32_e32 v128, 0xbfb8aa3b, v12
	v_exp_f32_e32 v132, v129
	v_pk_add_f32 v[130:131], v[130:131], 1.0 op_sel_hi:[1,0]
	v_mul_f32_e32 v129, 0xbfb8aa3b, v13
	v_exp_f32_e32 v128, v128
	v_exp_f32_e32 v129, v129
	v_mul_f32_e32 v134, 0xbfb8aa3b, v10
	v_rcp_f32_e32 v131, v131
	v_pk_add_f32 v[128:129], v[128:129], 1.0 op_sel_hi:[1,0]
	v_rcp_f32_e32 v130, v130
	v_exp_f32_e32 v134, v134
	v_rcp_f32_e32 v129, v129
	v_mul_f32_e32 v135, 0xbfb8aa3b, v11
	v_exp_f32_e32 v135, v135
	s_nop 0
	v_pk_add_f32 v[134:135], v[134:135], 1.0 op_sel_hi:[1,0]
	v_rcp_f32_e32 v128, v128
	v_mul_f32_e32 v133, 0xbfb8aa3b, v9
	v_exp_f32_e32 v133, v133
	v_rcp_f32_e32 v135, v135
	v_pk_add_f32 v[132:133], v[132:133], 1.0 op_sel_hi:[1,0]
	v_rcp_f32_e32 v134, v134
	v_rcp_f32_e32 v133, v133
	v_rcp_f32_e32 v132, v132

; #define EPI_ROWS(...) _Pragma("unroll") for (int ai = 0; ai < 2; ++ai) _Pragma("unroll") for (int m = 0; m < 4; ++m) { const int row = u.pm * 256 + ai * 128 + wr * 64 + m * 16 + fr; __VA_ARGS__ }
; DI u32x4 pack8(f32x4 a, f32x4 b) { u32x4 w; w.x = pk2(a[0], a[1]); w.y = pk2(a[2], a[3]); w.z = pk2(b[0], b[1]); w.w = pk2(b[2], b[3]); return w; }
; DI float sigmoidf_(float x) { return 1.f / (1.f + __expf(-x)); }
; DI float siluf_(float x) { return x / (1.f + __expf(-x)); }
; DI float softplusf_(float x) { return fmaxf(x, 0.f) + log1pf(expf(-fabsf(x))); }
; DI float softplus_fast(float x) { return fmaxf(x, 0.f) + __logf(1.f + __expf(-fabsf(x))); }
; DI float tanh_fast(float x) { const float e = __expf(2.f * x); return 1.f - 2.f / (e + 1.f); }
;     DI void operator()(const Acc& acc, const Unit& u, int wr, int wc, int fr, int fq) const {
;     ...
;             EPI_ROWS( _Pragma("unroll") for (int bj = 0; bj < 2; ++bj) { const int c0 = (pn - 12) * 256 + bj * 128 + wc * 32 + 8 * fq; f32x4 a = acc[ai][bj][m][0], b = acc[ai][bj][m][1];
;                     if (c0 < 64) { _Pragma("unroll") for (int e = 0; e < 4; ++e) { a[e] = tanh_fast(a[e]); b[e] = tanh_fast(b[e]); } }
;                     else if (c0 >= 128) { _Pragma("unroll") for (int e = 0; e < 4; ++e) { a[e] = sigmoidf_(a[e]); b[e] = sigmoidf_(b[e]); } }
;                     *(u32x4*)(LH + (size_t)row * 512 + c0) = pack8(a, b); } )
.LBB0_2957:
	s_andn2_saveexec_b64 s[34:35], s[34:35]
	s_cbranch_execz .LBB0_2959
	v_add_f32_e32 v129, v8, v8
	v_mul_f32_e32 v129, 0x3fb8aa3b, v129
	v_add_f32_e32 v128, v12, v12
	v_exp_f32_e32 v132, v129
	v_add_f32_e32 v129, v13, v13
	v_mul_f32_e32 v128, 0x3fb8aa3b, v128
	v_mul_f32_e32 v129, 0x3fb8aa3b, v129
	v_exp_f32_e32 v128, v128
	v_exp_f32_e32 v129, v129
	v_add_f32_e32 v130, v9, v9
	v_mul_f32_e32 v130, 0x3fb8aa3b, v130
	v_exp_f32_e32 v133, v130
	v_pk_add_f32 v[128:129], v[128:129], 1.0 op_sel_hi:[1,0]
	v_add_f32_e32 v130, v14, v14
	v_add_f32_e32 v131, v15, v15
	v_mul_f32_e32 v130, 0x3fb8aa3b, v130
	v_mul_f32_e32 v131, 0x3fb8aa3b, v131
	v_exp_f32_e32 v130, v130
	v_exp_f32_e32 v131, v131
	v_rcp_f32_e32 v135, v128
	s_nop 0
	v_mul_f32_e32 v128, 2.0, v135
	v_pk_add_f32 v[130:131], v[130:131], 1.0 op_sel_hi:[1,0]
	v_rcp_f32_e32 v135, v129
	s_nop 0
	v_mul_f32_e32 v129, 2.0, v135
	v_pk_add_f32 v[132:133], v[132:133], 1.0 op_sel_hi:[1,0]
	v_rcp_f32_e32 v135, v130
	s_nop 0
	v_mul_f32_e32 v130, 2.0, v135
	v_add_f32_e32 v134, v10, v10
	v_rcp_f32_e32 v135, v131
	s_nop 0
	v_mul_f32_e32 v131, 2.0, v135
	v_add_f32_e32 v135, v11, v11
	v_mul_f32_e32 v134, 0x3fb8aa3b, v134
	v_mul_f32_e32 v135, 0x3fb8aa3b, v135
	v_exp_f32_e32 v134, v134
	v_exp_f32_e32 v135, v135
	v_rcp_f32_e32 v155, v132
	s_nop 0
	v_mul_f32_e32 v132, 2.0, v155
	v_pk_add_f32 v[134:135], v[134:135], 1.0 op_sel_hi:[1,0]
	v_rcp_f32_e32 v155, v133
	s_nop 0
	v_mul_f32_e32 v133, 2.0, v155
	v_sub_f32_e32 v131, 1.0, v131
	v_rcp_f32_e32 v155, v134
	s_nop 0
	v_mul_f32_e32 v134, 2.0, v155
	v_sub_f32_e32 v130, 1.0, v130
	v_rcp_f32_e32 v155, v135
	s_nop 0
	v_mul_f32_e32 v135, 2.0, v155
	v_sub_f32_e32 v129, 1.0, v129
	v_sub_f32_e32 v128, 1.0, v128
	v_sub_f32_e32 v135, 1.0, v135
	v_sub_f32_e32 v134, 1.0, v134
	v_sub_f32_e32 v133, 1.0, v133
	v_sub_f32_e32 v132, 1.0, v132
.LBB0_2959:
	s_or_b64 exec, exec, s[34:35]
	v_cvt_pk_bf16_f32 v128, v128, v129
	v_cvt_pk_bf16_f32 v129, v130, v131
	v_cvt_pk_bf16_f32 v130, v132, v133
	v_cvt_pk_bf16_f32 v131, v134, v135
	flat_store_dwordx4 v[156:157], v[128:131] offset:256
	s_and_saveexec_b64 s[34:35], s[4:5]
	s_xor_b64 s[4:5], exec, s[34:35]
	s_cbranch_execz .LBB0_2963
	v_mov_b64_e32 v[134:135], v[18:19]
	v_mov_b64_e32 v[130:131], v[22:23]
	v_cmp_lt_u32_e32 vcc, s61, v152
	v_mov_b64_e32 v[132:133], v[16:17]
	v_mov_b64_e32 v[128:129], v[20:21]
	s_and_saveexec_b64 s[34:35], vcc
	s_cbranch_execz .LBB0_2962
	v_mul_f32_e32 v130, 0xbfb8aa3b, v22
	v_mul_f32_e32 v131, 0xbfb8aa3b, v23
	v_exp_f32_e32 v130, v130
	v_exp_f32_e32 v131, v131
	v_mul_f32_e32 v129, 0xbfb8aa3b, v16
	v_mul_f32_e32 v128, 0xbfb8aa3b, v20
	v_exp_f32_e32 v132, v129
	v_pk_add_f32 v[130:131], v[130:131], 1.0 op_sel_hi:[1,0]
	v_mul_f32_e32 v129, 0xbfb8aa3b, v21
	v_exp_f32_e32 v128, v128
	v_exp_f32_e32 v129, v129
	v_mul_f32_e32 v134, 0xbfb8aa3b, v18
	v_rcp_f32_e32 v131, v131
	v_pk_add_f32 v[128:129], v[128:129], 1.0 op_sel_hi:[1,0]
	v_rcp_f32_e32 v130, v130
	v_exp_f32_e32 v134, v134
	v_rcp_f32_e32 v129, v129
	v_mul_f32_e32 v135, 0xbfb8aa3b, v19
	v_exp_f32_e32 v135, v135
	s_nop 0
	v_pk_add_f32 v[134:135], v[134:135], 1.0 op_sel_hi:[1,0]
	v_rcp_f32_e32 v128, v128
	v_mul_f32_e32 v133, 0xbfb8aa3b, v17
	v_exp_f32_e32 v133, v133
	v_rcp_f32_e32 v135, v135
	v_pk_add_f32 v[132:133], v[132:133], 1.0 op_sel_hi:[1,0]
	v_rcp_f32_e32 v134, v134
	v_rcp_f32_e32 v133, v133
	v_rcp_f32_e32 v132, v132

; #define EPI_ROWS(...) _Pragma("unroll") for (int ai = 0; ai < 2; ++ai) _Pragma("unroll") for (int m = 0; m < 4; ++m) { const int row = u.pm * 256 + ai * 128 + wr * 64 + m * 16 + fr; __VA_ARGS__ }
; DI u32x4 pack8(f32x4 a, f32x4 b) { u32x4 w; w.x = pk2(a[0], a[1]); w.y = pk2(a[2], a[3]); w.z = pk2(b[0], b[1]); w.w = pk2(b[2], b[3]); return w; }
; DI float sigmoidf_(float x) { return 1.f / (1.f + __expf(-x)); }
; DI float siluf_(float x) { return x / (1.f + __expf(-x)); }
; DI float softplusf_(float x) { return fmaxf(x, 0.f) + log1pf(expf(-fabsf(x))); }
; DI float softplus_fast(float x) { return fmaxf(x, 0.f) + __logf(1.f + __expf(-fabsf(x))); }
; DI float tanh_fast(float x) { const float e = __expf(2.f * x); return 1.f - 2.f / (e + 1.f); }
;     DI void operator()(const Acc& acc, const Unit& u, int wr, int wc, int fr, int fq) const {
;     ...
;             EPI_ROWS( _Pragma("unroll") for (int bj = 0; bj < 2; ++bj) { const int c0 = (pn - 12) * 256 + bj * 128 + wc * 32 + 8 * fq; f32x4 a = acc[ai][bj][m][0], b = acc[ai][bj][m][1];
;                     if (c0 < 64) { _Pragma("unroll") for (int e = 0; e < 4; ++e) { a[e] = tanh_fast(a[e]); b[e] = tanh_fast(b[e]); } }
;                     else if (c0 >= 128) { _Pragma("unroll") for (int e = 0; e < 4; ++e) { a[e] = sigmoidf_(a[e]); b[e] = sigmoidf_(b[e]); } }
;                     *(u32x4*)(LH + (size_t)row * 512 + c0) = pack8(a, b); } )
.LBB0_2963:
	s_andn2_saveexec_b64 s[4:5], s[4:5]
	s_cbranch_execz .LBB0_2965
	v_add_f32_e32 v129, v16, v16
	v_mul_f32_e32 v129, 0x3fb8aa3b, v129
	v_add_f32_e32 v128, v20, v20
	v_exp_f32_e32 v132, v129
	v_add_f32_e32 v129, v21, v21
	v_mul_f32_e32 v128, 0x3fb8aa3b, v128
	v_mul_f32_e32 v129, 0x3fb8aa3b, v129
	v_exp_f32_e32 v128, v128
	v_exp_f32_e32 v129, v129
	v_add_f32_e32 v130, v17, v17
	v_mul_f32_e32 v130, 0x3fb8aa3b, v130
	v_exp_f32_e32 v133, v130
	v_pk_add_f32 v[128:129], v[128:129], 1.0 op_sel_hi:[1,0]
	v_add_f32_e32 v130, v22, v22
	v_add_f32_e32 v131, v23, v23
	v_mul_f32_e32 v130, 0x3fb8aa3b, v130
	v_mul_f32_e32 v131, 0x3fb8aa3b, v131
	v_exp_f32_e32 v130, v130
	v_exp_f32_e32 v131, v131
	v_rcp_f32_e32 v135, v128
	s_nop 0
	v_mul_f32_e32 v128, 2.0, v135
	v_pk_add_f32 v[130:131], v[130:131], 1.0 op_sel_hi:[1,0]
	v_rcp_f32_e32 v135, v129
	s_nop 0
	v_mul_f32_e32 v129, 2.0, v135
	v_pk_add_f32 v[132:133], v[132:133], 1.0 op_sel_hi:[1,0]
	v_rcp_f32_e32 v135, v130
	s_nop 0
	v_mul_f32_e32 v130, 2.0, v135
	v_add_f32_e32 v134, v18, v18
	v_rcp_f32_e32 v135, v131
	s_nop 0
	v_mul_f32_e32 v131, 2.0, v135
	v_add_f32_e32 v135, v19, v19
	v_mul_f32_e32 v134, 0x3fb8aa3b, v134
	v_mul_f32_e32 v135, 0x3fb8aa3b, v135
	v_exp_f32_e32 v134, v134
	v_exp_f32_e32 v135, v135
	v_rcp_f32_e32 v155, v132
	s_nop 0
	v_mul_f32_e32 v132, 2.0, v155
	v_pk_add_f32 v[134:135], v[134:135], 1.0 op_sel_hi:[1,0]
	v_rcp_f32_e32 v155, v133
	s_nop 0
	v_mul_f32_e32 v133, 2.0, v155
	v_sub_f32_e32 v131, 1.0, v131
	v_rcp_f32_e32 v155, v134
	s_nop 0
	v_mul_f32_e32 v134, 2.0, v155
	v_sub_f32_e32 v130, 1.0, v130
	v_rcp_f32_e32 v155, v135
	s_nop 0
	v_mul_f32_e32 v135, 2.0, v155
	v_sub_f32_e32 v129, 1.0, v129
	v_sub_f32_e32 v128, 1.0, v128
	v_sub_f32_e32 v135, 1.0, v135
	v_sub_f32_e32 v134, 1.0, v134
	v_sub_f32_e32 v133, 1.0, v133
	v_sub_f32_e32 v132, 1.0, v132
.LBB0_2965:
	s_or_b64 exec, exec, s[4:5]
	v_add_u32_e32 v154, 0xb0, v154
	v_ashrrev_i32_e32 v155, 31, v154
	v_lshlrev_b64 v[154:155], 10, v[154:155]
	v_lshl_add_u64 v[154:155], s[12:13], 0, v[154:155]
	v_cvt_pk_bf16_f32 v128, v128, v129
	v_cvt_pk_bf16_f32 v129, v130, v131
	v_cvt_pk_bf16_f32 v130, v132, v133
	v_cvt_pk_bf16_f32 v131, v134, v135
	v_lshl_add_u64 v[154:155], v[152:153], 1, v[154:155]
	flat_store_dwordx4 v[154:155], v[128:131]
	s_and_saveexec_b64 s[4:5], s[6:7]
	s_xor_b64 s[4:5], exec, s[4:5]
	s_cbranch_execz .LBB0_2969
	v_mov_b64_e32 v[134:135], v[2:3]
	v_mov_b64_e32 v[130:131], v[6:7]
	v_cmp_gt_u32_e32 vcc, s66, v152
	v_mov_b64_e32 v[132:133], v[0:1]
	v_mov_b64_e32 v[128:129], v[4:5]
	s_and_saveexec_b64 s[6:7], vcc
	s_cbranch_execz .LBB0_2968
	v_mul_f32_e32 v130, 0xbfb8aa3b, v6
	v_mul_f32_e32 v131, 0xbfb8aa3b, v7
	v_exp_f32_e32 v130, v130
	v_exp_f32_e32 v131, v131
	v_mul_f32_e32 v129, 0xbfb8aa3b, v0
	v_mul_f32_e32 v128, 0xbfb8aa3b, v4
	v_exp_f32_e32 v132, v129
	v_pk_add_f32 v[130:131], v[130:131], 1.0 op_sel_hi:[1,0]
	v_mul_f32_e32 v129, 0xbfb8aa3b, v5
	v_exp_f32_e32 v128, v128
	v_exp_f32_e32 v129, v129
	v_mul_f32_e32 v134, 0xbfb8aa3b, v2
	v_rcp_f32_e32 v131, v131
	v_pk_add_f32 v[128:129], v[128:129], 1.0 op_sel_hi:[1,0]
	v_rcp_f32_e32 v130, v130
	v_exp_f32_e32 v134, v134
	v_rcp_f32_e32 v129, v129
	v_mul_f32_e32 v135, 0xbfb8aa3b, v3
	v_exp_f32_e32 v135, v135
	s_nop 0
	v_pk_add_f32 v[134:135], v[134:135], 1.0 op_sel_hi:[1,0]
	v_rcp_f32_e32 v128, v128
	v_mul_f32_e32 v133, 0xbfb8aa3b, v1
	v_exp_f32_e32 v133, v133
	v_rcp_f32_e32 v135, v135
	v_pk_add_f32 v[132:133], v[132:133], 1.0 op_sel_hi:[1,0]
	v_rcp_f32_e32 v134, v134
	v_rcp_f32_e32 v133, v133
	v_rcp_f32_e32 v132, v132

; #define EPI_ROWS(...) _Pragma("unroll") for (int ai = 0; ai < 2; ++ai) _Pragma("unroll") for (int m = 0; m < 4; ++m) { const int row = u.pm * 256 + ai * 128 + wr * 64 + m * 16 + fr; __VA_ARGS__ }
; DI u32x4 pack8(f32x4 a, f32x4 b) { u32x4 w; w.x = pk2(a[0], a[1]); w.y = pk2(a[2], a[3]); w.z = pk2(b[0], b[1]); w.w = pk2(b[2], b[3]); return w; }
; DI float sigmoidf_(float x) { return 1.f / (1.f + __expf(-x)); }
; DI float siluf_(float x) { return x / (1.f + __expf(-x)); }
; DI float softplusf_(float x) { return fmaxf(x, 0.f) + log1pf(expf(-fabsf(x))); }
; DI float softplus_fast(float x) { return fmaxf(x, 0.f) + __logf(1.f + __expf(-fabsf(x))); }
; DI float tanh_fast(float x) { const float e = __expf(2.f * x); return 1.f - 2.f / (e + 1.f); }
;     DI void operator()(const Acc& acc, const Unit& u, int wr, int wc, int fr, int fq) const {
;     ...
;             EPI_ROWS( _Pragma("unroll") for (int bj = 0; bj < 2; ++bj) { const int c0 = (pn - 12) * 256 + bj * 128 + wc * 32 + 8 * fq; f32x4 a = acc[ai][bj][m][0], b = acc[ai][bj][m][1];
;                     if (c0 < 64) { _Pragma("unroll") for (int e = 0; e < 4; ++e) { a[e] = tanh_fast(a[e]); b[e] = tanh_fast(b[e]); } }
;                     else if (c0 >= 128) { _Pragma("unroll") for (int e = 0; e < 4; ++e) { a[e] = sigmoidf_(a[e]); b[e] = sigmoidf_(b[e]); } }
;                     *(u32x4*)(LH + (size_t)row * 512 + c0) = pack8(a, b); } )
.LBB0_2969:
	s_andn2_saveexec_b64 s[4:5], s[4:5]
	s_cbranch_execz .LBB0_2971
	v_add_f32_e32 v129, v0, v0
	v_mul_f32_e32 v129, 0x3fb8aa3b, v129
	v_add_f32_e32 v128, v4, v4
	v_exp_f32_e32 v132, v129
	v_add_f32_e32 v129, v5, v5
	v_mul_f32_e32 v128, 0x3fb8aa3b, v128
	v_mul_f32_e32 v129, 0x3fb8aa3b, v129
	v_exp_f32_e32 v128, v128
	v_exp_f32_e32 v129, v129
	v_add_f32_e32 v130, v1, v1
	v_mul_f32_e32 v130, 0x3fb8aa3b, v130
	v_exp_f32_e32 v133, v130
	v_pk_add_f32 v[128:129], v[128:129], 1.0 op_sel_hi:[1,0]
	v_add_f32_e32 v130, v6, v6
	v_add_f32_e32 v131, v7, v7
	v_mul_f32_e32 v130, 0x3fb8aa3b, v130
	v_mul_f32_e32 v131, 0x3fb8aa3b, v131
	v_exp_f32_e32 v130, v130
	v_exp_f32_e32 v131, v131
	v_rcp_f32_e32 v135, v128
	s_nop 0
	v_mul_f32_e32 v128, 2.0, v135
	v_pk_add_f32 v[130:131], v[130:131], 1.0 op_sel_hi:[1,0]
	v_rcp_f32_e32 v135, v129
	s_nop 0
	v_mul_f32_e32 v129, 2.0, v135
	v_pk_add_f32 v[132:133], v[132:133], 1.0 op_sel_hi:[1,0]
	v_rcp_f32_e32 v135, v130
	s_nop 0
	v_mul_f32_e32 v130, 2.0, v135
	v_add_f32_e32 v134, v2, v2
	v_rcp_f32_e32 v135, v131
	s_nop 0
	v_mul_f32_e32 v131, 2.0, v135
	v_add_f32_e32 v135, v3, v3
	v_mul_f32_e32 v134, 0x3fb8aa3b, v134
	v_mul_f32_e32 v135, 0x3fb8aa3b, v135
	v_exp_f32_e32 v134, v134
	v_exp_f32_e32 v135, v135
	v_rcp_f32_e32 v152, v132
	s_nop 0
	v_mul_f32_e32 v132, 2.0, v152
	v_pk_add_f32 v[134:135], v[134:135], 1.0 op_sel_hi:[1,0]
	v_rcp_f32_e32 v152, v133
	s_nop 0
	v_mul_f32_e32 v133, 2.0, v152
	v_sub_f32_e32 v131, 1.0, v131
	v_rcp_f32_e32 v152, v134
	s_nop 0
	v_mul_f32_e32 v134, 2.0, v152
	v_sub_f32_e32 v130, 1.0, v130
	v_rcp_f32_e32 v152, v135
	s_nop 0
	v_mul_f32_e32 v135, 2.0, v152
	v_sub_f32_e32 v129, 1.0, v129
	v_sub_f32_e32 v128, 1.0, v128
	v_sub_f32_e32 v135, 1.0, v135
	v_sub_f32_e32 v134, 1.0, v134
	v_sub_f32_e32 v133, 1.0, v133
	v_sub_f32_e32 v132, 1.0, v132

; DI float softplus_fast(float x) { return fmaxf(x, 0.f) + __logf(1.f + __expf(-fabsf(x))); }
; #define EPI_ROWS(...) _Pragma("unroll") for (int ai = 0; ai < 2; ++ai) _Pragma("unroll") for (int m = 0; m < 4; ++m) { const int row = u.pm * 256 + ai * 128 + wr * 64 + m * 16 + fr; __VA_ARGS__ }
; DI u32x4 pack8(f32x4 a, f32x4 b) { u32x4 w; w.x = pk2(a[0], a[1]); w.y = pk2(a[2], a[3]); w.z = pk2(b[0], b[1]); w.w = pk2(b[2], b[3]); return w; }
; DI float sigmoidf_(float x) { return 1.f / (1.f + __expf(-x)); }
;     DI void operator()(const Acc& acc, const Unit& u, int wr, int wc, int fr, int fq) const {
;         const int pn = u.pn;
;         EPI_ROWS( _Pragma("unroll") for (int bj = 0; bj < 2; ++bj) { const int c0 = (pn & 3) * 256 + bj * 128 + wc * 32 + 8 * fq;
;                 if (pn < 4) { u32x4 o;
;                     _Pragma("unroll") for (int n = 0; n < 2; ++n) _Pragma("unroll") for (int e2 = 0; e2 < 2; ++e2) {
;                         const float wa = -softplus_fast(-(w0[c0 + 4 * n + 2 * e2] + acc[ai][bj][m][n][2 * e2])) - 0.5f, wb = -softplus_fast(-(w0[c0 + 4 * n + 2 * e2 + 1] + acc[ai][bj][m][n][2 * e2 + 1])) - 0.5f;
;                         h16x2 hv = {(_Float16)(-__expf(wa)), (_Float16)(-__expf(wb))}; o[2 * n + e2] = __builtin_bit_cast(unsigned, hv); }
;                     *(u32x4*)(LD + (size_t)row * 1024 + c0) = o;
;                 } else { f32x4 a, b;
;                     _Pragma("unroll") for (int e = 0; e < 4; ++e) { a[e] = sigmoidf_(a0[c0 + e] + acc[ai][bj][m][0][e]); b[e] = sigmoidf_(a0[c0 + 4 + e] + acc[ai][bj][m][1][e]); }
;                     *(u32x4*)(AA + (size_t)row * 1024 + c0) = pack8(a, b); } } )
.LBB0_3051:
	s_lshl_b32 s5, s6, 8
	v_mov_b32_e32 v128, v156
	v_mov_b32_e32 v129, v157
	s_add_i32 s5, s5, s55
	s_nop 0
	v_add_u32_e32 v150, s5, v128
	s_lshl_b32 s5, s4, 8
	s_and_b32 s5, s5, 0x300
	s_or_b32 s5, s5, s57
	v_ashrrev_i32_e32 v151, 31, v150
	v_lshl_add_u32 v148, v129, 3, s5
	v_lshlrev_b64 v[128:129], 11, v[150:151]
	s_cmp_gt_i32 s4, 3
	v_ashrrev_i32_e32 v149, 31, v148
	v_lshl_add_u64 v[130:131], s[24:25], 0, v[128:129]
	s_cselect_b64 s[14:15], -1, 0
	s_cmp_lt_i32 s4, 4
	s_mov_b64 s[4:5], -1
	v_lshl_add_u64 v[144:145], v[148:149], 2, s[18:19]
	v_lshl_add_u64 v[154:155], v[148:149], 1, v[130:131]
	s_cbranch_scc1 .LBB0_3053
	global_load_dwordx4 v[164:167], v[144:145], off
	global_load_dwordx4 v[168:171], v[144:145], off offset:16
	s_waitcnt vmcnt(0)
	v_add_f32_e32 v130, v124, v164
	v_add_f32_e32 v131, v120, v168
	v_add_f32_e32 v146, v125, v165
	v_mul_f32_e32 v130, 0xbfb8aa3b, v130
	v_mul_f32_e32 v131, 0xbfb8aa3b, v131
	v_mul_f32_e32 v163, 0xbfb8aa3b, v146
	v_add_f32_e32 v147, v121, v169
	v_exp_f32_e32 v130, v130
	v_exp_f32_e32 v146, v131
	v_exp_f32_e32 v131, v163
	v_mul_f32_e32 v147, 0xbfb8aa3b, v147
	v_add_f32_e32 v151, v126, v166
	v_add_f32_e32 v153, v127, v167
	v_exp_f32_e32 v147, v147
	v_add_f32_e32 v152, v122, v170
	v_mul_f32_e32 v151, 0xbfb8aa3b, v151
	v_mul_f32_e32 v153, 0xbfb8aa3b, v153
	v_mul_f32_e32 v164, 0xbfb8aa3b, v152
	v_exp_f32_e32 v152, v151
	v_exp_f32_e32 v153, v153
	v_pk_add_f32 v[130:131], v[130:131], 1.0 op_sel_hi:[1,0]
	v_pk_add_f32 v[146:147], v[146:147], 1.0 op_sel_hi:[1,0]
	v_pk_add_f32 v[152:153], v[152:153], 1.0 op_sel_hi:[1,0]
	s_mov_b64 vcc, s[4:5]
	v_rcp_f32_e32 v151, v131
	s_mov_b64 vcc, s[6:7]
	v_rcp_f32_e32 v163, v130
	s_mov_b64 vcc, s[8:9]
	v_rcp_f32_e32 v147, v147
	s_mov_b64 vcc, s[10:11]
	v_rcp_f32_e32 v146, v146
	v_rcp_f32_e32 v153, v153
	v_add_f32_e32 v130, v123, v171
	v_mul_f32_e32 v130, 0xbfb8aa3b, v130
	v_exp_f32_e32 v164, v164
	v_exp_f32_e32 v165, v130
	s_nop 0
	v_pk_add_f32 v[130:131], v[164:165], 1.0 op_sel_hi:[1,0]
	s_mov_b64 vcc, s[12:13]
	v_rcp_f32_e32 v152, v152
	v_rcp_f32_e32 v131, v131
	s_mov_b64 s[4:5], 0
	v_rcp_f32_e32 v130, v130
	v_cvt_pk_bf16_f32 v164, v163, v151
	v_cvt_pk_bf16_f32 v165, v152, v153
	v_cvt_pk_bf16_f32 v166, v146, v147
	v_cvt_pk_bf16_f32 v167, v130, v131
	flat_store_dwordx4 v[154:155], v[164:167]

; DI float softplus_fast(float x) { return fmaxf(x, 0.f) + __logf(1.f + __expf(-fabsf(x))); }
; #define EPI_ROWS(...) _Pragma("unroll") for (int ai = 0; ai < 2; ++ai) _Pragma("unroll") for (int m = 0; m < 4; ++m) { const int row = u.pm * 256 + ai * 128 + wr * 64 + m * 16 + fr; __VA_ARGS__ }
; DI u32x4 pack8(f32x4 a, f32x4 b) { u32x4 w; w.x = pk2(a[0], a[1]); w.y = pk2(a[2], a[3]); w.z = pk2(b[0], b[1]); w.w = pk2(b[2], b[3]); return w; }
; DI float sigmoidf_(float x) { return 1.f / (1.f + __expf(-x)); }
;     DI void operator()(const Acc& acc, const Unit& u, int wr, int wc, int fr, int fq) const {
;         const int pn = u.pn;
;         EPI_ROWS( _Pragma("unroll") for (int bj = 0; bj < 2; ++bj) { const int c0 = (pn & 3) * 256 + bj * 128 + wc * 32 + 8 * fq;
;                 if (pn < 4) { u32x4 o;
;                     _Pragma("unroll") for (int n = 0; n < 2; ++n) _Pragma("unroll") for (int e2 = 0; e2 < 2; ++e2) {
;                         const float wa = -softplus_fast(-(w0[c0 + 4 * n + 2 * e2] + acc[ai][bj][m][n][2 * e2])) - 0.5f, wb = -softplus_fast(-(w0[c0 + 4 * n + 2 * e2 + 1] + acc[ai][bj][m][n][2 * e2 + 1])) - 0.5f;
;                         h16x2 hv = {(_Float16)(-__expf(wa)), (_Float16)(-__expf(wb))}; o[2 * n + e2] = __builtin_bit_cast(unsigned, hv); }
;                     *(u32x4*)(LD + (size_t)row * 1024 + c0) = o;
;                 } else { f32x4 a, b;
;                     _Pragma("unroll") for (int e = 0; e < 4; ++e) { a[e] = sigmoidf_(a0[c0 + e] + acc[ai][bj][m][0][e]); b[e] = sigmoidf_(a0[c0 + 4 + e] + acc[ai][bj][m][1][e]); }
;                     *(u32x4*)(AA + (size_t)row * 1024 + c0) = pack8(a, b); } } )
.LBB0_3055:
	s_nop 1
	v_cndmask_b32_e64 v120, 0, 1, s[14:15]
	v_cmp_ne_u32_e64 s[4:5], 1, v120
	s_andn2_b64 vcc, exec, s[14:15]
	s_mov_b64 s[6:7], -1
	s_cbranch_vccnz .LBB0_3057
	global_load_dwordx4 v[120:123], v[144:145], off offset:512
	global_load_dwordx4 v[124:127], v[144:145], off offset:528
	s_waitcnt vmcnt(0)
	v_add_f32_e32 v120, v116, v120
	v_add_f32_e32 v121, v117, v121
	v_mul_f32_e32 v120, 0xbfb8aa3b, v120
	v_mul_f32_e32 v121, 0xbfb8aa3b, v121
	v_add_f32_e32 v124, v112, v124
	v_add_f32_e32 v125, v113, v125
	v_exp_f32_e32 v120, v120
	v_exp_f32_e32 v121, v121
	v_add_f32_e32 v122, v118, v122
	v_add_f32_e32 v123, v119, v123
	v_mul_f32_e32 v124, 0xbfb8aa3b, v124
	v_mul_f32_e32 v125, 0xbfb8aa3b, v125
	v_mul_f32_e32 v128, 0xbfb8aa3b, v122
	v_mul_f32_e32 v129, 0xbfb8aa3b, v123
	v_exp_f32_e32 v122, v124
	v_exp_f32_e32 v123, v125
	v_exp_f32_e32 v124, v128
	v_exp_f32_e32 v125, v129
	v_pk_add_f32 v[120:121], v[120:121], 1.0 op_sel_hi:[1,0]
	v_pk_add_f32 v[122:123], v[122:123], 1.0 op_sel_hi:[1,0]
	v_pk_add_f32 v[124:125], v[124:125], 1.0 op_sel_hi:[1,0]
	s_mov_b64 vcc, s[6:7]
	v_rcp_f32_e32 v128, v121
	s_mov_b64 vcc, s[8:9]
	v_rcp_f32_e32 v129, v120
	s_mov_b64 vcc, s[10:11]
	v_rcp_f32_e32 v123, v123
	s_mov_b64 vcc, s[12:13]
	v_rcp_f32_e32 v122, v122
	v_add_f32_e32 v126, v114, v126
	v_rcp_f32_e32 v125, v125
	v_add_f32_e32 v120, v115, v127
	v_mul_f32_e32 v126, 0xbfb8aa3b, v126
	v_mul_f32_e32 v120, 0xbfb8aa3b, v120
	v_exp_f32_e32 v126, v126
	v_exp_f32_e32 v127, v120
	s_nop 0
	v_pk_add_f32 v[120:121], v[126:127], 1.0 op_sel_hi:[1,0]
	s_mov_b64 vcc, s[14:15]
	v_rcp_f32_e32 v124, v124
	v_rcp_f32_e32 v126, v121
	v_cvt_pk_bf16_f32 v122, v122, v123
	v_rcp_f32_e32 v127, v120
	v_cvt_pk_bf16_f32 v120, v129, v128
	v_cvt_pk_bf16_f32 v121, v124, v125
	v_cvt_pk_bf16_f32 v123, v127, v126
	s_mov_b64 s[6:7], 0
	flat_store_dwordx4 v[154:155], v[120:123] offset:256

; DI float softplus_fast(float x) { return fmaxf(x, 0.f) + __logf(1.f + __expf(-fabsf(x))); }
; #define EPI_ROWS(...) _Pragma("unroll") for (int ai = 0; ai < 2; ++ai) _Pragma("unroll") for (int m = 0; m < 4; ++m) { const int row = u.pm * 256 + ai * 128 + wr * 64 + m * 16 + fr; __VA_ARGS__ }
; DI u32x4 pack8(f32x4 a, f32x4 b) { u32x4 w; w.x = pk2(a[0], a[1]); w.y = pk2(a[2], a[3]); w.z = pk2(b[0], b[1]); w.w = pk2(b[2], b[3]); return w; }
; DI float sigmoidf_(float x) { return 1.f / (1.f + __expf(-x)); }
;     DI void operator()(const Acc& acc, const Unit& u, int wr, int wc, int fr, int fq) const {
;         const int pn = u.pn;
;         EPI_ROWS( _Pragma("unroll") for (int bj = 0; bj < 2; ++bj) { const int c0 = (pn & 3) * 256 + bj * 128 + wc * 32 + 8 * fq;
;                 if (pn < 4) { u32x4 o;
;                     _Pragma("unroll") for (int n = 0; n < 2; ++n) _Pragma("unroll") for (int e2 = 0; e2 < 2; ++e2) {
;                         const float wa = -softplus_fast(-(w0[c0 + 4 * n + 2 * e2] + acc[ai][bj][m][n][2 * e2])) - 0.5f, wb = -softplus_fast(-(w0[c0 + 4 * n + 2 * e2 + 1] + acc[ai][bj][m][n][2 * e2 + 1])) - 0.5f;
;                         h16x2 hv = {(_Float16)(-__expf(wa)), (_Float16)(-__expf(wb))}; o[2 * n + e2] = __builtin_bit_cast(unsigned, hv); }
;                     *(u32x4*)(LD + (size_t)row * 1024 + c0) = o;
;                 } else { f32x4 a, b;
;                     _Pragma("unroll") for (int e = 0; e < 4; ++e) { a[e] = sigmoidf_(a0[c0 + e] + acc[ai][bj][m][0][e]); b[e] = sigmoidf_(a0[c0 + 4 + e] + acc[ai][bj][m][1][e]); }
;                     *(u32x4*)(AA + (size_t)row * 1024 + c0) = pack8(a, b); } } )
.LBB0_3059:
	s_nop 1
	v_add_u32_e32 v112, 16, v150
	v_ashrrev_i32_e32 v113, 31, v112
	v_lshlrev_b64 v[112:113], 11, v[112:113]
	v_lshl_add_u64 v[114:115], s[24:25], 0, v[112:113]
	s_mov_b64 s[6:7], -1
	s_and_b64 vcc, exec, s[4:5]
	v_lshl_add_u64 v[118:119], v[148:149], 1, v[114:115]
	s_cbranch_vccnz .LBB0_3063
	global_load_dwordx4 v[114:117], v[144:145], off
	global_load_dwordx4 v[120:123], v[144:145], off offset:16
	s_waitcnt vmcnt(0)
	v_add_f32_e32 v114, v108, v114
	v_add_f32_e32 v115, v109, v115
	v_mul_f32_e32 v114, 0xbfb8aa3b, v114
	v_mul_f32_e32 v115, 0xbfb8aa3b, v115
	v_add_f32_e32 v120, v104, v120
	v_add_f32_e32 v121, v105, v121
	v_exp_f32_e32 v114, v114
	v_exp_f32_e32 v115, v115
	v_add_f32_e32 v116, v110, v116
	v_add_f32_e32 v117, v111, v117
	v_mul_f32_e32 v120, 0xbfb8aa3b, v120
	v_mul_f32_e32 v121, 0xbfb8aa3b, v121
	v_mul_f32_e32 v124, 0xbfb8aa3b, v116
	v_mul_f32_e32 v125, 0xbfb8aa3b, v117
	v_exp_f32_e32 v116, v120
	v_exp_f32_e32 v117, v121
	v_exp_f32_e32 v120, v124
	v_exp_f32_e32 v121, v125
	v_pk_add_f32 v[114:115], v[114:115], 1.0 op_sel_hi:[1,0]
	v_pk_add_f32 v[116:117], v[116:117], 1.0 op_sel_hi:[1,0]
	v_pk_add_f32 v[120:121], v[120:121], 1.0 op_sel_hi:[1,0]
	s_mov_b64 vcc, s[6:7]
	v_rcp_f32_e32 v124, v115
	s_mov_b64 vcc, s[8:9]
	v_rcp_f32_e32 v125, v114
	s_mov_b64 vcc, s[10:11]
	v_rcp_f32_e32 v117, v117
	s_mov_b64 vcc, s[12:13]
	v_rcp_f32_e32 v116, v116
	v_add_f32_e32 v122, v106, v122
	v_rcp_f32_e32 v121, v121
	v_add_f32_e32 v114, v107, v123
	v_mul_f32_e32 v122, 0xbfb8aa3b, v122
	v_mul_f32_e32 v114, 0xbfb8aa3b, v114
	v_exp_f32_e32 v122, v122
	v_exp_f32_e32 v123, v114
	s_nop 0
	v_pk_add_f32 v[114:115], v[122:123], 1.0 op_sel_hi:[1,0]
	s_mov_b64 vcc, s[14:15]
	v_rcp_f32_e32 v120, v120
	v_rcp_f32_e32 v122, v115
	v_cvt_pk_bf16_f32 v116, v116, v117
	v_rcp_f32_e32 v123, v114
	v_cvt_pk_bf16_f32 v114, v125, v124
	v_cvt_pk_bf16_f32 v115, v120, v121
	v_cvt_pk_bf16_f32 v117, v123, v122
	flat_store_dwordx4 v[118:119], v[114:117]
	v_lshl_add_u64 v[112:113], s[22:23], 0, v[112:113]
	s_nop 0
	v_lshl_add_u64 v[116:117], v[148:149], 1, v[112:113]
	s_cbranch_execz .LBB0_3064

; DI float softplus_fast(float x) { return fmaxf(x, 0.f) + __logf(1.f + __expf(-fabsf(x))); }
; #define EPI_ROWS(...) _Pragma("unroll") for (int ai = 0; ai < 2; ++ai) _Pragma("unroll") for (int m = 0; m < 4; ++m) { const int row = u.pm * 256 + ai * 128 + wr * 64 + m * 16 + fr; __VA_ARGS__ }
; DI u32x4 pack8(f32x4 a, f32x4 b) { u32x4 w; w.x = pk2(a[0], a[1]); w.y = pk2(a[2], a[3]); w.z = pk2(b[0], b[1]); w.w = pk2(b[2], b[3]); return w; }
; DI float sigmoidf_(float x) { return 1.f / (1.f + __expf(-x)); }
;     DI void operator()(const Acc& acc, const Unit& u, int wr, int wc, int fr, int fq) const {
;         const int pn = u.pn;
;         EPI_ROWS( _Pragma("unroll") for (int bj = 0; bj < 2; ++bj) { const int c0 = (pn & 3) * 256 + bj * 128 + wc * 32 + 8 * fq;
;                 if (pn < 4) { u32x4 o;
;                     _Pragma("unroll") for (int n = 0; n < 2; ++n) _Pragma("unroll") for (int e2 = 0; e2 < 2; ++e2) {
;                         const float wa = -softplus_fast(-(w0[c0 + 4 * n + 2 * e2] + acc[ai][bj][m][n][2 * e2])) - 0.5f, wb = -softplus_fast(-(w0[c0 + 4 * n + 2 * e2 + 1] + acc[ai][bj][m][n][2 * e2 + 1])) - 0.5f;
;                         h16x2 hv = {(_Float16)(-__expf(wa)), (_Float16)(-__expf(wb))}; o[2 * n + e2] = __builtin_bit_cast(unsigned, hv); }
;                     *(u32x4*)(LD + (size_t)row * 1024 + c0) = o;
;                 } else { f32x4 a, b;
;                     _Pragma("unroll") for (int e = 0; e < 4; ++e) { a[e] = sigmoidf_(a0[c0 + e] + acc[ai][bj][m][0][e]); b[e] = sigmoidf_(a0[c0 + 4 + e] + acc[ai][bj][m][1][e]); }
;                     *(u32x4*)(AA + (size_t)row * 1024 + c0) = pack8(a, b); } } )
.LBB0_3062:
	global_load_dwordx4 v[104:107], v[144:145], off offset:512
	global_load_dwordx4 v[108:111], v[144:145], off offset:528
	s_waitcnt vmcnt(0)
	v_add_f32_e32 v104, v100, v104
	v_add_f32_e32 v105, v101, v105
	v_mul_f32_e32 v104, 0xbfb8aa3b, v104
	v_mul_f32_e32 v105, 0xbfb8aa3b, v105
	v_add_f32_e32 v108, v96, v108
	v_add_f32_e32 v109, v97, v109
	v_exp_f32_e32 v104, v104
	v_exp_f32_e32 v105, v105
	v_add_f32_e32 v106, v102, v106
	v_add_f32_e32 v107, v103, v107
	v_mul_f32_e32 v108, 0xbfb8aa3b, v108
	v_mul_f32_e32 v109, 0xbfb8aa3b, v109
	v_mul_f32_e32 v112, 0xbfb8aa3b, v106
	v_mul_f32_e32 v113, 0xbfb8aa3b, v107
	v_exp_f32_e32 v106, v108
	v_exp_f32_e32 v107, v109
	v_exp_f32_e32 v108, v112
	v_exp_f32_e32 v109, v113
	v_pk_add_f32 v[104:105], v[104:105], 1.0 op_sel_hi:[1,0]
	v_pk_add_f32 v[106:107], v[106:107], 1.0 op_sel_hi:[1,0]
	v_pk_add_f32 v[108:109], v[108:109], 1.0 op_sel_hi:[1,0]
	s_mov_b64 vcc, s[6:7]
	v_rcp_f32_e32 v112, v105
	s_mov_b64 vcc, s[8:9]
	v_rcp_f32_e32 v113, v104
	s_mov_b64 vcc, s[10:11]
	v_rcp_f32_e32 v107, v107
	s_mov_b64 vcc, s[12:13]
	v_rcp_f32_e32 v106, v106
	v_add_f32_e32 v110, v98, v110
	v_rcp_f32_e32 v109, v109
	v_add_f32_e32 v104, v99, v111
	v_mul_f32_e32 v110, 0xbfb8aa3b, v110
	v_mul_f32_e32 v104, 0xbfb8aa3b, v104
	v_exp_f32_e32 v110, v110
	v_exp_f32_e32 v111, v104
	s_nop 0
	v_pk_add_f32 v[104:105], v[110:111], 1.0 op_sel_hi:[1,0]
	s_mov_b64 vcc, s[14:15]
	v_rcp_f32_e32 v108, v108
	v_rcp_f32_e32 v110, v105
	v_cvt_pk_bf16_f32 v106, v106, v107
	v_rcp_f32_e32 v111, v104
	v_cvt_pk_bf16_f32 v104, v113, v112
	v_cvt_pk_bf16_f32 v105, v108, v109
	v_cvt_pk_bf16_f32 v107, v111, v110
	flat_store_dwordx4 v[118:119], v[104:107] offset:256
	s_cbranch_execz .LBB0_3066
	s_branch .LBB0_3067

; DI float softplus_fast(float x) { return fmaxf(x, 0.f) + __logf(1.f + __expf(-fabsf(x))); }
; #define EPI_ROWS(...) _Pragma("unroll") for (int ai = 0; ai < 2; ++ai) _Pragma("unroll") for (int m = 0; m < 4; ++m) { const int row = u.pm * 256 + ai * 128 + wr * 64 + m * 16 + fr; __VA_ARGS__ }
; DI u32x4 pack8(f32x4 a, f32x4 b) { u32x4 w; w.x = pk2(a[0], a[1]); w.y = pk2(a[2], a[3]); w.z = pk2(b[0], b[1]); w.w = pk2(b[2], b[3]); return w; }
; DI float sigmoidf_(float x) { return 1.f / (1.f + __expf(-x)); }
;     DI void operator()(const Acc& acc, const Unit& u, int wr, int wc, int fr, int fq) const {
;         const int pn = u.pn;
;         EPI_ROWS( _Pragma("unroll") for (int bj = 0; bj < 2; ++bj) { const int c0 = (pn & 3) * 256 + bj * 128 + wc * 32 + 8 * fq;
;                 if (pn < 4) { u32x4 o;
;                     _Pragma("unroll") for (int n = 0; n < 2; ++n) _Pragma("unroll") for (int e2 = 0; e2 < 2; ++e2) {
;                         const float wa = -softplus_fast(-(w0[c0 + 4 * n + 2 * e2] + acc[ai][bj][m][n][2 * e2])) - 0.5f, wb = -softplus_fast(-(w0[c0 + 4 * n + 2 * e2 + 1] + acc[ai][bj][m][n][2 * e2 + 1])) - 0.5f;
;                         h16x2 hv = {(_Float16)(-__expf(wa)), (_Float16)(-__expf(wb))}; o[2 * n + e2] = __builtin_bit_cast(unsigned, hv); }
;                     *(u32x4*)(LD + (size_t)row * 1024 + c0) = o;
;                 } else { f32x4 a, b;
;                     _Pragma("unroll") for (int e = 0; e < 4; ++e) { a[e] = sigmoidf_(a0[c0 + e] + acc[ai][bj][m][0][e]); b[e] = sigmoidf_(a0[c0 + 4 + e] + acc[ai][bj][m][1][e]); }
;                     *(u32x4*)(AA + (size_t)row * 1024 + c0) = pack8(a, b); } } )
.LBB0_3067:
	s_nop 1
	v_add_u32_e32 v96, 32, v150
	v_ashrrev_i32_e32 v97, 31, v96
	v_lshlrev_b64 v[96:97], 11, v[96:97]
	v_lshl_add_u64 v[98:99], s[24:25], 0, v[96:97]
	s_mov_b64 s[6:7], -1
	s_and_b64 vcc, exec, s[4:5]
	v_lshl_add_u64 v[102:103], v[148:149], 1, v[98:99]
	s_cbranch_vccnz .LBB0_3071
	global_load_dwordx4 v[98:101], v[144:145], off
	global_load_dwordx4 v[104:107], v[144:145], off offset:16
	s_waitcnt vmcnt(0)
	v_add_f32_e32 v98, v92, v98
	v_add_f32_e32 v99, v93, v99
	v_mul_f32_e32 v98, 0xbfb8aa3b, v98
	v_mul_f32_e32 v99, 0xbfb8aa3b, v99
	v_add_f32_e32 v104, v88, v104
	v_add_f32_e32 v105, v89, v105
	v_exp_f32_e32 v98, v98
	v_exp_f32_e32 v99, v99
	v_add_f32_e32 v100, v94, v100
	v_add_f32_e32 v101, v95, v101
	v_mul_f32_e32 v104, 0xbfb8aa3b, v104
	v_mul_f32_e32 v105, 0xbfb8aa3b, v105
	v_mul_f32_e32 v108, 0xbfb8aa3b, v100
	v_mul_f32_e32 v109, 0xbfb8aa3b, v101
	v_exp_f32_e32 v100, v104
	v_exp_f32_e32 v101, v105
	v_exp_f32_e32 v104, v108
	v_exp_f32_e32 v105, v109
	v_pk_add_f32 v[98:99], v[98:99], 1.0 op_sel_hi:[1,0]
	v_pk_add_f32 v[100:101], v[100:101], 1.0 op_sel_hi:[1,0]
	v_pk_add_f32 v[104:105], v[104:105], 1.0 op_sel_hi:[1,0]
	s_mov_b64 vcc, s[6:7]
	v_rcp_f32_e32 v108, v99
	s_mov_b64 vcc, s[8:9]
	v_rcp_f32_e32 v109, v98
	s_mov_b64 vcc, s[10:11]
	v_rcp_f32_e32 v101, v101
	s_mov_b64 vcc, s[12:13]
	v_rcp_f32_e32 v100, v100
	v_add_f32_e32 v106, v90, v106
	v_rcp_f32_e32 v105, v105
	v_add_f32_e32 v98, v91, v107
	v_mul_f32_e32 v106, 0xbfb8aa3b, v106
	v_mul_f32_e32 v98, 0xbfb8aa3b, v98
	v_exp_f32_e32 v106, v106
	v_exp_f32_e32 v107, v98
	s_nop 0
	v_pk_add_f32 v[98:99], v[106:107], 1.0 op_sel_hi:[1,0]
	s_mov_b64 vcc, s[14:15]
	v_rcp_f32_e32 v104, v104
	v_rcp_f32_e32 v106, v99
	v_cvt_pk_bf16_f32 v100, v100, v101
	v_rcp_f32_e32 v107, v98
	v_cvt_pk_bf16_f32 v98, v109, v108
	v_cvt_pk_bf16_f32 v99, v104, v105
	v_cvt_pk_bf16_f32 v101, v107, v106
	flat_store_dwordx4 v[102:103], v[98:101]
	v_lshl_add_u64 v[96:97], s[22:23], 0, v[96:97]
	s_nop 0
	v_lshl_add_u64 v[100:101], v[148:149], 1, v[96:97]
	s_cbranch_execz .LBB0_3072

; DI float softplus_fast(float x) { return fmaxf(x, 0.f) + __logf(1.f + __expf(-fabsf(x))); }
; #define EPI_ROWS(...) _Pragma("unroll") for (int ai = 0; ai < 2; ++ai) _Pragma("unroll") for (int m = 0; m < 4; ++m) { const int row = u.pm * 256 + ai * 128 + wr * 64 + m * 16 + fr; __VA_ARGS__ }
; DI u32x4 pack8(f32x4 a, f32x4 b) { u32x4 w; w.x = pk2(a[0], a[1]); w.y = pk2(a[2], a[3]); w.z = pk2(b[0], b[1]); w.w = pk2(b[2], b[3]); return w; }
; DI float sigmoidf_(float x) { return 1.f / (1.f + __expf(-x)); }
;     DI void operator()(const Acc& acc, const Unit& u, int wr, int wc, int fr, int fq) const {
;         const int pn = u.pn;
;         EPI_ROWS( _Pragma("unroll") for (int bj = 0; bj < 2; ++bj) { const int c0 = (pn & 3) * 256 + bj * 128 + wc * 32 + 8 * fq;
;                 if (pn < 4) { u32x4 o;
;                     _Pragma("unroll") for (int n = 0; n < 2; ++n) _Pragma("unroll") for (int e2 = 0; e2 < 2; ++e2) {
;                         const float wa = -softplus_fast(-(w0[c0 + 4 * n + 2 * e2] + acc[ai][bj][m][n][2 * e2])) - 0.5f, wb = -softplus_fast(-(w0[c0 + 4 * n + 2 * e2 + 1] + acc[ai][bj][m][n][2 * e2 + 1])) - 0.5f;
;                         h16x2 hv = {(_Float16)(-__expf(wa)), (_Float16)(-__expf(wb))}; o[2 * n + e2] = __builtin_bit_cast(unsigned, hv); }
;                     *(u32x4*)(LD + (size_t)row * 1024 + c0) = o;
;                 } else { f32x4 a, b;
;                     _Pragma("unroll") for (int e = 0; e < 4; ++e) { a[e] = sigmoidf_(a0[c0 + e] + acc[ai][bj][m][0][e]); b[e] = sigmoidf_(a0[c0 + 4 + e] + acc[ai][bj][m][1][e]); }
;                     *(u32x4*)(AA + (size_t)row * 1024 + c0) = pack8(a, b); } } )
.LBB0_3070:
	global_load_dwordx4 v[88:91], v[144:145], off offset:512
	global_load_dwordx4 v[92:95], v[144:145], off offset:528
	s_waitcnt vmcnt(0)
	v_add_f32_e32 v88, v84, v88
	v_add_f32_e32 v89, v85, v89
	v_mul_f32_e32 v88, 0xbfb8aa3b, v88
	v_mul_f32_e32 v89, 0xbfb8aa3b, v89
	v_add_f32_e32 v92, v80, v92
	v_add_f32_e32 v93, v81, v93
	v_exp_f32_e32 v88, v88
	v_exp_f32_e32 v89, v89
	v_add_f32_e32 v90, v86, v90
	v_add_f32_e32 v91, v87, v91
	v_mul_f32_e32 v92, 0xbfb8aa3b, v92
	v_mul_f32_e32 v93, 0xbfb8aa3b, v93
	v_mul_f32_e32 v96, 0xbfb8aa3b, v90
	v_mul_f32_e32 v97, 0xbfb8aa3b, v91
	v_exp_f32_e32 v90, v92
	v_exp_f32_e32 v91, v93
	v_exp_f32_e32 v92, v96
	v_exp_f32_e32 v93, v97
	v_pk_add_f32 v[88:89], v[88:89], 1.0 op_sel_hi:[1,0]
	v_pk_add_f32 v[90:91], v[90:91], 1.0 op_sel_hi:[1,0]
	v_pk_add_f32 v[92:93], v[92:93], 1.0 op_sel_hi:[1,0]
	s_mov_b64 vcc, s[6:7]
	v_rcp_f32_e32 v96, v89
	s_mov_b64 vcc, s[8:9]
	v_rcp_f32_e32 v97, v88
	s_mov_b64 vcc, s[10:11]
	v_rcp_f32_e32 v91, v91
	s_mov_b64 vcc, s[12:13]
	v_rcp_f32_e32 v90, v90
	v_add_f32_e32 v94, v82, v94
	v_rcp_f32_e32 v93, v93
	v_add_f32_e32 v88, v83, v95
	v_mul_f32_e32 v94, 0xbfb8aa3b, v94
	v_mul_f32_e32 v88, 0xbfb8aa3b, v88
	v_exp_f32_e32 v94, v94
	v_exp_f32_e32 v95, v88
	s_nop 0
	v_pk_add_f32 v[88:89], v[94:95], 1.0 op_sel_hi:[1,0]
	s_mov_b64 vcc, s[14:15]
	v_rcp_f32_e32 v92, v92
	v_rcp_f32_e32 v94, v89
	v_cvt_pk_bf16_f32 v90, v90, v91
	v_rcp_f32_e32 v95, v88
	v_cvt_pk_bf16_f32 v88, v97, v96
	v_cvt_pk_bf16_f32 v89, v92, v93
	v_cvt_pk_bf16_f32 v91, v95, v94
	flat_store_dwordx4 v[102:103], v[88:91] offset:256
	s_cbranch_execz .LBB0_3074
	s_branch .LBB0_3075

; DI float softplus_fast(float x) { return fmaxf(x, 0.f) + __logf(1.f + __expf(-fabsf(x))); }
; #define EPI_ROWS(...) _Pragma("unroll") for (int ai = 0; ai < 2; ++ai) _Pragma("unroll") for (int m = 0; m < 4; ++m) { const int row = u.pm * 256 + ai * 128 + wr * 64 + m * 16 + fr; __VA_ARGS__ }
; DI u32x4 pack8(f32x4 a, f32x4 b) { u32x4 w; w.x = pk2(a[0], a[1]); w.y = pk2(a[2], a[3]); w.z = pk2(b[0], b[1]); w.w = pk2(b[2], b[3]); return w; }
; DI float sigmoidf_(float x) { return 1.f / (1.f + __expf(-x)); }
;     DI void operator()(const Acc& acc, const Unit& u, int wr, int wc, int fr, int fq) const {
;         const int pn = u.pn;
;         EPI_ROWS( _Pragma("unroll") for (int bj = 0; bj < 2; ++bj) { const int c0 = (pn & 3) * 256 + bj * 128 + wc * 32 + 8 * fq;
;                 if (pn < 4) { u32x4 o;
;                     _Pragma("unroll") for (int n = 0; n < 2; ++n) _Pragma("unroll") for (int e2 = 0; e2 < 2; ++e2) {
;                         const float wa = -softplus_fast(-(w0[c0 + 4 * n + 2 * e2] + acc[ai][bj][m][n][2 * e2])) - 0.5f, wb = -softplus_fast(-(w0[c0 + 4 * n + 2 * e2 + 1] + acc[ai][bj][m][n][2 * e2 + 1])) - 0.5f;
;                         h16x2 hv = {(_Float16)(-__expf(wa)), (_Float16)(-__expf(wb))}; o[2 * n + e2] = __builtin_bit_cast(unsigned, hv); }
;                     *(u32x4*)(LD + (size_t)row * 1024 + c0) = o;
;                 } else { f32x4 a, b;
;                     _Pragma("unroll") for (int e = 0; e < 4; ++e) { a[e] = sigmoidf_(a0[c0 + e] + acc[ai][bj][m][0][e]); b[e] = sigmoidf_(a0[c0 + 4 + e] + acc[ai][bj][m][1][e]); }
;                     *(u32x4*)(AA + (size_t)row * 1024 + c0) = pack8(a, b); } } )
.LBB0_3075:
	s_nop 1
	v_add_u32_e32 v80, 48, v150
	v_ashrrev_i32_e32 v81, 31, v80
	v_lshlrev_b64 v[80:81], 11, v[80:81]
	v_lshl_add_u64 v[82:83], s[24:25], 0, v[80:81]
	s_mov_b64 s[6:7], -1
	s_and_b64 vcc, exec, s[4:5]
	v_lshl_add_u64 v[86:87], v[148:149], 1, v[82:83]
	s_cbranch_vccnz .LBB0_3079
	global_load_dwordx4 v[82:85], v[144:145], off
	global_load_dwordx4 v[88:91], v[144:145], off offset:16
	s_waitcnt vmcnt(0)
	v_add_f32_e32 v82, v76, v82
	v_add_f32_e32 v83, v77, v83
	v_mul_f32_e32 v82, 0xbfb8aa3b, v82
	v_mul_f32_e32 v83, 0xbfb8aa3b, v83
	v_add_f32_e32 v88, v72, v88
	v_add_f32_e32 v89, v73, v89
	v_exp_f32_e32 v82, v82
	v_exp_f32_e32 v83, v83
	v_add_f32_e32 v84, v78, v84
	v_add_f32_e32 v85, v79, v85
	v_mul_f32_e32 v88, 0xbfb8aa3b, v88
	v_mul_f32_e32 v89, 0xbfb8aa3b, v89
	v_mul_f32_e32 v92, 0xbfb8aa3b, v84
	v_mul_f32_e32 v93, 0xbfb8aa3b, v85
	v_exp_f32_e32 v84, v88
	v_exp_f32_e32 v85, v89
	v_exp_f32_e32 v88, v92
	v_exp_f32_e32 v89, v93
	v_pk_add_f32 v[82:83], v[82:83], 1.0 op_sel_hi:[1,0]
	v_pk_add_f32 v[84:85], v[84:85], 1.0 op_sel_hi:[1,0]
	v_pk_add_f32 v[88:89], v[88:89], 1.0 op_sel_hi:[1,0]
	s_mov_b64 vcc, s[6:7]
	v_rcp_f32_e32 v92, v83
	s_mov_b64 vcc, s[8:9]
	v_rcp_f32_e32 v93, v82
	s_mov_b64 vcc, s[10:11]
	v_rcp_f32_e32 v85, v85
	s_mov_b64 vcc, s[12:13]
	v_rcp_f32_e32 v84, v84
	v_add_f32_e32 v90, v74, v90
	v_rcp_f32_e32 v89, v89
	v_add_f32_e32 v82, v75, v91
	v_mul_f32_e32 v90, 0xbfb8aa3b, v90
	v_mul_f32_e32 v82, 0xbfb8aa3b, v82
	v_exp_f32_e32 v90, v90
	v_exp_f32_e32 v91, v82
	s_nop 0
	v_pk_add_f32 v[82:83], v[90:91], 1.0 op_sel_hi:[1,0]
	s_mov_b64 vcc, s[14:15]
	v_rcp_f32_e32 v88, v88
	v_rcp_f32_e32 v90, v83
	v_cvt_pk_bf16_f32 v84, v84, v85
	v_rcp_f32_e32 v91, v82
	v_cvt_pk_bf16_f32 v82, v93, v92
	v_cvt_pk_bf16_f32 v83, v88, v89
	v_cvt_pk_bf16_f32 v85, v91, v90
	flat_store_dwordx4 v[86:87], v[82:85]
	v_lshl_add_u64 v[80:81], s[22:23], 0, v[80:81]
	s_nop 0
	v_lshl_add_u64 v[84:85], v[148:149], 1, v[80:81]
	s_cbranch_execz .LBB0_3080

; DI float softplus_fast(float x) { return fmaxf(x, 0.f) + __logf(1.f + __expf(-fabsf(x))); }
; #define EPI_ROWS(...) _Pragma("unroll") for (int ai = 0; ai < 2; ++ai) _Pragma("unroll") for (int m = 0; m < 4; ++m) { const int row = u.pm * 256 + ai * 128 + wr * 64 + m * 16 + fr; __VA_ARGS__ }
; DI u32x4 pack8(f32x4 a, f32x4 b) { u32x4 w; w.x = pk2(a[0], a[1]); w.y = pk2(a[2], a[3]); w.z = pk2(b[0], b[1]); w.w = pk2(b[2], b[3]); return w; }
; DI float sigmoidf_(float x) { return 1.f / (1.f + __expf(-x)); }
;     DI void operator()(const Acc& acc, const Unit& u, int wr, int wc, int fr, int fq) const {
;         const int pn = u.pn;
;         EPI_ROWS( _Pragma("unroll") for (int bj = 0; bj < 2; ++bj) { const int c0 = (pn & 3) * 256 + bj * 128 + wc * 32 + 8 * fq;
;                 if (pn < 4) { u32x4 o;
;                     _Pragma("unroll") for (int n = 0; n < 2; ++n) _Pragma("unroll") for (int e2 = 0; e2 < 2; ++e2) {
;                         const float wa = -softplus_fast(-(w0[c0 + 4 * n + 2 * e2] + acc[ai][bj][m][n][2 * e2])) - 0.5f, wb = -softplus_fast(-(w0[c0 + 4 * n + 2 * e2 + 1] + acc[ai][bj][m][n][2 * e2 + 1])) - 0.5f;
;                         h16x2 hv = {(_Float16)(-__expf(wa)), (_Float16)(-__expf(wb))}; o[2 * n + e2] = __builtin_bit_cast(unsigned, hv); }
;                     *(u32x4*)(LD + (size_t)row * 1024 + c0) = o;
;                 } else { f32x4 a, b;
;                     _Pragma("unroll") for (int e = 0; e < 4; ++e) { a[e] = sigmoidf_(a0[c0 + e] + acc[ai][bj][m][0][e]); b[e] = sigmoidf_(a0[c0 + 4 + e] + acc[ai][bj][m][1][e]); }
;                     *(u32x4*)(AA + (size_t)row * 1024 + c0) = pack8(a, b); } } )
.LBB0_3078:
	global_load_dwordx4 v[72:75], v[144:145], off offset:512
	global_load_dwordx4 v[76:79], v[144:145], off offset:528
	s_waitcnt vmcnt(0)
	v_add_f32_e32 v72, v68, v72
	v_add_f32_e32 v73, v69, v73
	v_mul_f32_e32 v72, 0xbfb8aa3b, v72
	v_mul_f32_e32 v73, 0xbfb8aa3b, v73
	v_add_f32_e32 v76, v64, v76
	v_add_f32_e32 v77, v65, v77
	v_exp_f32_e32 v72, v72
	v_exp_f32_e32 v73, v73
	v_add_f32_e32 v74, v70, v74
	v_add_f32_e32 v75, v71, v75
	v_mul_f32_e32 v76, 0xbfb8aa3b, v76
	v_mul_f32_e32 v77, 0xbfb8aa3b, v77
	v_mul_f32_e32 v80, 0xbfb8aa3b, v74
	v_mul_f32_e32 v81, 0xbfb8aa3b, v75
	v_exp_f32_e32 v74, v76
	v_exp_f32_e32 v75, v77
	v_exp_f32_e32 v76, v80
	v_exp_f32_e32 v77, v81
	v_pk_add_f32 v[72:73], v[72:73], 1.0 op_sel_hi:[1,0]
	v_pk_add_f32 v[74:75], v[74:75], 1.0 op_sel_hi:[1,0]
	v_pk_add_f32 v[76:77], v[76:77], 1.0 op_sel_hi:[1,0]
	s_mov_b64 vcc, s[6:7]
	v_rcp_f32_e32 v80, v73
	s_mov_b64 vcc, s[8:9]
	v_rcp_f32_e32 v81, v72
	s_mov_b64 vcc, s[10:11]
	v_rcp_f32_e32 v75, v75
	s_mov_b64 vcc, s[12:13]
	v_rcp_f32_e32 v74, v74
	v_add_f32_e32 v78, v66, v78
	v_rcp_f32_e32 v77, v77
	v_add_f32_e32 v72, v67, v79
	v_mul_f32_e32 v78, 0xbfb8aa3b, v78
	v_mul_f32_e32 v72, 0xbfb8aa3b, v72
	v_exp_f32_e32 v78, v78
	v_exp_f32_e32 v79, v72
	s_nop 0
	v_pk_add_f32 v[72:73], v[78:79], 1.0 op_sel_hi:[1,0]
	s_mov_b64 vcc, s[14:15]
	v_rcp_f32_e32 v76, v76
	v_rcp_f32_e32 v78, v73
	v_cvt_pk_bf16_f32 v74, v74, v75
	v_rcp_f32_e32 v79, v72
	v_cvt_pk_bf16_f32 v72, v81, v80
	v_cvt_pk_bf16_f32 v73, v76, v77
	v_cvt_pk_bf16_f32 v75, v79, v78
	flat_store_dwordx4 v[86:87], v[72:75] offset:256
	s_cbranch_execz .LBB0_3082
	s_branch .LBB0_3083

; DI float softplus_fast(float x) { return fmaxf(x, 0.f) + __logf(1.f + __expf(-fabsf(x))); }
; #define EPI_ROWS(...) _Pragma("unroll") for (int ai = 0; ai < 2; ++ai) _Pragma("unroll") for (int m = 0; m < 4; ++m) { const int row = u.pm * 256 + ai * 128 + wr * 64 + m * 16 + fr; __VA_ARGS__ }
; DI u32x4 pack8(f32x4 a, f32x4 b) { u32x4 w; w.x = pk2(a[0], a[1]); w.y = pk2(a[2], a[3]); w.z = pk2(b[0], b[1]); w.w = pk2(b[2], b[3]); return w; }
; DI float sigmoidf_(float x) { return 1.f / (1.f + __expf(-x)); }
;     DI void operator()(const Acc& acc, const Unit& u, int wr, int wc, int fr, int fq) const {
;         const int pn = u.pn;
;         EPI_ROWS( _Pragma("unroll") for (int bj = 0; bj < 2; ++bj) { const int c0 = (pn & 3) * 256 + bj * 128 + wc * 32 + 8 * fq;
;                 if (pn < 4) { u32x4 o;
;                     _Pragma("unroll") for (int n = 0; n < 2; ++n) _Pragma("unroll") for (int e2 = 0; e2 < 2; ++e2) {
;                         const float wa = -softplus_fast(-(w0[c0 + 4 * n + 2 * e2] + acc[ai][bj][m][n][2 * e2])) - 0.5f, wb = -softplus_fast(-(w0[c0 + 4 * n + 2 * e2 + 1] + acc[ai][bj][m][n][2 * e2 + 1])) - 0.5f;
;                         h16x2 hv = {(_Float16)(-__expf(wa)), (_Float16)(-__expf(wb))}; o[2 * n + e2] = __builtin_bit_cast(unsigned, hv); }
;                     *(u32x4*)(LD + (size_t)row * 1024 + c0) = o;
;                 } else { f32x4 a, b;
;                     _Pragma("unroll") for (int e = 0; e < 4; ++e) { a[e] = sigmoidf_(a0[c0 + e] + acc[ai][bj][m][0][e]); b[e] = sigmoidf_(a0[c0 + 4 + e] + acc[ai][bj][m][1][e]); }
;                     *(u32x4*)(AA + (size_t)row * 1024 + c0) = pack8(a, b); } } )
.LBB0_3083:
	s_nop 1
	v_add_u32_e32 v64, 0x80, v150
	v_ashrrev_i32_e32 v65, 31, v64
	v_lshlrev_b64 v[64:65], 11, v[64:65]
	v_lshl_add_u64 v[66:67], s[24:25], 0, v[64:65]
	s_mov_b64 s[6:7], -1
	s_and_b64 vcc, exec, s[4:5]
	v_lshl_add_u64 v[70:71], v[148:149], 1, v[66:67]
	s_cbranch_vccnz .LBB0_3087
	global_load_dwordx4 v[66:69], v[144:145], off
	global_load_dwordx4 v[72:75], v[144:145], off offset:16
	s_waitcnt vmcnt(0)
	v_add_f32_e32 v66, v60, v66
	v_add_f32_e32 v67, v61, v67
	v_mul_f32_e32 v66, 0xbfb8aa3b, v66
	v_mul_f32_e32 v67, 0xbfb8aa3b, v67
	v_add_f32_e32 v72, v56, v72
	v_add_f32_e32 v73, v57, v73
	v_exp_f32_e32 v66, v66
	v_exp_f32_e32 v67, v67
	v_add_f32_e32 v68, v62, v68
	v_add_f32_e32 v69, v63, v69
	v_mul_f32_e32 v72, 0xbfb8aa3b, v72
	v_mul_f32_e32 v73, 0xbfb8aa3b, v73
	v_mul_f32_e32 v76, 0xbfb8aa3b, v68
	v_mul_f32_e32 v77, 0xbfb8aa3b, v69
	v_exp_f32_e32 v68, v72
	v_exp_f32_e32 v69, v73
	v_exp_f32_e32 v72, v76
	v_exp_f32_e32 v73, v77
	v_pk_add_f32 v[66:67], v[66:67], 1.0 op_sel_hi:[1,0]
	v_pk_add_f32 v[68:69], v[68:69], 1.0 op_sel_hi:[1,0]
	v_pk_add_f32 v[72:73], v[72:73], 1.0 op_sel_hi:[1,0]
	s_mov_b64 vcc, s[6:7]
	v_rcp_f32_e32 v76, v67
	s_mov_b64 vcc, s[8:9]
	v_rcp_f32_e32 v77, v66
	s_mov_b64 vcc, s[10:11]
	v_rcp_f32_e32 v69, v69
	s_mov_b64 vcc, s[12:13]
	v_rcp_f32_e32 v68, v68
	v_add_f32_e32 v74, v58, v74
	v_rcp_f32_e32 v73, v73
	v_add_f32_e32 v66, v59, v75
	v_mul_f32_e32 v74, 0xbfb8aa3b, v74
	v_mul_f32_e32 v66, 0xbfb8aa3b, v66
	v_exp_f32_e32 v74, v74
	v_exp_f32_e32 v75, v66
	s_nop 0
	v_pk_add_f32 v[66:67], v[74:75], 1.0 op_sel_hi:[1,0]
	s_mov_b64 vcc, s[14:15]
	v_rcp_f32_e32 v72, v72
	v_rcp_f32_e32 v74, v67
	v_cvt_pk_bf16_f32 v68, v68, v69
	v_rcp_f32_e32 v75, v66
	v_cvt_pk_bf16_f32 v66, v77, v76
	v_cvt_pk_bf16_f32 v67, v72, v73
	v_cvt_pk_bf16_f32 v69, v75, v74
	flat_store_dwordx4 v[70:71], v[66:69]
	v_lshl_add_u64 v[64:65], s[22:23], 0, v[64:65]
	s_nop 0
	v_lshl_add_u64 v[68:69], v[148:149], 1, v[64:65]
	s_cbranch_execz .LBB0_3088

; DI float softplus_fast(float x) { return fmaxf(x, 0.f) + __logf(1.f + __expf(-fabsf(x))); }
; #define EPI_ROWS(...) _Pragma("unroll") for (int ai = 0; ai < 2; ++ai) _Pragma("unroll") for (int m = 0; m < 4; ++m) { const int row = u.pm * 256 + ai * 128 + wr * 64 + m * 16 + fr; __VA_ARGS__ }
; DI u32x4 pack8(f32x4 a, f32x4 b) { u32x4 w; w.x = pk2(a[0], a[1]); w.y = pk2(a[2], a[3]); w.z = pk2(b[0], b[1]); w.w = pk2(b[2], b[3]); return w; }
; DI float sigmoidf_(float x) { return 1.f / (1.f + __expf(-x)); }
;     DI void operator()(const Acc& acc, const Unit& u, int wr, int wc, int fr, int fq) const {
;         const int pn = u.pn;
;         EPI_ROWS( _Pragma("unroll") for (int bj = 0; bj < 2; ++bj) { const int c0 = (pn & 3) * 256 + bj * 128 + wc * 32 + 8 * fq;
;                 if (pn < 4) { u32x4 o;
;                     _Pragma("unroll") for (int n = 0; n < 2; ++n) _Pragma("unroll") for (int e2 = 0; e2 < 2; ++e2) {
;                         const float wa = -softplus_fast(-(w0[c0 + 4 * n + 2 * e2] + acc[ai][bj][m][n][2 * e2])) - 0.5f, wb = -softplus_fast(-(w0[c0 + 4 * n + 2 * e2 + 1] + acc[ai][bj][m][n][2 * e2 + 1])) - 0.5f;
;                         h16x2 hv = {(_Float16)(-__expf(wa)), (_Float16)(-__expf(wb))}; o[2 * n + e2] = __builtin_bit_cast(unsigned, hv); }
;                     *(u32x4*)(LD + (size_t)row * 1024 + c0) = o;
;                 } else { f32x4 a, b;
;                     _Pragma("unroll") for (int e = 0; e < 4; ++e) { a[e] = sigmoidf_(a0[c0 + e] + acc[ai][bj][m][0][e]); b[e] = sigmoidf_(a0[c0 + 4 + e] + acc[ai][bj][m][1][e]); }
;                     *(u32x4*)(AA + (size_t)row * 1024 + c0) = pack8(a, b); } } )
.LBB0_3086:
	global_load_dwordx4 v[56:59], v[144:145], off offset:512
	global_load_dwordx4 v[60:63], v[144:145], off offset:528
	s_waitcnt vmcnt(0)
	v_add_f32_e32 v56, v52, v56
	v_add_f32_e32 v57, v53, v57
	v_mul_f32_e32 v56, 0xbfb8aa3b, v56
	v_mul_f32_e32 v57, 0xbfb8aa3b, v57
	v_add_f32_e32 v60, v48, v60
	v_add_f32_e32 v61, v49, v61
	v_exp_f32_e32 v56, v56
	v_exp_f32_e32 v57, v57
	v_add_f32_e32 v58, v54, v58
	v_add_f32_e32 v59, v55, v59
	v_mul_f32_e32 v60, 0xbfb8aa3b, v60
	v_mul_f32_e32 v61, 0xbfb8aa3b, v61
	v_mul_f32_e32 v64, 0xbfb8aa3b, v58
	v_mul_f32_e32 v65, 0xbfb8aa3b, v59
	v_exp_f32_e32 v58, v60
	v_exp_f32_e32 v59, v61
	v_exp_f32_e32 v60, v64
	v_exp_f32_e32 v61, v65
	v_pk_add_f32 v[56:57], v[56:57], 1.0 op_sel_hi:[1,0]
	v_pk_add_f32 v[58:59], v[58:59], 1.0 op_sel_hi:[1,0]
	v_pk_add_f32 v[60:61], v[60:61], 1.0 op_sel_hi:[1,0]
	s_mov_b64 vcc, s[6:7]
	v_rcp_f32_e32 v64, v57
	s_mov_b64 vcc, s[8:9]
	v_rcp_f32_e32 v65, v56
	s_mov_b64 vcc, s[10:11]
	v_rcp_f32_e32 v59, v59
	s_mov_b64 vcc, s[12:13]
	v_rcp_f32_e32 v58, v58
	v_add_f32_e32 v62, v50, v62
	v_rcp_f32_e32 v61, v61
	v_add_f32_e32 v56, v51, v63
	v_mul_f32_e32 v62, 0xbfb8aa3b, v62
	v_mul_f32_e32 v56, 0xbfb8aa3b, v56
	v_exp_f32_e32 v62, v62
	v_exp_f32_e32 v63, v56
	s_nop 0
	v_pk_add_f32 v[56:57], v[62:63], 1.0 op_sel_hi:[1,0]
	s_mov_b64 vcc, s[14:15]
	v_rcp_f32_e32 v60, v60
	v_rcp_f32_e32 v62, v57
	v_cvt_pk_bf16_f32 v58, v58, v59
	v_rcp_f32_e32 v63, v56
	v_cvt_pk_bf16_f32 v56, v65, v64
	v_cvt_pk_bf16_f32 v57, v60, v61
	v_cvt_pk_bf16_f32 v59, v63, v62
	flat_store_dwordx4 v[70:71], v[56:59] offset:256
	s_cbranch_execz .LBB0_3090
	s_branch .LBB0_3091

; DI float softplus_fast(float x) { return fmaxf(x, 0.f) + __logf(1.f + __expf(-fabsf(x))); }
; #define EPI_ROWS(...) _Pragma("unroll") for (int ai = 0; ai < 2; ++ai) _Pragma("unroll") for (int m = 0; m < 4; ++m) { const int row = u.pm * 256 + ai * 128 + wr * 64 + m * 16 + fr; __VA_ARGS__ }
; DI u32x4 pack8(f32x4 a, f32x4 b) { u32x4 w; w.x = pk2(a[0], a[1]); w.y = pk2(a[2], a[3]); w.z = pk2(b[0], b[1]); w.w = pk2(b[2], b[3]); return w; }
; DI float sigmoidf_(float x) { return 1.f / (1.f + __expf(-x)); }
;     DI void operator()(const Acc& acc, const Unit& u, int wr, int wc, int fr, int fq) const {
;         const int pn = u.pn;
;         EPI_ROWS( _Pragma("unroll") for (int bj = 0; bj < 2; ++bj) { const int c0 = (pn & 3) * 256 + bj * 128 + wc * 32 + 8 * fq;
;                 if (pn < 4) { u32x4 o;
;                     _Pragma("unroll") for (int n = 0; n < 2; ++n) _Pragma("unroll") for (int e2 = 0; e2 < 2; ++e2) {
;                         const float wa = -softplus_fast(-(w0[c0 + 4 * n + 2 * e2] + acc[ai][bj][m][n][2 * e2])) - 0.5f, wb = -softplus_fast(-(w0[c0 + 4 * n + 2 * e2 + 1] + acc[ai][bj][m][n][2 * e2 + 1])) - 0.5f;
;                         h16x2 hv = {(_Float16)(-__expf(wa)), (_Float16)(-__expf(wb))}; o[2 * n + e2] = __builtin_bit_cast(unsigned, hv); }
;                     *(u32x4*)(LD + (size_t)row * 1024 + c0) = o;
;                 } else { f32x4 a, b;
;                     _Pragma("unroll") for (int e = 0; e < 4; ++e) { a[e] = sigmoidf_(a0[c0 + e] + acc[ai][bj][m][0][e]); b[e] = sigmoidf_(a0[c0 + 4 + e] + acc[ai][bj][m][1][e]); }
;                     *(u32x4*)(AA + (size_t)row * 1024 + c0) = pack8(a, b); } } )
.LBB0_3091:
	s_nop 1
	v_add_u32_e32 v48, 0x90, v150
	v_ashrrev_i32_e32 v49, 31, v48
	v_lshlrev_b64 v[48:49], 11, v[48:49]
	v_lshl_add_u64 v[50:51], s[24:25], 0, v[48:49]
	s_mov_b64 s[6:7], -1
	s_and_b64 vcc, exec, s[4:5]
	v_lshl_add_u64 v[54:55], v[148:149], 1, v[50:51]
	s_cbranch_vccnz .LBB0_3095
	global_load_dwordx4 v[50:53], v[144:145], off
	global_load_dwordx4 v[56:59], v[144:145], off offset:16
	s_waitcnt vmcnt(0)
	v_add_f32_e32 v50, v44, v50
	v_add_f32_e32 v51, v45, v51
	v_mul_f32_e32 v50, 0xbfb8aa3b, v50
	v_mul_f32_e32 v51, 0xbfb8aa3b, v51
	v_add_f32_e32 v56, v40, v56
	v_add_f32_e32 v57, v41, v57
	v_exp_f32_e32 v50, v50
	v_exp_f32_e32 v51, v51
	v_add_f32_e32 v52, v46, v52
	v_add_f32_e32 v53, v47, v53
	v_mul_f32_e32 v56, 0xbfb8aa3b, v56
	v_mul_f32_e32 v57, 0xbfb8aa3b, v57
	v_mul_f32_e32 v60, 0xbfb8aa3b, v52
	v_mul_f32_e32 v61, 0xbfb8aa3b, v53
	v_exp_f32_e32 v52, v56
	v_exp_f32_e32 v53, v57
	v_exp_f32_e32 v56, v60
	v_exp_f32_e32 v57, v61
	v_pk_add_f32 v[50:51], v[50:51], 1.0 op_sel_hi:[1,0]
	v_pk_add_f32 v[52:53], v[52:53], 1.0 op_sel_hi:[1,0]
	v_pk_add_f32 v[56:57], v[56:57], 1.0 op_sel_hi:[1,0]
	s_mov_b64 vcc, s[6:7]
	v_rcp_f32_e32 v60, v51
	s_mov_b64 vcc, s[8:9]
	v_rcp_f32_e32 v61, v50
	s_mov_b64 vcc, s[10:11]
	v_rcp_f32_e32 v53, v53
	s_mov_b64 vcc, s[12:13]
	v_rcp_f32_e32 v52, v52
	v_add_f32_e32 v58, v42, v58
	v_rcp_f32_e32 v57, v57
	v_add_f32_e32 v50, v43, v59
	v_mul_f32_e32 v58, 0xbfb8aa3b, v58
	v_mul_f32_e32 v50, 0xbfb8aa3b, v50
	v_exp_f32_e32 v58, v58
	v_exp_f32_e32 v59, v50
	s_nop 0
	v_pk_add_f32 v[50:51], v[58:59], 1.0 op_sel_hi:[1,0]
	s_mov_b64 vcc, s[14:15]
	v_rcp_f32_e32 v56, v56
	v_rcp_f32_e32 v58, v51
	v_cvt_pk_bf16_f32 v52, v52, v53
	v_rcp_f32_e32 v59, v50
	v_cvt_pk_bf16_f32 v50, v61, v60
	v_cvt_pk_bf16_f32 v51, v56, v57
	v_cvt_pk_bf16_f32 v53, v59, v58
	flat_store_dwordx4 v[54:55], v[50:53]
	v_lshl_add_u64 v[48:49], s[22:23], 0, v[48:49]
	s_nop 0
	v_lshl_add_u64 v[52:53], v[148:149], 1, v[48:49]
	s_cbranch_execz .LBB0_3096

; DI float softplus_fast(float x) { return fmaxf(x, 0.f) + __logf(1.f + __expf(-fabsf(x))); }
; #define EPI_ROWS(...) _Pragma("unroll") for (int ai = 0; ai < 2; ++ai) _Pragma("unroll") for (int m = 0; m < 4; ++m) { const int row = u.pm * 256 + ai * 128 + wr * 64 + m * 16 + fr; __VA_ARGS__ }
; DI u32x4 pack8(f32x4 a, f32x4 b) { u32x4 w; w.x = pk2(a[0], a[1]); w.y = pk2(a[2], a[3]); w.z = pk2(b[0], b[1]); w.w = pk2(b[2], b[3]); return w; }
; DI float sigmoidf_(float x) { return 1.f / (1.f + __expf(-x)); }
;     DI void operator()(const Acc& acc, const Unit& u, int wr, int wc, int fr, int fq) const {
;         const int pn = u.pn;
;         EPI_ROWS( _Pragma("unroll") for (int bj = 0; bj < 2; ++bj) { const int c0 = (pn & 3) * 256 + bj * 128 + wc * 32 + 8 * fq;
;                 if (pn < 4) { u32x4 o;
;                     _Pragma("unroll") for (int n = 0; n < 2; ++n) _Pragma("unroll") for (int e2 = 0; e2 < 2; ++e2) {
;                         const float wa = -softplus_fast(-(w0[c0 + 4 * n + 2 * e2] + acc[ai][bj][m][n][2 * e2])) - 0.5f, wb = -softplus_fast(-(w0[c0 + 4 * n + 2 * e2 + 1] + acc[ai][bj][m][n][2 * e2 + 1])) - 0.5f;
;                         h16x2 hv = {(_Float16)(-__expf(wa)), (_Float16)(-__expf(wb))}; o[2 * n + e2] = __builtin_bit_cast(unsigned, hv); }
;                     *(u32x4*)(LD + (size_t)row * 1024 + c0) = o;
;                 } else { f32x4 a, b;
;                     _Pragma("unroll") for (int e = 0; e < 4; ++e) { a[e] = sigmoidf_(a0[c0 + e] + acc[ai][bj][m][0][e]); b[e] = sigmoidf_(a0[c0 + 4 + e] + acc[ai][bj][m][1][e]); }
;                     *(u32x4*)(AA + (size_t)row * 1024 + c0) = pack8(a, b); } } )
.LBB0_3094:
	global_load_dwordx4 v[40:43], v[144:145], off offset:512
	global_load_dwordx4 v[44:47], v[144:145], off offset:528
	s_waitcnt vmcnt(0)
	v_add_f32_e32 v40, v36, v40
	v_add_f32_e32 v41, v37, v41
	v_mul_f32_e32 v40, 0xbfb8aa3b, v40
	v_mul_f32_e32 v41, 0xbfb8aa3b, v41
	v_add_f32_e32 v44, v32, v44
	v_add_f32_e32 v45, v33, v45
	v_exp_f32_e32 v40, v40
	v_exp_f32_e32 v41, v41
	v_add_f32_e32 v42, v38, v42
	v_add_f32_e32 v43, v39, v43
	v_mul_f32_e32 v44, 0xbfb8aa3b, v44
	v_mul_f32_e32 v45, 0xbfb8aa3b, v45
	v_mul_f32_e32 v48, 0xbfb8aa3b, v42
	v_mul_f32_e32 v49, 0xbfb8aa3b, v43
	v_exp_f32_e32 v42, v44
	v_exp_f32_e32 v43, v45
	v_exp_f32_e32 v44, v48
	v_exp_f32_e32 v45, v49
	v_pk_add_f32 v[40:41], v[40:41], 1.0 op_sel_hi:[1,0]
	v_pk_add_f32 v[42:43], v[42:43], 1.0 op_sel_hi:[1,0]
	v_pk_add_f32 v[44:45], v[44:45], 1.0 op_sel_hi:[1,0]
	s_mov_b64 vcc, s[6:7]
	v_rcp_f32_e32 v48, v41
	s_mov_b64 vcc, s[8:9]
	v_rcp_f32_e32 v49, v40
	s_mov_b64 vcc, s[10:11]
	v_rcp_f32_e32 v43, v43
	s_mov_b64 vcc, s[12:13]
	v_rcp_f32_e32 v42, v42
	v_add_f32_e32 v46, v34, v46
	v_rcp_f32_e32 v45, v45
	v_add_f32_e32 v40, v35, v47
	v_mul_f32_e32 v46, 0xbfb8aa3b, v46
	v_mul_f32_e32 v40, 0xbfb8aa3b, v40
	v_exp_f32_e32 v46, v46
	v_exp_f32_e32 v47, v40
	s_nop 0
	v_pk_add_f32 v[40:41], v[46:47], 1.0 op_sel_hi:[1,0]
	s_mov_b64 vcc, s[14:15]
	v_rcp_f32_e32 v44, v44
	v_rcp_f32_e32 v46, v41
	v_cvt_pk_bf16_f32 v42, v42, v43
	v_rcp_f32_e32 v47, v40
	v_cvt_pk_bf16_f32 v40, v49, v48
	v_cvt_pk_bf16_f32 v41, v44, v45
	v_cvt_pk_bf16_f32 v43, v47, v46
	flat_store_dwordx4 v[54:55], v[40:43] offset:256
	s_cbranch_execz .LBB0_3098
	s_branch .LBB0_3099

.LBB0_3099:
	s_nop 1
	v_add_u32_e32 v32, 0xa0, v150
	v_ashrrev_i32_e32 v33, 31, v32
	v_lshlrev_b64 v[32:33], 11, v[32:33]
	v_lshl_add_u64 v[34:35], s[24:25], 0, v[32:33]
	s_mov_b64 s[6:7], -1
	s_and_b64 vcc, exec, s[4:5]
	v_lshl_add_u64 v[38:39], v[148:149], 1, v[34:35]
	s_cbranch_vccnz .LBB0_3103
	global_load_dwordx4 v[34:37], v[144:145], off
	global_load_dwordx4 v[40:43], v[144:145], off offset:16
	s_waitcnt vmcnt(0)
	v_add_f32_e32 v34, v28, v34
	v_add_f32_e32 v35, v29, v35
	v_mul_f32_e32 v34, 0xbfb8aa3b, v34
	v_mul_f32_e32 v35, 0xbfb8aa3b, v35
	v_add_f32_e32 v40, v24, v40
	v_add_f32_e32 v41, v25, v41
	v_exp_f32_e32 v34, v34
	v_exp_f32_e32 v35, v35
	v_add_f32_e32 v36, v30, v36
	v_add_f32_e32 v37, v31, v37
	v_mul_f32_e32 v40, 0xbfb8aa3b, v40
	v_mul_f32_e32 v41, 0xbfb8aa3b, v41
	v_mul_f32_e32 v44, 0xbfb8aa3b, v36
	v_mul_f32_e32 v45, 0xbfb8aa3b, v37
	v_exp_f32_e32 v36, v40
	v_exp_f32_e32 v37, v41
	v_exp_f32_e32 v40, v44
	v_exp_f32_e32 v41, v45
	v_pk_add_f32 v[34:35], v[34:35], 1.0 op_sel_hi:[1,0]
	v_pk_add_f32 v[36:37], v[36:37], 1.0 op_sel_hi:[1,0]
	v_pk_add_f32 v[40:41], v[40:41], 1.0 op_sel_hi:[1,0]
	s_mov_b64 vcc, s[6:7]
	v_rcp_f32_e32 v44, v35
	s_mov_b64 vcc, s[8:9]
	v_rcp_f32_e32 v45, v34
	s_mov_b64 vcc, s[10:11]
	v_rcp_f32_e32 v37, v37
	s_mov_b64 vcc, s[12:13]
	v_rcp_f32_e32 v36, v36
	v_add_f32_e32 v42, v26, v42
	v_rcp_f32_e32 v41, v41
	v_add_f32_e32 v34, v27, v43
	v_mul_f32_e32 v42, 0xbfb8aa3b, v42
	v_mul_f32_e32 v34, 0xbfb8aa3b, v34
	v_exp_f32_e32 v42, v42
	v_exp_f32_e32 v43, v34
	s_nop 0
	v_pk_add_f32 v[34:35], v[42:43], 1.0 op_sel_hi:[1,0]
	s_mov_b64 vcc, s[14:15]
	v_rcp_f32_e32 v40, v40
	v_rcp_f32_e32 v42, v35
	v_cvt_pk_bf16_f32 v36, v36, v37
	v_rcp_f32_e32 v43, v34
	v_cvt_pk_bf16_f32 v34, v45, v44
	v_cvt_pk_bf16_f32 v35, v40, v41
	v_cvt_pk_bf16_f32 v37, v43, v42
	flat_store_dwordx4 v[38:39], v[34:37]
	v_lshl_add_u64 v[32:33], s[22:23], 0, v[32:33]
	s_nop 0
	v_lshl_add_u64 v[36:37], v[148:149], 1, v[32:33]
	s_cbranch_execz .LBB0_3104

.LBB0_3102:
	global_load_dwordx4 v[24:27], v[144:145], off offset:512
	global_load_dwordx4 v[28:31], v[144:145], off offset:528
	s_waitcnt vmcnt(0)
	v_add_f32_e32 v24, v20, v24
	v_add_f32_e32 v25, v21, v25
	v_mul_f32_e32 v24, 0xbfb8aa3b, v24
	v_mul_f32_e32 v25, 0xbfb8aa3b, v25
	v_add_f32_e32 v28, v16, v28
	v_add_f32_e32 v29, v17, v29
	v_exp_f32_e32 v24, v24
	v_exp_f32_e32 v25, v25
	v_add_f32_e32 v26, v22, v26
	v_add_f32_e32 v27, v23, v27
	v_mul_f32_e32 v28, 0xbfb8aa3b, v28
	v_mul_f32_e32 v29, 0xbfb8aa3b, v29
	v_mul_f32_e32 v32, 0xbfb8aa3b, v26
	v_mul_f32_e32 v33, 0xbfb8aa3b, v27
	v_exp_f32_e32 v26, v28
	v_exp_f32_e32 v27, v29
	v_exp_f32_e32 v28, v32
	v_exp_f32_e32 v29, v33
	v_pk_add_f32 v[24:25], v[24:25], 1.0 op_sel_hi:[1,0]
	v_pk_add_f32 v[26:27], v[26:27], 1.0 op_sel_hi:[1,0]
	v_pk_add_f32 v[28:29], v[28:29], 1.0 op_sel_hi:[1,0]
	s_mov_b64 vcc, s[6:7]
	v_rcp_f32_e32 v32, v25
	s_mov_b64 vcc, s[8:9]
	v_rcp_f32_e32 v33, v24
	s_mov_b64 vcc, s[10:11]
	v_rcp_f32_e32 v27, v27
	s_mov_b64 vcc, s[12:13]
	v_rcp_f32_e32 v26, v26
	v_add_f32_e32 v30, v18, v30
	v_rcp_f32_e32 v29, v29
	v_add_f32_e32 v24, v19, v31
	v_mul_f32_e32 v30, 0xbfb8aa3b, v30
	v_mul_f32_e32 v24, 0xbfb8aa3b, v24
	v_exp_f32_e32 v30, v30
	v_exp_f32_e32 v31, v24
	s_nop 0
	v_pk_add_f32 v[24:25], v[30:31], 1.0 op_sel_hi:[1,0]
	s_mov_b64 vcc, s[14:15]
	v_rcp_f32_e32 v28, v28
	v_rcp_f32_e32 v30, v25
	v_cvt_pk_bf16_f32 v26, v26, v27
	v_rcp_f32_e32 v31, v24
	v_cvt_pk_bf16_f32 v24, v33, v32
	v_cvt_pk_bf16_f32 v25, v28, v29
	v_cvt_pk_bf16_f32 v27, v31, v30
	flat_store_dwordx4 v[38:39], v[24:27] offset:256
	s_cbranch_execz .LBB0_3106
	s_branch .LBB0_3107

.LBB0_3107:
	s_nop 1
	v_add_u32_e32 v16, 0xb0, v150
	v_ashrrev_i32_e32 v17, 31, v16
	v_lshlrev_b64 v[16:17], 11, v[16:17]
	v_lshl_add_u64 v[18:19], s[24:25], 0, v[16:17]
	s_mov_b64 s[6:7], -1
	s_and_b64 vcc, exec, s[4:5]
	v_lshl_add_u64 v[22:23], v[148:149], 1, v[18:19]
	s_cbranch_vccnz .LBB0_3112
	global_load_dwordx4 v[18:21], v[144:145], off
	global_load_dwordx4 v[24:27], v[144:145], off offset:16
	s_waitcnt vmcnt(0)
	v_add_f32_e32 v18, v12, v18
	v_add_f32_e32 v19, v13, v19
	v_mul_f32_e32 v18, 0xbfb8aa3b, v18
	v_mul_f32_e32 v19, 0xbfb8aa3b, v19
	v_add_f32_e32 v24, v8, v24
	v_add_f32_e32 v25, v9, v25
	v_exp_f32_e32 v18, v18
	v_exp_f32_e32 v19, v19
	v_add_f32_e32 v20, v14, v20
	v_add_f32_e32 v21, v15, v21
	v_mul_f32_e32 v24, 0xbfb8aa3b, v24
	v_mul_f32_e32 v25, 0xbfb8aa3b, v25
	v_mul_f32_e32 v28, 0xbfb8aa3b, v20
	v_mul_f32_e32 v29, 0xbfb8aa3b, v21
	v_exp_f32_e32 v20, v24
	v_exp_f32_e32 v21, v25
	v_exp_f32_e32 v24, v28
	v_exp_f32_e32 v25, v29
	v_pk_add_f32 v[18:19], v[18:19], 1.0 op_sel_hi:[1,0]
	v_pk_add_f32 v[20:21], v[20:21], 1.0 op_sel_hi:[1,0]
	v_pk_add_f32 v[24:25], v[24:25], 1.0 op_sel_hi:[1,0]
	s_mov_b64 vcc, s[6:7]
	v_rcp_f32_e32 v28, v19
	s_mov_b64 vcc, s[8:9]
	v_rcp_f32_e32 v29, v18
	s_mov_b64 vcc, s[10:11]
	v_rcp_f32_e32 v21, v21
	s_mov_b64 vcc, s[12:13]
	v_rcp_f32_e32 v20, v20
	v_add_f32_e32 v26, v10, v26
	v_rcp_f32_e32 v25, v25
	v_add_f32_e32 v18, v11, v27
	v_mul_f32_e32 v26, 0xbfb8aa3b, v26
	v_mul_f32_e32 v18, 0xbfb8aa3b, v18
	v_exp_f32_e32 v26, v26
	v_exp_f32_e32 v27, v18
	s_nop 0
	v_pk_add_f32 v[18:19], v[26:27], 1.0 op_sel_hi:[1,0]
	s_mov_b64 vcc, s[14:15]
	v_rcp_f32_e32 v24, v24
	v_rcp_f32_e32 v26, v19
	v_cvt_pk_bf16_f32 v20, v20, v21
	v_rcp_f32_e32 v27, v18
	v_cvt_pk_bf16_f32 v18, v29, v28
	v_cvt_pk_bf16_f32 v19, v24, v25
	v_cvt_pk_bf16_f32 v21, v27, v26
	flat_store_dwordx4 v[22:23], v[18:21]
	v_lshl_add_u64 v[16:17], s[22:23], 0, v[16:17]
	s_nop 0
	v_lshl_add_u64 v[20:21], v[148:149], 1, v[16:17]
	s_cbranch_execz .LBB0_3113

.LBB0_3110:
	global_load_dwordx4 v[8:11], v[144:145], off offset:512
	global_load_dwordx4 v[12:15], v[144:145], off offset:528
	s_waitcnt vmcnt(0)
	v_add_f32_e32 v8, v4, v8
	v_add_f32_e32 v9, v5, v9
	v_mul_f32_e32 v8, 0xbfb8aa3b, v8
	v_mul_f32_e32 v9, 0xbfb8aa3b, v9
	v_add_f32_e32 v12, v0, v12
	v_add_f32_e32 v13, v1, v13
	v_exp_f32_e32 v8, v8
	v_exp_f32_e32 v9, v9
	v_add_f32_e32 v10, v6, v10
	v_add_f32_e32 v11, v7, v11
	v_mul_f32_e32 v12, 0xbfb8aa3b, v12
	v_mul_f32_e32 v13, 0xbfb8aa3b, v13
	v_mul_f32_e32 v16, 0xbfb8aa3b, v10
	v_mul_f32_e32 v17, 0xbfb8aa3b, v11
	v_exp_f32_e32 v10, v12
	v_exp_f32_e32 v11, v13
	v_exp_f32_e32 v12, v16
	v_exp_f32_e32 v13, v17
	v_pk_add_f32 v[8:9], v[8:9], 1.0 op_sel_hi:[1,0]
	v_pk_add_f32 v[10:11], v[10:11], 1.0 op_sel_hi:[1,0]
	v_pk_add_f32 v[12:13], v[12:13], 1.0 op_sel_hi:[1,0]
	s_mov_b64 vcc, s[4:5]
	v_rcp_f32_e32 v16, v9
	s_mov_b64 vcc, s[6:7]
	v_rcp_f32_e32 v17, v8
	s_mov_b64 vcc, s[8:9]
	v_rcp_f32_e32 v11, v11
	s_mov_b64 vcc, s[10:11]
	v_rcp_f32_e32 v10, v10
	v_add_f32_e32 v14, v2, v14
	v_rcp_f32_e32 v13, v13
	v_add_f32_e32 v8, v3, v15
	v_mul_f32_e32 v14, 0xbfb8aa3b, v14
	v_mul_f32_e32 v8, 0xbfb8aa3b, v8
	v_exp_f32_e32 v14, v14
	v_exp_f32_e32 v15, v8
	s_nop 0
	v_pk_add_f32 v[8:9], v[14:15], 1.0 op_sel_hi:[1,0]
	s_mov_b64 vcc, s[12:13]
	v_rcp_f32_e32 v12, v12
	v_rcp_f32_e32 v14, v9
	v_cvt_pk_bf16_f32 v10, v10, v11
	v_rcp_f32_e32 v15, v8
	v_cvt_pk_bf16_f32 v8, v17, v16
	v_cvt_pk_bf16_f32 v9, v12, v13
	v_cvt_pk_bf16_f32 v11, v15, v14
	flat_store_dwordx4 v[22:23], v[8:11] offset:256
	s_cbranch_execz .LBB0_3115

.Lscan_chunk:
	s_lshl_b32 s40, s47, 5
	s_and_b32 s40, s40, 32
	s_mul_i32 s41, s40, 0x500
	v_add_u32_e32 v74, s41, v45
	v_lshl_add_u32 v75, s40, 5, v63
	v_lshl_add_u32 v72, s40, 9, v66
	ds_read_b128 v[0:3], v74
	ds_read_b32 v42, v75
	ds_read_b128 v[4:7], v74 offset:256
	ds_read_b128 v[8:11], v74 offset:512
	ds_read_b128 v[12:15], v74 offset:768
	ds_read_b128 v[16:19], v74 offset:1024
	ds_read_b128 v[20:23], v74 offset:1280
	ds_read_b32 v62, v75 offset:32
	ds_read_b128 v[24:27], v74 offset:1536
	ds_read_b128 v[28:31], v74 offset:1792
	ds_read_b128 v[32:35], v74 offset:2048
	ds_read_b128 v[36:39], v74 offset:2304
	s_waitcnt lgkmcnt(7)
	v_pk_mul_f32 v[0:1], v[58:59], v[0:1]
	ds_read_b128 v[46:49], v74 offset:2560
	v_pk_fma_f32 v[0:1], v[60:61], v[2:3], v[0:1]
	ds_read_b32 v44, v75 offset:64
	v_add_f32_e32 v0, v0, v1
	v_pk_mul_f32 v[12:13], v[12:13], v[42:43] op_sel_hi:[1,0]
	v_pk_mul_f32 v[14:15], v[14:15], v[42:43] op_sel_hi:[1,0]
	v_add_f32_dpp v0, v0, v0 quad_perm:[1,0,3,2] row_mask:0xf bank_mask:0xf bound_ctrl:1
	v_pk_fma_f32 v[12:13], v[58:59], v[4:5], v[12:13]
	v_pk_fma_f32 v[14:15], v[60:61], v[6:7], v[14:15]
	v_add_f32_dpp v0, v0, v0 quad_perm:[2,3,0,1] row_mask:0xf bank_mask:0xf bound_ctrl:1
	ds_read_b128 v[50:53], v74 offset:2816
	ds_read_b128 v[54:57], v74 offset:3072
	v_add_f32_dpp v0, v0, v0 row_half_mirror row_mask:0xf bank_mask:0xf bound_ctrl:1
	ds_read_b128 v[68:71], v74 offset:3328
	ds_read_b128 v[76:79], v74 offset:3584
	v_add_f32_dpp v0, v0, v0 row_mirror row_mask:0xf bank_mask:0xf bound_ctrl:1
	s_nop 0
	v_pk_fma_f32 v[58:59], v[8:9], v[0:1], v[12:13] op_sel_hi:[1,0,1]
	v_pk_fma_f32 v[60:61], v[10:11], v[0:1], v[14:15] op_sel_hi:[1,0,1]
	s_waitcnt lgkmcnt(7)
	v_pk_mul_f32 v[20:21], v[58:59], v[20:21]
	ds_read_b128 v[0:3], v74 offset:3840
	v_pk_fma_f32 v[20:21], v[60:61], v[22:23], v[20:21]
	ds_read_b32 v42, v75 offset:96
	v_add_f32_e32 v20, v20, v21
	v_pk_mul_f32 v[32:33], v[32:33], v[62:63] op_sel_hi:[1,0]
	v_pk_mul_f32 v[34:35], v[34:35], v[62:63] op_sel_hi:[1,0]
	v_add_f32_dpp v20, v20, v20 quad_perm:[1,0,3,2] row_mask:0xf bank_mask:0xf bound_ctrl:1
	v_pk_fma_f32 v[32:33], v[58:59], v[24:25], v[32:33]
	v_pk_fma_f32 v[34:35], v[60:61], v[26:27], v[34:35]
	v_pk_mul_f32 v[64:65], v[16:17], v[58:59]
	v_add_f32_dpp v20, v20, v20 quad_perm:[2,3,0,1] row_mask:0xf bank_mask:0xf bound_ctrl:1
	v_pk_fma_f32 v[64:65], v[18:19], v[60:61], v[64:65]
	ds_read_b128 v[4:7], v74 offset:4096
	v_add_f32_dpp v20, v20, v20 row_half_mirror row_mask:0xf bank_mask:0xf bound_ctrl:1
	ds_read_b128 v[8:11], v74 offset:4352
	ds_read_b128 v[12:15], v74 offset:4608
	v_add_f32_dpp v20, v20, v20 row_mirror row_mask:0xf bank_mask:0xf bound_ctrl:1
	ds_read_b128 v[16:19], v74 offset:4864
	v_pk_fma_f32 v[58:59], v[28:29], v[20:21], v[32:33] op_sel_hi:[1,0,1]
	v_pk_fma_f32 v[60:61], v[30:31], v[20:21], v[34:35] op_sel_hi:[1,0,1]
	v_add_f32_e32 v64, v64, v65
	ds_write_b32 v72, v64
	s_waitcnt lgkmcnt(8)
	v_pk_mul_f32 v[46:47], v[58:59], v[46:47]
	ds_read_b128 v[20:23], v74 offset:5120
	v_pk_fma_f32 v[46:47], v[60:61], v[48:49], v[46:47]
	ds_read_b32 v62, v75 offset:128
	v_add_f32_e32 v46, v46, v47
	v_pk_mul_f32 v[68:69], v[68:69], v[44:45] op_sel_hi:[1,0]
	v_pk_mul_f32 v[70:71], v[70:71], v[44:45] op_sel_hi:[1,0]
	v_add_f32_dpp v46, v46, v46 quad_perm:[1,0,3,2] row_mask:0xf bank_mask:0xf bound_ctrl:1
	v_pk_fma_f32 v[68:69], v[58:59], v[50:51], v[68:69]
	v_pk_fma_f32 v[70:71], v[60:61], v[52:53], v[70:71]
	v_pk_mul_f32 v[64:65], v[36:37], v[58:59]
	v_add_f32_dpp v46, v46, v46 quad_perm:[2,3,0,1] row_mask:0xf bank_mask:0xf bound_ctrl:1
	v_pk_fma_f32 v[64:65], v[38:39], v[60:61], v[64:65]
	ds_read_b128 v[24:27], v74 offset:5376
	v_add_f32_dpp v46, v46, v46 row_half_mirror row_mask:0xf bank_mask:0xf bound_ctrl:1
	ds_read_b128 v[28:31], v74 offset:5632
	ds_read_b128 v[32:35], v74 offset:5888
	v_add_f32_dpp v46, v46, v46 row_mirror row_mask:0xf bank_mask:0xf bound_ctrl:1
	ds_read_b128 v[36:39], v74 offset:6144
	v_pk_fma_f32 v[58:59], v[54:55], v[46:47], v[68:69] op_sel_hi:[1,0,1]
	v_pk_fma_f32 v[60:61], v[56:57], v[46:47], v[70:71] op_sel_hi:[1,0,1]
	v_add_f32_e32 v64, v64, v65
	ds_write_b32 v72, v64 offset:512
	s_waitcnt lgkmcnt(9)
	v_pk_mul_f32 v[0:1], v[58:59], v[0:1]
	ds_read_b128 v[46:49], v74 offset:6400
	v_pk_fma_f32 v[0:1], v[60:61], v[2:3], v[0:1]
	ds_read_b32 v44, v75 offset:160
	v_add_f32_e32 v0, v0, v1
	v_pk_mul_f32 v[12:13], v[12:13], v[42:43] op_sel_hi:[1,0]
	v_pk_mul_f32 v[14:15], v[14:15], v[42:43] op_sel_hi:[1,0]
	v_add_f32_dpp v0, v0, v0 quad_perm:[1,0,3,2] row_mask:0xf bank_mask:0xf bound_ctrl:1
	v_pk_fma_f32 v[12:13], v[58:59], v[4:5], v[12:13]
	v_pk_fma_f32 v[14:15], v[60:61], v[6:7], v[14:15]
	v_pk_mul_f32 v[64:65], v[76:77], v[58:59]
	v_add_f32_dpp v0, v0, v0 quad_perm:[2,3,0,1] row_mask:0xf bank_mask:0xf bound_ctrl:1
	v_pk_fma_f32 v[64:65], v[78:79], v[60:61], v[64:65]
	ds_read_b128 v[50:53], v74 offset:6656
	v_add_f32_dpp v0, v0, v0 row_half_mirror row_mask:0xf bank_mask:0xf bound_ctrl:1
	ds_read_b128 v[54:57], v74 offset:6912
	ds_read_b128 v[68:71], v74 offset:7168
	v_add_f32_dpp v0, v0, v0 row_mirror row_mask:0xf bank_mask:0xf bound_ctrl:1
	ds_read_b128 v[76:79], v74 offset:7424
	v_pk_fma_f32 v[58:59], v[8:9], v[0:1], v[12:13] op_sel_hi:[1,0,1]
	v_pk_fma_f32 v[60:61], v[10:11], v[0:1], v[14:15] op_sel_hi:[1,0,1]
	v_add_f32_e32 v64, v64, v65
	ds_write_b32 v72, v64 offset:1024
	s_waitcnt lgkmcnt(9)
	v_pk_mul_f32 v[20:21], v[58:59], v[20:21]
	ds_read_b128 v[0:3], v74 offset:7680
	v_pk_fma_f32 v[20:21], v[60:61], v[22:23], v[20:21]
	ds_read_b32 v42, v75 offset:192
	v_add_f32_e32 v20, v20, v21
	v_pk_mul_f32 v[32:33], v[32:33], v[62:63] op_sel_hi:[1,0]
	v_pk_mul_f32 v[34:35], v[34:35], v[62:63] op_sel_hi:[1,0]
	v_add_f32_dpp v20, v20, v20 quad_perm:[1,0,3,2] row_mask:0xf bank_mask:0xf bound_ctrl:1
	v_pk_fma_f32 v[32:33], v[58:59], v[24:25], v[32:33]
	v_pk_fma_f32 v[34:35], v[60:61], v[26:27], v[34:35]
	v_pk_mul_f32 v[64:65], v[16:17], v[58:59]
	v_add_f32_dpp v20, v20, v20 quad_perm:[2,3,0,1] row_mask:0xf bank_mask:0xf bound_ctrl:1
	v_pk_fma_f32 v[64:65], v[18:19], v[60:61], v[64:65]
	ds_read_b128 v[4:7], v74 offset:7936
	v_add_f32_dpp v20, v20, v20 row_half_mirror row_mask:0xf bank_mask:0xf bound_ctrl:1
	ds_read_b128 v[8:11], v74 offset:8192
	ds_read_b128 v[12:15], v74 offset:8448
	v_add_f32_dpp v20, v20, v20 row_mirror row_mask:0xf bank_mask:0xf bound_ctrl:1
	ds_read_b128 v[16:19], v74 offset:8704
	v_pk_fma_f32 v[58:59], v[28:29], v[20:21], v[32:33] op_sel_hi:[1,0,1]
	v_pk_fma_f32 v[60:61], v[30:31], v[20:21], v[34:35] op_sel_hi:[1,0,1]
	v_add_f32_e32 v64, v64, v65
	ds_write_b32 v72, v64 offset:1536
	s_waitcnt lgkmcnt(9)
	v_pk_mul_f32 v[46:47], v[58:59], v[46:47]
	ds_read_b128 v[20:23], v74 offset:8960
	v_pk_fma_f32 v[46:47], v[60:61], v[48:49], v[46:47]
	ds_read_b32 v62, v75 offset:224
	v_add_f32_e32 v46, v46, v47
	v_pk_mul_f32 v[68:69], v[68:69], v[44:45] op_sel_hi:[1,0]
	v_pk_mul_f32 v[70:71], v[70:71], v[44:45] op_sel_hi:[1,0]
	v_add_f32_dpp v46, v46, v46 quad_perm:[1,0,3,2] row_mask:0xf bank_mask:0xf bound_ctrl:1
	v_pk_fma_f32 v[68:69], v[58:59], v[50:51], v[68:69]
	v_pk_fma_f32 v[70:71], v[60:61], v[52:53], v[70:71]
	v_pk_mul_f32 v[64:65], v[36:37], v[58:59]
	v_add_f32_dpp v46, v46, v46 quad_perm:[2,3,0,1] row_mask:0xf bank_mask:0xf bound_ctrl:1
	v_pk_fma_f32 v[64:65], v[38:39], v[60:61], v[64:65]
	ds_read_b128 v[24:27], v74 offset:9216
	v_add_f32_dpp v46, v46, v46 row_half_mirror row_mask:0xf bank_mask:0xf bound_ctrl:1
	ds_read_b128 v[28:31], v74 offset:9472
	ds_read_b128 v[32:35], v74 offset:9728
	v_add_f32_dpp v46, v46, v46 row_mirror row_mask:0xf bank_mask:0xf bound_ctrl:1
	ds_read_b128 v[36:39], v74 offset:9984
	v_pk_fma_f32 v[58:59], v[54:55], v[46:47], v[68:69] op_sel_hi:[1,0,1]
	v_pk_fma_f32 v[60:61], v[56:57], v[46:47], v[70:71] op_sel_hi:[1,0,1]
	v_add_f32_e32 v64, v64, v65
	ds_write_b32 v72, v64 offset:2048
	s_waitcnt lgkmcnt(9)
	v_pk_mul_f32 v[0:1], v[58:59], v[0:1]
	ds_read_b128 v[46:49], v74 offset:10240
	v_pk_fma_f32 v[0:1], v[60:61], v[2:3], v[0:1]
	ds_read_b32 v44, v75 offset:256
	v_add_f32_e32 v0, v0, v1
	v_pk_mul_f32 v[12:13], v[12:13], v[42:43] op_sel_hi:[1,0]
	v_pk_mul_f32 v[14:15], v[14:15], v[42:43] op_sel_hi:[1,0]
	v_add_f32_dpp v0, v0, v0 quad_perm:[1,0,3,2] row_mask:0xf bank_mask:0xf bound_ctrl:1
	v_pk_fma_f32 v[12:13], v[58:59], v[4:5], v[12:13]
	v_pk_fma_f32 v[14:15], v[60:61], v[6:7], v[14:15]
	v_pk_mul_f32 v[64:65], v[76:77], v[58:59]
	v_add_f32_dpp v0, v0, v0 quad_perm:[2,3,0,1] row_mask:0xf bank_mask:0xf bound_ctrl:1
	v_pk_fma_f32 v[64:65], v[78:79], v[60:61], v[64:65]
	ds_read_b128 v[50:53], v74 offset:10496
	v_add_f32_dpp v0, v0, v0 row_half_mirror row_mask:0xf bank_mask:0xf bound_ctrl:1
	ds_read_b128 v[54:57], v74 offset:10752
	ds_read_b128 v[68:71], v74 offset:11008
	v_add_f32_dpp v0, v0, v0 row_mirror row_mask:0xf bank_mask:0xf bound_ctrl:1
	ds_read_b128 v[76:79], v74 offset:11264
	v_pk_fma_f32 v[58:59], v[8:9], v[0:1], v[12:13] op_sel_hi:[1,0,1]
	v_pk_fma_f32 v[60:61], v[10:11], v[0:1], v[14:15] op_sel_hi:[1,0,1]
	v_add_f32_e32 v64, v64, v65
	ds_write_b32 v72, v64 offset:2560
	s_waitcnt lgkmcnt(9)
	v_pk_mul_f32 v[20:21], v[58:59], v[20:21]
	ds_read_b128 v[0:3], v74 offset:11520
	v_pk_fma_f32 v[20:21], v[60:61], v[22:23], v[20:21]
	ds_read_b32 v42, v75 offset:288
	v_add_f32_e32 v20, v20, v21
	v_pk_mul_f32 v[32:33], v[32:33], v[62:63] op_sel_hi:[1,0]
	v_pk_mul_f32 v[34:35], v[34:35], v[62:63] op_sel_hi:[1,0]
	v_add_f32_dpp v20, v20, v20 quad_perm:[1,0,3,2] row_mask:0xf bank_mask:0xf bound_ctrl:1
	v_pk_fma_f32 v[32:33], v[58:59], v[24:25], v[32:33]
	v_pk_fma_f32 v[34:35], v[60:61], v[26:27], v[34:35]
	v_pk_mul_f32 v[64:65], v[16:17], v[58:59]
	v_add_f32_dpp v20, v20, v20 quad_perm:[2,3,0,1] row_mask:0xf bank_mask:0xf bound_ctrl:1
	v_pk_fma_f32 v[64:65], v[18:19], v[60:61], v[64:65]
	ds_read_b128 v[4:7], v74 offset:11776
	v_add_f32_dpp v20, v20, v20 row_half_mirror row_mask:0xf bank_mask:0xf bound_ctrl:1
	ds_read_b128 v[8:11], v74 offset:12032
	ds_read_b128 v[12:15], v74 offset:12288
	v_add_f32_dpp v20, v20, v20 row_mirror row_mask:0xf bank_mask:0xf bound_ctrl:1
	ds_read_b128 v[16:19], v74 offset:12544
	v_pk_fma_f32 v[58:59], v[28:29], v[20:21], v[32:33] op_sel_hi:[1,0,1]
	v_pk_fma_f32 v[60:61], v[30:31], v[20:21], v[34:35] op_sel_hi:[1,0,1]
	v_add_f32_e32 v64, v64, v65
	ds_write_b32 v72, v64 offset:3072
	s_waitcnt lgkmcnt(9)
	v_pk_mul_f32 v[46:47], v[58:59], v[46:47]
	ds_read_b128 v[20:23], v74 offset:12800
	v_pk_fma_f32 v[46:47], v[60:61], v[48:49], v[46:47]
	ds_read_b32 v62, v75 offset:320
	v_add_f32_e32 v46, v46, v47
	v_pk_mul_f32 v[68:69], v[68:69], v[44:45] op_sel_hi:[1,0]
	v_pk_mul_f32 v[70:71], v[70:71], v[44:45] op_sel_hi:[1,0]
	v_add_f32_dpp v46, v46, v46 quad_perm:[1,0,3,2] row_mask:0xf bank_mask:0xf bound_ctrl:1
	v_pk_fma_f32 v[68:69], v[58:59], v[50:51], v[68:69]
	v_pk_fma_f32 v[70:71], v[60:61], v[52:53], v[70:71]
	v_pk_mul_f32 v[64:65], v[36:37], v[58:59]
	v_add_f32_dpp v46, v46, v46 quad_perm:[2,3,0,1] row_mask:0xf bank_mask:0xf bound_ctrl:1
	v_pk_fma_f32 v[64:65], v[38:39], v[60:61], v[64:65]
	ds_read_b128 v[24:27], v74 offset:13056
	v_add_f32_dpp v46, v46, v46 row_half_mirror row_mask:0xf bank_mask:0xf bound_ctrl:1
	ds_read_b128 v[28:31], v74 offset:13312
	ds_read_b128 v[32:35], v74 offset:13568
	v_add_f32_dpp v46, v46, v46 row_mirror row_mask:0xf bank_mask:0xf bound_ctrl:1
	ds_read_b128 v[36:39], v74 offset:13824
	v_pk_fma_f32 v[58:59], v[54:55], v[46:47], v[68:69] op_sel_hi:[1,0,1]
	v_pk_fma_f32 v[60:61], v[56:57], v[46:47], v[70:71] op_sel_hi:[1,0,1]
	v_add_f32_e32 v64, v64, v65
	ds_write_b32 v72, v64 offset:3584
	s_waitcnt lgkmcnt(9)
	v_pk_mul_f32 v[0:1], v[58:59], v[0:1]
	ds_read_b128 v[46:49], v74 offset:14080
	v_pk_fma_f32 v[0:1], v[60:61], v[2:3], v[0:1]
	ds_read_b32 v44, v75 offset:352
	v_add_f32_e32 v0, v0, v1
	v_pk_mul_f32 v[12:13], v[12:13], v[42:43] op_sel_hi:[1,0]
	v_pk_mul_f32 v[14:15], v[14:15], v[42:43] op_sel_hi:[1,0]
	v_add_f32_dpp v0, v0, v0 quad_perm:[1,0,3,2] row_mask:0xf bank_mask:0xf bound_ctrl:1
	v_pk_fma_f32 v[12:13], v[58:59], v[4:5], v[12:13]
	v_pk_fma_f32 v[14:15], v[60:61], v[6:7], v[14:15]
	v_pk_mul_f32 v[64:65], v[76:77], v[58:59]
	v_add_f32_dpp v0, v0, v0 quad_perm:[2,3,0,1] row_mask:0xf bank_mask:0xf bound_ctrl:1
	v_pk_fma_f32 v[64:65], v[78:79], v[60:61], v[64:65]
	ds_read_b128 v[50:53], v74 offset:14336
	v_add_f32_dpp v0, v0, v0 row_half_mirror row_mask:0xf bank_mask:0xf bound_ctrl:1
	ds_read_b128 v[54:57], v74 offset:14592
	ds_read_b128 v[68:71], v74 offset:14848
	v_add_f32_dpp v0, v0, v0 row_mirror row_mask:0xf bank_mask:0xf bound_ctrl:1
	ds_read_b128 v[76:79], v74 offset:15104
	v_pk_fma_f32 v[58:59], v[8:9], v[0:1], v[12:13] op_sel_hi:[1,0,1]
	v_pk_fma_f32 v[60:61], v[10:11], v[0:1], v[14:15] op_sel_hi:[1,0,1]
	v_add_f32_e32 v64, v64, v65
	ds_write_b32 v72, v64 offset:4096
	s_waitcnt lgkmcnt(9)
	v_pk_mul_f32 v[20:21], v[58:59], v[20:21]
	ds_read_b128 v[0:3], v74 offset:15360
	v_pk_fma_f32 v[20:21], v[60:61], v[22:23], v[20:21]
	ds_read_b32 v42, v75 offset:384
	v_add_f32_e32 v20, v20, v21
	v_pk_mul_f32 v[32:33], v[32:33], v[62:63] op_sel_hi:[1,0]
	v_pk_mul_f32 v[34:35], v[34:35], v[62:63] op_sel_hi:[1,0]
	v_add_f32_dpp v20, v20, v20 quad_perm:[1,0,3,2] row_mask:0xf bank_mask:0xf bound_ctrl:1
	v_pk_fma_f32 v[32:33], v[58:59], v[24:25], v[32:33]
	v_pk_fma_f32 v[34:35], v[60:61], v[26:27], v[34:35]
	v_pk_mul_f32 v[64:65], v[16:17], v[58:59]
	v_add_f32_dpp v20, v20, v20 quad_perm:[2,3,0,1] row_mask:0xf bank_mask:0xf bound_ctrl:1
	v_pk_fma_f32 v[64:65], v[18:19], v[60:61], v[64:65]
	ds_read_b128 v[4:7], v74 offset:15616
	v_add_f32_dpp v20, v20, v20 row_half_mirror row_mask:0xf bank_mask:0xf bound_ctrl:1
	ds_read_b128 v[8:11], v74 offset:15872
	ds_read_b128 v[12:15], v74 offset:16128
	v_add_f32_dpp v20, v20, v20 row_mirror row_mask:0xf bank_mask:0xf bound_ctrl:1
	ds_read_b128 v[16:19], v74 offset:16384
	v_pk_fma_f32 v[58:59], v[28:29], v[20:21], v[32:33] op_sel_hi:[1,0,1]
	v_pk_fma_f32 v[60:61], v[30:31], v[20:21], v[34:35] op_sel_hi:[1,0,1]
	v_add_f32_e32 v64, v64, v65
	ds_write_b32 v72, v64 offset:4608
	s_waitcnt lgkmcnt(9)
	v_pk_mul_f32 v[46:47], v[58:59], v[46:47]
	ds_read_b128 v[20:23], v74 offset:16640
	v_pk_fma_f32 v[46:47], v[60:61], v[48:49], v[46:47]
	ds_read_b32 v62, v75 offset:416
	v_add_f32_e32 v46, v46, v47
	v_pk_mul_f32 v[68:69], v[68:69], v[44:45] op_sel_hi:[1,0]
	v_pk_mul_f32 v[70:71], v[70:71], v[44:45] op_sel_hi:[1,0]
	v_add_f32_dpp v46, v46, v46 quad_perm:[1,0,3,2] row_mask:0xf bank_mask:0xf bound_ctrl:1
	v_pk_fma_f32 v[68:69], v[58:59], v[50:51], v[68:69]
	v_pk_fma_f32 v[70:71], v[60:61], v[52:53], v[70:71]
	v_pk_mul_f32 v[64:65], v[36:37], v[58:59]
	v_add_f32_dpp v46, v46, v46 quad_perm:[2,3,0,1] row_mask:0xf bank_mask:0xf bound_ctrl:1
	v_pk_fma_f32 v[64:65], v[38:39], v[60:61], v[64:65]
	ds_read_b128 v[24:27], v74 offset:16896
	v_add_f32_dpp v46, v46, v46 row_half_mirror row_mask:0xf bank_mask:0xf bound_ctrl:1
	ds_read_b128 v[28:31], v74 offset:17152
	ds_read_b128 v[32:35], v74 offset:17408
	v_add_f32_dpp v46, v46, v46 row_mirror row_mask:0xf bank_mask:0xf bound_ctrl:1
	ds_read_b128 v[36:39], v74 offset:17664
	v_pk_fma_f32 v[58:59], v[54:55], v[46:47], v[68:69] op_sel_hi:[1,0,1]
	v_pk_fma_f32 v[60:61], v[56:57], v[46:47], v[70:71] op_sel_hi:[1,0,1]
	v_add_f32_e32 v64, v64, v65
	ds_write_b32 v72, v64 offset:5120
	s_waitcnt lgkmcnt(9)
	v_pk_mul_f32 v[0:1], v[58:59], v[0:1]
	ds_read_b128 v[46:49], v74 offset:17920
	v_pk_fma_f32 v[0:1], v[60:61], v[2:3], v[0:1]
	ds_read_b32 v44, v75 offset:448
	v_add_f32_e32 v0, v0, v1
	v_pk_mul_f32 v[12:13], v[12:13], v[42:43] op_sel_hi:[1,0]
	v_pk_mul_f32 v[14:15], v[14:15], v[42:43] op_sel_hi:[1,0]
	v_add_f32_dpp v0, v0, v0 quad_perm:[1,0,3,2] row_mask:0xf bank_mask:0xf bound_ctrl:1
	v_pk_fma_f32 v[12:13], v[58:59], v[4:5], v[12:13]
	v_pk_fma_f32 v[14:15], v[60:61], v[6:7], v[14:15]
	v_pk_mul_f32 v[64:65], v[76:77], v[58:59]
	v_add_f32_dpp v0, v0, v0 quad_perm:[2,3,0,1] row_mask:0xf bank_mask:0xf bound_ctrl:1
	v_pk_fma_f32 v[64:65], v[78:79], v[60:61], v[64:65]
	ds_read_b128 v[50:53], v74 offset:18176
	v_add_f32_dpp v0, v0, v0 row_half_mirror row_mask:0xf bank_mask:0xf bound_ctrl:1
	ds_read_b128 v[54:57], v74 offset:18432
	ds_read_b128 v[68:71], v74 offset:18688
	v_add_f32_dpp v0, v0, v0 row_mirror row_mask:0xf bank_mask:0xf bound_ctrl:1
	ds_read_b128 v[76:79], v74 offset:18944
	v_pk_fma_f32 v[58:59], v[8:9], v[0:1], v[12:13] op_sel_hi:[1,0,1]
	v_pk_fma_f32 v[60:61], v[10:11], v[0:1], v[14:15] op_sel_hi:[1,0,1]
	v_add_f32_e32 v64, v64, v65
	ds_write_b32 v72, v64 offset:5632
	s_waitcnt lgkmcnt(9)
	v_pk_mul_f32 v[20:21], v[58:59], v[20:21]
	ds_read_b128 v[0:3], v74 offset:19200
	v_pk_fma_f32 v[20:21], v[60:61], v[22:23], v[20:21]
	ds_read_b32 v42, v75 offset:480
	v_add_f32_e32 v20, v20, v21
	v_pk_mul_f32 v[32:33], v[32:33], v[62:63] op_sel_hi:[1,0]
	v_pk_mul_f32 v[34:35], v[34:35], v[62:63] op_sel_hi:[1,0]
	v_add_f32_dpp v20, v20, v20 quad_perm:[1,0,3,2] row_mask:0xf bank_mask:0xf bound_ctrl:1
	v_pk_fma_f32 v[32:33], v[58:59], v[24:25], v[32:33]
	v_pk_fma_f32 v[34:35], v[60:61], v[26:27], v[34:35]
	v_pk_mul_f32 v[64:65], v[16:17], v[58:59]
	v_add_f32_dpp v20, v20, v20 quad_perm:[2,3,0,1] row_mask:0xf bank_mask:0xf bound_ctrl:1
	v_pk_fma_f32 v[64:65], v[18:19], v[60:61], v[64:65]
	ds_read_b128 v[4:7], v74 offset:19456
	v_add_f32_dpp v20, v20, v20 row_half_mirror row_mask:0xf bank_mask:0xf bound_ctrl:1
	ds_read_b128 v[8:11], v74 offset:19712
	ds_read_b128 v[12:15], v74 offset:19968
	v_add_f32_dpp v20, v20, v20 row_mirror row_mask:0xf bank_mask:0xf bound_ctrl:1
	ds_read_b128 v[16:19], v74 offset:20224
	v_pk_fma_f32 v[58:59], v[28:29], v[20:21], v[32:33] op_sel_hi:[1,0,1]
	v_pk_fma_f32 v[60:61], v[30:31], v[20:21], v[34:35] op_sel_hi:[1,0,1]
	v_add_f32_e32 v64, v64, v65
	ds_write_b32 v72, v64 offset:6144
	s_waitcnt lgkmcnt(9)
	v_pk_mul_f32 v[46:47], v[58:59], v[46:47]
	ds_read_b128 v[20:23], v74 offset:20480
	v_pk_fma_f32 v[46:47], v[60:61], v[48:49], v[46:47]
	ds_read_b32 v62, v75 offset:512
	v_add_f32_e32 v46, v46, v47
	v_pk_mul_f32 v[68:69], v[68:69], v[44:45] op_sel_hi:[1,0]
	v_pk_mul_f32 v[70:71], v[70:71], v[44:45] op_sel_hi:[1,0]
	v_add_f32_dpp v46, v46, v46 quad_perm:[1,0,3,2] row_mask:0xf bank_mask:0xf bound_ctrl:1
	v_pk_fma_f32 v[68:69], v[58:59], v[50:51], v[68:69]
	v_pk_fma_f32 v[70:71], v[60:61], v[52:53], v[70:71]
	v_pk_mul_f32 v[64:65], v[36:37], v[58:59]
	v_add_f32_dpp v46, v46, v46 quad_perm:[2,3,0,1] row_mask:0xf bank_mask:0xf bound_ctrl:1
	v_pk_fma_f32 v[64:65], v[38:39], v[60:61], v[64:65]
	ds_read_b128 v[24:27], v74 offset:20736
	v_add_f32_dpp v46, v46, v46 row_half_mirror row_mask:0xf bank_mask:0xf bound_ctrl:1
	ds_read_b128 v[28:31], v74 offset:20992
	ds_read_b128 v[32:35], v74 offset:21248
	v_add_f32_dpp v46, v46, v46 row_mirror row_mask:0xf bank_mask:0xf bound_ctrl:1
	ds_read_b128 v[36:39], v74 offset:21504
	v_pk_fma_f32 v[58:59], v[54:55], v[46:47], v[68:69] op_sel_hi:[1,0,1]
	v_pk_fma_f32 v[60:61], v[56:57], v[46:47], v[70:71] op_sel_hi:[1,0,1]
	v_add_f32_e32 v64, v64, v65
	ds_write_b32 v72, v64 offset:6656
	s_waitcnt lgkmcnt(9)
	v_pk_mul_f32 v[0:1], v[58:59], v[0:1]
	ds_read_b128 v[46:49], v74 offset:21760
	v_pk_fma_f32 v[0:1], v[60:61], v[2:3], v[0:1]
	ds_read_b32 v44, v75 offset:544
	v_add_f32_e32 v0, v0, v1
	v_pk_mul_f32 v[12:13], v[12:13], v[42:43] op_sel_hi:[1,0]
	v_pk_mul_f32 v[14:15], v[14:15], v[42:43] op_sel_hi:[1,0]
	v_add_f32_dpp v0, v0, v0 quad_perm:[1,0,3,2] row_mask:0xf bank_mask:0xf bound_ctrl:1
	v_pk_fma_f32 v[12:13], v[58:59], v[4:5], v[12:13]
	v_pk_fma_f32 v[14:15], v[60:61], v[6:7], v[14:15]
	v_pk_mul_f32 v[64:65], v[76:77], v[58:59]
	v_add_f32_dpp v0, v0, v0 quad_perm:[2,3,0,1] row_mask:0xf bank_mask:0xf bound_ctrl:1
	v_pk_fma_f32 v[64:65], v[78:79], v[60:61], v[64:65]
	ds_read_b128 v[50:53], v74 offset:22016
	v_add_f32_dpp v0, v0, v0 row_half_mirror row_mask:0xf bank_mask:0xf bound_ctrl:1
	ds_read_b128 v[54:57], v74 offset:22272
	ds_read_b128 v[68:71], v74 offset:22528
	v_add_f32_dpp v0, v0, v0 row_mirror row_mask:0xf bank_mask:0xf bound_ctrl:1
	ds_read_b128 v[76:79], v74 offset:22784
	v_pk_fma_f32 v[58:59], v[8:9], v[0:1], v[12:13] op_sel_hi:[1,0,1]
	v_pk_fma_f32 v[60:61], v[10:11], v[0:1], v[14:15] op_sel_hi:[1,0,1]
	v_add_f32_e32 v64, v64, v65
	ds_write_b32 v72, v64 offset:7168
	s_waitcnt lgkmcnt(9)
	v_pk_mul_f32 v[20:21], v[58:59], v[20:21]
	ds_read_b128 v[0:3], v74 offset:23040
	v_pk_fma_f32 v[20:21], v[60:61], v[22:23], v[20:21]
	ds_read_b32 v42, v75 offset:576
	v_add_f32_e32 v20, v20, v21
	v_pk_mul_f32 v[32:33], v[32:33], v[62:63] op_sel_hi:[1,0]
	v_pk_mul_f32 v[34:35], v[34:35], v[62:63] op_sel_hi:[1,0]
	v_add_f32_dpp v20, v20, v20 quad_perm:[1,0,3,2] row_mask:0xf bank_mask:0xf bound_ctrl:1
	v_pk_fma_f32 v[32:33], v[58:59], v[24:25], v[32:33]
	v_pk_fma_f32 v[34:35], v[60:61], v[26:27], v[34:35]
	v_pk_mul_f32 v[64:65], v[16:17], v[58:59]
	v_add_f32_dpp v20, v20, v20 quad_perm:[2,3,0,1] row_mask:0xf bank_mask:0xf bound_ctrl:1
	v_pk_fma_f32 v[64:65], v[18:19], v[60:61], v[64:65]
	ds_read_b128 v[4:7], v74 offset:23296
	v_add_f32_dpp v20, v20, v20 row_half_mirror row_mask:0xf bank_mask:0xf bound_ctrl:1
	ds_read_b128 v[8:11], v74 offset:23552
	ds_read_b128 v[12:15], v74 offset:23808
	v_add_f32_dpp v20, v20, v20 row_mirror row_mask:0xf bank_mask:0xf bound_ctrl:1
	ds_read_b128 v[16:19], v74 offset:24064
	v_pk_fma_f32 v[58:59], v[28:29], v[20:21], v[32:33] op_sel_hi:[1,0,1]
	v_pk_fma_f32 v[60:61], v[30:31], v[20:21], v[34:35] op_sel_hi:[1,0,1]
	v_add_f32_e32 v64, v64, v65
	ds_write_b32 v72, v64 offset:7680
	s_waitcnt lgkmcnt(9)
	v_pk_mul_f32 v[46:47], v[58:59], v[46:47]
	ds_read_b128 v[20:23], v74 offset:24320
	v_pk_fma_f32 v[46:47], v[60:61], v[48:49], v[46:47]
	ds_read_b32 v62, v75 offset:608
	v_add_f32_e32 v46, v46, v47
	v_pk_mul_f32 v[68:69], v[68:69], v[44:45] op_sel_hi:[1,0]
	v_pk_mul_f32 v[70:71], v[70:71], v[44:45] op_sel_hi:[1,0]
	v_add_f32_dpp v46, v46, v46 quad_perm:[1,0,3,2] row_mask:0xf bank_mask:0xf bound_ctrl:1
	v_pk_fma_f32 v[68:69], v[58:59], v[50:51], v[68:69]
	v_pk_fma_f32 v[70:71], v[60:61], v[52:53], v[70:71]
	v_pk_mul_f32 v[64:65], v[36:37], v[58:59]
	v_add_f32_dpp v46, v46, v46 quad_perm:[2,3,0,1] row_mask:0xf bank_mask:0xf bound_ctrl:1
	v_pk_fma_f32 v[64:65], v[38:39], v[60:61], v[64:65]
	ds_read_b128 v[24:27], v74 offset:24576
	v_add_f32_dpp v46, v46, v46 row_half_mirror row_mask:0xf bank_mask:0xf bound_ctrl:1
	ds_read_b128 v[28:31], v74 offset:24832
	ds_read_b128 v[32:35], v74 offset:25088
	v_add_f32_dpp v46, v46, v46 row_mirror row_mask:0xf bank_mask:0xf bound_ctrl:1
	ds_read_b128 v[36:39], v74 offset:25344
	v_pk_fma_f32 v[58:59], v[54:55], v[46:47], v[68:69] op_sel_hi:[1,0,1]
	v_pk_fma_f32 v[60:61], v[56:57], v[46:47], v[70:71] op_sel_hi:[1,0,1]
	v_add_f32_e32 v64, v64, v65
	ds_write_b32 v72, v64 offset:8192
	s_waitcnt lgkmcnt(9)
	v_pk_mul_f32 v[0:1], v[58:59], v[0:1]
	ds_read_b128 v[46:49], v74 offset:25600
	v_pk_fma_f32 v[0:1], v[60:61], v[2:3], v[0:1]
	ds_read_b32 v44, v75 offset:640
	v_add_f32_e32 v0, v0, v1
	v_pk_mul_f32 v[12:13], v[12:13], v[42:43] op_sel_hi:[1,0]
	v_pk_mul_f32 v[14:15], v[14:15], v[42:43] op_sel_hi:[1,0]
	v_add_f32_dpp v0, v0, v0 quad_perm:[1,0,3,2] row_mask:0xf bank_mask:0xf bound_ctrl:1
	v_pk_fma_f32 v[12:13], v[58:59], v[4:5], v[12:13]
	v_pk_fma_f32 v[14:15], v[60:61], v[6:7], v[14:15]
	v_pk_mul_f32 v[64:65], v[76:77], v[58:59]
	v_add_f32_dpp v0, v0, v0 quad_perm:[2,3,0,1] row_mask:0xf bank_mask:0xf bound_ctrl:1
	v_pk_fma_f32 v[64:65], v[78:79], v[60:61], v[64:65]
	ds_read_b128 v[50:53], v74 offset:25856
	v_add_f32_dpp v0, v0, v0 row_half_mirror row_mask:0xf bank_mask:0xf bound_ctrl:1
	ds_read_b128 v[54:57], v74 offset:26112
	ds_read_b128 v[68:71], v74 offset:26368
	v_add_f32_dpp v0, v0, v0 row_mirror row_mask:0xf bank_mask:0xf bound_ctrl:1
	ds_read_b128 v[76:79], v74 offset:26624
	v_pk_fma_f32 v[58:59], v[8:9], v[0:1], v[12:13] op_sel_hi:[1,0,1]
	v_pk_fma_f32 v[60:61], v[10:11], v[0:1], v[14:15] op_sel_hi:[1,0,1]
	v_add_f32_e32 v64, v64, v65
	ds_write_b32 v72, v64 offset:8704
	s_waitcnt lgkmcnt(9)
	v_pk_mul_f32 v[20:21], v[58:59], v[20:21]
	ds_read_b128 v[0:3], v74 offset:26880
	v_pk_fma_f32 v[20:21], v[60:61], v[22:23], v[20:21]
	ds_read_b32 v42, v75 offset:672
	v_add_f32_e32 v20, v20, v21
	v_pk_mul_f32 v[32:33], v[32:33], v[62:63] op_sel_hi:[1,0]
	v_pk_mul_f32 v[34:35], v[34:35], v[62:63] op_sel_hi:[1,0]
	v_add_f32_dpp v20, v20, v20 quad_perm:[1,0,3,2] row_mask:0xf bank_mask:0xf bound_ctrl:1
	v_pk_fma_f32 v[32:33], v[58:59], v[24:25], v[32:33]
	v_pk_fma_f32 v[34:35], v[60:61], v[26:27], v[34:35]
	v_pk_mul_f32 v[64:65], v[16:17], v[58:59]
	v_add_f32_dpp v20, v20, v20 quad_perm:[2,3,0,1] row_mask:0xf bank_mask:0xf bound_ctrl:1
	v_pk_fma_f32 v[64:65], v[18:19], v[60:61], v[64:65]
	ds_read_b128 v[4:7], v74 offset:27136
	v_add_f32_dpp v20, v20, v20 row_half_mirror row_mask:0xf bank_mask:0xf bound_ctrl:1
	ds_read_b128 v[8:11], v74 offset:27392
	ds_read_b128 v[12:15], v74 offset:27648
	v_add_f32_dpp v20, v20, v20 row_mirror row_mask:0xf bank_mask:0xf bound_ctrl:1
	ds_read_b128 v[16:19], v74 offset:27904
	v_pk_fma_f32 v[58:59], v[28:29], v[20:21], v[32:33] op_sel_hi:[1,0,1]
	v_pk_fma_f32 v[60:61], v[30:31], v[20:21], v[34:35] op_sel_hi:[1,0,1]
	v_add_f32_e32 v64, v64, v65
	ds_write_b32 v72, v64 offset:9216
	s_waitcnt lgkmcnt(9)
	v_pk_mul_f32 v[46:47], v[58:59], v[46:47]
	ds_read_b128 v[20:23], v74 offset:28160
	v_pk_fma_f32 v[46:47], v[60:61], v[48:49], v[46:47]
	ds_read_b32 v62, v75 offset:704
	v_add_f32_e32 v46, v46, v47
	v_pk_mul_f32 v[68:69], v[68:69], v[44:45] op_sel_hi:[1,0]
	v_pk_mul_f32 v[70:71], v[70:71], v[44:45] op_sel_hi:[1,0]
	v_add_f32_dpp v46, v46, v46 quad_perm:[1,0,3,2] row_mask:0xf bank_mask:0xf bound_ctrl:1
	v_pk_fma_f32 v[68:69], v[58:59], v[50:51], v[68:69]
	v_pk_fma_f32 v[70:71], v[60:61], v[52:53], v[70:71]
	v_pk_mul_f32 v[64:65], v[36:37], v[58:59]
	v_add_f32_dpp v46, v46, v46 quad_perm:[2,3,0,1] row_mask:0xf bank_mask:0xf bound_ctrl:1
	v_pk_fma_f32 v[64:65], v[38:39], v[60:61], v[64:65]
	ds_read_b128 v[24:27], v74 offset:28416
	v_add_f32_dpp v46, v46, v46 row_half_mirror row_mask:0xf bank_mask:0xf bound_ctrl:1
	ds_read_b128 v[28:31], v74 offset:28672
	ds_read_b128 v[32:35], v74 offset:28928
	v_add_f32_dpp v46, v46, v46 row_mirror row_mask:0xf bank_mask:0xf bound_ctrl:1
	ds_read_b128 v[36:39], v74 offset:29184
	v_pk_fma_f32 v[58:59], v[54:55], v[46:47], v[68:69] op_sel_hi:[1,0,1]
	v_pk_fma_f32 v[60:61], v[56:57], v[46:47], v[70:71] op_sel_hi:[1,0,1]
	v_add_f32_e32 v64, v64, v65
	ds_write_b32 v72, v64 offset:9728
	s_waitcnt lgkmcnt(9)
	v_pk_mul_f32 v[0:1], v[58:59], v[0:1]
	ds_read_b128 v[46:49], v74 offset:29440
	v_pk_fma_f32 v[0:1], v[60:61], v[2:3], v[0:1]
	ds_read_b32 v44, v75 offset:736
	v_add_f32_e32 v0, v0, v1
	v_pk_mul_f32 v[12:13], v[12:13], v[42:43] op_sel_hi:[1,0]
	v_pk_mul_f32 v[14:15], v[14:15], v[42:43] op_sel_hi:[1,0]
	v_add_f32_dpp v0, v0, v0 quad_perm:[1,0,3,2] row_mask:0xf bank_mask:0xf bound_ctrl:1
	v_pk_fma_f32 v[12:13], v[58:59], v[4:5], v[12:13]
	v_pk_fma_f32 v[14:15], v[60:61], v[6:7], v[14:15]
	v_pk_mul_f32 v[64:65], v[76:77], v[58:59]
	v_add_f32_dpp v0, v0, v0 quad_perm:[2,3,0,1] row_mask:0xf bank_mask:0xf bound_ctrl:1
	v_pk_fma_f32 v[64:65], v[78:79], v[60:61], v[64:65]
	ds_read_b128 v[50:53], v74 offset:29696
	v_add_f32_dpp v0, v0, v0 row_half_mirror row_mask:0xf bank_mask:0xf bound_ctrl:1
	ds_read_b128 v[54:57], v74 offset:29952
	ds_read_b128 v[68:71], v74 offset:30208
	v_add_f32_dpp v0, v0, v0 row_mirror row_mask:0xf bank_mask:0xf bound_ctrl:1
	ds_read_b128 v[76:79], v74 offset:30464
	v_pk_fma_f32 v[58:59], v[8:9], v[0:1], v[12:13] op_sel_hi:[1,0,1]
	v_pk_fma_f32 v[60:61], v[10:11], v[0:1], v[14:15] op_sel_hi:[1,0,1]
	v_add_f32_e32 v64, v64, v65
	ds_write_b32 v72, v64 offset:10240
	s_waitcnt lgkmcnt(9)
	v_pk_mul_f32 v[20:21], v[58:59], v[20:21]
	ds_read_b128 v[0:3], v74 offset:30720
	v_pk_fma_f32 v[20:21], v[60:61], v[22:23], v[20:21]
	ds_read_b32 v42, v75 offset:768
	v_add_f32_e32 v20, v20, v21
	v_pk_mul_f32 v[32:33], v[32:33], v[62:63] op_sel_hi:[1,0]
	v_pk_mul_f32 v[34:35], v[34:35], v[62:63] op_sel_hi:[1,0]
	v_add_f32_dpp v20, v20, v20 quad_perm:[1,0,3,2] row_mask:0xf bank_mask:0xf bound_ctrl:1
	v_pk_fma_f32 v[32:33], v[58:59], v[24:25], v[32:33]
	v_pk_fma_f32 v[34:35], v[60:61], v[26:27], v[34:35]
	v_pk_mul_f32 v[64:65], v[16:17], v[58:59]
	v_add_f32_dpp v20, v20, v20 quad_perm:[2,3,0,1] row_mask:0xf bank_mask:0xf bound_ctrl:1
	v_pk_fma_f32 v[64:65], v[18:19], v[60:61], v[64:65]
	ds_read_b128 v[4:7], v74 offset:30976
	v_add_f32_dpp v20, v20, v20 row_half_mirror row_mask:0xf bank_mask:0xf bound_ctrl:1
	ds_read_b128 v[8:11], v74 offset:31232
	ds_read_b128 v[12:15], v74 offset:31488
	v_add_f32_dpp v20, v20, v20 row_mirror row_mask:0xf bank_mask:0xf bound_ctrl:1
	ds_read_b128 v[16:19], v74 offset:31744
	v_pk_fma_f32 v[58:59], v[28:29], v[20:21], v[32:33] op_sel_hi:[1,0,1]
	v_pk_fma_f32 v[60:61], v[30:31], v[20:21], v[34:35] op_sel_hi:[1,0,1]
	v_add_f32_e32 v64, v64, v65
	ds_write_b32 v72, v64 offset:10752
	s_waitcnt lgkmcnt(9)
	v_pk_mul_f32 v[46:47], v[58:59], v[46:47]
	ds_read_b128 v[20:23], v74 offset:32000
	v_pk_fma_f32 v[46:47], v[60:61], v[48:49], v[46:47]
	ds_read_b32 v62, v75 offset:800
	v_add_f32_e32 v46, v46, v47
	v_pk_mul_f32 v[68:69], v[68:69], v[44:45] op_sel_hi:[1,0]
	v_pk_mul_f32 v[70:71], v[70:71], v[44:45] op_sel_hi:[1,0]
	v_add_f32_dpp v46, v46, v46 quad_perm:[1,0,3,2] row_mask:0xf bank_mask:0xf bound_ctrl:1
	v_pk_fma_f32 v[68:69], v[58:59], v[50:51], v[68:69]
	v_pk_fma_f32 v[70:71], v[60:61], v[52:53], v[70:71]
	v_pk_mul_f32 v[64:65], v[36:37], v[58:59]
	v_add_f32_dpp v46, v46, v46 quad_perm:[2,3,0,1] row_mask:0xf bank_mask:0xf bound_ctrl:1
	v_pk_fma_f32 v[64:65], v[38:39], v[60:61], v[64:65]
	ds_read_b128 v[24:27], v74 offset:32256
	v_add_f32_dpp v46, v46, v46 row_half_mirror row_mask:0xf bank_mask:0xf bound_ctrl:1
	ds_read_b128 v[28:31], v74 offset:32512
	ds_read_b128 v[32:35], v74 offset:32768
	v_add_f32_dpp v46, v46, v46 row_mirror row_mask:0xf bank_mask:0xf bound_ctrl:1
	ds_read_b128 v[36:39], v74 offset:33024
	v_pk_fma_f32 v[58:59], v[54:55], v[46:47], v[68:69] op_sel_hi:[1,0,1]
	v_pk_fma_f32 v[60:61], v[56:57], v[46:47], v[70:71] op_sel_hi:[1,0,1]
	v_add_f32_e32 v64, v64, v65
	ds_write_b32 v72, v64 offset:11264
	s_waitcnt lgkmcnt(9)
	v_pk_mul_f32 v[0:1], v[58:59], v[0:1]
	ds_read_b128 v[46:49], v74 offset:33280
	v_pk_fma_f32 v[0:1], v[60:61], v[2:3], v[0:1]
	ds_read_b32 v44, v75 offset:832
	v_add_f32_e32 v0, v0, v1
	v_pk_mul_f32 v[12:13], v[12:13], v[42:43] op_sel_hi:[1,0]
	v_pk_mul_f32 v[14:15], v[14:15], v[42:43] op_sel_hi:[1,0]
	v_add_f32_dpp v0, v0, v0 quad_perm:[1,0,3,2] row_mask:0xf bank_mask:0xf bound_ctrl:1
	v_pk_fma_f32 v[12:13], v[58:59], v[4:5], v[12:13]
	v_pk_fma_f32 v[14:15], v[60:61], v[6:7], v[14:15]
	v_pk_mul_f32 v[64:65], v[76:77], v[58:59]
	v_add_f32_dpp v0, v0, v0 quad_perm:[2,3,0,1] row_mask:0xf bank_mask:0xf bound_ctrl:1
	v_pk_fma_f32 v[64:65], v[78:79], v[60:61], v[64:65]
	ds_read_b128 v[50:53], v74 offset:33536
	v_add_f32_dpp v0, v0, v0 row_half_mirror row_mask:0xf bank_mask:0xf bound_ctrl:1
	ds_read_b128 v[54:57], v74 offset:33792
	ds_read_b128 v[68:71], v74 offset:34048
	v_add_f32_dpp v0, v0, v0 row_mirror row_mask:0xf bank_mask:0xf bound_ctrl:1
	ds_read_b128 v[76:79], v74 offset:34304
	v_pk_fma_f32 v[58:59], v[8:9], v[0:1], v[12:13] op_sel_hi:[1,0,1]
	v_pk_fma_f32 v[60:61], v[10:11], v[0:1], v[14:15] op_sel_hi:[1,0,1]
	v_add_f32_e32 v64, v64, v65
	ds_write_b32 v72, v64 offset:11776
	s_waitcnt lgkmcnt(9)
	v_pk_mul_f32 v[20:21], v[58:59], v[20:21]
	ds_read_b128 v[0:3], v74 offset:34560
	v_pk_fma_f32 v[20:21], v[60:61], v[22:23], v[20:21]
	ds_read_b32 v42, v75 offset:864
	v_add_f32_e32 v20, v20, v21
	v_pk_mul_f32 v[32:33], v[32:33], v[62:63] op_sel_hi:[1,0]
	v_pk_mul_f32 v[34:35], v[34:35], v[62:63] op_sel_hi:[1,0]
	v_add_f32_dpp v20, v20, v20 quad_perm:[1,0,3,2] row_mask:0xf bank_mask:0xf bound_ctrl:1
	v_pk_fma_f32 v[32:33], v[58:59], v[24:25], v[32:33]
	v_pk_fma_f32 v[34:35], v[60:61], v[26:27], v[34:35]
	v_pk_mul_f32 v[64:65], v[16:17], v[58:59]
	v_add_f32_dpp v20, v20, v20 quad_perm:[2,3,0,1] row_mask:0xf bank_mask:0xf bound_ctrl:1
	v_pk_fma_f32 v[64:65], v[18:19], v[60:61], v[64:65]
	ds_read_b128 v[4:7], v74 offset:34816
	v_add_f32_dpp v20, v20, v20 row_half_mirror row_mask:0xf bank_mask:0xf bound_ctrl:1
	ds_read_b128 v[8:11], v74 offset:35072
	ds_read_b128 v[12:15], v74 offset:35328
	v_add_f32_dpp v20, v20, v20 row_mirror row_mask:0xf bank_mask:0xf bound_ctrl:1
	ds_read_b128 v[16:19], v74 offset:35584
	v_pk_fma_f32 v[58:59], v[28:29], v[20:21], v[32:33] op_sel_hi:[1,0,1]
	v_pk_fma_f32 v[60:61], v[30:31], v[20:21], v[34:35] op_sel_hi:[1,0,1]
	v_add_f32_e32 v64, v64, v65
	ds_write_b32 v72, v64 offset:12288
	s_waitcnt lgkmcnt(9)
	v_pk_mul_f32 v[46:47], v[58:59], v[46:47]
	ds_read_b128 v[20:23], v74 offset:35840
	v_pk_fma_f32 v[46:47], v[60:61], v[48:49], v[46:47]
	ds_read_b32 v62, v75 offset:896
	v_add_f32_e32 v46, v46, v47
	v_pk_mul_f32 v[68:69], v[68:69], v[44:45] op_sel_hi:[1,0]
	v_pk_mul_f32 v[70:71], v[70:71], v[44:45] op_sel_hi:[1,0]
	v_add_f32_dpp v46, v46, v46 quad_perm:[1,0,3,2] row_mask:0xf bank_mask:0xf bound_ctrl:1
	v_pk_fma_f32 v[68:69], v[58:59], v[50:51], v[68:69]
	v_pk_fma_f32 v[70:71], v[60:61], v[52:53], v[70:71]
	v_pk_mul_f32 v[64:65], v[36:37], v[58:59]
	v_add_f32_dpp v46, v46, v46 quad_perm:[2,3,0,1] row_mask:0xf bank_mask:0xf bound_ctrl:1
	v_pk_fma_f32 v[64:65], v[38:39], v[60:61], v[64:65]
	ds_read_b128 v[24:27], v74 offset:36096
	v_add_f32_dpp v46, v46, v46 row_half_mirror row_mask:0xf bank_mask:0xf bound_ctrl:1
	ds_read_b128 v[28:31], v74 offset:36352
	ds_read_b128 v[32:35], v74 offset:36608
	v_add_f32_dpp v46, v46, v46 row_mirror row_mask:0xf bank_mask:0xf bound_ctrl:1
	ds_read_b128 v[36:39], v74 offset:36864
	v_pk_fma_f32 v[58:59], v[54:55], v[46:47], v[68:69] op_sel_hi:[1,0,1]
	v_pk_fma_f32 v[60:61], v[56:57], v[46:47], v[70:71] op_sel_hi:[1,0,1]
	v_add_f32_e32 v64, v64, v65
	ds_write_b32 v72, v64 offset:12800
	s_waitcnt lgkmcnt(9)
	v_pk_mul_f32 v[0:1], v[58:59], v[0:1]
	ds_read_b128 v[46:49], v74 offset:37120
	v_pk_fma_f32 v[0:1], v[60:61], v[2:3], v[0:1]
	ds_read_b32 v44, v75 offset:928
	v_add_f32_e32 v0, v0, v1
	v_pk_mul_f32 v[12:13], v[12:13], v[42:43] op_sel_hi:[1,0]
	v_pk_mul_f32 v[14:15], v[14:15], v[42:43] op_sel_hi:[1,0]
	v_add_f32_dpp v0, v0, v0 quad_perm:[1,0,3,2] row_mask:0xf bank_mask:0xf bound_ctrl:1
	v_pk_fma_f32 v[12:13], v[58:59], v[4:5], v[12:13]
	v_pk_fma_f32 v[14:15], v[60:61], v[6:7], v[14:15]
	v_pk_mul_f32 v[64:65], v[76:77], v[58:59]
	v_add_f32_dpp v0, v0, v0 quad_perm:[2,3,0,1] row_mask:0xf bank_mask:0xf bound_ctrl:1
	v_pk_fma_f32 v[64:65], v[78:79], v[60:61], v[64:65]
	ds_read_b128 v[50:53], v74 offset:37376
	v_add_f32_dpp v0, v0, v0 row_half_mirror row_mask:0xf bank_mask:0xf bound_ctrl:1
	ds_read_b128 v[54:57], v74 offset:37632
	ds_read_b128 v[68:71], v74 offset:37888
	v_add_f32_dpp v0, v0, v0 row_mirror row_mask:0xf bank_mask:0xf bound_ctrl:1
	ds_read_b128 v[76:79], v74 offset:38144
	v_pk_fma_f32 v[58:59], v[8:9], v[0:1], v[12:13] op_sel_hi:[1,0,1]
	v_pk_fma_f32 v[60:61], v[10:11], v[0:1], v[14:15] op_sel_hi:[1,0,1]
	v_add_f32_e32 v64, v64, v65
	ds_write_b32 v72, v64 offset:13312
	s_waitcnt lgkmcnt(9)
	v_pk_mul_f32 v[20:21], v[58:59], v[20:21]
	ds_read_b128 v[0:3], v74 offset:38400
	v_pk_fma_f32 v[20:21], v[60:61], v[22:23], v[20:21]
	ds_read_b32 v42, v75 offset:960
	v_add_f32_e32 v20, v20, v21
	v_pk_mul_f32 v[32:33], v[32:33], v[62:63] op_sel_hi:[1,0]
	v_pk_mul_f32 v[34:35], v[34:35], v[62:63] op_sel_hi:[1,0]
	v_add_f32_dpp v20, v20, v20 quad_perm:[1,0,3,2] row_mask:0xf bank_mask:0xf bound_ctrl:1
	v_pk_fma_f32 v[32:33], v[58:59], v[24:25], v[32:33]
	v_pk_fma_f32 v[34:35], v[60:61], v[26:27], v[34:35]
	v_pk_mul_f32 v[64:65], v[16:17], v[58:59]
	v_add_f32_dpp v20, v20, v20 quad_perm:[2,3,0,1] row_mask:0xf bank_mask:0xf bound_ctrl:1
	v_pk_fma_f32 v[64:65], v[18:19], v[60:61], v[64:65]
	ds_read_b128 v[4:7], v74 offset:38656
	v_add_f32_dpp v20, v20, v20 row_half_mirror row_mask:0xf bank_mask:0xf bound_ctrl:1
	ds_read_b128 v[8:11], v74 offset:38912
	ds_read_b128 v[12:15], v74 offset:39168
	v_add_f32_dpp v20, v20, v20 row_mirror row_mask:0xf bank_mask:0xf bound_ctrl:1
	ds_read_b128 v[16:19], v74 offset:39424
	v_pk_fma_f32 v[58:59], v[28:29], v[20:21], v[32:33] op_sel_hi:[1,0,1]
	v_pk_fma_f32 v[60:61], v[30:31], v[20:21], v[34:35] op_sel_hi:[1,0,1]
	v_add_f32_e32 v64, v64, v65
	ds_write_b32 v72, v64 offset:13824
	s_waitcnt lgkmcnt(9)
	v_pk_mul_f32 v[46:47], v[58:59], v[46:47]
	ds_read_b128 v[20:23], v74 offset:39680
	v_pk_fma_f32 v[46:47], v[60:61], v[48:49], v[46:47]
	ds_read_b32 v62, v75 offset:992
	v_add_f32_e32 v46, v46, v47
	v_pk_mul_f32 v[68:69], v[68:69], v[44:45] op_sel_hi:[1,0]
	v_pk_mul_f32 v[70:71], v[70:71], v[44:45] op_sel_hi:[1,0]
	v_add_f32_dpp v46, v46, v46 quad_perm:[1,0,3,2] row_mask:0xf bank_mask:0xf bound_ctrl:1
	v_pk_fma_f32 v[68:69], v[58:59], v[50:51], v[68:69]
	v_pk_fma_f32 v[70:71], v[60:61], v[52:53], v[70:71]
	v_pk_mul_f32 v[64:65], v[36:37], v[58:59]
	v_add_f32_dpp v46, v46, v46 quad_perm:[2,3,0,1] row_mask:0xf bank_mask:0xf bound_ctrl:1
	v_pk_fma_f32 v[64:65], v[38:39], v[60:61], v[64:65]
	ds_read_b128 v[24:27], v74 offset:39936
	v_add_f32_dpp v46, v46, v46 row_half_mirror row_mask:0xf bank_mask:0xf bound_ctrl:1
	ds_read_b128 v[28:31], v74 offset:40192
	ds_read_b128 v[32:35], v74 offset:40448
	v_add_f32_dpp v46, v46, v46 row_mirror row_mask:0xf bank_mask:0xf bound_ctrl:1
	ds_read_b128 v[36:39], v74 offset:40704
	v_pk_fma_f32 v[58:59], v[54:55], v[46:47], v[68:69] op_sel_hi:[1,0,1]
	v_pk_fma_f32 v[60:61], v[56:57], v[46:47], v[70:71] op_sel_hi:[1,0,1]
	v_add_f32_e32 v64, v64, v65
	ds_write_b32 v72, v64 offset:14336
	s_waitcnt lgkmcnt(9)
	v_pk_mul_f32 v[0:1], v[58:59], v[0:1]
	v_pk_mul_f32 v[12:13], v[12:13], v[42:43] op_sel_hi:[1,0]
	v_pk_fma_f32 v[0:1], v[60:61], v[2:3], v[0:1]
	v_pk_mul_f32 v[14:15], v[14:15], v[42:43] op_sel_hi:[1,0]
	v_add_f32_e32 v0, v0, v1
	v_pk_fma_f32 v[12:13], v[58:59], v[4:5], v[12:13]
	v_pk_fma_f32 v[14:15], v[60:61], v[6:7], v[14:15]
	v_add_f32_dpp v0, v0, v0 quad_perm:[1,0,3,2] row_mask:0xf bank_mask:0xf bound_ctrl:1
	v_pk_mul_f32 v[64:65], v[76:77], v[58:59]
	s_nop 0
	v_add_f32_dpp v0, v0, v0 quad_perm:[2,3,0,1] row_mask:0xf bank_mask:0xf bound_ctrl:1
	v_pk_fma_f32 v[64:65], v[78:79], v[60:61], v[64:65]
	s_nop 0
	v_add_f32_dpp v0, v0, v0 row_half_mirror row_mask:0xf bank_mask:0xf bound_ctrl:1
	v_add_f32_e32 v64, v64, v65
	ds_write_b32 v72, v64 offset:14848
	v_add_f32_dpp v0, v0, v0 row_mirror row_mask:0xf bank_mask:0xf bound_ctrl:1
	s_nop 0
	v_pk_fma_f32 v[58:59], v[8:9], v[0:1], v[12:13] op_sel_hi:[1,0,1]
	v_pk_fma_f32 v[60:61], v[10:11], v[0:1], v[14:15] op_sel_hi:[1,0,1]
	s_waitcnt lgkmcnt(3)
	v_pk_mul_f32 v[20:21], v[58:59], v[20:21]
	v_pk_mul_f32 v[32:33], v[32:33], v[62:63] op_sel_hi:[1,0]
	v_pk_fma_f32 v[20:21], v[60:61], v[22:23], v[20:21]
	v_pk_mul_f32 v[34:35], v[34:35], v[62:63] op_sel_hi:[1,0]
	v_add_f32_e32 v20, v20, v21
	v_pk_fma_f32 v[32:33], v[58:59], v[24:25], v[32:33]
	v_pk_fma_f32 v[34:35], v[60:61], v[26:27], v[34:35]
	v_add_f32_dpp v20, v20, v20 quad_perm:[1,0,3,2] row_mask:0xf bank_mask:0xf bound_ctrl:1
	v_pk_mul_f32 v[64:65], v[16:17], v[58:59]
	s_nop 0
	v_add_f32_dpp v20, v20, v20 quad_perm:[2,3,0,1] row_mask:0xf bank_mask:0xf bound_ctrl:1
	v_pk_fma_f32 v[64:65], v[18:19], v[60:61], v[64:65]
	s_nop 0
	v_add_f32_dpp v20, v20, v20 row_half_mirror row_mask:0xf bank_mask:0xf bound_ctrl:1
	v_add_f32_e32 v64, v64, v65
	ds_write_b32 v72, v64 offset:15360
	v_add_f32_dpp v20, v20, v20 row_mirror row_mask:0xf bank_mask:0xf bound_ctrl:1
	s_nop 0
	v_pk_fma_f32 v[58:59], v[28:29], v[20:21], v[32:33] op_sel_hi:[1,0,1]
	v_pk_fma_f32 v[60:61], v[30:31], v[20:21], v[34:35] op_sel_hi:[1,0,1]
	s_waitcnt lgkmcnt(3)
	v_pk_mul_f32 v[64:65], v[36:37], v[58:59]
	s_add_i32 s47, s47, 1
	v_pk_fma_f32 v[64:65], v[38:39], v[60:61], v[64:65]
	s_cmpk_eq_i32 s47, 0x100
	v_add_f32_e32 v64, v64, v65
	ds_write_b32 v72, v64 offset:15872
	s_waitcnt lgkmcnt(0)
	s_barrier
	s_cbranch_scc0 .Lscan_chunk

.LBB0_3535:
	v_mov_b32_e32 v150, v145
	v_mov_b32_e32 v151, v144
	s_lshl_b32 s13, s45, 7
	s_or_b32 s13, s13, s39
	v_lshl_add_u32 v152, v150, 3, s13
	v_mul_f32_e32 v150, 0xbfb8aa3b, v124
	v_exp_f32_e32 v154, v150
	v_mul_f32_e32 v150, 0xbfb8aa3b, v125
	v_exp_f32_e32 v155, v150
	s_lshl_b32 s13, s20, 8
	s_add_i32 s13, s13, s38
	v_add_u32_e32 v150, s13, v151
	v_pk_add_f32 v[154:155], v[154:155], 1.0 op_sel_hi:[1,0]
	v_mul_f32_e32 v156, 0xbfb8aa3b, v116
	v_exp_f32_e32 v156, v156
	v_ashrrev_i32_e32 v153, 31, v152
	v_mul_f32_e32 v157, 0xbfb8aa3b, v117
	v_rcp_f32_e32 v151, v155
	s_nop 0
	v_mul_f32_e32 v125, v125, v151
	v_exp_f32_e32 v157, v157
	s_nop 0
	v_pk_add_f32 v[156:157], v[156:157], 1.0 op_sel_hi:[1,0]
	v_rcp_f32_e32 v151, v154
	s_nop 0
	v_mul_f32_e32 v124, v124, v151
	v_pk_mul_f32 v[120:121], v[124:125], v[120:121]
	v_rcp_f32_e32 v124, v157
	s_nop 0
	v_mul_f32_e32 v117, v117, v124
	v_mul_f32_e32 v124, 0xbfb8aa3b, v126
	v_mul_f32_e32 v125, 0xbfb8aa3b, v127
	v_exp_f32_e32 v124, v124
	v_exp_f32_e32 v125, v125
	v_rcp_f32_e32 v151, v156
	s_nop 0
	v_mul_f32_e32 v116, v116, v151
	v_pk_mul_f32 v[154:155], v[116:117], v[112:113]
	v_pk_add_f32 v[124:125], v[124:125], 1.0 op_sel_hi:[1,0]
	v_mul_f32_e32 v112, 0xbfb8aa3b, v118
	v_exp_f32_e32 v112, v112
	v_rcp_f32_e32 v113, v125
	s_nop 0
	v_mul_f32_e32 v117, v127, v113
	v_mul_f32_e32 v113, 0xbfb8aa3b, v119
	v_exp_f32_e32 v113, v113
	s_nop 0
	v_pk_add_f32 v[112:113], v[112:113], 1.0 op_sel_hi:[1,0]
	v_rcp_f32_e32 v116, v124
	s_nop 0
	v_mul_f32_e32 v116, v126, v116
	v_pk_mul_f32 v[122:123], v[116:117], v[122:123]
	v_rcp_f32_e32 v116, v113
	s_nop 0
	v_mul_f32_e32 v113, v119, v116
	v_rcp_f32_e32 v116, v112
	s_nop 0
	v_mul_f32_e32 v112, v118, v116
	v_pk_mul_f32 v[124:125], v[112:113], v[114:115]
	v_mov_b64_e32 v[112:113], s[6:7]
	v_mad_i64_i32 v[116:117], s[22:23], v150, s44, v[112:113]
	v_lshlrev_b64 v[114:115], 1, v[152:153]
	v_lshl_add_u64 v[126:127], v[116:117], 0, v[114:115]
	v_mul_f32_e32 v117, 0xbfb8aa3b, v108
	v_cvt_pk_bf16_f32 v116, v120, v121
	v_exp_f32_e32 v120, v117
	v_mul_f32_e32 v117, 0xbfb8aa3b, v109
	v_exp_f32_e32 v121, v117
	v_cvt_pk_bf16_f32 v117, v122, v123
	v_cvt_pk_bf16_f32 v118, v154, v155
	v_cvt_pk_bf16_f32 v119, v124, v125
	v_pk_add_f32 v[120:121], v[120:121], 1.0 op_sel_hi:[1,0]
	global_store_dwordx4 v[126:127], v[116:119], off sc0 sc1
	s_nop 1
	v_mul_f32_e32 v116, 0xbfb8aa3b, v100
	v_exp_f32_e32 v116, v116
	v_rcp_f32_e32 v117, v121
	s_nop 0
	v_mul_f32_e32 v109, v109, v117
	v_mul_f32_e32 v117, 0xbfb8aa3b, v101
	v_exp_f32_e32 v117, v117
	s_nop 0
	v_pk_add_f32 v[116:117], v[116:117], 1.0 op_sel_hi:[1,0]
	v_rcp_f32_e32 v118, v120
	s_nop 0
	v_mul_f32_e32 v108, v108, v118
	v_pk_mul_f32 v[104:105], v[108:109], v[104:105]
	v_rcp_f32_e32 v108, v117
	s_nop 0
	v_mul_f32_e32 v101, v101, v108
	v_mul_f32_e32 v108, 0xbfb8aa3b, v110
	v_mul_f32_e32 v109, 0xbfb8aa3b, v111
	v_exp_f32_e32 v108, v108
	v_exp_f32_e32 v109, v109
	v_rcp_f32_e32 v117, v116
	s_nop 0
	v_mul_f32_e32 v100, v100, v117
	v_pk_mul_f32 v[100:101], v[100:101], v[96:97]
	v_pk_add_f32 v[108:109], v[108:109], 1.0 op_sel_hi:[1,0]
	v_mul_f32_e32 v96, 0xbfb8aa3b, v102
	v_exp_f32_e32 v96, v96
	v_rcp_f32_e32 v97, v109
	s_nop 0
	v_mul_f32_e32 v109, v111, v97
	v_mul_f32_e32 v97, 0xbfb8aa3b, v103
	v_exp_f32_e32 v97, v97
	s_nop 0
	v_pk_add_f32 v[96:97], v[96:97], 1.0 op_sel_hi:[1,0]
	v_rcp_f32_e32 v111, v108
	s_nop 0
	v_mul_f32_e32 v108, v110, v111
	v_pk_mul_f32 v[106:107], v[108:109], v[106:107]
	v_rcp_f32_e32 v108, v97
	s_nop 0
	v_mul_f32_e32 v97, v103, v108
	v_rcp_f32_e32 v103, v96
	s_nop 0
	v_mul_f32_e32 v96, v102, v103
	v_pk_mul_f32 v[102:103], v[96:97], v[98:99]
	v_add_u32_e32 v96, 16, v150
	v_mad_i64_i32 v[96:97], s[22:23], v96, s44, v[112:113]
	v_lshl_add_u64 v[108:109], v[96:97], 0, v[114:115]
	v_mul_f32_e32 v97, 0xbfb8aa3b, v92
	v_cvt_pk_bf16_f32 v96, v104, v105
	v_exp_f32_e32 v104, v97
	v_mul_f32_e32 v97, 0xbfb8aa3b, v93
	v_exp_f32_e32 v105, v97
	v_cvt_pk_bf16_f32 v98, v100, v101
	v_cvt_pk_bf16_f32 v99, v102, v103
	v_cvt_pk_bf16_f32 v97, v106, v107
	v_pk_add_f32 v[100:101], v[104:105], 1.0 op_sel_hi:[1,0]
	global_store_dwordx4 v[108:109], v[96:99], off sc0 sc1
	s_nop 1
	v_mul_f32_e32 v96, 0xbfb8aa3b, v84
	v_exp_f32_e32 v96, v96
	v_rcp_f32_e32 v97, v101
	s_nop 0
	v_mul_f32_e32 v93, v93, v97
	v_mul_f32_e32 v97, 0xbfb8aa3b, v85
	v_exp_f32_e32 v97, v97
	s_nop 0
	v_pk_add_f32 v[96:97], v[96:97], 1.0 op_sel_hi:[1,0]
	v_rcp_f32_e32 v98, v100
	s_nop 0
	v_mul_f32_e32 v92, v92, v98
	v_pk_mul_f32 v[88:89], v[92:93], v[88:89]
	v_rcp_f32_e32 v92, v97
	s_nop 0
	v_mul_f32_e32 v85, v85, v92
	v_mul_f32_e32 v92, 0xbfb8aa3b, v94
	v_mul_f32_e32 v93, 0xbfb8aa3b, v95
	v_exp_f32_e32 v92, v92
	v_exp_f32_e32 v93, v93
	v_rcp_f32_e32 v97, v96
	s_nop 0
	v_mul_f32_e32 v84, v84, v97
	v_pk_mul_f32 v[84:85], v[84:85], v[80:81]
	v_pk_add_f32 v[92:93], v[92:93], 1.0 op_sel_hi:[1,0]
	v_mul_f32_e32 v80, 0xbfb8aa3b, v86
	v_exp_f32_e32 v80, v80
	v_rcp_f32_e32 v81, v93
	s_nop 0
	v_mul_f32_e32 v93, v95, v81
	v_mul_f32_e32 v81, 0xbfb8aa3b, v87
	v_exp_f32_e32 v81, v81
	s_nop 0
	v_pk_add_f32 v[80:81], v[80:81], 1.0 op_sel_hi:[1,0]
	v_rcp_f32_e32 v95, v92
	s_nop 0
	v_mul_f32_e32 v92, v94, v95
	v_pk_mul_f32 v[90:91], v[92:93], v[90:91]
	v_rcp_f32_e32 v92, v81
	s_nop 0
	v_mul_f32_e32 v81, v87, v92
	v_rcp_f32_e32 v87, v80
	s_nop 0
	v_mul_f32_e32 v80, v86, v87
	v_pk_mul_f32 v[86:87], v[80:81], v[82:83]
	v_add_u32_e32 v80, 32, v150
	v_mad_i64_i32 v[80:81], s[22:23], v80, s44, v[112:113]
	v_lshl_add_u64 v[92:93], v[80:81], 0, v[114:115]
	v_mul_f32_e32 v81, 0xbfb8aa3b, v76
	v_cvt_pk_bf16_f32 v80, v88, v89
	v_exp_f32_e32 v88, v81
	v_mul_f32_e32 v81, 0xbfb8aa3b, v77
	v_exp_f32_e32 v89, v81
	v_cvt_pk_bf16_f32 v82, v84, v85
	v_cvt_pk_bf16_f32 v83, v86, v87
	v_cvt_pk_bf16_f32 v81, v90, v91
	v_pk_add_f32 v[84:85], v[88:89], 1.0 op_sel_hi:[1,0]
	global_store_dwordx4 v[92:93], v[80:83], off sc0 sc1
	s_nop 1
	v_mul_f32_e32 v80, 0xbfb8aa3b, v68
	v_exp_f32_e32 v80, v80
	v_rcp_f32_e32 v81, v85
	s_nop 0
	v_mul_f32_e32 v77, v77, v81
	v_mul_f32_e32 v81, 0xbfb8aa3b, v69
	v_exp_f32_e32 v81, v81
	s_nop 0
	v_pk_add_f32 v[80:81], v[80:81], 1.0 op_sel_hi:[1,0]
	v_rcp_f32_e32 v82, v84
	s_nop 0
	v_mul_f32_e32 v76, v76, v82
	v_pk_mul_f32 v[72:73], v[76:77], v[72:73]
	v_rcp_f32_e32 v76, v81
	s_nop 0
	v_mul_f32_e32 v69, v69, v76
	v_mul_f32_e32 v76, 0xbfb8aa3b, v78
	v_mul_f32_e32 v77, 0xbfb8aa3b, v79
	v_exp_f32_e32 v76, v76
	v_exp_f32_e32 v77, v77
	v_rcp_f32_e32 v81, v80
	s_nop 0
	v_mul_f32_e32 v68, v68, v81
	v_pk_mul_f32 v[68:69], v[68:69], v[64:65]
	v_pk_add_f32 v[76:77], v[76:77], 1.0 op_sel_hi:[1,0]
	v_mul_f32_e32 v64, 0xbfb8aa3b, v70
	v_exp_f32_e32 v64, v64
	v_rcp_f32_e32 v65, v77
	s_nop 0
	v_mul_f32_e32 v77, v79, v65
	v_mul_f32_e32 v65, 0xbfb8aa3b, v71
	v_exp_f32_e32 v65, v65
	s_nop 0
	v_pk_add_f32 v[64:65], v[64:65], 1.0 op_sel_hi:[1,0]
	v_rcp_f32_e32 v79, v76
	s_nop 0
	v_mul_f32_e32 v76, v78, v79
	v_pk_mul_f32 v[74:75], v[76:77], v[74:75]
	v_rcp_f32_e32 v76, v65
	s_nop 0
	v_mul_f32_e32 v65, v71, v76
	v_rcp_f32_e32 v71, v64
	s_nop 0
	v_mul_f32_e32 v64, v70, v71
	v_pk_mul_f32 v[70:71], v[64:65], v[66:67]
	v_add_u32_e32 v64, 48, v150
	v_mad_i64_i32 v[64:65], s[22:23], v64, s44, v[112:113]
	v_mul_f32_e32 v66, 0xbfb8aa3b, v60
	v_lshl_add_u64 v[76:77], v[64:65], 0, v[114:115]
	v_cvt_pk_bf16_f32 v64, v72, v73
	v_exp_f32_e32 v72, v66
	v_mul_f32_e32 v66, 0xbfb8aa3b, v61
	v_exp_f32_e32 v73, v66
	v_cvt_pk_bf16_f32 v65, v74, v75
	v_cvt_pk_bf16_f32 v66, v68, v69
	v_cvt_pk_bf16_f32 v67, v70, v71
	global_store_dwordx4 v[76:77], v[64:67], off sc0 sc1
	s_nop 1
	v_pk_add_f32 v[64:65], v[72:73], 1.0 op_sel_hi:[1,0]
	v_mul_f32_e32 v66, 0xbfb8aa3b, v52
	v_exp_f32_e32 v66, v66
	v_add_u32_e32 v69, 0x80, v150
	v_rcp_f32_e32 v67, v65
	s_nop 0
	v_mul_f32_e32 v61, v61, v67
	v_mul_f32_e32 v67, 0xbfb8aa3b, v53
	v_exp_f32_e32 v67, v67
	s_nop 0
	v_pk_add_f32 v[66:67], v[66:67], 1.0 op_sel_hi:[1,0]
	v_rcp_f32_e32 v65, v64
	s_nop 0
	v_mul_f32_e32 v60, v60, v65
	v_pk_mul_f32 v[56:57], v[60:61], v[56:57]
	v_rcp_f32_e32 v60, v67
	s_nop 0
	v_mul_f32_e32 v53, v53, v60
	v_mul_f32_e32 v60, 0xbfb8aa3b, v62
	v_mul_f32_e32 v61, 0xbfb8aa3b, v63
	v_exp_f32_e32 v60, v60
	v_exp_f32_e32 v61, v61
	v_rcp_f32_e32 v64, v66
	s_nop 0
	v_mul_f32_e32 v52, v52, v64
	v_pk_mul_f32 v[52:53], v[52:53], v[48:49]
	v_pk_add_f32 v[60:61], v[60:61], 1.0 op_sel_hi:[1,0]
	v_mul_f32_e32 v48, 0xbfb8aa3b, v54
	v_exp_f32_e32 v48, v48
	v_rcp_f32_e32 v49, v61
	s_nop 0
	v_mul_f32_e32 v61, v63, v49
	v_mul_f32_e32 v49, 0xbfb8aa3b, v55
	v_exp_f32_e32 v49, v49
	s_nop 0
	v_pk_add_f32 v[48:49], v[48:49], 1.0 op_sel_hi:[1,0]
	v_rcp_f32_e32 v63, v60
	s_nop 0
	v_mul_f32_e32 v60, v62, v63
	v_pk_mul_f32 v[58:59], v[60:61], v[58:59]
	v_rcp_f32_e32 v60, v49
	s_nop 0
	v_mul_f32_e32 v49, v55, v60
	v_rcp_f32_e32 v55, v48
	s_nop 0
	v_mul_f32_e32 v48, v54, v55
	v_pk_mul_f32 v[54:55], v[48:49], v[50:51]
	v_mad_i64_i32 v[48:49], s[22:23], v69, s44, v[112:113]
	v_lshl_add_u64 v[60:61], v[48:49], 0, v[114:115]
	v_mul_f32_e32 v49, 0xbfb8aa3b, v44
	v_cvt_pk_bf16_f32 v48, v56, v57
	v_exp_f32_e32 v56, v49
	v_mul_f32_e32 v49, 0xbfb8aa3b, v45
	v_exp_f32_e32 v57, v49
	v_cvt_pk_bf16_f32 v50, v52, v53
	v_cvt_pk_bf16_f32 v51, v54, v55
	v_cvt_pk_bf16_f32 v49, v58, v59
	v_pk_add_f32 v[52:53], v[56:57], 1.0 op_sel_hi:[1,0]
	global_store_dwordx4 v[60:61], v[48:51], off sc0 sc1
	s_nop 1
	v_mul_f32_e32 v48, 0xbfb8aa3b, v36
	v_exp_f32_e32 v48, v48
	v_rcp_f32_e32 v49, v53
	s_nop 0
	v_mul_f32_e32 v45, v45, v49
	v_mul_f32_e32 v49, 0xbfb8aa3b, v37
	v_exp_f32_e32 v49, v49
	s_nop 0
	v_pk_add_f32 v[48:49], v[48:49], 1.0 op_sel_hi:[1,0]
	v_rcp_f32_e32 v50, v52
	s_nop 0
	v_mul_f32_e32 v44, v44, v50
	v_pk_mul_f32 v[40:41], v[44:45], v[40:41]
	v_rcp_f32_e32 v44, v49
	s_nop 0
	v_mul_f32_e32 v37, v37, v44
	v_mul_f32_e32 v44, 0xbfb8aa3b, v46
	v_mul_f32_e32 v45, 0xbfb8aa3b, v47
	v_exp_f32_e32 v44, v44
	v_exp_f32_e32 v45, v45
	v_rcp_f32_e32 v49, v48
	s_nop 0
	v_mul_f32_e32 v36, v36, v49
	v_pk_mul_f32 v[36:37], v[36:37], v[32:33]
	v_pk_add_f32 v[44:45], v[44:45], 1.0 op_sel_hi:[1,0]
	v_mul_f32_e32 v32, 0xbfb8aa3b, v38
	v_exp_f32_e32 v32, v32
	v_rcp_f32_e32 v33, v45
	s_nop 0
	v_mul_f32_e32 v45, v47, v33
	v_mul_f32_e32 v33, 0xbfb8aa3b, v39
	v_exp_f32_e32 v33, v33
	s_nop 0
	v_pk_add_f32 v[32:33], v[32:33], 1.0 op_sel_hi:[1,0]
	v_rcp_f32_e32 v47, v44
	s_nop 0
	v_mul_f32_e32 v44, v46, v47
	v_pk_mul_f32 v[42:43], v[44:45], v[42:43]
	v_rcp_f32_e32 v44, v33
	s_nop 0
	v_mul_f32_e32 v33, v39, v44
	v_rcp_f32_e32 v39, v32
	s_nop 0
	v_mul_f32_e32 v32, v38, v39
	v_pk_mul_f32 v[38:39], v[32:33], v[34:35]
	v_add_u32_e32 v32, 0x90, v150
	v_mad_i64_i32 v[32:33], s[22:23], v32, s44, v[112:113]
	v_lshl_add_u64 v[44:45], v[32:33], 0, v[114:115]
	v_mul_f32_e32 v33, 0xbfb8aa3b, v28
	v_cvt_pk_bf16_f32 v32, v40, v41
	v_exp_f32_e32 v40, v33
	v_mul_f32_e32 v33, 0xbfb8aa3b, v29
	v_exp_f32_e32 v41, v33
	v_cvt_pk_bf16_f32 v34, v36, v37
	v_cvt_pk_bf16_f32 v35, v38, v39
	v_cvt_pk_bf16_f32 v33, v42, v43
	v_pk_add_f32 v[36:37], v[40:41], 1.0 op_sel_hi:[1,0]
	global_store_dwordx4 v[44:45], v[32:35], off sc0 sc1
	s_nop 1
	v_mul_f32_e32 v32, 0xbfb8aa3b, v20
	v_exp_f32_e32 v32, v32
	v_rcp_f32_e32 v33, v37
	s_nop 0
	v_mul_f32_e32 v29, v29, v33
	v_mul_f32_e32 v33, 0xbfb8aa3b, v21
	v_exp_f32_e32 v33, v33
	s_nop 0
	v_pk_add_f32 v[32:33], v[32:33], 1.0 op_sel_hi:[1,0]
	v_rcp_f32_e32 v34, v36
	s_nop 0
	v_mul_f32_e32 v28, v28, v34
	v_pk_mul_f32 v[24:25], v[28:29], v[24:25]
	v_rcp_f32_e32 v28, v33
	s_nop 0
	v_mul_f32_e32 v21, v21, v28
	v_mul_f32_e32 v28, 0xbfb8aa3b, v30
	v_mul_f32_e32 v29, 0xbfb8aa3b, v31
	v_exp_f32_e32 v28, v28
	v_exp_f32_e32 v29, v29
	v_rcp_f32_e32 v33, v32
	s_nop 0
	v_mul_f32_e32 v20, v20, v33
	v_pk_mul_f32 v[20:21], v[20:21], v[16:17]
	v_pk_add_f32 v[28:29], v[28:29], 1.0 op_sel_hi:[1,0]
	v_mul_f32_e32 v16, 0xbfb8aa3b, v22
	v_exp_f32_e32 v16, v16
	v_rcp_f32_e32 v17, v29
	s_nop 0
	v_mul_f32_e32 v29, v31, v17
	v_mul_f32_e32 v17, 0xbfb8aa3b, v23
	v_exp_f32_e32 v17, v17
	s_nop 0
	v_pk_add_f32 v[16:17], v[16:17], 1.0 op_sel_hi:[1,0]
	v_rcp_f32_e32 v31, v28
	s_nop 0
	v_mul_f32_e32 v28, v30, v31
	v_pk_mul_f32 v[26:27], v[28:29], v[26:27]
	v_rcp_f32_e32 v28, v17
	s_nop 0
	v_mul_f32_e32 v17, v23, v28
	v_rcp_f32_e32 v23, v16
	s_nop 0
	v_mul_f32_e32 v16, v22, v23
	v_pk_mul_f32 v[22:23], v[16:17], v[18:19]
	v_add_u32_e32 v16, 0xa0, v150
	v_mad_i64_i32 v[16:17], s[22:23], v16, s44, v[112:113]
	v_lshl_add_u64 v[28:29], v[16:17], 0, v[114:115]
	v_mul_f32_e32 v17, 0xbfb8aa3b, v12
	v_cvt_pk_bf16_f32 v16, v24, v25
	v_exp_f32_e32 v24, v17
	v_mul_f32_e32 v17, 0xbfb8aa3b, v13
	v_exp_f32_e32 v25, v17
	v_cvt_pk_bf16_f32 v18, v20, v21
	v_cvt_pk_bf16_f32 v19, v22, v23
	v_cvt_pk_bf16_f32 v17, v26, v27
	v_pk_add_f32 v[20:21], v[24:25], 1.0 op_sel_hi:[1,0]
	global_store_dwordx4 v[28:29], v[16:19], off sc0 sc1
	s_nop 1
	v_mul_f32_e32 v16, 0xbfb8aa3b, v4
	v_exp_f32_e32 v16, v16
	v_rcp_f32_e32 v17, v21
	s_nop 0
	v_mul_f32_e32 v13, v13, v17
	v_mul_f32_e32 v17, 0xbfb8aa3b, v5
	v_exp_f32_e32 v17, v17
	s_nop 0
	v_pk_add_f32 v[16:17], v[16:17], 1.0 op_sel_hi:[1,0]
	v_rcp_f32_e32 v18, v20
	s_nop 0
	v_mul_f32_e32 v12, v12, v18
	v_pk_mul_f32 v[8:9], v[12:13], v[8:9]
	v_rcp_f32_e32 v12, v17
	s_nop 0
	v_mul_f32_e32 v5, v5, v12
	v_mul_f32_e32 v12, 0xbfb8aa3b, v14
	v_mul_f32_e32 v13, 0xbfb8aa3b, v15
	v_exp_f32_e32 v12, v12
	v_exp_f32_e32 v13, v13
	v_rcp_f32_e32 v17, v16
	s_nop 0
	v_mul_f32_e32 v4, v4, v17
	v_pk_mul_f32 v[4:5], v[4:5], v[0:1]
	v_pk_add_f32 v[12:13], v[12:13], 1.0 op_sel_hi:[1,0]
	v_mul_f32_e32 v0, 0xbfb8aa3b, v6
	v_exp_f32_e32 v0, v0
	v_rcp_f32_e32 v1, v13
	s_nop 0
	v_mul_f32_e32 v13, v15, v1
	v_mul_f32_e32 v1, 0xbfb8aa3b, v7
	v_exp_f32_e32 v1, v1
	s_nop 0
	v_pk_add_f32 v[0:1], v[0:1], 1.0 op_sel_hi:[1,0]
	v_rcp_f32_e32 v15, v12
	s_nop 0
	v_mul_f32_e32 v12, v14, v15
	v_pk_mul_f32 v[10:11], v[12:13], v[10:11]
	v_rcp_f32_e32 v12, v1
	s_nop 0
	v_mul_f32_e32 v1, v7, v12
	v_rcp_f32_e32 v7, v0
	s_nop 0
	v_mul_f32_e32 v0, v6, v7
	v_pk_mul_f32 v[6:7], v[0:1], v[2:3]
	v_add_u32_e32 v0, 0xb0, v150
	v_mad_i64_i32 v[0:1], s[22:23], v0, s44, v[112:113]
	v_lshl_add_u64 v[12:13], v[0:1], 0, v[114:115]
	v_cvt_pk_bf16_f32 v0, v8, v9
	v_cvt_pk_bf16_f32 v1, v10, v11
	v_cvt_pk_bf16_f32 v2, v4, v5
	v_cvt_pk_bf16_f32 v3, v6, v7
	global_store_dwordx4 v[12:13], v[0:3], off sc0 sc1
	s_nop 1
	s_andn2_b64 vcc, exec, s[0:1]
	s_mov_b64 s[0:1], -1
	s_cbranch_vccnz .LBB0_3528
	s_andn2_b64 vcc, exec, s[4:5]
	s_cbranch_vccnz .LBB0_3527
	s_barrier
	s_branch .LBB0_3527
